# residual-update epilogues of phases 7/10/12 rewritten: loads batched (16B vectors) instead of 64 serialized load-wait-store round trips; attention instruction trims
# speedup vs baseline: 1.1365x; 1.0454x over previous
.LBB0_277:
	s_mov_b64 s[8:9], 0x1000
	global_load_dword v22, v[0:1], off
	global_load_dword v23, v[0:1], off offset:4
	global_load_dword v24, v[0:1], off offset:8
	global_load_dword v25, v[0:1], off offset:12
	global_load_dword v26, v[0:1], off offset:16
	global_load_dword v27, v[0:1], off offset:20
	global_load_dword v28, v[0:1], off offset:24
	global_load_dword v29, v[0:1], off offset:28
	global_load_dword v30, v[0:1], off offset:32
	global_load_dword v31, v[0:1], off offset:36
	global_load_dword v32, v[0:1], off offset:40
	global_load_dword v33, v[0:1], off offset:44
	global_load_dword v34, v[0:1], off offset:48
	global_load_dword v35, v[0:1], off offset:52
	global_load_dword v36, v[0:1], off offset:56
	global_load_dword v37, v[0:1], off offset:60
	global_load_dword v38, v[2:3], off
	global_load_dword v39, v[2:3], off offset:1024
	global_load_dword v40, v[2:3], off offset:2048
	global_load_dword v41, v[2:3], off offset:3072
	v_lshl_add_u64 v[2:3], v[2:3], 0, s[8:9]
	global_load_dword v42, v[2:3], off
	global_load_dword v43, v[2:3], off offset:1024
	global_load_dword v44, v[2:3], off offset:2048
	global_load_dword v45, v[2:3], off offset:3072
	v_lshl_add_u64 v[2:3], v[2:3], 0, s[8:9]
	global_load_dword v46, v[2:3], off
	global_load_dword v47, v[2:3], off offset:1024
	global_load_dword v48, v[2:3], off offset:2048
	global_load_dword v49, v[2:3], off offset:3072
	v_lshl_add_u64 v[2:3], v[2:3], 0, s[8:9]
	global_load_dword v50, v[2:3], off
	global_load_dword v51, v[2:3], off offset:1024
	global_load_dword v52, v[2:3], off offset:2048
	global_load_dword v53, v[2:3], off offset:3072
	v_lshl_add_u64 v[2:3], v[2:3], 0, s[8:9]
	v_add_u32_e32 v7, 16, v7
	v_cmp_ge_i32_e32 vcc, v7, v6
	v_lshl_add_u64 v[0:1], v[0:1], 0, 64
	s_nop 1
	s_or_b64 s[6:7], vcc, s[6:7]
	s_waitcnt vmcnt(0)
	v_fmac_f32_e32 v8, v22, v38
	v_fmac_f32_e32 v8, v23, v39
	v_fmac_f32_e32 v8, v24, v40
	v_fmac_f32_e32 v8, v25, v41
	v_fmac_f32_e32 v8, v26, v42
	v_fmac_f32_e32 v8, v27, v43
	v_fmac_f32_e32 v8, v28, v44
	v_fmac_f32_e32 v8, v29, v45
	v_fmac_f32_e32 v8, v30, v46
	v_fmac_f32_e32 v8, v31, v47
	v_fmac_f32_e32 v8, v32, v48
	v_fmac_f32_e32 v8, v33, v49
	v_fmac_f32_e32 v8, v34, v50
	v_fmac_f32_e32 v8, v35, v51
	v_fmac_f32_e32 v8, v36, v52
	v_fmac_f32_e32 v8, v37, v53
	s_andn2_b64 exec, exec, s[6:7]
	s_cbranch_execnz .LBB0_277
	s_or_b64 exec, exec, s[6:7]
	v_lshlrev_b32_e32 v0, 2, v20
	v_cmp_gt_i32_e32 vcc, 32, v20
	ds_write_b32 v0, v8
	s_waitcnt lgkmcnt(0)
	s_barrier
	s_and_saveexec_b64 s[6:7], vcc
	s_cbranch_execz .LBB0_280
	ds_read2_b32 v[2:3], v0 offset1:32
	v_readlane_b32 s5, v251, 46
	s_waitcnt lgkmcnt(0)
	v_add_f32_e32 v1, v3, v2
	ds_read2_b32 v[2:3], v0 offset0:64 offset1:96
	s_waitcnt lgkmcnt(0)
	v_add_f32_e32 v1, v1, v2
	v_add_f32_e32 v1, v1, v3
	ds_read2_b32 v[2:3], v0 offset0:128 offset1:160
	s_waitcnt lgkmcnt(0)
	v_add_f32_e32 v1, v1, v2
	v_add_f32_e32 v2, v1, v3
	ds_read2_b32 v[0:1], v0 offset0:192 offset1:224
	s_waitcnt lgkmcnt(0)
	v_add_f32_e32 v0, v2, v0
	v_add_f32_e32 v2, v0, v1
	v_add_u32_e32 v0, s5, v20
	v_ashrrev_i32_e32 v1, 31, v0
	v_lshl_add_u64 v[0:1], v[0:1], 2, s[0:1]
	v_add_co_u32_e32 v0, vcc, 0xe280000, v0
	s_nop 1
	v_addc_co_u32_e32 v1, vcc, 0, v1, vcc
	global_store_dword v[0:1], v2, off

.LBB0_1112:
	s_cmp_lt_i32 s40, 0
	s_cbranch_scc1 .LBB0_1111
	v_mov_b32_e32 v0, v161
	v_mov_b32_e32 v31, v186
	s_add_i32 s12, s41, 0xffffe000
	s_mov_b32 s13, s77
	s_lshl_b64 s[78:79], s[12:13], 11
	v_lshlrev_b32_e32 v1, 4, v31
	v_ashrrev_i32_e32 v32, 3, v31
	v_and_b32_e32 v30, 0x70, v1
	s_add_u32 vcc_lo, s39, s78
	v_readlane_b32 s13, v254, 36
	v_lshl_or_b32 v34, v32, 11, v30
	s_addc_u32 vcc_hi, s13, s79
	v_add_u32_e32 v35, 0x10000, v34
	v_add_u32_e32 v38, 0x20000, v34
	v_add_u32_e32 v39, 0x30000, v34
	s_barrier
	global_load_dwordx4 v[14:17], v34, vcc
	global_load_dwordx4 v[18:21], v35, vcc
	global_load_dwordx4 v[22:25], v38, vcc
	global_load_dwordx4 v[26:29], v39, vcc
	global_load_dwordx4 v[46:49], v34, s[10:11]
	global_load_dwordx4 v[50:53], v35, s[10:11]
	v_lshrrev_b32_e32 v33, 1, v31
	v_and_b32_e32 v31, 31, v31
	v_and_or_b32 v45, v33, 32, v31
	v_and_or_b32 v31, v33, s44, v31
	v_and_b32_e32 v78, 16, v33
	v_mad_u64_u32 v[32:33], s[78:79], v32, s43, v[30:31]
	v_mad_u64_u32 v[36:37], s[78:79], v31, s43, v[78:79]
	v_mad_u32_u24 v33, v45, s43, v78
	v_mov_b32_e32 v1, v0
	v_mov_b32_e32 v2, v0
	v_mov_b32_e32 v3, v0
	v_mov_b32_e32 v4, v0
	v_mov_b32_e32 v5, v0
	v_mov_b32_e32 v6, v0
	v_mov_b32_e32 v7, v0
	s_waitcnt vmcnt(6)
	v_mov_b32_e32 v8, v0
	v_mov_b32_e32 v9, v0
	v_mov_b32_e32 v10, v0
	v_mov_b32_e32 v11, v0
	v_mov_b32_e32 v12, v0
	v_mov_b32_e32 v13, v0
	s_waitcnt vmcnt(5)
	ds_write_b128 v32, v[14:17]
	s_waitcnt vmcnt(4)
	ds_write_b128 v32, v[18:21] offset:4608
	s_waitcnt vmcnt(3)
	ds_write_b128 v32, v[22:25] offset:9216
	s_waitcnt vmcnt(2)
	ds_write_b128 v32, v[26:29] offset:13824
	s_waitcnt vmcnt(1)
	ds_write_b128 v32, v[46:49] offset:36864
	s_waitcnt vmcnt(0)
	ds_write_b128 v32, v[50:53] offset:41472
	global_load_dwordx4 v[46:49], v34, vcc offset:128
	global_load_dwordx4 v[50:53], v35, vcc offset:128
	global_load_dwordx4 v[58:61], v38, vcc offset:128
	global_load_dwordx4 v[62:65], v39, vcc offset:128
	global_load_dwordx4 v[66:69], v34, s[18:19]
	global_load_dwordx4 v[70:73], v35, s[18:19]
	s_waitcnt lgkmcnt(0)
	s_barrier
	ds_read_b128 v[74:77], v36
	ds_read_b128 v[78:81], v36 offset:4608
	ds_read_b128 v[82:85], v36 offset:32
	ds_read_b128 v[86:89], v33 offset:36864
	v_mov_b32_e32 v14, v0
	v_mov_b32_e32 v15, v0
	ds_read_b128 v[90:93], v36 offset:4640
	ds_read_b128 v[94:97], v33 offset:36896
	s_waitcnt lgkmcnt(2)
	v_mfma_f32_32x32x16_bf16 v[16:31], v[74:77], v[86:89], v[0:15]
	v_mfma_f32_32x32x16_bf16 v[0:15], v[78:81], v[86:89], v[0:15]
	s_waitcnt lgkmcnt(0)
	v_mfma_f32_32x32x16_bf16 v[16:31], v[82:85], v[94:97], v[16:31]
	v_mfma_f32_32x32x16_bf16 v[0:15], v[90:93], v[94:97], v[0:15]
	ds_read_b128 v[74:77], v36 offset:64
	ds_read_b128 v[82:85], v36 offset:4672
	ds_read_b128 v[78:81], v33 offset:36928
	s_waitcnt lgkmcnt(0)
	v_mfma_f32_32x32x16_bf16 v[16:31], v[74:77], v[78:81], v[16:31]
	v_mfma_f32_32x32x16_bf16 v[0:15], v[82:85], v[78:81], v[0:15]
	global_load_dwordx4 v[74:77], v34, vcc offset:256
	global_load_dwordx4 v[78:81], v35, vcc offset:256
	global_load_dwordx4 v[82:85], v38, vcc offset:256
	global_load_dwordx4 v[86:89], v39, vcc offset:256
	global_load_dwordx4 v[90:93], v34, s[20:21]
	global_load_dwordx4 v[94:97], v35, s[20:21]
	s_waitcnt vmcnt(11)
	ds_write_b128 v32, v[46:49] offset:18432
	s_waitcnt vmcnt(10)
	ds_write_b128 v32, v[50:53] offset:23040
	s_waitcnt vmcnt(9)
	ds_write_b128 v32, v[58:61] offset:27648
	s_waitcnt vmcnt(8)
	ds_write_b128 v32, v[62:65] offset:32256
	ds_read_b128 v[46:49], v36 offset:96
	ds_read_b128 v[58:61], v36 offset:4704
	ds_read_b128 v[50:53], v33 offset:36960
	s_waitcnt vmcnt(7)
	ds_write_b128 v32, v[66:69] offset:46080
	s_waitcnt vmcnt(6)
	ds_write_b128 v32, v[70:73] offset:50688
	s_waitcnt lgkmcnt(2)
	v_mfma_f32_32x32x16_bf16 v[16:31], v[46:49], v[50:53], v[16:31]
	s_waitcnt lgkmcnt(0)
	s_barrier
	v_mfma_f32_32x32x16_bf16 v[0:15], v[58:61], v[50:53], v[0:15]
	ds_read_b128 v[46:49], v36 offset:18432
	ds_read_b128 v[58:61], v36 offset:23040
	ds_read_b128 v[50:53], v33 offset:46080
	ds_read_b128 v[62:65], v36 offset:18464
	ds_read_b128 v[66:69], v36 offset:23072
	ds_read_b128 v[70:73], v33 offset:46112
	s_waitcnt lgkmcnt(3)
	v_mfma_f32_32x32x16_bf16 v[16:31], v[46:49], v[50:53], v[16:31]
	v_mfma_f32_32x32x16_bf16 v[0:15], v[58:61], v[50:53], v[0:15]
	global_load_dwordx4 v[46:49], v34, vcc offset:384
	global_load_dwordx4 v[50:53], v35, vcc offset:384
	global_load_dwordx4 v[58:61], v38, vcc offset:384
	global_load_dwordx4 v[98:101], v39, vcc offset:384
	global_load_dwordx4 v[102:105], v34, s[22:23]
	global_load_dwordx4 v[106:109], v35, s[22:23]
	ds_read_b128 v[110:113], v36 offset:18496
	ds_read_b128 v[114:117], v36 offset:23104
	ds_read_b128 v[118:121], v33 offset:46144
	s_waitcnt vmcnt(11)
	ds_write_b128 v32, v[74:77]
	s_waitcnt vmcnt(10)
	ds_write_b128 v32, v[78:81] offset:4608
	s_waitcnt vmcnt(9)
	ds_write_b128 v32, v[82:85] offset:9216
	s_waitcnt vmcnt(8)
	ds_write_b128 v32, v[86:89] offset:13824
	s_waitcnt lgkmcnt(7)
	v_mfma_f32_32x32x16_bf16 v[16:31], v[62:65], v[70:73], v[16:31]
	v_mfma_f32_32x32x16_bf16 v[0:15], v[66:69], v[70:73], v[0:15]
	ds_read_b128 v[62:65], v36 offset:18528
	ds_read_b128 v[66:69], v36 offset:23136
	ds_read_b128 v[70:73], v33 offset:46176
	s_waitcnt vmcnt(7)
	ds_write_b128 v32, v[90:93] offset:36864
	s_waitcnt vmcnt(6)
	ds_write_b128 v32, v[94:97] offset:41472
	s_waitcnt lgkmcnt(0)
	s_barrier
	v_mfma_f32_32x32x16_bf16 v[16:31], v[110:113], v[118:121], v[16:31]
	v_mfma_f32_32x32x16_bf16 v[0:15], v[114:117], v[118:121], v[0:15]
	v_mfma_f32_32x32x16_bf16 v[16:31], v[62:65], v[70:73], v[16:31]
	v_mfma_f32_32x32x16_bf16 v[0:15], v[66:69], v[70:73], v[0:15]
	ds_read_b128 v[62:65], v36
	ds_read_b128 v[70:73], v36 offset:4608
	ds_read_b128 v[66:69], v33 offset:36864
	ds_read_b128 v[74:77], v36 offset:32
	ds_read_b128 v[78:81], v36 offset:4640
	ds_read_b128 v[82:85], v33 offset:36896
	s_waitcnt lgkmcnt(3)
	v_mfma_f32_32x32x16_bf16 v[16:31], v[62:65], v[66:69], v[16:31]
	v_mfma_f32_32x32x16_bf16 v[0:15], v[70:73], v[66:69], v[0:15]
	global_load_dwordx4 v[62:65], v34, vcc offset:512
	global_load_dwordx4 v[66:69], v35, vcc offset:512
	global_load_dwordx4 v[70:73], v38, vcc offset:512
	global_load_dwordx4 v[86:89], v39, vcc offset:512
	global_load_dwordx4 v[90:93], v34, s[24:25]
	global_load_dwordx4 v[94:97], v35, s[24:25]
	ds_read_b128 v[110:113], v36 offset:64
	ds_read_b128 v[114:117], v36 offset:4672
	ds_read_b128 v[118:121], v33 offset:36928
	s_waitcnt vmcnt(11)
	ds_write_b128 v32, v[46:49] offset:18432
	s_waitcnt vmcnt(10)
	ds_write_b128 v32, v[50:53] offset:23040
	s_waitcnt vmcnt(9)
	ds_write_b128 v32, v[58:61] offset:27648
	s_waitcnt vmcnt(8)
	ds_write_b128 v32, v[98:101] offset:32256
	s_waitcnt lgkmcnt(7)
	v_mfma_f32_32x32x16_bf16 v[16:31], v[74:77], v[82:85], v[16:31]
	v_mfma_f32_32x32x16_bf16 v[0:15], v[78:81], v[82:85], v[0:15]
	ds_read_b128 v[46:49], v36 offset:96
	ds_read_b128 v[50:53], v36 offset:4704
	ds_read_b128 v[58:61], v33 offset:36960
	s_waitcnt vmcnt(7)
	ds_write_b128 v32, v[102:105] offset:46080
	s_waitcnt vmcnt(6)
	ds_write_b128 v32, v[106:109] offset:50688
	s_waitcnt lgkmcnt(0)
	s_barrier
	v_mfma_f32_32x32x16_bf16 v[16:31], v[110:113], v[118:121], v[16:31]
	v_mfma_f32_32x32x16_bf16 v[0:15], v[114:117], v[118:121], v[0:15]
	v_mfma_f32_32x32x16_bf16 v[16:31], v[46:49], v[58:61], v[16:31]
	v_mfma_f32_32x32x16_bf16 v[0:15], v[50:53], v[58:61], v[0:15]
	ds_read_b128 v[46:49], v36 offset:18432
	ds_read_b128 v[58:61], v36 offset:23040
	ds_read_b128 v[50:53], v33 offset:46080
	ds_read_b128 v[74:77], v36 offset:18464
	ds_read_b128 v[78:81], v36 offset:23072
	ds_read_b128 v[82:85], v33 offset:46112
	s_waitcnt lgkmcnt(3)
	v_mfma_f32_32x32x16_bf16 v[16:31], v[46:49], v[50:53], v[16:31]
	v_mfma_f32_32x32x16_bf16 v[0:15], v[58:61], v[50:53], v[0:15]
	global_load_dwordx4 v[46:49], v34, vcc offset:640
	global_load_dwordx4 v[50:53], v35, vcc offset:640
	global_load_dwordx4 v[58:61], v38, vcc offset:640
	global_load_dwordx4 v[98:101], v39, vcc offset:640
	global_load_dwordx4 v[102:105], v34, s[26:27]
	global_load_dwordx4 v[106:109], v35, s[26:27]
	ds_read_b128 v[110:113], v36 offset:18496
	ds_read_b128 v[114:117], v36 offset:23104
	ds_read_b128 v[118:121], v33 offset:46144
	s_waitcnt vmcnt(11)
	ds_write_b128 v32, v[62:65]
	s_waitcnt vmcnt(10)
	ds_write_b128 v32, v[66:69] offset:4608
	s_waitcnt vmcnt(9)
	ds_write_b128 v32, v[70:73] offset:9216
	s_waitcnt vmcnt(8)
	ds_write_b128 v32, v[86:89] offset:13824
	s_waitcnt lgkmcnt(7)
	v_mfma_f32_32x32x16_bf16 v[16:31], v[74:77], v[82:85], v[16:31]
	v_mfma_f32_32x32x16_bf16 v[0:15], v[78:81], v[82:85], v[0:15]
	ds_read_b128 v[62:65], v36 offset:18528
	ds_read_b128 v[66:69], v36 offset:23136
	ds_read_b128 v[70:73], v33 offset:46176
	s_waitcnt vmcnt(7)
	ds_write_b128 v32, v[90:93] offset:36864
	s_waitcnt vmcnt(6)
	ds_write_b128 v32, v[94:97] offset:41472
	s_waitcnt lgkmcnt(0)
	s_barrier
	v_mfma_f32_32x32x16_bf16 v[16:31], v[110:113], v[118:121], v[16:31]
	v_mfma_f32_32x32x16_bf16 v[0:15], v[114:117], v[118:121], v[0:15]
	v_mfma_f32_32x32x16_bf16 v[16:31], v[62:65], v[70:73], v[16:31]
	v_mfma_f32_32x32x16_bf16 v[0:15], v[66:69], v[70:73], v[0:15]
	ds_read_b128 v[62:65], v36
	ds_read_b128 v[70:73], v36 offset:4608
	ds_read_b128 v[66:69], v33 offset:36864
	ds_read_b128 v[74:77], v36 offset:32
	ds_read_b128 v[78:81], v36 offset:4640
	ds_read_b128 v[82:85], v33 offset:36896
	s_waitcnt lgkmcnt(3)
	v_mfma_f32_32x32x16_bf16 v[16:31], v[62:65], v[66:69], v[16:31]
	v_mfma_f32_32x32x16_bf16 v[0:15], v[70:73], v[66:69], v[0:15]
	global_load_dwordx4 v[62:65], v34, vcc offset:768
	global_load_dwordx4 v[66:69], v35, vcc offset:768
	global_load_dwordx4 v[70:73], v38, vcc offset:768
	global_load_dwordx4 v[86:89], v39, vcc offset:768
	global_load_dwordx4 v[90:93], v34, s[28:29]
	global_load_dwordx4 v[94:97], v35, s[28:29]
	ds_read_b128 v[110:113], v36 offset:64
	ds_read_b128 v[114:117], v36 offset:4672
	ds_read_b128 v[118:121], v33 offset:36928
	s_waitcnt vmcnt(11)
	ds_write_b128 v32, v[46:49] offset:18432
	s_waitcnt vmcnt(10)
	ds_write_b128 v32, v[50:53] offset:23040
	s_waitcnt vmcnt(9)
	ds_write_b128 v32, v[58:61] offset:27648
	s_waitcnt vmcnt(8)
	ds_write_b128 v32, v[98:101] offset:32256
	s_waitcnt lgkmcnt(7)
	v_mfma_f32_32x32x16_bf16 v[16:31], v[74:77], v[82:85], v[16:31]
	v_mfma_f32_32x32x16_bf16 v[0:15], v[78:81], v[82:85], v[0:15]
	ds_read_b128 v[46:49], v36 offset:96
	ds_read_b128 v[50:53], v36 offset:4704
	ds_read_b128 v[58:61], v33 offset:36960
	s_waitcnt vmcnt(7)
	ds_write_b128 v32, v[102:105] offset:46080
	s_waitcnt vmcnt(6)
	ds_write_b128 v32, v[106:109] offset:50688
	s_waitcnt lgkmcnt(0)
	s_barrier
	v_mfma_f32_32x32x16_bf16 v[16:31], v[110:113], v[118:121], v[16:31]
	v_mfma_f32_32x32x16_bf16 v[0:15], v[114:117], v[118:121], v[0:15]
	v_mfma_f32_32x32x16_bf16 v[16:31], v[46:49], v[58:61], v[16:31]
	v_mfma_f32_32x32x16_bf16 v[0:15], v[50:53], v[58:61], v[0:15]
	ds_read_b128 v[46:49], v36 offset:18432
	ds_read_b128 v[58:61], v36 offset:23040
	ds_read_b128 v[50:53], v33 offset:46080
	ds_read_b128 v[74:77], v36 offset:18464
	ds_read_b128 v[78:81], v36 offset:23072
	ds_read_b128 v[82:85], v33 offset:46112
	s_waitcnt lgkmcnt(3)
	v_mfma_f32_32x32x16_bf16 v[16:31], v[46:49], v[50:53], v[16:31]
	v_mfma_f32_32x32x16_bf16 v[0:15], v[58:61], v[50:53], v[0:15]
	global_load_dwordx4 v[46:49], v34, vcc offset:896
	global_load_dwordx4 v[50:53], v35, vcc offset:896
	global_load_dwordx4 v[58:61], v38, vcc offset:896
	global_load_dwordx4 v[98:101], v39, vcc offset:896
	global_load_dwordx4 v[102:105], v34, s[30:31]
	global_load_dwordx4 v[106:109], v35, s[30:31]
	ds_read_b128 v[110:113], v36 offset:18496
	ds_read_b128 v[114:117], v36 offset:23104
	ds_read_b128 v[118:121], v33 offset:46144
	s_waitcnt vmcnt(11)
	ds_write_b128 v32, v[62:65]
	s_waitcnt vmcnt(10)
	ds_write_b128 v32, v[66:69] offset:4608
	s_waitcnt vmcnt(9)
	ds_write_b128 v32, v[70:73] offset:9216
	s_waitcnt vmcnt(8)
	ds_write_b128 v32, v[86:89] offset:13824
	s_waitcnt lgkmcnt(7)
	v_mfma_f32_32x32x16_bf16 v[16:31], v[74:77], v[82:85], v[16:31]
	v_mfma_f32_32x32x16_bf16 v[0:15], v[78:81], v[82:85], v[0:15]
	ds_read_b128 v[62:65], v36 offset:18528
	ds_read_b128 v[66:69], v36 offset:23136
	ds_read_b128 v[70:73], v33 offset:46176
	s_waitcnt vmcnt(7)
	ds_write_b128 v32, v[90:93] offset:36864
	s_waitcnt vmcnt(6)
	ds_write_b128 v32, v[94:97] offset:41472
	s_waitcnt lgkmcnt(0)
	s_barrier
	v_mfma_f32_32x32x16_bf16 v[16:31], v[110:113], v[118:121], v[16:31]
	v_mfma_f32_32x32x16_bf16 v[0:15], v[114:117], v[118:121], v[0:15]
	v_mfma_f32_32x32x16_bf16 v[16:31], v[62:65], v[70:73], v[16:31]
	v_mfma_f32_32x32x16_bf16 v[0:15], v[66:69], v[70:73], v[0:15]
	ds_read_b128 v[62:65], v36
	ds_read_b128 v[70:73], v36 offset:4608
	ds_read_b128 v[66:69], v33 offset:36864
	ds_read_b128 v[74:77], v36 offset:32
	ds_read_b128 v[78:81], v36 offset:4640
	ds_read_b128 v[82:85], v33 offset:36896
	s_waitcnt lgkmcnt(3)
	v_mfma_f32_32x32x16_bf16 v[16:31], v[62:65], v[66:69], v[16:31]
	v_mfma_f32_32x32x16_bf16 v[0:15], v[70:73], v[66:69], v[0:15]
	global_load_dwordx4 v[62:65], v34, vcc offset:1024
	global_load_dwordx4 v[66:69], v35, vcc offset:1024
	global_load_dwordx4 v[70:73], v38, vcc offset:1024
	global_load_dwordx4 v[86:89], v39, vcc offset:1024
	global_load_dwordx4 v[90:93], v34, s[34:35]
	global_load_dwordx4 v[94:97], v35, s[34:35]
	ds_read_b128 v[110:113], v36 offset:64
	ds_read_b128 v[114:117], v36 offset:4672
	ds_read_b128 v[118:121], v33 offset:36928
	s_waitcnt vmcnt(11)
	ds_write_b128 v32, v[46:49] offset:18432
	s_waitcnt vmcnt(10)
	ds_write_b128 v32, v[50:53] offset:23040
	s_waitcnt vmcnt(9)
	ds_write_b128 v32, v[58:61] offset:27648
	s_waitcnt vmcnt(8)
	ds_write_b128 v32, v[98:101] offset:32256
	s_waitcnt lgkmcnt(7)
	v_mfma_f32_32x32x16_bf16 v[16:31], v[74:77], v[82:85], v[16:31]
	v_mfma_f32_32x32x16_bf16 v[0:15], v[78:81], v[82:85], v[0:15]
	ds_read_b128 v[46:49], v36 offset:96
	ds_read_b128 v[50:53], v36 offset:4704
	ds_read_b128 v[58:61], v33 offset:36960
	s_waitcnt vmcnt(7)
	ds_write_b128 v32, v[102:105] offset:46080
	s_waitcnt vmcnt(6)
	ds_write_b128 v32, v[106:109] offset:50688
	s_waitcnt lgkmcnt(0)
	s_barrier
	v_mfma_f32_32x32x16_bf16 v[16:31], v[110:113], v[118:121], v[16:31]
	v_mfma_f32_32x32x16_bf16 v[0:15], v[114:117], v[118:121], v[0:15]
	v_mfma_f32_32x32x16_bf16 v[16:31], v[46:49], v[58:61], v[16:31]
	v_mfma_f32_32x32x16_bf16 v[0:15], v[50:53], v[58:61], v[0:15]
	ds_read_b128 v[46:49], v36 offset:18432
	ds_read_b128 v[58:61], v36 offset:23040
	ds_read_b128 v[50:53], v33 offset:46080
	ds_read_b128 v[74:77], v36 offset:18464
	ds_read_b128 v[78:81], v36 offset:23072
	ds_read_b128 v[82:85], v33 offset:46112
	s_waitcnt lgkmcnt(3)
	v_mfma_f32_32x32x16_bf16 v[16:31], v[46:49], v[50:53], v[16:31]
	v_mfma_f32_32x32x16_bf16 v[0:15], v[58:61], v[50:53], v[0:15]
	global_load_dwordx4 v[46:49], v34, vcc offset:1152
	global_load_dwordx4 v[50:53], v35, vcc offset:1152
	global_load_dwordx4 v[58:61], v38, vcc offset:1152
	global_load_dwordx4 v[98:101], v39, vcc offset:1152
	global_load_dwordx4 v[102:105], v34, s[14:15]
	global_load_dwordx4 v[106:109], v35, s[14:15]
	ds_read_b128 v[110:113], v36 offset:18496
	ds_read_b128 v[114:117], v36 offset:23104
	ds_read_b128 v[118:121], v33 offset:46144
	s_waitcnt vmcnt(11)
	ds_write_b128 v32, v[62:65]
	s_waitcnt vmcnt(10)
	ds_write_b128 v32, v[66:69] offset:4608
	s_waitcnt vmcnt(9)
	ds_write_b128 v32, v[70:73] offset:9216
	s_waitcnt vmcnt(8)
	ds_write_b128 v32, v[86:89] offset:13824
	s_waitcnt lgkmcnt(7)
	v_mfma_f32_32x32x16_bf16 v[16:31], v[74:77], v[82:85], v[16:31]
	v_mfma_f32_32x32x16_bf16 v[0:15], v[78:81], v[82:85], v[0:15]
	ds_read_b128 v[62:65], v36 offset:18528
	ds_read_b128 v[66:69], v36 offset:23136
	ds_read_b128 v[70:73], v33 offset:46176
	s_waitcnt vmcnt(7)
	ds_write_b128 v32, v[90:93] offset:36864
	s_waitcnt vmcnt(6)
	ds_write_b128 v32, v[94:97] offset:41472
	s_waitcnt lgkmcnt(0)
	s_barrier
	v_mfma_f32_32x32x16_bf16 v[16:31], v[110:113], v[118:121], v[16:31]
	v_mfma_f32_32x32x16_bf16 v[0:15], v[114:117], v[118:121], v[0:15]
	v_mfma_f32_32x32x16_bf16 v[16:31], v[62:65], v[70:73], v[16:31]
	v_mfma_f32_32x32x16_bf16 v[0:15], v[66:69], v[70:73], v[0:15]
	ds_read_b128 v[62:65], v36
	ds_read_b128 v[70:73], v36 offset:4608
	ds_read_b128 v[66:69], v33 offset:36864
	ds_read_b128 v[74:77], v36 offset:32
	ds_read_b128 v[78:81], v36 offset:4640
	ds_read_b128 v[82:85], v33 offset:36896
	s_waitcnt lgkmcnt(3)
	v_mfma_f32_32x32x16_bf16 v[16:31], v[62:65], v[66:69], v[16:31]
	v_mfma_f32_32x32x16_bf16 v[0:15], v[70:73], v[66:69], v[0:15]
	global_load_dwordx4 v[62:65], v34, vcc offset:1280
	global_load_dwordx4 v[66:69], v35, vcc offset:1280
	global_load_dwordx4 v[70:73], v38, vcc offset:1280
	global_load_dwordx4 v[86:89], v39, vcc offset:1280
	global_load_dwordx4 v[90:93], v34, s[52:53]
	global_load_dwordx4 v[94:97], v35, s[52:53]
	ds_read_b128 v[110:113], v36 offset:64
	ds_read_b128 v[114:117], v36 offset:4672
	ds_read_b128 v[118:121], v33 offset:36928
	s_waitcnt vmcnt(11)
	ds_write_b128 v32, v[46:49] offset:18432
	s_waitcnt vmcnt(10)
	ds_write_b128 v32, v[50:53] offset:23040
	s_waitcnt vmcnt(9)
	ds_write_b128 v32, v[58:61] offset:27648
	s_waitcnt vmcnt(8)
	ds_write_b128 v32, v[98:101] offset:32256
	s_waitcnt lgkmcnt(7)
	v_mfma_f32_32x32x16_bf16 v[16:31], v[74:77], v[82:85], v[16:31]
	v_mfma_f32_32x32x16_bf16 v[0:15], v[78:81], v[82:85], v[0:15]
	ds_read_b128 v[46:49], v36 offset:96
	ds_read_b128 v[50:53], v36 offset:4704
	ds_read_b128 v[58:61], v33 offset:36960
	s_waitcnt vmcnt(7)
	ds_write_b128 v32, v[102:105] offset:46080
	s_waitcnt vmcnt(6)
	ds_write_b128 v32, v[106:109] offset:50688
	s_waitcnt lgkmcnt(0)
	s_barrier
	v_mfma_f32_32x32x16_bf16 v[16:31], v[110:113], v[118:121], v[16:31]
	v_mfma_f32_32x32x16_bf16 v[0:15], v[114:117], v[118:121], v[0:15]
	v_mfma_f32_32x32x16_bf16 v[16:31], v[46:49], v[58:61], v[16:31]
	v_mfma_f32_32x32x16_bf16 v[0:15], v[50:53], v[58:61], v[0:15]
	ds_read_b128 v[46:49], v36 offset:18432
	ds_read_b128 v[58:61], v36 offset:23040
	ds_read_b128 v[50:53], v33 offset:46080
	ds_read_b128 v[74:77], v36 offset:18464
	ds_read_b128 v[78:81], v36 offset:23072
	ds_read_b128 v[82:85], v33 offset:46112
	s_waitcnt lgkmcnt(3)
	v_mfma_f32_32x32x16_bf16 v[16:31], v[46:49], v[50:53], v[16:31]
	v_mfma_f32_32x32x16_bf16 v[0:15], v[58:61], v[50:53], v[0:15]
	global_load_dwordx4 v[46:49], v34, vcc offset:1408
	global_load_dwordx4 v[50:53], v35, vcc offset:1408
	global_load_dwordx4 v[58:61], v38, vcc offset:1408
	global_load_dwordx4 v[98:101], v39, vcc offset:1408
	global_load_dwordx4 v[102:105], v34, s[96:97]
	global_load_dwordx4 v[106:109], v35, s[96:97]
	ds_read_b128 v[110:113], v36 offset:18496
	ds_read_b128 v[114:117], v36 offset:23104
	ds_read_b128 v[118:121], v33 offset:46144
	s_waitcnt vmcnt(11)
	ds_write_b128 v32, v[62:65]
	s_waitcnt vmcnt(10)
	ds_write_b128 v32, v[66:69] offset:4608
	s_waitcnt vmcnt(9)
	ds_write_b128 v32, v[70:73] offset:9216
	s_waitcnt vmcnt(8)
	ds_write_b128 v32, v[86:89] offset:13824
	s_waitcnt lgkmcnt(7)
	v_mfma_f32_32x32x16_bf16 v[16:31], v[74:77], v[82:85], v[16:31]
	v_mfma_f32_32x32x16_bf16 v[0:15], v[78:81], v[82:85], v[0:15]
	ds_read_b128 v[62:65], v36 offset:18528
	ds_read_b128 v[66:69], v36 offset:23136
	ds_read_b128 v[70:73], v33 offset:46176
	s_waitcnt vmcnt(7)
	ds_write_b128 v32, v[90:93] offset:36864
	s_waitcnt vmcnt(6)
	ds_write_b128 v32, v[94:97] offset:41472
	s_waitcnt lgkmcnt(0)
	s_barrier
	v_mfma_f32_32x32x16_bf16 v[16:31], v[110:113], v[118:121], v[16:31]
	v_mfma_f32_32x32x16_bf16 v[0:15], v[114:117], v[118:121], v[0:15]
	v_mfma_f32_32x32x16_bf16 v[16:31], v[62:65], v[70:73], v[16:31]
	v_mfma_f32_32x32x16_bf16 v[0:15], v[66:69], v[70:73], v[0:15]
	ds_read_b128 v[62:65], v36
	ds_read_b128 v[70:73], v36 offset:4608
	ds_read_b128 v[66:69], v33 offset:36864
	ds_read_b128 v[74:77], v36 offset:32
	ds_read_b128 v[78:81], v36 offset:4640
	ds_read_b128 v[82:85], v33 offset:36896
	s_waitcnt lgkmcnt(3)
	v_mfma_f32_32x32x16_bf16 v[16:31], v[62:65], v[66:69], v[16:31]
	v_mfma_f32_32x32x16_bf16 v[0:15], v[70:73], v[66:69], v[0:15]
	global_load_dwordx4 v[62:65], v34, vcc offset:1536
	global_load_dwordx4 v[66:69], v35, vcc offset:1536
	global_load_dwordx4 v[70:73], v38, vcc offset:1536
	global_load_dwordx4 v[86:89], v39, vcc offset:1536
	global_load_dwordx4 v[90:93], v34, s[68:69]
	global_load_dwordx4 v[94:97], v35, s[68:69]
	ds_read_b128 v[110:113], v36 offset:64
	ds_read_b128 v[114:117], v36 offset:4672
	ds_read_b128 v[118:121], v33 offset:36928
	s_waitcnt vmcnt(11)
	ds_write_b128 v32, v[46:49] offset:18432
	s_waitcnt vmcnt(10)
	ds_write_b128 v32, v[50:53] offset:23040
	s_waitcnt vmcnt(9)
	ds_write_b128 v32, v[58:61] offset:27648
	s_waitcnt vmcnt(8)
	ds_write_b128 v32, v[98:101] offset:32256
	s_waitcnt lgkmcnt(7)
	v_mfma_f32_32x32x16_bf16 v[16:31], v[74:77], v[82:85], v[16:31]
	v_mfma_f32_32x32x16_bf16 v[0:15], v[78:81], v[82:85], v[0:15]
	ds_read_b128 v[46:49], v36 offset:96
	ds_read_b128 v[50:53], v36 offset:4704
	ds_read_b128 v[58:61], v33 offset:36960
	s_waitcnt vmcnt(7)
	ds_write_b128 v32, v[102:105] offset:46080
	s_waitcnt vmcnt(6)
	ds_write_b128 v32, v[106:109] offset:50688
	s_waitcnt lgkmcnt(0)
	s_barrier
	v_mfma_f32_32x32x16_bf16 v[16:31], v[110:113], v[118:121], v[16:31]
	v_mfma_f32_32x32x16_bf16 v[0:15], v[114:117], v[118:121], v[0:15]
	v_mfma_f32_32x32x16_bf16 v[16:31], v[46:49], v[58:61], v[16:31]
	v_mfma_f32_32x32x16_bf16 v[0:15], v[50:53], v[58:61], v[0:15]
	ds_read_b128 v[46:49], v36 offset:18432
	ds_read_b128 v[58:61], v36 offset:23040
	ds_read_b128 v[50:53], v33 offset:46080
	ds_read_b128 v[74:77], v36 offset:18464
	ds_read_b128 v[78:81], v36 offset:23072
	ds_read_b128 v[82:85], v33 offset:46112
	s_waitcnt lgkmcnt(3)
	v_mfma_f32_32x32x16_bf16 v[16:31], v[46:49], v[50:53], v[16:31]
	v_mfma_f32_32x32x16_bf16 v[0:15], v[58:61], v[50:53], v[0:15]
	global_load_dwordx4 v[46:49], v34, vcc offset:1664
	global_load_dwordx4 v[50:53], v35, vcc offset:1664
	global_load_dwordx4 v[58:61], v38, vcc offset:1664
	global_load_dwordx4 v[98:101], v39, vcc offset:1664
	global_load_dwordx4 v[102:105], v34, s[70:71]
	global_load_dwordx4 v[106:109], v35, s[70:71]
	ds_read_b128 v[110:113], v36 offset:18496
	ds_read_b128 v[114:117], v36 offset:23104
	ds_read_b128 v[118:121], v33 offset:46144
	s_waitcnt vmcnt(11)
	ds_write_b128 v32, v[62:65]
	s_waitcnt vmcnt(10)
	ds_write_b128 v32, v[66:69] offset:4608
	s_waitcnt vmcnt(9)
	ds_write_b128 v32, v[70:73] offset:9216
	s_waitcnt vmcnt(8)
	ds_write_b128 v32, v[86:89] offset:13824
	s_waitcnt lgkmcnt(7)
	v_mfma_f32_32x32x16_bf16 v[16:31], v[74:77], v[82:85], v[16:31]
	v_mfma_f32_32x32x16_bf16 v[0:15], v[78:81], v[82:85], v[0:15]
	ds_read_b128 v[62:65], v36 offset:18528
	ds_read_b128 v[66:69], v36 offset:23136
	ds_read_b128 v[70:73], v33 offset:46176
	s_waitcnt vmcnt(7)
	ds_write_b128 v32, v[90:93] offset:36864
	s_waitcnt vmcnt(6)
	ds_write_b128 v32, v[94:97] offset:41472
	s_waitcnt lgkmcnt(0)
	s_barrier
	v_mfma_f32_32x32x16_bf16 v[16:31], v[110:113], v[118:121], v[16:31]
	v_mfma_f32_32x32x16_bf16 v[0:15], v[114:117], v[118:121], v[0:15]
	v_mfma_f32_32x32x16_bf16 v[16:31], v[62:65], v[70:73], v[16:31]
	v_mfma_f32_32x32x16_bf16 v[0:15], v[66:69], v[70:73], v[0:15]
	ds_read_b128 v[62:65], v36
	ds_read_b128 v[70:73], v36 offset:4608
	ds_read_b128 v[66:69], v33 offset:36864
	ds_read_b128 v[74:77], v36 offset:32
	ds_read_b128 v[78:81], v36 offset:4640
	ds_read_b128 v[82:85], v33 offset:36896
	s_waitcnt lgkmcnt(3)
	v_mfma_f32_32x32x16_bf16 v[16:31], v[62:65], v[66:69], v[16:31]
	v_mfma_f32_32x32x16_bf16 v[0:15], v[70:73], v[66:69], v[0:15]
	global_load_dwordx4 v[62:65], v34, vcc offset:1792
	global_load_dwordx4 v[66:69], v35, vcc offset:1792
	global_load_dwordx4 v[70:73], v38, vcc offset:1792
	global_load_dwordx4 v[86:89], v39, vcc offset:1792
	global_load_dwordx4 v[90:93], v34, s[72:73]
	global_load_dwordx4 v[94:97], v35, s[72:73]
	ds_read_b128 v[110:113], v36 offset:64
	ds_read_b128 v[114:117], v36 offset:4672
	ds_read_b128 v[118:121], v33 offset:36928
	s_waitcnt vmcnt(11)
	ds_write_b128 v32, v[46:49] offset:18432
	s_waitcnt vmcnt(10)
	ds_write_b128 v32, v[50:53] offset:23040
	s_waitcnt vmcnt(9)
	ds_write_b128 v32, v[58:61] offset:27648
	s_waitcnt vmcnt(8)
	ds_write_b128 v32, v[98:101] offset:32256
	s_waitcnt lgkmcnt(7)
	v_mfma_f32_32x32x16_bf16 v[16:31], v[74:77], v[82:85], v[16:31]
	v_mfma_f32_32x32x16_bf16 v[0:15], v[78:81], v[82:85], v[0:15]
	ds_read_b128 v[46:49], v36 offset:96
	ds_read_b128 v[50:53], v36 offset:4704
	ds_read_b128 v[58:61], v33 offset:36960
	s_waitcnt vmcnt(7)
	ds_write_b128 v32, v[102:105] offset:46080
	s_waitcnt vmcnt(6)
	ds_write_b128 v32, v[106:109] offset:50688
	s_waitcnt lgkmcnt(0)
	s_barrier
	v_mfma_f32_32x32x16_bf16 v[16:31], v[110:113], v[118:121], v[16:31]
	v_mfma_f32_32x32x16_bf16 v[0:15], v[114:117], v[118:121], v[0:15]
	v_mfma_f32_32x32x16_bf16 v[16:31], v[46:49], v[58:61], v[16:31]
	v_mfma_f32_32x32x16_bf16 v[0:15], v[50:53], v[58:61], v[0:15]
	ds_read_b128 v[58:61], v36 offset:23040
	ds_read_b128 v[50:53], v33 offset:46080
	ds_read_b128 v[46:49], v36 offset:18432
	ds_read_b128 v[78:81], v36 offset:23072
	ds_read_b128 v[74:77], v36 offset:18464
	ds_read_b128 v[82:85], v33 offset:46112
	s_waitcnt lgkmcnt(4)
	v_mfma_f32_32x32x16_bf16 v[0:15], v[58:61], v[50:53], v[0:15]
	s_waitcnt lgkmcnt(3)
	v_mfma_f32_32x32x16_bf16 v[16:31], v[46:49], v[50:53], v[16:31]
	global_load_dwordx4 v[46:49], v34, vcc offset:1920
	global_load_dwordx4 v[50:53], v35, vcc offset:1920
	global_load_dwordx4 v[58:61], v38, vcc offset:1920
	global_load_dwordx4 v[98:101], v39, vcc offset:1920
	global_load_dwordx4 v[102:105], v34, s[74:75]
	global_load_dwordx4 v[106:109], v35, s[74:75]
	ds_read_b128 v[114:117], v36 offset:23104
	ds_read_b128 v[110:113], v36 offset:18496
	ds_read_b128 v[118:121], v33 offset:46144
	s_waitcnt vmcnt(11)
	ds_write_b128 v32, v[62:65]
	s_waitcnt vmcnt(10)
	ds_write_b128 v32, v[66:69] offset:4608
	s_waitcnt vmcnt(9)
	ds_write_b128 v32, v[70:73] offset:9216
	s_waitcnt vmcnt(8)
	ds_write_b128 v32, v[86:89] offset:13824
	s_waitcnt lgkmcnt(7)
	v_mfma_f32_32x32x16_bf16 v[0:15], v[78:81], v[82:85], v[0:15]
	ds_read_b128 v[66:69], v36 offset:23136
	ds_read_b128 v[62:65], v36 offset:18528
	ds_read_b128 v[70:73], v33 offset:46176
	s_waitcnt vmcnt(7)
	ds_write_b128 v32, v[90:93] offset:36864
	s_waitcnt vmcnt(6)
	ds_write_b128 v32, v[94:97] offset:41472
	s_waitcnt lgkmcnt(0)
	s_barrier
	v_mfma_f32_32x32x16_bf16 v[0:15], v[114:117], v[118:121], v[0:15]
	v_mfma_f32_32x32x16_bf16 v[0:15], v[66:69], v[70:73], v[0:15]
	ds_read_b128 v[66:69], v33 offset:36864
	v_mfma_f32_32x32x16_bf16 v[16:31], v[74:77], v[82:85], v[16:31]
	v_mfma_f32_32x32x16_bf16 v[16:31], v[110:113], v[118:121], v[16:31]
	v_mfma_f32_32x32x16_bf16 v[16:31], v[62:65], v[70:73], v[16:31]
	ds_read_b128 v[62:65], v36
	s_waitcnt lgkmcnt(0)
	v_mfma_f32_32x32x16_bf16 v[16:31], v[62:65], v[66:69], v[16:31]
	ds_read_b128 v[62:65], v36 offset:4608
	s_waitcnt lgkmcnt(0)
	v_mfma_f32_32x32x16_bf16 v[0:15], v[62:65], v[66:69], v[0:15]
	ds_read_b128 v[62:65], v36 offset:32
	ds_read_b128 v[66:69], v33 offset:36896
	s_waitcnt lgkmcnt(0)
	v_mfma_f32_32x32x16_bf16 v[16:31], v[62:65], v[66:69], v[16:31]
	ds_read_b128 v[62:65], v36 offset:4640
	s_waitcnt lgkmcnt(0)
	v_mfma_f32_32x32x16_bf16 v[0:15], v[62:65], v[66:69], v[0:15]
	ds_read_b128 v[62:65], v36 offset:64
	ds_read_b128 v[66:69], v33 offset:36928
	s_waitcnt lgkmcnt(0)
	v_mfma_f32_32x32x16_bf16 v[16:31], v[62:65], v[66:69], v[16:31]
	ds_read_b128 v[62:65], v36 offset:4672
	s_waitcnt vmcnt(3)
	ds_write_b128 v32, v[58:61] offset:27648
	s_waitcnt vmcnt(2)
	ds_write_b128 v32, v[98:101] offset:32256
	ds_write_b128 v32, v[46:49] offset:18432
	ds_write_b128 v32, v[50:53] offset:23040
	ds_read_b128 v[46:49], v36 offset:96
	ds_read_b128 v[50:53], v33 offset:36960
	s_waitcnt lgkmcnt(0)
	v_mfma_f32_32x32x16_bf16 v[16:31], v[46:49], v[50:53], v[16:31]
	ds_read_b128 v[46:49], v36 offset:4704
	v_add_u32_e32 v58, s41, v57
	v_add_u32_e32 v45, 0xffffe000, v58
	v_mfma_f32_32x32x16_bf16 v[0:15], v[62:65], v[66:69], v[0:15]
	s_waitcnt lgkmcnt(0)
	v_mfma_f32_32x32x16_bf16 v[0:15], v[46:49], v[50:53], v[0:15]
	s_waitcnt vmcnt(1)
	ds_write_b128 v32, v[102:105] offset:46080
	s_waitcnt vmcnt(0)
	ds_write_b128 v32, v[106:109] offset:50688
	s_waitcnt lgkmcnt(0)
	s_barrier
	ds_read_b128 v[46:49], v36 offset:18432
	ds_read_b128 v[50:53], v33 offset:46080
	s_waitcnt lgkmcnt(0)
	v_mfma_f32_32x32x16_bf16 v[16:31], v[46:49], v[50:53], v[16:31]
	ds_read_b128 v[46:49], v36 offset:23040
	s_waitcnt lgkmcnt(0)
	v_mfma_f32_32x32x16_bf16 v[0:15], v[46:49], v[50:53], v[0:15]
	ds_read_b128 v[46:49], v36 offset:18464
	ds_read_b128 v[50:53], v33 offset:46112
	s_waitcnt lgkmcnt(0)
	v_mfma_f32_32x32x16_bf16 v[16:31], v[46:49], v[50:53], v[16:31]
	ds_read_b128 v[46:49], v36 offset:23072
	s_waitcnt lgkmcnt(0)
	v_mfma_f32_32x32x16_bf16 v[0:15], v[46:49], v[50:53], v[0:15]
	ds_read_b128 v[46:49], v36 offset:18496
	ds_read_b128 v[50:53], v33 offset:46144
	ds_read_b128 v[32:35], v33 offset:46176
	s_waitcnt lgkmcnt(1)
	v_mfma_f32_32x32x16_bf16 v[16:31], v[46:49], v[50:53], v[16:31]
	ds_read_b128 v[46:49], v36 offset:23104
	s_waitcnt lgkmcnt(0)
	v_mfma_f32_32x32x16_bf16 v[0:15], v[46:49], v[50:53], v[0:15]
	ds_read_b128 v[46:49], v36 offset:18528
	ds_read_b128 v[36:39], v36 offset:23136
	s_waitcnt lgkmcnt(0)
	s_barrier
	v_mfma_f32_32x32x16_bf16 v[16:31], v[46:49], v[32:35], v[16:31]
	v_mfma_f32_32x32x16_bf16 v[0:15], v[36:39], v[32:35], v[0:15]
	s_and_saveexec_b64 s[78:79], s[2:3]
	s_xor_b64 s[78:79], exec, s[78:79]
	s_cbranch_execz .LBB0_1117
	s_and_saveexec_b64 s[80:81], s[4:5]
	s_cbranch_execz .LBB0_1116
	s_nop 5
	v_mul_f32_e32 v32, 0xbfb8aa3b, v16
	v_exp_f32_e32 v32, v32
	s_movk_i32 s13, 0x60
	v_add_f32_e32 v32, 1.0, v32
	v_rcp_f32_e32 v34, v32
	s_nop 0
	v_mad_i64_i32 v[32:33], vcc, v45, s13, v[40:41]
	global_store_dword v[32:33], v34, off

.LBB0_1119:
	s_or_b64 exec, exec, s[78:79]
	v_add_u32_e32 v16, 0xffffe001, v58
	s_and_saveexec_b64 s[12:13], s[2:3]
	s_xor_b64 s[12:13], exec, s[12:13]
	s_cbranch_execz .LBB0_1123
	s_and_saveexec_b64 s[78:79], s[4:5]
	s_cbranch_execz .LBB0_1122
	v_mul_f32_e32 v45, 0xbfb8aa3b, v17
	v_exp_f32_e32 v45, v45
	s_movk_i32 s33, 0x60
	v_add_f32_e32 v45, 1.0, v45
	v_rcp_f32_e32 v45, v45
	s_nop 0
	v_mad_i64_i32 v[60:61], s[80:81], v16, s33, v[40:41]
	global_store_dword v[60:61], v45, off

.LBB0_1125:
	s_or_b64 exec, exec, s[12:13]
	v_add_u32_e32 v16, 0xffffe002, v58
	s_and_saveexec_b64 s[12:13], s[2:3]
	s_xor_b64 s[12:13], exec, s[12:13]
	s_cbranch_execz .LBB0_1129
	s_and_saveexec_b64 s[78:79], s[4:5]
	s_cbranch_execz .LBB0_1128
	v_mul_f32_e32 v17, 0xbfb8aa3b, v18
	v_exp_f32_e32 v17, v17
	s_movk_i32 s33, 0x60
	v_add_f32_e32 v17, 1.0, v17
	v_rcp_f32_e32 v45, v17
	s_nop 0
	v_mad_i64_i32 v[16:17], s[80:81], v16, s33, v[40:41]
	global_store_dword v[16:17], v45, off

.LBB0_1131:
	s_or_b64 exec, exec, s[12:13]
	v_add_u32_e32 v16, 0xffffe003, v58
	s_and_saveexec_b64 s[12:13], s[2:3]
	s_xor_b64 s[12:13], exec, s[12:13]
	s_cbranch_execz .LBB0_1135
	s_and_saveexec_b64 s[78:79], s[4:5]
	s_cbranch_execz .LBB0_1134
	v_mul_f32_e32 v17, 0xbfb8aa3b, v19
	v_exp_f32_e32 v17, v17
	s_movk_i32 s33, 0x60
	v_add_f32_e32 v17, 1.0, v17
	v_rcp_f32_e32 v18, v17
	s_nop 0
	v_mad_i64_i32 v[16:17], s[80:81], v16, s33, v[40:41]
	global_store_dword v[16:17], v18, off

.LBB0_1137:
	s_or_b64 exec, exec, s[12:13]
	v_add_u32_e32 v16, 0xffffe008, v58
	s_and_saveexec_b64 s[12:13], s[2:3]
	s_xor_b64 s[12:13], exec, s[12:13]
	s_cbranch_execz .LBB0_1141
	s_and_saveexec_b64 s[78:79], s[4:5]
	s_cbranch_execz .LBB0_1140
	v_mul_f32_e32 v17, 0xbfb8aa3b, v20
	v_exp_f32_e32 v17, v17
	s_movk_i32 s33, 0x60
	v_add_f32_e32 v17, 1.0, v17
	v_rcp_f32_e32 v18, v17
	s_nop 0
	v_mad_i64_i32 v[16:17], s[80:81], v16, s33, v[40:41]
	global_store_dword v[16:17], v18, off

.LBB0_1143:
	s_or_b64 exec, exec, s[12:13]
	v_add_u32_e32 v16, 0xffffe009, v58
	s_and_saveexec_b64 s[12:13], s[2:3]
	s_xor_b64 s[12:13], exec, s[12:13]
	s_cbranch_execz .LBB0_1147
	s_and_saveexec_b64 s[78:79], s[4:5]
	s_cbranch_execz .LBB0_1146
	v_mul_f32_e32 v17, 0xbfb8aa3b, v21
	v_exp_f32_e32 v17, v17
	s_movk_i32 s33, 0x60
	v_add_f32_e32 v17, 1.0, v17
	v_rcp_f32_e32 v18, v17
	s_nop 0
	v_mad_i64_i32 v[16:17], s[80:81], v16, s33, v[40:41]
	global_store_dword v[16:17], v18, off

.LBB0_1149:
	s_or_b64 exec, exec, s[12:13]
	v_add_u32_e32 v16, 0xffffe00a, v58
	s_and_saveexec_b64 s[12:13], s[2:3]
	s_xor_b64 s[12:13], exec, s[12:13]
	s_cbranch_execz .LBB0_1153
	s_and_saveexec_b64 s[78:79], s[4:5]
	s_cbranch_execz .LBB0_1152
	v_mul_f32_e32 v17, 0xbfb8aa3b, v22
	v_exp_f32_e32 v17, v17
	s_movk_i32 s33, 0x60
	v_add_f32_e32 v17, 1.0, v17
	v_rcp_f32_e32 v18, v17
	s_nop 0
	v_mad_i64_i32 v[16:17], s[80:81], v16, s33, v[40:41]
	global_store_dword v[16:17], v18, off

.LBB0_1155:
	s_or_b64 exec, exec, s[12:13]
	v_add_u32_e32 v16, 0xffffe00b, v58
	s_and_saveexec_b64 s[12:13], s[2:3]
	s_xor_b64 s[12:13], exec, s[12:13]
	s_cbranch_execz .LBB0_1159
	s_and_saveexec_b64 s[78:79], s[4:5]
	s_cbranch_execz .LBB0_1158
	v_mul_f32_e32 v17, 0xbfb8aa3b, v23
	v_exp_f32_e32 v17, v17
	s_movk_i32 s33, 0x60
	v_add_f32_e32 v17, 1.0, v17
	v_rcp_f32_e32 v18, v17
	s_nop 0
	v_mad_i64_i32 v[16:17], s[80:81], v16, s33, v[40:41]
	global_store_dword v[16:17], v18, off

.LBB0_1161:
	s_or_b64 exec, exec, s[12:13]
	v_add_u32_e32 v16, 0xffffe010, v58
	s_and_saveexec_b64 s[12:13], s[2:3]
	s_xor_b64 s[12:13], exec, s[12:13]
	s_cbranch_execz .LBB0_1165
	s_and_saveexec_b64 s[78:79], s[4:5]
	s_cbranch_execz .LBB0_1164
	v_mul_f32_e32 v17, 0xbfb8aa3b, v24
	v_exp_f32_e32 v17, v17
	s_movk_i32 s33, 0x60
	v_add_f32_e32 v17, 1.0, v17
	v_rcp_f32_e32 v18, v17
	s_nop 0
	v_mad_i64_i32 v[16:17], s[80:81], v16, s33, v[40:41]
	global_store_dword v[16:17], v18, off

.LBB0_1167:
	s_or_b64 exec, exec, s[12:13]
	v_add_u32_e32 v16, 0xffffe011, v58
	s_and_saveexec_b64 s[12:13], s[2:3]
	s_xor_b64 s[12:13], exec, s[12:13]
	s_cbranch_execz .LBB0_1171
	s_and_saveexec_b64 s[78:79], s[4:5]
	s_cbranch_execz .LBB0_1170
	v_mul_f32_e32 v17, 0xbfb8aa3b, v25
	v_exp_f32_e32 v17, v17
	s_movk_i32 s33, 0x60
	v_add_f32_e32 v17, 1.0, v17
	v_rcp_f32_e32 v18, v17
	s_nop 0
	v_mad_i64_i32 v[16:17], s[80:81], v16, s33, v[40:41]
	global_store_dword v[16:17], v18, off

.LBB0_1173:
	s_or_b64 exec, exec, s[12:13]
	v_add_u32_e32 v16, 0xffffe012, v58
	s_and_saveexec_b64 s[12:13], s[2:3]
	s_xor_b64 s[12:13], exec, s[12:13]
	s_cbranch_execz .LBB0_1177
	s_and_saveexec_b64 s[78:79], s[4:5]
	s_cbranch_execz .LBB0_1176
	v_mul_f32_e32 v17, 0xbfb8aa3b, v26
	v_exp_f32_e32 v17, v17
	s_movk_i32 s33, 0x60
	v_add_f32_e32 v17, 1.0, v17
	v_rcp_f32_e32 v18, v17
	s_nop 0
	v_mad_i64_i32 v[16:17], s[80:81], v16, s33, v[40:41]
	global_store_dword v[16:17], v18, off

.LBB0_1179:
	s_or_b64 exec, exec, s[12:13]
	v_add_u32_e32 v16, 0xffffe013, v58
	s_and_saveexec_b64 s[12:13], s[2:3]
	s_xor_b64 s[12:13], exec, s[12:13]
	s_cbranch_execz .LBB0_1183
	s_and_saveexec_b64 s[78:79], s[4:5]
	s_cbranch_execz .LBB0_1182
	v_mul_f32_e32 v17, 0xbfb8aa3b, v27
	v_exp_f32_e32 v17, v17
	s_movk_i32 s33, 0x60
	v_add_f32_e32 v17, 1.0, v17
	v_rcp_f32_e32 v18, v17
	s_nop 0
	v_mad_i64_i32 v[16:17], s[80:81], v16, s33, v[40:41]
	global_store_dword v[16:17], v18, off

.LBB0_1185:
	s_or_b64 exec, exec, s[12:13]
	v_add_u32_e32 v16, 0xffffe018, v58
	s_and_saveexec_b64 s[12:13], s[2:3]
	s_xor_b64 s[12:13], exec, s[12:13]
	s_cbranch_execz .LBB0_1189
	s_and_saveexec_b64 s[78:79], s[4:5]
	s_cbranch_execz .LBB0_1188
	v_mul_f32_e32 v17, 0xbfb8aa3b, v28
	v_exp_f32_e32 v17, v17
	s_movk_i32 s33, 0x60
	v_add_f32_e32 v17, 1.0, v17
	v_rcp_f32_e32 v18, v17
	s_nop 0
	v_mad_i64_i32 v[16:17], s[80:81], v16, s33, v[40:41]
	global_store_dword v[16:17], v18, off

.LBB0_1191:
	s_or_b64 exec, exec, s[12:13]
	v_add_u32_e32 v16, 0xffffe019, v58
	s_and_saveexec_b64 s[12:13], s[2:3]
	s_xor_b64 s[12:13], exec, s[12:13]
	s_cbranch_execz .LBB0_1195
	s_and_saveexec_b64 s[78:79], s[4:5]
	s_cbranch_execz .LBB0_1194
	v_mul_f32_e32 v17, 0xbfb8aa3b, v29
	v_exp_f32_e32 v17, v17
	s_movk_i32 s33, 0x60
	v_add_f32_e32 v17, 1.0, v17
	v_rcp_f32_e32 v18, v17
	s_nop 0
	v_mad_i64_i32 v[16:17], s[80:81], v16, s33, v[40:41]
	global_store_dword v[16:17], v18, off

.LBB0_1197:
	s_or_b64 exec, exec, s[12:13]
	v_add_u32_e32 v16, 0xffffe01a, v58
	s_and_saveexec_b64 s[12:13], s[2:3]
	s_xor_b64 s[12:13], exec, s[12:13]
	s_cbranch_execz .LBB0_1201
	s_and_saveexec_b64 s[78:79], s[4:5]
	s_cbranch_execz .LBB0_1200
	v_mul_f32_e32 v17, 0xbfb8aa3b, v30
	v_exp_f32_e32 v17, v17
	s_movk_i32 s33, 0x60
	v_add_f32_e32 v17, 1.0, v17
	v_rcp_f32_e32 v18, v17
	s_nop 0
	v_mad_i64_i32 v[16:17], s[80:81], v16, s33, v[40:41]
	global_store_dword v[16:17], v18, off

.LBB0_1203:
	s_or_b64 exec, exec, s[12:13]
	v_add_u32_e32 v45, 0xffffe01b, v58
	s_and_saveexec_b64 s[12:13], s[2:3]
	s_xor_b64 s[12:13], exec, s[12:13]
	s_cbranch_execz .LBB0_1207
	s_and_saveexec_b64 s[78:79], s[4:5]
	s_cbranch_execz .LBB0_1206
	v_mul_f32_e32 v16, 0xbfb8aa3b, v31
	v_exp_f32_e32 v16, v16
	s_movk_i32 s33, 0x60
	v_add_f32_e32 v16, 1.0, v16
	v_rcp_f32_e32 v18, v16
	s_nop 0
	v_mad_i64_i32 v[16:17], s[80:81], v45, s33, v[40:41]
	global_store_dword v[16:17], v18, off

.LBB0_1209:
	s_or_b64 exec, exec, s[12:13]
	v_add_u32_e32 v16, 0xffffe020, v58
	s_and_saveexec_b64 s[12:13], s[2:3]
	s_xor_b64 s[12:13], exec, s[12:13]
	s_cbranch_execz .LBB0_1213
	s_and_saveexec_b64 s[78:79], s[4:5]
	s_cbranch_execz .LBB0_1212
	v_mul_f32_e32 v17, 0xbfb8aa3b, v0
	v_exp_f32_e32 v17, v17
	s_movk_i32 s33, 0x60
	v_add_f32_e32 v17, 1.0, v17
	v_rcp_f32_e32 v18, v17
	s_nop 0
	v_mad_i64_i32 v[16:17], s[80:81], v16, s33, v[40:41]
	global_store_dword v[16:17], v18, off

.LBB0_1215:
	s_or_b64 exec, exec, s[12:13]
	v_add_u32_e32 v0, 0xffffe021, v58
	s_and_saveexec_b64 s[12:13], s[2:3]
	s_xor_b64 s[12:13], exec, s[12:13]
	s_cbranch_execz .LBB0_1219
	s_and_saveexec_b64 s[78:79], s[4:5]
	s_cbranch_execz .LBB0_1218
	v_mul_f32_e32 v16, 0xbfb8aa3b, v1
	v_exp_f32_e32 v16, v16
	s_movk_i32 s33, 0x60
	v_add_f32_e32 v16, 1.0, v16
	v_rcp_f32_e32 v18, v16
	s_nop 0
	v_mad_i64_i32 v[16:17], s[80:81], v0, s33, v[40:41]
	global_store_dword v[16:17], v18, off

.LBB0_1221:
	s_or_b64 exec, exec, s[12:13]
	v_add_u32_e32 v0, 0xffffe022, v58
	s_and_saveexec_b64 s[12:13], s[2:3]
	s_xor_b64 s[12:13], exec, s[12:13]
	s_cbranch_execz .LBB0_1225
	s_and_saveexec_b64 s[78:79], s[4:5]
	s_cbranch_execz .LBB0_1224
	v_mul_f32_e32 v1, 0xbfb8aa3b, v2
	v_exp_f32_e32 v1, v1
	s_movk_i32 s33, 0x60
	v_add_f32_e32 v1, 1.0, v1
	v_rcp_f32_e32 v16, v1
	s_nop 0
	v_mad_i64_i32 v[0:1], s[80:81], v0, s33, v[40:41]
	global_store_dword v[0:1], v16, off

.LBB0_1227:
	s_or_b64 exec, exec, s[12:13]
	v_add_u32_e32 v0, 0xffffe023, v58
	s_and_saveexec_b64 s[12:13], s[2:3]
	s_xor_b64 s[12:13], exec, s[12:13]
	s_cbranch_execz .LBB0_1231
	s_and_saveexec_b64 s[78:79], s[4:5]
	s_cbranch_execz .LBB0_1230
	v_mul_f32_e32 v1, 0xbfb8aa3b, v3
	v_exp_f32_e32 v1, v1
	s_movk_i32 s33, 0x60
	v_add_f32_e32 v1, 1.0, v1
	v_rcp_f32_e32 v2, v1
	s_nop 0
	v_mad_i64_i32 v[0:1], s[80:81], v0, s33, v[40:41]
	global_store_dword v[0:1], v2, off

.LBB0_1233:
	s_or_b64 exec, exec, s[12:13]
	v_add_u32_e32 v0, 0xffffe028, v58
	s_and_saveexec_b64 s[12:13], s[2:3]
	s_xor_b64 s[12:13], exec, s[12:13]
	s_cbranch_execz .LBB0_1237
	s_and_saveexec_b64 s[78:79], s[4:5]
	s_cbranch_execz .LBB0_1236
	v_mul_f32_e32 v1, 0xbfb8aa3b, v4
	v_exp_f32_e32 v1, v1
	s_movk_i32 s33, 0x60
	v_add_f32_e32 v1, 1.0, v1
	v_rcp_f32_e32 v2, v1
	s_nop 0
	v_mad_i64_i32 v[0:1], s[80:81], v0, s33, v[40:41]
	global_store_dword v[0:1], v2, off

.LBB0_1239:
	s_or_b64 exec, exec, s[12:13]
	v_add_u32_e32 v0, 0xffffe029, v58
	s_and_saveexec_b64 s[12:13], s[2:3]
	s_xor_b64 s[12:13], exec, s[12:13]
	s_cbranch_execz .LBB0_1243
	s_and_saveexec_b64 s[78:79], s[4:5]
	s_cbranch_execz .LBB0_1242
	v_mul_f32_e32 v1, 0xbfb8aa3b, v5
	v_exp_f32_e32 v1, v1
	s_movk_i32 s33, 0x60
	v_add_f32_e32 v1, 1.0, v1
	v_rcp_f32_e32 v2, v1
	s_nop 0
	v_mad_i64_i32 v[0:1], s[80:81], v0, s33, v[40:41]
	global_store_dword v[0:1], v2, off

.LBB0_1245:
	s_or_b64 exec, exec, s[12:13]
	v_add_u32_e32 v0, 0xffffe02a, v58
	s_and_saveexec_b64 s[12:13], s[2:3]
	s_xor_b64 s[12:13], exec, s[12:13]
	s_cbranch_execz .LBB0_1249
	s_and_saveexec_b64 s[78:79], s[4:5]
	s_cbranch_execz .LBB0_1248
	v_mul_f32_e32 v1, 0xbfb8aa3b, v6
	v_exp_f32_e32 v1, v1
	s_movk_i32 s33, 0x60
	v_add_f32_e32 v1, 1.0, v1
	v_rcp_f32_e32 v2, v1
	s_nop 0
	v_mad_i64_i32 v[0:1], s[80:81], v0, s33, v[40:41]
	global_store_dword v[0:1], v2, off

.LBB0_1251:
	s_or_b64 exec, exec, s[12:13]
	v_add_u32_e32 v0, 0xffffe02b, v58
	s_and_saveexec_b64 s[12:13], s[2:3]
	s_xor_b64 s[12:13], exec, s[12:13]
	s_cbranch_execz .LBB0_1255
	s_and_saveexec_b64 s[78:79], s[4:5]
	s_cbranch_execz .LBB0_1254
	v_mul_f32_e32 v1, 0xbfb8aa3b, v7
	v_exp_f32_e32 v1, v1
	s_movk_i32 s33, 0x60
	v_add_f32_e32 v1, 1.0, v1
	v_rcp_f32_e32 v2, v1
	s_nop 0
	v_mad_i64_i32 v[0:1], s[80:81], v0, s33, v[40:41]
	global_store_dword v[0:1], v2, off

.LBB0_1257:
	s_or_b64 exec, exec, s[12:13]
	v_add_u32_e32 v0, 0xffffe030, v58
	s_and_saveexec_b64 s[12:13], s[2:3]
	s_xor_b64 s[12:13], exec, s[12:13]
	s_cbranch_execz .LBB0_1261
	s_and_saveexec_b64 s[78:79], s[4:5]
	s_cbranch_execz .LBB0_1260
	v_mul_f32_e32 v1, 0xbfb8aa3b, v8
	v_exp_f32_e32 v1, v1
	s_movk_i32 s33, 0x60
	v_add_f32_e32 v1, 1.0, v1
	v_rcp_f32_e32 v2, v1
	s_nop 0
	v_mad_i64_i32 v[0:1], s[80:81], v0, s33, v[40:41]
	global_store_dword v[0:1], v2, off

.LBB0_1263:
	s_or_b64 exec, exec, s[12:13]
	v_add_u32_e32 v0, 0xffffe031, v58
	s_and_saveexec_b64 s[12:13], s[2:3]
	s_xor_b64 s[12:13], exec, s[12:13]
	s_cbranch_execz .LBB0_1267
	s_and_saveexec_b64 s[78:79], s[4:5]
	s_cbranch_execz .LBB0_1266
	v_mul_f32_e32 v1, 0xbfb8aa3b, v9
	v_exp_f32_e32 v1, v1
	s_movk_i32 s33, 0x60
	v_add_f32_e32 v1, 1.0, v1
	v_rcp_f32_e32 v2, v1
	s_nop 0
	v_mad_i64_i32 v[0:1], s[80:81], v0, s33, v[40:41]
	global_store_dword v[0:1], v2, off

.LBB0_1269:
	s_or_b64 exec, exec, s[12:13]
	v_add_u32_e32 v0, 0xffffe032, v58
	s_and_saveexec_b64 s[12:13], s[2:3]
	s_xor_b64 s[12:13], exec, s[12:13]
	s_cbranch_execz .LBB0_1273
	s_and_saveexec_b64 s[78:79], s[4:5]
	s_cbranch_execz .LBB0_1272
	v_mul_f32_e32 v1, 0xbfb8aa3b, v10
	v_exp_f32_e32 v1, v1
	s_movk_i32 s33, 0x60
	v_add_f32_e32 v1, 1.0, v1
	v_rcp_f32_e32 v2, v1
	s_nop 0
	v_mad_i64_i32 v[0:1], s[80:81], v0, s33, v[40:41]
	global_store_dword v[0:1], v2, off

.LBB0_1275:
	s_or_b64 exec, exec, s[12:13]
	v_add_u32_e32 v0, 0xffffe033, v58
	s_and_saveexec_b64 s[12:13], s[2:3]
	s_xor_b64 s[12:13], exec, s[12:13]
	s_cbranch_execz .LBB0_1279
	s_and_saveexec_b64 s[78:79], s[4:5]
	s_cbranch_execz .LBB0_1278
	v_mul_f32_e32 v1, 0xbfb8aa3b, v11
	v_exp_f32_e32 v1, v1
	s_movk_i32 s33, 0x60
	v_add_f32_e32 v1, 1.0, v1
	v_rcp_f32_e32 v2, v1
	s_nop 0
	v_mad_i64_i32 v[0:1], s[80:81], v0, s33, v[40:41]
	global_store_dword v[0:1], v2, off

.LBB0_1281:
	s_or_b64 exec, exec, s[12:13]
	v_add_u32_e32 v0, 0xffffe038, v58
	s_and_saveexec_b64 s[12:13], s[2:3]
	s_xor_b64 s[12:13], exec, s[12:13]
	s_cbranch_execz .LBB0_1285
	s_and_saveexec_b64 s[78:79], s[4:5]
	s_cbranch_execz .LBB0_1284
	v_mul_f32_e32 v1, 0xbfb8aa3b, v12
	v_exp_f32_e32 v1, v1
	s_movk_i32 s33, 0x60
	v_add_f32_e32 v1, 1.0, v1
	v_rcp_f32_e32 v2, v1
	s_nop 0
	v_mad_i64_i32 v[0:1], s[80:81], v0, s33, v[40:41]
	global_store_dword v[0:1], v2, off

.LBB0_1287:
	s_or_b64 exec, exec, s[12:13]
	v_add_u32_e32 v0, 0xffffe039, v58
	s_and_saveexec_b64 s[12:13], s[2:3]
	s_xor_b64 s[12:13], exec, s[12:13]
	s_cbranch_execz .LBB0_1291
	s_and_saveexec_b64 s[78:79], s[4:5]
	s_cbranch_execz .LBB0_1290
	v_mul_f32_e32 v1, 0xbfb8aa3b, v13
	v_exp_f32_e32 v1, v1
	s_movk_i32 s33, 0x60
	v_add_f32_e32 v1, 1.0, v1
	v_rcp_f32_e32 v2, v1
	s_nop 0
	v_mad_i64_i32 v[0:1], s[80:81], v0, s33, v[40:41]
	global_store_dword v[0:1], v2, off

.LBB0_1293:
	s_or_b64 exec, exec, s[12:13]
	v_add_u32_e32 v0, 0xffffe03a, v58
	s_and_saveexec_b64 s[12:13], s[2:3]
	s_xor_b64 s[12:13], exec, s[12:13]
	s_cbranch_execz .LBB0_1297
	s_and_saveexec_b64 s[78:79], s[4:5]
	s_cbranch_execz .LBB0_1296
	v_mul_f32_e32 v1, 0xbfb8aa3b, v14
	v_exp_f32_e32 v1, v1
	s_movk_i32 s33, 0x60
	v_add_f32_e32 v1, 1.0, v1
	v_rcp_f32_e32 v2, v1
	s_nop 0
	v_mad_i64_i32 v[0:1], s[80:81], v0, s33, v[40:41]
	global_store_dword v[0:1], v2, off

.LBB0_1299:
	s_or_b64 exec, exec, s[12:13]
	v_add_u32_e32 v0, 0xffffe03b, v58
	s_and_saveexec_b64 s[12:13], s[2:3]
	s_xor_b64 s[12:13], exec, s[12:13]
	s_cbranch_execz .LBB0_1303
	s_and_saveexec_b64 s[78:79], s[4:5]
	s_cbranch_execz .LBB0_1302
	v_mul_f32_e32 v1, 0xbfb8aa3b, v15
	v_exp_f32_e32 v1, v1
	s_movk_i32 s33, 0x60
	v_add_f32_e32 v1, 1.0, v1
	v_rcp_f32_e32 v2, v1
	s_nop 0
	v_mad_i64_i32 v[0:1], s[80:81], v0, s33, v[40:41]
	global_store_dword v[0:1], v2, off

.LBB0_1898:
	v_mov_b32_e32 v71, v69
	s_nop 1
	v_permlane16_swap_b32_e32 v69, v71
	v_max_f32_e32 v69, v71, v69
	v_mov_b32_e32 v71, v69
	s_nop 1
	v_permlane32_swap_b32_e32 v69, v71
	v_max3_f32 v69, v85, v69, v71
	v_sub_f32_e32 v71, v85, v69
	v_mul_f32_e32 v71, 0x3e38aa3b, v71
	v_exp_f32_e32 v76, v71
	v_mov_b32_e32 v85, v69
	v_mul_f32_e32 v83, v83, v76
	v_pk_mul_f32 v[2:3], v[2:3], v[76:77] op_sel_hi:[1,0]
	v_pk_mul_f32 v[0:1], v[0:1], v[76:77] op_sel_hi:[1,0]
	v_pk_mul_f32 v[10:11], v[10:11], v[76:77] op_sel_hi:[1,0]
	v_pk_mul_f32 v[8:9], v[8:9], v[76:77] op_sel_hi:[1,0]
	v_pk_mul_f32 v[26:27], v[26:27], v[76:77] op_sel_hi:[1,0]
	v_pk_mul_f32 v[24:25], v[24:25], v[76:77] op_sel_hi:[1,0]
	v_pk_mul_f32 v[18:19], v[18:19], v[76:77] op_sel_hi:[1,0]
	v_pk_mul_f32 v[16:17], v[16:17], v[76:77] op_sel_hi:[1,0]
	v_mul_f32_e32 v76, 0xbe38aa3b, v69
	v_fmamk_f32 v69, v115, 0x3e38aa3b, v76
	v_exp_f32_e32 v69, v69
	v_fmamk_f32 v71, v114, 0x3e38aa3b, v76
	v_exp_f32_e32 v71, v71
	v_fmamk_f32 v73, v113, 0x3e38aa3b, v76
	v_exp_f32_e32 v73, v73
	v_fmamk_f32 v75, v112, 0x3e38aa3b, v76
	v_exp_f32_e32 v75, v75
	v_add_f32_e32 v77, v71, v69
	v_add_f32_e32 v77, v73, v77
	v_add_f32_e32 v112, v75, v77
	v_fmamk_f32 v77, v111, 0x3e38aa3b, v76
	v_exp_f32_e32 v77, v77
	v_fmamk_f32 v78, v110, 0x3e38aa3b, v76
	v_exp_f32_e32 v78, v78
	v_fmamk_f32 v79, v109, 0x3e38aa3b, v76
	v_exp_f32_e32 v79, v79
	v_fmamk_f32 v108, v108, 0x3e38aa3b, v76
	v_exp_f32_e32 v108, v108
	v_fmamk_f32 v65, v65, 0x3e38aa3b, v76
	v_add_f32_e32 v109, v77, v112
	v_exp_f32_e32 v65, v65
	v_fmamk_f32 v66, v66, 0x3e38aa3b, v76
	v_add_f32_e32 v109, v78, v109
	v_exp_f32_e32 v66, v66
	v_fmamk_f32 v67, v67, 0x3e38aa3b, v76
	v_add_f32_e32 v109, v79, v109
	v_exp_f32_e32 v67, v67
	v_fmamk_f32 v68, v68, 0x3e38aa3b, v76
	v_add_f32_e32 v109, v108, v109
	v_exp_f32_e32 v68, v68
	v_fmamk_f32 v70, v70, 0x3e38aa3b, v76
	v_add_f32_e32 v109, v65, v109
	v_exp_f32_e32 v70, v70
	v_fmamk_f32 v72, v72, 0x3e38aa3b, v76
	v_fmamk_f32 v74, v74, 0x3e38aa3b, v76
	v_fmac_f32_e32 v76, 0x3e38aa3b, v64
	v_add_f32_e32 v109, v66, v109
	v_exp_f32_e32 v72, v72
	v_exp_f32_e32 v74, v74
	v_exp_f32_e32 v76, v76
	v_add_f32_e32 v109, v67, v109
	v_add_f32_e32 v109, v68, v109
	v_add_f32_e32 v64, v70, v109

.LBB0_1902:
	v_mov_b32_e32 v64, v186
	s_nop 0
	v_bfe_u32 v108, v64, 4, 2
	v_and_b32_e32 v91, 15, v64
	v_lshlrev_b32_e32 v90, 4, v108
	v_mad_u32_u24 v104, v91, s43, v90
	ds_read_b128 v[64:67], v104
	ds_read_b128 v[72:75], v104 offset:64
	ds_read_b128 v[76:79], v104 offset:2368
	ds_read_b128 v[100:103], v104 offset:4672
	s_waitcnt lgkmcnt(3)
	v_mfma_f32_16x16x32_bf16 v[68:71], v[64:67], v[32:35], 0
	s_waitcnt lgkmcnt(2)
	v_mfma_f32_16x16x32_bf16 v[92:95], v[72:75], v[36:39], v[68:71]
	s_nop 5
	ds_read_b128 v[68:71], v104 offset:2304
	v_mfma_f32_16x16x32_bf16 v[64:67], v[64:67], v[40:43], 0
	v_mfma_f32_16x16x32_bf16 v[64:67], v[72:75], v[44:47], v[64:67]
	s_waitcnt lgkmcnt(0)
	v_mfma_f32_16x16x32_bf16 v[72:75], v[68:71], v[32:35], 0
	v_mfma_f32_16x16x32_bf16 v[96:99], v[76:79], v[36:39], v[72:75]
	v_mfma_f32_16x16x32_bf16 v[68:71], v[68:71], v[40:43], 0
	s_nop 5
	ds_read_b128 v[72:75], v104 offset:4608
	v_mfma_f32_16x16x32_bf16 v[68:71], v[76:79], v[44:47], v[68:71]
	s_waitcnt lgkmcnt(0)
	v_mfma_f32_16x16x32_bf16 v[76:79], v[72:75], v[32:35], 0
	v_mfma_f32_16x16x32_bf16 v[112:115], v[100:103], v[36:39], v[76:79]
	s_nop 6
	ds_read_b128 v[76:79], v104 offset:6912
	ds_read_b128 v[104:107], v104 offset:6976
	v_mfma_f32_16x16x32_bf16 v[72:75], v[72:75], v[40:43], 0
	v_mfma_f32_16x16x32_bf16 v[72:75], v[100:103], v[44:47], v[72:75]
	s_waitcnt lgkmcnt(1)
	v_mfma_f32_16x16x32_bf16 v[100:103], v[76:79], v[32:35], 0
	v_mfma_f32_16x16x32_bf16 v[76:79], v[76:79], v[40:43], 0
	s_waitcnt lgkmcnt(0)
	v_mfma_f32_16x16x32_bf16 v[100:103], v[104:107], v[36:39], v[100:103]
	v_mfma_f32_16x16x32_bf16 v[76:79], v[104:107], v[44:47], v[76:79]
	v_lshlrev_b32_e32 v104, 3, v108
	v_sub_u32_e32 v116, v89, v104
	v_add_u32_e32 v117, 0x7f, v116
	v_cmp_gt_i32_e32 vcc, 0, v117
	v_cmp_lt_i32_e64 s[0:1], 0, v116
	s_or_b64 s[0:1], s[0:1], vcc
	v_cmp_gt_i32_e32 vcc, 1, v117
	v_cmp_lt_i32_e64 s[2:3], 1, v116
	s_or_b64 s[2:3], s[2:3], vcc
	v_cmp_gt_i32_e32 vcc, 2, v117
	v_cmp_lt_i32_e64 s[4:5], 2, v116
	s_or_b64 s[4:5], s[4:5], vcc
	v_cmp_gt_i32_e32 vcc, 3, v117
	v_cmp_lt_i32_e64 s[6:7], 3, v116
	s_or_b64 s[6:7], s[6:7], vcc
	v_cmp_gt_i32_e32 vcc, 4, v117
	v_cmp_lt_i32_e64 s[8:9], 4, v116
	s_or_b64 s[8:9], s[8:9], vcc
	v_cmp_gt_i32_e32 vcc, 5, v117
	v_cmp_lt_i32_e64 s[10:11], 5, v116
	s_or_b64 s[10:11], s[10:11], vcc
	v_cmp_gt_i32_e32 vcc, 6, v117
	v_cmp_lt_i32_e64 s[14:15], 6, v116
	s_or_b64 s[14:15], s[14:15], vcc
	v_cmp_gt_i32_e32 vcc, 7, v117
	v_cmp_lt_i32_e64 s[16:17], 7, v116
	s_or_b64 s[16:17], s[16:17], vcc
	v_cmp_gt_i32_e32 vcc, 32, v117
	v_cmp_lt_i32_e64 s[18:19], 32, v116
	v_cndmask_b32_e64 v92, v92, v207, s[0:1]
	v_cndmask_b32_e64 v93, v93, v207, s[2:3]
	s_or_b64 s[18:19], s[18:19], vcc
	v_cmp_gt_i32_e32 vcc, 33, v117
	v_cmp_lt_i32_e64 s[20:21], 33, v116
	v_cndmask_b32_e64 v104, v96, v207, s[8:9]
	v_cndmask_b32_e64 v106, v98, v207, s[14:15]
	s_or_b64 s[20:21], s[20:21], vcc
	v_cmp_gt_i32_e32 vcc, 34, v117
	v_cmp_lt_i32_e64 s[22:23], 34, v116
	v_max_f32_e32 v96, v93, v93
	v_max_f32_e32 v98, v92, v92
	v_cndmask_b32_e64 v94, v94, v207, s[4:5]
	v_cndmask_b32_e64 v95, v95, v207, s[6:7]
	s_or_b64 s[22:23], s[22:23], vcc
	v_cmp_gt_i32_e32 vcc, 35, v117
	v_cmp_lt_i32_e64 s[24:25], 35, v116
	v_max_f32_e32 v96, v98, v96
	v_cndmask_b32_e64 v105, v97, v207, s[10:11]
	s_or_b64 s[24:25], s[24:25], vcc
	v_cmp_gt_i32_e32 vcc, 36, v117
	v_cmp_lt_i32_e64 s[26:27], 36, v116
	v_max3_f32 v96, v96, v94, v95
	v_cndmask_b32_e64 v107, v99, v207, s[16:17]
	s_or_b64 s[26:27], s[26:27], vcc
	v_cmp_gt_i32_e32 vcc, 37, v117
	v_cmp_lt_i32_e64 s[28:29], 37, v116
	v_max3_f32 v96, v96, v104, v105
	v_cndmask_b32_e64 v111, v112, v207, s[18:19]
	v_cndmask_b32_e64 v110, v113, v207, s[20:21]
	s_or_b64 s[28:29], s[28:29], vcc
	v_cmp_gt_i32_e32 vcc, 38, v117
	v_cmp_lt_i32_e64 s[30:31], 38, v116
	v_max3_f32 v96, v96, v106, v107
	v_cndmask_b32_e64 v109, v114, v207, s[22:23]
	v_cndmask_b32_e64 v108, v115, v207, s[24:25]
	s_or_b64 s[30:31], s[30:31], vcc
	v_cmp_gt_i32_e32 vcc, 39, v117
	v_cmp_lt_i32_e64 s[34:35], 39, v116
	v_max3_f32 v96, v96, v111, v110
	v_cndmask_b32_e64 v97, v100, v207, s[26:27]
	v_cndmask_b32_e64 v99, v101, v207, s[28:29]
	s_or_b64 s[34:35], s[34:35], vcc
	v_max3_f32 v96, v96, v109, v108
	v_cndmask_b32_e64 v101, v102, v207, s[30:31]
	v_cndmask_b32_e64 v103, v103, v207, s[34:35]
	v_max3_f32 v96, v96, v97, v99
	v_max3_f32 v96, v96, v101, v103
	v_sub_f32_e32 v98, v96, v84
	v_mul_f32_e32 v98, 0x3e38aa3b, v98
	v_cmp_lt_f32_e32 vcc, s42, v98
	s_cbranch_vccz .LBB0_1904
	v_mov_b32_e32 v98, v96
	s_nop 1
	v_permlane16_swap_b32_e32 v96, v98
	v_max_f32_e32 v96, v98, v96
	v_mov_b32_e32 v98, v96
	s_nop 1
	v_permlane32_swap_b32_e32 v96, v98
	v_max3_f32 v112, v84, v96, v98
	v_sub_f32_e32 v84, v84, v112
	v_mul_f32_e32 v84, 0x3e38aa3b, v84
	v_exp_f32_e32 v84, v84
	v_mov_b32_e32 v113, v85
	v_mul_f32_e32 v82, v82, v84
	v_pk_mul_f32 v[6:7], v[6:7], v[84:85] op_sel_hi:[1,0]
	v_pk_mul_f32 v[4:5], v[4:5], v[84:85] op_sel_hi:[1,0]
	v_pk_mul_f32 v[14:15], v[14:15], v[84:85] op_sel_hi:[1,0]
	v_pk_mul_f32 v[12:13], v[12:13], v[84:85] op_sel_hi:[1,0]
	v_pk_mul_f32 v[22:23], v[22:23], v[84:85] op_sel_hi:[1,0]
	v_pk_mul_f32 v[20:21], v[20:21], v[84:85] op_sel_hi:[1,0]
	v_pk_mul_f32 v[30:31], v[30:31], v[84:85] op_sel_hi:[1,0]
	v_pk_mul_f32 v[28:29], v[28:29], v[84:85] op_sel_hi:[1,0]
	v_mul_f32_e32 v84, 0xbe38aa3b, v112
	v_fmamk_f32 v85, v92, 0x3e38aa3b, v84
	v_exp_f32_e32 v96, v85
	v_fmamk_f32 v85, v93, 0x3e38aa3b, v84
	v_exp_f32_e32 v98, v85
	v_fmamk_f32 v85, v94, 0x3e38aa3b, v84
	v_exp_f32_e32 v100, v85
	v_fmamk_f32 v85, v95, 0x3e38aa3b, v84
	v_exp_f32_e32 v102, v85
	v_fmamk_f32 v92, v104, 0x3e38aa3b, v84
	v_add_f32_e32 v85, 0, v96
	v_exp_f32_e32 v104, v92
	v_fmamk_f32 v92, v105, 0x3e38aa3b, v84
	v_add_f32_e32 v85, v98, v85
	v_exp_f32_e32 v105, v92
	v_fmamk_f32 v92, v106, 0x3e38aa3b, v84
	v_add_f32_e32 v85, v100, v85
	v_exp_f32_e32 v106, v92
	v_fmamk_f32 v92, v107, 0x3e38aa3b, v84
	v_add_f32_e32 v85, v102, v85
	v_exp_f32_e32 v107, v92
	v_fmamk_f32 v92, v111, 0x3e38aa3b, v84
	v_add_f32_e32 v85, v104, v85
	v_exp_f32_e32 v92, v92
	v_fmamk_f32 v93, v110, 0x3e38aa3b, v84
	v_add_f32_e32 v85, v105, v85
	v_exp_f32_e32 v93, v93
	v_fmamk_f32 v94, v109, 0x3e38aa3b, v84
	v_add_f32_e32 v85, v106, v85
	v_exp_f32_e32 v94, v94
	v_fmamk_f32 v95, v108, 0x3e38aa3b, v84
	v_add_f32_e32 v85, v107, v85
	v_exp_f32_e32 v95, v95
	v_fmamk_f32 v97, v97, 0x3e38aa3b, v84
	v_add_f32_e32 v85, v92, v85
	v_exp_f32_e32 v97, v97
	v_fmamk_f32 v99, v99, 0x3e38aa3b, v84
	v_add_f32_e32 v85, v93, v85
	v_exp_f32_e32 v99, v99
	v_fmamk_f32 v101, v101, 0x3e38aa3b, v84
	v_add_f32_e32 v85, v94, v85
	v_exp_f32_e32 v101, v101
	v_fmac_f32_e32 v84, 0x3e38aa3b, v103
	v_add_f32_e32 v85, v95, v85
	v_exp_f32_e32 v103, v84
	v_add_f32_e32 v84, v97, v85
	v_add_f32_e32 v84, v99, v84
	v_add_f32_e32 v84, v101, v84
	v_add_f32_e32 v108, v103, v84
	v_mov_b64_e32 v[84:85], v[112:113]
	s_branch .LBB0_1905

.LBB0_1925:
	v_mov_b32_e32 v6, v186
	s_nop 0
	v_and_b32_e32 v7, 15, v6
	v_bfe_u32 v6, v6, 4, 2
	v_lshlrev_b32_e32 v11, 4, v6
	v_mad_u32_u24 v7, v7, s43, v11
	ds_read_b128 v[54:57], v7
	ds_read_b128 v[58:61], v7 offset:64
	v_lshlrev_b32_e32 v6, 3, v6
	s_waitcnt lgkmcnt(1)
	v_mfma_f32_16x16x32_bf16 v[62:65], v[54:57], v[20:23], 0
	v_sub_u32_e32 v6, v9, v6
	v_cmp_gt_i32_e64 s[0:1], 0, v6
	v_cmp_gt_i32_e64 s[2:3], 1, v6
	v_mfma_f32_16x16x32_bf16 v[54:57], v[54:57], v[28:31], 0
	v_cmp_gt_i32_e64 s[4:5], 2, v6
	v_cmp_gt_i32_e64 s[6:7], 3, v6
	v_cmp_gt_i32_e64 s[8:9], 4, v6
	s_waitcnt lgkmcnt(0)
	v_mfma_f32_16x16x32_bf16 v[62:65], v[58:61], v[24:27], v[62:65]
	v_cmp_gt_i32_e64 s[10:11], 5, v6
	v_cmp_gt_i32_e64 s[14:15], 6, v6
	v_cmp_gt_i32_e64 s[16:17], 7, v6
	v_mfma_f32_16x16x32_bf16 v[54:57], v[58:61], v[32:35], v[54:57]
	ds_read_b128 v[58:61], v7 offset:2304
	ds_read_b128 v[66:69], v7 offset:2368
	ds_read_b128 v[78:81], v7 offset:4608
	ds_read_b128 v[84:87], v7 offset:4672
	ds_read_b128 v[92:95], v7 offset:6912
	ds_read_b128 v[96:99], v7 offset:6976
	s_waitcnt lgkmcnt(5)
	v_mfma_f32_16x16x32_bf16 v[74:77], v[58:61], v[20:23], 0
	v_cndmask_b32_e64 v18, v62, v207, s[0:1]
	v_cndmask_b32_e64 v39, v63, v207, s[2:3]
	v_cndmask_b32_e64 v41, v64, v207, s[4:5]
	v_mfma_f32_16x16x32_bf16 v[58:61], v[58:61], v[28:31], 0
	v_cmp_gt_i32_e64 s[18:19], 32, v6
	v_cmp_gt_i32_e64 s[20:21], 33, v6
	v_cmp_gt_i32_e64 s[22:23], 34, v6
	s_waitcnt lgkmcnt(4)
	v_mfma_f32_16x16x32_bf16 v[88:91], v[66:69], v[24:27], v[74:77]
	v_cmp_gt_i32_e64 s[24:25], 35, v6
	v_cmp_gt_i32_e64 s[26:27], 36, v6
	v_cmp_gt_i32_e64 s[28:29], 37, v6
	v_mfma_f32_16x16x32_bf16 v[58:61], v[66:69], v[32:35], v[58:61]
	v_cndmask_b32_e64 v75, v65, v207, s[6:7]
	v_cmp_gt_i32_e64 s[30:31], 38, v6
	v_cmp_gt_i32_e64 s[34:35], 39, v6
	s_waitcnt lgkmcnt(3)
	v_mfma_f32_16x16x32_bf16 v[66:69], v[78:81], v[20:23], 0
	v_max_f32_e32 v6, v39, v18
	v_mfma_f32_16x16x32_bf16 v[76:79], v[78:81], v[28:31], 0
	v_cndmask_b32_e64 v14, v88, v207, s[8:9]
	v_cndmask_b32_e64 v42, v89, v207, s[10:11]
	v_max3_f32 v6, v6, v41, v75
	s_waitcnt lgkmcnt(2)
	v_mfma_f32_16x16x32_bf16 v[62:65], v[84:87], v[32:35], v[76:79]
	v_cndmask_b32_e64 v43, v90, v207, s[14:15]
	v_cndmask_b32_e64 v71, v91, v207, s[16:17]
	v_max3_f32 v6, v6, v14, v42
	s_waitcnt lgkmcnt(1)
	v_mfma_f32_16x16x32_bf16 v[76:79], v[92:95], v[20:23], 0
	v_max3_f32 v6, v6, v43, v71
	v_mfma_f32_16x16x32_bf16 v[66:69], v[84:87], v[24:27], v[66:69]
	s_waitcnt lgkmcnt(0)
	v_mfma_f32_16x16x32_bf16 v[76:79], v[96:99], v[24:27], v[76:79]
	s_nop 5
	v_cndmask_b32_e64 v15, v66, v207, s[18:19]
	v_cndmask_b32_e64 v45, v67, v207, s[20:21]
	v_cndmask_b32_e64 v19, v68, v207, s[22:23]
	v_cndmask_b32_e64 v74, v69, v207, s[24:25]
	v_mfma_f32_16x16x32_bf16 v[66:69], v[92:95], v[28:31], 0
	v_max3_f32 v6, v6, v15, v45
	v_cndmask_b32_e64 v17, v76, v207, s[26:27]
	v_cndmask_b32_e64 v37, v77, v207, s[28:29]
	v_max3_f32 v6, v6, v19, v74
	v_cndmask_b32_e64 v38, v78, v207, s[30:31]
	v_cndmask_b32_e64 v70, v79, v207, s[34:35]
	v_max3_f32 v6, v6, v17, v37
	v_mfma_f32_16x16x32_bf16 v[66:69], v[96:99], v[32:35], v[66:69]
	v_max3_f32 v6, v6, v38, v70
	v_sub_f32_e32 v7, v6, v2
	v_mul_f32_e32 v7, 0x3e38aa3b, v7
	v_cmp_lt_f32_e32 vcc, s42, v7
	s_cbranch_vccz .LBB0_1930
	v_mov_b32_e32 v7, v6
	s_nop 1
	v_permlane16_swap_b32_e32 v6, v7
	v_max_f32_e32 v6, v7, v6
	v_mov_b32_e32 v7, v6
	s_nop 1
	v_permlane32_swap_b32_e32 v6, v7
	v_max3_f32 v6, v2, v6, v7
	v_mul_f32_e32 v13, 0xbe38aa3b, v6
	v_fmamk_f32 v76, v18, 0x3e38aa3b, v13
	v_exp_f32_e32 v76, v76
	v_fmamk_f32 v77, v39, 0x3e38aa3b, v13
	v_exp_f32_e32 v77, v77
	v_sub_f32_e32 v7, v2, v6
	v_add_f32_e32 v76, 0, v76
	v_mul_f32_e32 v7, 0x3e38aa3b, v7
	v_add_f32_e32 v76, v77, v76
	v_fmamk_f32 v77, v41, 0x3e38aa3b, v13
	v_exp_f32_e32 v77, v77
	v_exp_f32_e32 v11, v7
	v_mov_b32_e32 v7, v3
	v_add_f32_e32 v76, v77, v76
	v_fmamk_f32 v77, v75, 0x3e38aa3b, v13
	v_exp_f32_e32 v77, v77
	v_mul_f32_e32 v11, v10, v11
	v_add_f32_e32 v76, v77, v76
	v_fmamk_f32 v77, v14, 0x3e38aa3b, v13
	v_exp_f32_e32 v77, v77
	s_nop 0
	v_add_f32_e32 v76, v77, v76
	v_fmamk_f32 v77, v42, 0x3e38aa3b, v13
	v_exp_f32_e32 v77, v77
	s_nop 0
	v_add_f32_e32 v76, v77, v76
	v_fmamk_f32 v77, v43, 0x3e38aa3b, v13
	v_exp_f32_e32 v77, v77
	s_nop 0
	v_add_f32_e32 v76, v77, v76
	v_fmamk_f32 v77, v71, 0x3e38aa3b, v13
	v_exp_f32_e32 v77, v77
	s_nop 0
	v_add_f32_e32 v76, v77, v76
	v_fmamk_f32 v77, v15, 0x3e38aa3b, v13
	v_exp_f32_e32 v77, v77
	s_nop 0
	v_add_f32_e32 v76, v77, v76
	v_fmamk_f32 v77, v45, 0x3e38aa3b, v13
	v_exp_f32_e32 v77, v77
	s_nop 0
	v_add_f32_e32 v76, v77, v76
	v_fmamk_f32 v77, v19, 0x3e38aa3b, v13
	v_exp_f32_e32 v77, v77
	s_nop 0
	v_add_f32_e32 v76, v77, v76
	v_fmamk_f32 v77, v74, 0x3e38aa3b, v13
	v_exp_f32_e32 v77, v77
	s_nop 0
	v_add_f32_e32 v76, v77, v76
	v_fmamk_f32 v77, v17, 0x3e38aa3b, v13
	v_exp_f32_e32 v77, v77
	s_nop 0
	v_add_f32_e32 v76, v77, v76
	v_fmamk_f32 v77, v37, 0x3e38aa3b, v13
	v_exp_f32_e32 v77, v77
	s_nop 0
	v_add_f32_e32 v76, v77, v76
	v_fmamk_f32 v77, v38, 0x3e38aa3b, v13
	v_exp_f32_e32 v77, v77
	v_fmac_f32_e32 v13, 0x3e38aa3b, v70
	v_exp_f32_e32 v13, v13
	v_add_f32_e32 v76, v77, v76
	v_add_f32_e32 v13, v13, v76
	s_cbranch_execnz .LBB0_1928

.LBB0_1928:
	v_cndmask_b32_e64 v70, v54, v207, s[0:1]
	v_cndmask_b32_e64 v55, v55, v207, s[2:3]
	v_max_f32_e32 v2, v55, v55
	v_max_f32_e32 v3, v70, v70
	v_cndmask_b32_e64 v54, v56, v207, s[4:5]
	v_cndmask_b32_e64 v45, v57, v207, s[6:7]
	v_max_f32_e32 v2, v3, v2
	v_cndmask_b32_e64 v43, v58, v207, s[8:9]
	v_cndmask_b32_e64 v42, v59, v207, s[10:11]
	v_max3_f32 v2, v2, v54, v45
	v_cndmask_b32_e64 v41, v60, v207, s[14:15]
	v_cndmask_b32_e64 v39, v61, v207, s[16:17]
	v_max3_f32 v2, v2, v43, v42
	v_cndmask_b32_e64 v38, v62, v207, s[18:19]
	v_cndmask_b32_e64 v37, v63, v207, s[20:21]
	v_max3_f32 v2, v2, v41, v39
	v_cndmask_b32_e64 v19, v64, v207, s[22:23]
	v_cndmask_b32_e64 v18, v65, v207, s[24:25]
	v_max3_f32 v2, v2, v38, v37
	v_cndmask_b32_e64 v17, v66, v207, s[26:27]
	v_cndmask_b32_e64 v15, v67, v207, s[28:29]
	v_max3_f32 v2, v2, v19, v18
	v_cndmask_b32_e64 v14, v68, v207, s[30:31]
	v_cndmask_b32_e64 v10, v69, v207, s[34:35]
	v_max3_f32 v2, v2, v17, v15
	v_max3_f32 v2, v2, v14, v10
	v_sub_f32_e32 v3, v2, v7
	v_mul_f32_e32 v3, 0x3e38aa3b, v3
	v_cmp_lt_f32_e32 vcc, s42, v3
	s_cbranch_vccz .LBB0_1931
	v_mov_b32_e32 v3, v2
	s_nop 1
	v_permlane16_swap_b32_e32 v2, v3
	v_max_f32_e32 v2, v3, v2
	v_mov_b32_e32 v3, v2
	s_nop 1
	v_permlane32_swap_b32_e32 v2, v3
	v_max3_f32 v3, v7, v2, v3
	v_mul_f32_e32 v57, 0xbe38aa3b, v3
	v_fmamk_f32 v58, v70, 0x3e38aa3b, v57
	v_exp_f32_e32 v58, v58
	v_fmamk_f32 v59, v55, 0x3e38aa3b, v57
	v_exp_f32_e32 v59, v59
	v_sub_f32_e32 v2, v7, v3
	v_add_f32_e32 v58, 0, v58
	v_mul_f32_e32 v2, 0x3e38aa3b, v2
	v_add_f32_e32 v58, v59, v58
	v_fmamk_f32 v59, v54, 0x3e38aa3b, v57
	v_exp_f32_e32 v59, v59
	v_exp_f32_e32 v56, v2
	v_mov_b32_e32 v2, v6
	v_add_f32_e32 v58, v59, v58
	v_fmamk_f32 v59, v45, 0x3e38aa3b, v57
	v_exp_f32_e32 v59, v59
	v_mul_f32_e32 v56, v5, v56
	v_add_f32_e32 v58, v59, v58
	v_fmamk_f32 v59, v43, 0x3e38aa3b, v57
	v_exp_f32_e32 v59, v59
	s_nop 0
	v_add_f32_e32 v58, v59, v58
	v_fmamk_f32 v59, v42, 0x3e38aa3b, v57
	v_exp_f32_e32 v59, v59
	s_nop 0
	v_add_f32_e32 v58, v59, v58
	v_fmamk_f32 v59, v41, 0x3e38aa3b, v57
	v_exp_f32_e32 v59, v59
	s_nop 0
	v_add_f32_e32 v58, v59, v58
	v_fmamk_f32 v59, v39, 0x3e38aa3b, v57
	v_exp_f32_e32 v59, v59
	s_nop 0
	v_add_f32_e32 v58, v59, v58
	v_fmamk_f32 v59, v38, 0x3e38aa3b, v57
	v_exp_f32_e32 v59, v59
	s_nop 0
	v_add_f32_e32 v58, v59, v58
	v_fmamk_f32 v59, v37, 0x3e38aa3b, v57
	v_exp_f32_e32 v59, v59
	s_nop 0
	v_add_f32_e32 v58, v59, v58
	v_fmamk_f32 v59, v19, 0x3e38aa3b, v57
	v_exp_f32_e32 v59, v59
	s_nop 0
	v_add_f32_e32 v58, v59, v58
	v_fmamk_f32 v59, v18, 0x3e38aa3b, v57
	v_exp_f32_e32 v59, v59
	s_nop 0
	v_add_f32_e32 v58, v59, v58
	v_fmamk_f32 v59, v17, 0x3e38aa3b, v57
	v_exp_f32_e32 v59, v59
	s_nop 0
	v_add_f32_e32 v58, v59, v58
	v_fmamk_f32 v59, v15, 0x3e38aa3b, v57
	v_exp_f32_e32 v59, v59
	s_nop 0
	v_add_f32_e32 v58, v59, v58
	v_fmamk_f32 v59, v14, 0x3e38aa3b, v57
	v_exp_f32_e32 v59, v59
	v_fmac_f32_e32 v57, 0x3e38aa3b, v10
	v_exp_f32_e32 v57, v57
	v_add_f32_e32 v58, v59, v58
	v_add_f32_e32 v57, v57, v58
	s_movk_i32 s34, 0x3fff
	s_cbranch_execnz .LBB0_1922
	s_branch .LBB0_1921

.LBB0_1935:
	v_mov_b32_e32 v103, v101
	s_nop 1
	v_permlane16_swap_b32_e32 v101, v103
	v_max_f32_e32 v101, v103, v101
	v_mov_b32_e32 v103, v101
	s_nop 1
	v_permlane32_swap_b32_e32 v101, v103
	v_max3_f32 v101, v137, v101, v103
	v_sub_f32_e32 v103, v137, v101
	v_mul_f32_e32 v103, 0x3e16c740, v103
	v_exp_f32_e32 v108, v103
	v_mov_b32_e32 v137, v101
	v_mul_f32_e32 v135, v135, v108
	v_pk_mul_f32 v[42:43], v[42:43], v[108:109] op_sel_hi:[1,0]
	v_pk_mul_f32 v[40:41], v[40:41], v[108:109] op_sel_hi:[1,0]
	v_pk_mul_f32 v[74:75], v[74:75], v[108:109] op_sel_hi:[1,0]
	v_pk_mul_f32 v[72:73], v[72:73], v[108:109] op_sel_hi:[1,0]
	v_pk_mul_f32 v[82:83], v[82:83], v[108:109] op_sel_hi:[1,0]
	v_pk_mul_f32 v[80:81], v[80:81], v[108:109] op_sel_hi:[1,0]
	v_pk_mul_f32 v[90:91], v[90:91], v[108:109] op_sel_hi:[1,0]
	v_pk_mul_f32 v[88:89], v[88:89], v[108:109] op_sel_hi:[1,0]
	v_mul_f32_e32 v108, 0xbe16c740, v101
	v_fmamk_f32 v101, v149, 0x3e16c740, v108
	v_exp_f32_e32 v101, v101
	v_fmamk_f32 v103, v148, 0x3e16c740, v108
	v_exp_f32_e32 v103, v103
	v_fmamk_f32 v105, v147, 0x3e16c740, v108
	v_exp_f32_e32 v105, v105
	v_fmamk_f32 v107, v146, 0x3e16c740, v108
	v_exp_f32_e32 v107, v107
	v_add_f32_e32 v109, v103, v101
	v_add_f32_e32 v109, v105, v109
	v_add_f32_e32 v146, v107, v109
	v_fmamk_f32 v109, v145, 0x3e16c740, v108
	v_exp_f32_e32 v109, v109
	v_fmamk_f32 v110, v144, 0x3e16c740, v108
	v_exp_f32_e32 v110, v110
	v_fmamk_f32 v111, v143, 0x3e16c740, v108
	v_exp_f32_e32 v111, v111
	v_fmamk_f32 v142, v142, 0x3e16c740, v108
	v_exp_f32_e32 v142, v142
	v_fmamk_f32 v97, v97, 0x3e16c740, v108
	v_add_f32_e32 v143, v109, v146
	v_exp_f32_e32 v97, v97
	v_fmamk_f32 v98, v98, 0x3e16c740, v108
	v_add_f32_e32 v143, v110, v143
	v_exp_f32_e32 v98, v98
	v_fmamk_f32 v99, v99, 0x3e16c740, v108
	v_add_f32_e32 v143, v111, v143
	v_exp_f32_e32 v99, v99
	v_fmamk_f32 v100, v100, 0x3e16c740, v108
	v_add_f32_e32 v143, v142, v143
	v_exp_f32_e32 v100, v100
	v_fmamk_f32 v102, v102, 0x3e16c740, v108
	v_add_f32_e32 v143, v97, v143
	v_exp_f32_e32 v102, v102
	v_fmamk_f32 v104, v104, 0x3e16c740, v108
	v_fmamk_f32 v106, v106, 0x3e16c740, v108
	v_fmac_f32_e32 v108, 0x3e16c740, v96
	v_add_f32_e32 v143, v98, v143
	v_exp_f32_e32 v104, v104
	v_exp_f32_e32 v106, v106
	v_exp_f32_e32 v108, v108
	v_add_f32_e32 v143, v99, v143
	v_add_f32_e32 v143, v100, v143
	v_add_f32_e32 v96, v102, v143

.LBB0_1941:
	s_add_i32 s3, s2, 0xffffff40
	v_cmp_le_i32_e32 vcc, s3, v133
	s_and_saveexec_b64 s[8:9], vcc
	s_cbranch_execz .LBB0_1959
	s_add_i32 s3, s2, 0xffffff7f
	v_cmp_le_i32_e32 vcc, s3, v139
	s_and_saveexec_b64 s[10:11], vcc
	s_xor_b64 s[10:11], exec, s[10:11]
	s_cbranch_execz .LBB0_1950
	v_mov_b32_e32 v96, v186
	s_nop 0
	v_and_b32_e32 v141, 15, v96
	v_and_b32_e32 v140, 48, v96
	v_mad_u32_u24 v146, v141, s36, v140
	ds_read_b128 v[96:99], v146
	ds_read_b128 v[104:107], v146 offset:64
	ds_read_b128 v[108:111], v146 offset:3392
	ds_read_b128 v[116:119], v146 offset:6720
	ds_read_b128 v[124:127], v146 offset:6784
	ds_read_b128 v[142:145], v146 offset:10048
	s_waitcnt lgkmcnt(5)
	v_mfma_f32_16x16x32_bf16 v[100:103], v[96:99], v[16:19], 0
	v_mfma_f32_16x16x32_bf16 v[96:99], v[96:99], v[8:11], 0
	s_waitcnt lgkmcnt(4)
	v_mfma_f32_16x16x32_bf16 v[100:103], v[104:107], v[0:3], v[100:103]
	v_mfma_f32_16x16x32_bf16 v[96:99], v[104:107], v[12:15], v[96:99]
	ds_read_b128 v[104:107], v146 offset:128
	s_waitcnt lgkmcnt(0)
	v_mfma_f32_16x16x32_bf16 v[112:115], v[104:107], v[4:7], v[100:103]
	s_nop 3
	ds_read_b128 v[100:103], v146 offset:3328
	v_mfma_f32_16x16x32_bf16 v[96:99], v[104:107], v[20:23], v[96:99]
	s_waitcnt lgkmcnt(0)
	v_mfma_f32_16x16x32_bf16 v[104:107], v[100:103], v[16:19], 0
	v_mfma_f32_16x16x32_bf16 v[100:103], v[100:103], v[8:11], 0
	v_mfma_f32_16x16x32_bf16 v[104:107], v[108:111], v[0:3], v[104:107]
	v_mfma_f32_16x16x32_bf16 v[100:103], v[108:111], v[12:15], v[100:103]
	ds_read_b128 v[108:111], v146 offset:3456
	s_waitcnt lgkmcnt(0)
	v_mfma_f32_16x16x32_bf16 v[120:123], v[108:111], v[4:7], v[104:107]
	v_mfma_f32_16x16x32_bf16 v[104:107], v[108:111], v[20:23], v[100:103]
	s_nop 3
	ds_read_b128 v[100:103], v146 offset:6656
	s_waitcnt lgkmcnt(0)
	v_mfma_f32_16x16x32_bf16 v[108:111], v[100:103], v[16:19], 0
	v_mfma_f32_16x16x32_bf16 v[100:103], v[100:103], v[8:11], 0
	v_mfma_f32_16x16x32_bf16 v[108:111], v[116:119], v[0:3], v[108:111]
	v_mfma_f32_16x16x32_bf16 v[100:103], v[116:119], v[12:15], v[100:103]
	v_mfma_f32_16x16x32_bf16 v[116:119], v[124:127], v[4:7], v[108:111]
	s_nop 5
	ds_read_b128 v[108:111], v146 offset:9984
	v_mfma_f32_16x16x32_bf16 v[100:103], v[124:127], v[20:23], v[100:103]
	s_waitcnt lgkmcnt(0)
	v_mfma_f32_16x16x32_bf16 v[124:127], v[108:111], v[16:19], 0
	v_mfma_f32_16x16x32_bf16 v[108:111], v[108:111], v[8:11], 0
	v_mfma_f32_16x16x32_bf16 v[124:127], v[142:145], v[0:3], v[124:127]
	v_mfma_f32_16x16x32_bf16 v[108:111], v[142:145], v[12:15], v[108:111]
	ds_read_b128 v[142:145], v146 offset:10112
	s_waitcnt lgkmcnt(0)
	v_mfma_f32_16x16x32_bf16 v[124:127], v[142:145], v[4:7], v[124:127]
	v_mfma_f32_16x16x32_bf16 v[108:111], v[142:145], v[20:23], v[108:111]
	v_max_f32_e32 v142, v113, v112
	v_max3_f32 v142, v142, v114, v115
	v_max3_f32 v142, v142, v120, v121
	v_max3_f32 v142, v142, v122, v123
	v_max3_f32 v142, v142, v116, v117
	v_max3_f32 v142, v142, v118, v119
	s_nop 0
	v_max3_f32 v142, v142, v124, v125
	v_max3_f32 v142, v142, v126, v127
	v_sub_f32_e32 v143, v142, v136
	v_mul_f32_e32 v143, 0x3e16c740, v143
	v_cmp_lt_f32_e32 vcc, s42, v143
	s_cbranch_vccz .LBB0_1945
	v_mov_b32_e32 v143, v142
	s_nop 1
	v_permlane16_swap_b32_e32 v142, v143
	v_max_f32_e32 v142, v143, v142
	v_mov_b32_e32 v143, v142
	s_nop 1
	v_permlane32_swap_b32_e32 v142, v143
	v_max3_f32 v146, v136, v142, v143
	v_sub_f32_e32 v136, v136, v146
	v_mul_f32_e32 v136, 0x3e16c740, v136
	v_exp_f32_e32 v136, v136
	v_mov_b32_e32 v147, v137
	v_mul_f32_e32 v134, v134, v136
	v_pk_mul_f32 v[50:51], v[50:51], v[136:137] op_sel_hi:[1,0]
	v_pk_mul_f32 v[48:49], v[48:49], v[136:137] op_sel_hi:[1,0]
	v_pk_mul_f32 v[78:79], v[78:79], v[136:137] op_sel_hi:[1,0]
	v_pk_mul_f32 v[76:77], v[76:77], v[136:137] op_sel_hi:[1,0]
	v_pk_mul_f32 v[86:87], v[86:87], v[136:137] op_sel_hi:[1,0]
	v_pk_mul_f32 v[84:85], v[84:85], v[136:137] op_sel_hi:[1,0]
	v_pk_mul_f32 v[94:95], v[94:95], v[136:137] op_sel_hi:[1,0]
	v_pk_mul_f32 v[92:93], v[92:93], v[136:137] op_sel_hi:[1,0]
	v_mul_f32_e32 v136, 0xbe16c740, v146
	v_fmamk_f32 v112, v112, 0x3e16c740, v136
	v_exp_f32_e32 v142, v112
	v_fmamk_f32 v112, v113, 0x3e16c740, v136
	v_exp_f32_e32 v143, v112
	v_fmamk_f32 v112, v114, 0x3e16c740, v136
	v_exp_f32_e32 v144, v112
	v_fmamk_f32 v112, v115, 0x3e16c740, v136
	v_exp_f32_e32 v145, v112
	v_fmamk_f32 v113, v120, 0x3e16c740, v136
	v_add_f32_e32 v112, 0, v142
	v_exp_f32_e32 v120, v113
	v_fmamk_f32 v113, v121, 0x3e16c740, v136
	v_add_f32_e32 v112, v143, v112
	v_exp_f32_e32 v121, v113
	v_fmamk_f32 v113, v122, 0x3e16c740, v136
	v_add_f32_e32 v112, v144, v112
	v_exp_f32_e32 v122, v113
	v_fmamk_f32 v113, v123, 0x3e16c740, v136
	v_add_f32_e32 v112, v145, v112
	v_exp_f32_e32 v123, v113
	v_add_f32_e32 v112, v120, v112
	v_add_f32_e32 v112, v121, v112
	v_add_f32_e32 v112, v122, v112
	v_add_f32_e32 v137, v123, v112
	v_fmamk_f32 v112, v116, 0x3e16c740, v136
	v_exp_f32_e32 v112, v112
	v_fmamk_f32 v113, v117, 0x3e16c740, v136
	v_exp_f32_e32 v113, v113
	v_fmamk_f32 v114, v118, 0x3e16c740, v136
	v_exp_f32_e32 v114, v114
	v_fmamk_f32 v115, v119, 0x3e16c740, v136
	v_exp_f32_e32 v115, v115
	v_add_f32_e32 v116, v112, v137
	v_add_f32_e32 v116, v113, v116
	v_add_f32_e32 v116, v114, v116
	v_add_f32_e32 v137, v115, v116
	v_fmamk_f32 v116, v124, 0x3e16c740, v136
	v_exp_f32_e32 v116, v116
	v_fmamk_f32 v117, v125, 0x3e16c740, v136
	v_exp_f32_e32 v117, v117
	v_fmamk_f32 v118, v126, 0x3e16c740, v136
	v_exp_f32_e32 v118, v118
	v_fmac_f32_e32 v136, 0x3e16c740, v127
	v_exp_f32_e32 v119, v136
	v_add_f32_e32 v124, v116, v137
	v_add_f32_e32 v124, v117, v124
	v_add_f32_e32 v124, v118, v124
	v_add_f32_e32 v124, v119, v124
	v_mov_b64_e32 v[136:137], v[146:147]
	s_branch .LBB0_1946
.LBB0_1945:
	v_mul_f32_e32 v146, 0xbe16c740, v136
	v_fmamk_f32 v112, v112, 0x3e16c740, v146
	v_exp_f32_e32 v142, v112
	v_fmamk_f32 v112, v113, 0x3e16c740, v146
	v_exp_f32_e32 v143, v112
	v_fmamk_f32 v112, v114, 0x3e16c740, v146
	v_exp_f32_e32 v144, v112
	v_fmamk_f32 v112, v115, 0x3e16c740, v146
	v_exp_f32_e32 v145, v112
	v_fmamk_f32 v112, v120, 0x3e16c740, v146
	v_exp_f32_e32 v120, v112
	v_fmamk_f32 v112, v121, 0x3e16c740, v146
	v_exp_f32_e32 v121, v112
	v_fmamk_f32 v112, v122, 0x3e16c740, v146
	v_exp_f32_e32 v122, v112
	v_fmamk_f32 v112, v123, 0x3e16c740, v146
	v_exp_f32_e32 v123, v112
	v_fmamk_f32 v112, v116, 0x3e16c740, v146
	v_fmamk_f32 v116, v124, 0x3e16c740, v146
	v_add_f32_e32 v124, v143, v142
	v_add_f32_e32 v124, v144, v124
	v_add_f32_e32 v124, v145, v124
	v_exp_f32_e32 v112, v112
	v_fmamk_f32 v113, v117, 0x3e16c740, v146
	v_add_f32_e32 v124, v124, v120
	v_exp_f32_e32 v113, v113
	v_fmamk_f32 v114, v118, 0x3e16c740, v146
	v_add_f32_e32 v124, v121, v124
	v_exp_f32_e32 v114, v114
	v_fmamk_f32 v115, v119, 0x3e16c740, v146
	v_add_f32_e32 v124, v122, v124
	v_exp_f32_e32 v115, v115
	v_add_f32_e32 v124, v123, v124
	v_exp_f32_e32 v116, v116
	v_fmamk_f32 v117, v125, 0x3e16c740, v146
	v_add_f32_e32 v124, v124, v112
	v_exp_f32_e32 v117, v117
	v_fmamk_f32 v118, v126, 0x3e16c740, v146
	v_add_f32_e32 v124, v113, v124
	v_exp_f32_e32 v118, v118
	v_fmac_f32_e32 v146, 0x3e16c740, v127
	v_add_f32_e32 v124, v114, v124
	v_exp_f32_e32 v119, v146
	v_add_f32_e32 v124, v115, v124
	v_add_f32_e32 v124, v124, v116
	v_add_f32_e32 v124, v117, v124
	v_add_f32_e32 v124, v118, v124
	v_add_f32_e32 v124, v119, v124
.LBB0_1946:
	v_add_f32_e32 v134, v134, v124
	v_max_f32_e32 v124, v97, v96
	v_max3_f32 v124, v124, v98, v99
	v_max3_f32 v124, v124, v104, v105
	v_max3_f32 v124, v124, v106, v107
	v_max3_f32 v124, v124, v100, v101
	v_max3_f32 v124, v124, v102, v103
	v_max3_f32 v124, v124, v108, v109
	v_max3_f32 v124, v124, v110, v111
	v_sub_f32_e32 v125, v124, v137
	v_mul_f32_e32 v125, 0x3e16c740, v125
	v_cmp_lt_f32_e32 vcc, s42, v125
	s_cbranch_vccz .LBB0_1948
	v_mov_b32_e32 v125, v124
	s_nop 1
	v_permlane16_swap_b32_e32 v124, v125
	v_max_f32_e32 v124, v125, v124
	v_mov_b32_e32 v125, v124
	s_nop 1
	v_permlane32_swap_b32_e32 v124, v125
	v_max3_f32 v125, v137, v124, v125
	v_sub_f32_e32 v124, v137, v125
	v_mul_f32_e32 v124, 0x3e16c740, v124
	v_exp_f32_e32 v124, v124
	v_mul_f32_e32 v147, 0xbe16c740, v125
	v_fmamk_f32 v96, v96, 0x3e16c740, v147
	v_mov_b32_e32 v137, v125
	v_mul_f32_e32 v135, v135, v124
	v_pk_mul_f32 v[42:43], v[42:43], v[124:125] op_sel_hi:[1,0]
	v_pk_mul_f32 v[40:41], v[40:41], v[124:125] op_sel_hi:[1,0]
	v_pk_mul_f32 v[74:75], v[74:75], v[124:125] op_sel_hi:[1,0]
	v_pk_mul_f32 v[72:73], v[72:73], v[124:125] op_sel_hi:[1,0]
	v_pk_mul_f32 v[82:83], v[82:83], v[124:125] op_sel_hi:[1,0]
	v_pk_mul_f32 v[80:81], v[80:81], v[124:125] op_sel_hi:[1,0]
	v_pk_mul_f32 v[90:91], v[90:91], v[124:125] op_sel_hi:[1,0]
	v_pk_mul_f32 v[88:89], v[88:89], v[124:125] op_sel_hi:[1,0]
	v_exp_f32_e32 v124, v96
	v_fmamk_f32 v96, v97, 0x3e16c740, v147
	v_exp_f32_e32 v125, v96
	v_fmamk_f32 v96, v98, 0x3e16c740, v147
	v_exp_f32_e32 v126, v96
	v_fmamk_f32 v96, v99, 0x3e16c740, v147
	v_exp_f32_e32 v127, v96
	v_fmamk_f32 v97, v104, 0x3e16c740, v147
	v_add_f32_e32 v96, 0, v124
	v_exp_f32_e32 v146, v97
	v_fmamk_f32 v97, v105, 0x3e16c740, v147
	v_add_f32_e32 v96, v125, v96
	v_exp_f32_e32 v105, v97
	v_fmamk_f32 v97, v106, 0x3e16c740, v147
	v_add_f32_e32 v96, v126, v96
	v_exp_f32_e32 v106, v97
	v_fmamk_f32 v97, v107, 0x3e16c740, v147
	v_add_f32_e32 v96, v127, v96
	v_exp_f32_e32 v107, v97
	v_fmamk_f32 v97, v100, 0x3e16c740, v147
	v_add_f32_e32 v96, v146, v96
	v_exp_f32_e32 v97, v97
	v_fmamk_f32 v98, v101, 0x3e16c740, v147
	v_add_f32_e32 v96, v105, v96
	v_exp_f32_e32 v98, v98
	v_fmamk_f32 v99, v102, 0x3e16c740, v147
	v_add_f32_e32 v96, v106, v96
	v_exp_f32_e32 v99, v99
	v_fmamk_f32 v100, v103, 0x3e16c740, v147
	v_add_f32_e32 v96, v107, v96
	v_exp_f32_e32 v100, v100
	v_fmamk_f32 v101, v108, 0x3e16c740, v147
	v_fmamk_f32 v102, v109, 0x3e16c740, v147
	v_fmamk_f32 v103, v110, 0x3e16c740, v147
	v_fmac_f32_e32 v147, 0x3e16c740, v111
	v_add_f32_e32 v96, v97, v96
	v_exp_f32_e32 v101, v101
	v_exp_f32_e32 v102, v102
	v_exp_f32_e32 v103, v103
	v_exp_f32_e32 v104, v147
	v_add_f32_e32 v96, v98, v96
	v_add_f32_e32 v96, v99, v96
	s_branch .LBB0_1949
.LBB0_1948:
	v_mul_f32_e32 v147, 0xbe16c740, v137
	v_fmamk_f32 v96, v96, 0x3e16c740, v147
	v_exp_f32_e32 v124, v96
	v_fmamk_f32 v96, v97, 0x3e16c740, v147
	v_exp_f32_e32 v125, v96
	v_fmamk_f32 v96, v98, 0x3e16c740, v147
	v_exp_f32_e32 v126, v96
	v_fmamk_f32 v96, v99, 0x3e16c740, v147
	v_exp_f32_e32 v127, v96
	v_fmamk_f32 v96, v104, 0x3e16c740, v147
	v_exp_f32_e32 v146, v96
	v_fmamk_f32 v96, v105, 0x3e16c740, v147
	v_exp_f32_e32 v105, v96
	v_fmamk_f32 v96, v106, 0x3e16c740, v147
	v_exp_f32_e32 v106, v96
	v_fmamk_f32 v96, v107, 0x3e16c740, v147
	v_exp_f32_e32 v107, v96
	v_fmamk_f32 v96, v100, 0x3e16c740, v147
	v_exp_f32_e32 v97, v96
	v_fmamk_f32 v96, v101, 0x3e16c740, v147
	v_exp_f32_e32 v98, v96
	v_fmamk_f32 v96, v102, 0x3e16c740, v147
	v_exp_f32_e32 v99, v96
	v_fmamk_f32 v96, v103, 0x3e16c740, v147
	v_exp_f32_e32 v100, v96
	v_fmamk_f32 v96, v108, 0x3e16c740, v147
	v_exp_f32_e32 v101, v96
	v_fmamk_f32 v96, v109, 0x3e16c740, v147
	v_exp_f32_e32 v102, v96
	v_fmamk_f32 v96, v110, 0x3e16c740, v147
	v_exp_f32_e32 v103, v96
	v_add_f32_e32 v96, v125, v124
	v_add_f32_e32 v96, v126, v96
	v_add_f32_e32 v96, v127, v96
	v_add_f32_e32 v96, v146, v96
	v_add_f32_e32 v96, v105, v96
	v_add_f32_e32 v96, v106, v96
	v_add_f32_e32 v96, v107, v96
	v_add_f32_e32 v96, v97, v96
	v_add_f32_e32 v96, v98, v96
	v_fmac_f32_e32 v147, 0x3e16c740, v111
	v_add_f32_e32 v96, v99, v96
	v_exp_f32_e32 v104, v147

.LBB0_1950:
	s_andn2_saveexec_b64 s[10:11], s[10:11]
	s_cbranch_execz .LBB0_1958
	v_mov_b32_e32 v96, v186
	s_nop 0
	v_bfe_u32 v126, v96, 4, 2
	v_and_b32_e32 v113, 15, v96
	v_lshlrev_b32_e32 v112, 4, v126
	v_mad_u32_u24 v127, v113, s36, v112
	ds_read_b128 v[96:99], v127
	ds_read_b128 v[104:107], v127 offset:64
	ds_read_b128 v[108:111], v127 offset:3392
	ds_read_b128 v[118:121], v127 offset:6720
	ds_read_b128 v[122:125], v127 offset:10048
	s_waitcnt lgkmcnt(4)
	v_mfma_f32_16x16x32_bf16 v[100:103], v[96:99], v[16:19], 0
	v_mfma_f32_16x16x32_bf16 v[96:99], v[96:99], v[8:11], 0
	s_waitcnt lgkmcnt(3)
	v_mfma_f32_16x16x32_bf16 v[100:103], v[104:107], v[0:3], v[100:103]
	v_mfma_f32_16x16x32_bf16 v[96:99], v[104:107], v[12:15], v[96:99]
	ds_read_b128 v[104:107], v127 offset:128
	s_waitcnt lgkmcnt(0)
	v_mfma_f32_16x16x32_bf16 v[114:117], v[104:107], v[4:7], v[100:103]
	s_nop 3
	ds_read_b128 v[100:103], v127 offset:3328
	v_mfma_f32_16x16x32_bf16 v[96:99], v[104:107], v[20:23], v[96:99]
	s_waitcnt lgkmcnt(0)
	v_mfma_f32_16x16x32_bf16 v[104:107], v[100:103], v[16:19], 0
	v_mfma_f32_16x16x32_bf16 v[100:103], v[100:103], v[8:11], 0
	v_mfma_f32_16x16x32_bf16 v[104:107], v[108:111], v[0:3], v[104:107]
	v_mfma_f32_16x16x32_bf16 v[100:103], v[108:111], v[12:15], v[100:103]
	ds_read_b128 v[108:111], v127 offset:3456
	s_waitcnt lgkmcnt(0)
	v_mfma_f32_16x16x32_bf16 v[144:147], v[108:111], v[4:7], v[104:107]
	s_nop 3
	ds_read_b128 v[104:107], v127 offset:6656
	v_mfma_f32_16x16x32_bf16 v[100:103], v[108:111], v[20:23], v[100:103]
	s_waitcnt lgkmcnt(0)
	v_mfma_f32_16x16x32_bf16 v[108:111], v[104:107], v[16:19], 0
	v_mfma_f32_16x16x32_bf16 v[104:107], v[104:107], v[8:11], 0
	v_mfma_f32_16x16x32_bf16 v[108:111], v[118:121], v[0:3], v[108:111]
	v_mfma_f32_16x16x32_bf16 v[104:107], v[118:121], v[12:15], v[104:107]
	ds_read_b128 v[118:121], v127 offset:6784
	s_waitcnt lgkmcnt(0)
	v_mfma_f32_16x16x32_bf16 v[148:151], v[118:121], v[4:7], v[108:111]
	s_nop 3
	ds_read_b128 v[108:111], v127 offset:9984
	v_mfma_f32_16x16x32_bf16 v[104:107], v[118:121], v[20:23], v[104:107]
	s_waitcnt lgkmcnt(0)
	v_mfma_f32_16x16x32_bf16 v[118:121], v[108:111], v[16:19], 0
	v_mfma_f32_16x16x32_bf16 v[108:111], v[108:111], v[8:11], 0
	v_mfma_f32_16x16x32_bf16 v[118:121], v[122:125], v[0:3], v[118:121]
	v_mfma_f32_16x16x32_bf16 v[108:111], v[122:125], v[12:15], v[108:111]
	ds_read_b128 v[122:125], v127 offset:10112
	s_waitcnt lgkmcnt(0)
	v_mfma_f32_16x16x32_bf16 v[152:155], v[122:125], v[4:7], v[118:121]
	s_nop 3
	v_lshlrev_b32_e32 v118, 3, v126
	v_sub_u32_e32 v142, v132, v118
	v_mfma_f32_16x16x32_bf16 v[108:111], v[122:125], v[20:23], v[108:111]
	v_add_u32_e32 v125, -16, v142
	v_cmp_lt_i32_e32 vcc, -1, v125
	s_nop 1
	v_cndmask_b32_e32 v118, v207, v114, vcc
	v_cmp_lt_i32_e32 vcc, 0, v125
	s_nop 1
	v_cndmask_b32_e32 v120, v207, v115, vcc
	v_cmp_lt_i32_e32 vcc, 1, v125
	v_max_f32_e32 v143, v120, v120
	s_nop 0
	v_cndmask_b32_e32 v122, v207, v116, vcc
	v_cmp_lt_i32_e32 vcc, 2, v125
	s_nop 1
	v_cndmask_b32_e32 v124, v207, v117, vcc
	v_cmp_lt_i32_e32 vcc, 3, v125
	s_nop 1
	v_cndmask_b32_e32 v126, v207, v144, vcc
	v_cmp_lt_i32_e32 vcc, 4, v125
	v_max_f32_e32 v144, v118, v118
	v_max_f32_e32 v143, v144, v143
	v_cndmask_b32_e32 v127, v207, v145, vcc
	v_cmp_lt_i32_e32 vcc, 5, v125
	v_max3_f32 v143, v143, v122, v124
	v_max3_f32 v143, v143, v126, v127
	v_cndmask_b32_e32 v140, v207, v146, vcc
	v_cmp_lt_i32_e32 vcc, 6, v125
	s_nop 1
	v_cndmask_b32_e32 v141, v207, v147, vcc
	v_cmp_lt_i32_e32 vcc, 31, v125
	v_max3_f32 v143, v143, v140, v141
	s_nop 0
	v_cndmask_b32_e32 v114, v207, v148, vcc
	v_cmp_lt_i32_e32 vcc, 32, v125
	s_nop 1
	v_cndmask_b32_e32 v115, v207, v149, vcc
	v_cmp_lt_i32_e32 vcc, 33, v125
	v_max3_f32 v143, v143, v114, v115
	s_nop 0
	v_cndmask_b32_e32 v116, v207, v150, vcc
	v_cmp_lt_i32_e32 vcc, 34, v125
	s_nop 1
	v_cndmask_b32_e32 v117, v207, v151, vcc
	v_cmp_lt_i32_e32 vcc, 35, v125
	v_max3_f32 v143, v143, v116, v117
	s_nop 0
	v_cndmask_b32_e32 v119, v207, v152, vcc
	v_cmp_lt_i32_e32 vcc, 36, v125
	s_nop 1
	v_cndmask_b32_e32 v121, v207, v153, vcc
	v_cmp_lt_i32_e32 vcc, 37, v125
	v_max3_f32 v143, v143, v119, v121
	s_nop 0
	v_cndmask_b32_e32 v123, v207, v154, vcc
	v_cmp_lt_i32_e32 vcc, 38, v125
	s_nop 1
	v_cndmask_b32_e32 v125, v207, v155, vcc
	v_max3_f32 v143, v143, v123, v125
	v_sub_f32_e32 v144, v143, v136
	v_mul_f32_e32 v144, 0x3e16c740, v144
	v_cmp_lt_f32_e32 vcc, s42, v144
	s_cbranch_vccz .LBB0_1953
	v_mov_b32_e32 v144, v143
	s_nop 1
	v_permlane16_swap_b32_e32 v143, v144
	v_max_f32_e32 v143, v144, v143
	v_mov_b32_e32 v144, v143
	s_nop 1
	v_permlane32_swap_b32_e32 v143, v144
	v_max3_f32 v144, v136, v143, v144
	v_sub_f32_e32 v136, v136, v144
	v_mul_f32_e32 v136, 0x3e16c740, v136
	v_exp_f32_e32 v136, v136
	v_mov_b32_e32 v145, v137
	v_mul_f32_e32 v134, v134, v136
	v_pk_mul_f32 v[50:51], v[50:51], v[136:137] op_sel_hi:[1,0]
	v_pk_mul_f32 v[48:49], v[48:49], v[136:137] op_sel_hi:[1,0]
	v_pk_mul_f32 v[78:79], v[78:79], v[136:137] op_sel_hi:[1,0]
	v_pk_mul_f32 v[76:77], v[76:77], v[136:137] op_sel_hi:[1,0]
	v_pk_mul_f32 v[86:87], v[86:87], v[136:137] op_sel_hi:[1,0]
	v_pk_mul_f32 v[84:85], v[84:85], v[136:137] op_sel_hi:[1,0]
	v_pk_mul_f32 v[94:95], v[94:95], v[136:137] op_sel_hi:[1,0]
	v_pk_mul_f32 v[92:93], v[92:93], v[136:137] op_sel_hi:[1,0]
	v_mul_f32_e32 v136, 0xbe16c740, v144
	v_fmamk_f32 v118, v118, 0x3e16c740, v136
	v_exp_f32_e32 v118, v118
	v_fmamk_f32 v120, v120, 0x3e16c740, v136
	v_exp_f32_e32 v120, v120
	v_fmamk_f32 v122, v122, 0x3e16c740, v136
	v_exp_f32_e32 v122, v122
	v_fmamk_f32 v124, v124, 0x3e16c740, v136
	v_exp_f32_e32 v124, v124
	v_fmamk_f32 v126, v126, 0x3e16c740, v136
	v_add_f32_e32 v137, 0, v118
	v_exp_f32_e32 v126, v126
	v_fmamk_f32 v127, v127, 0x3e16c740, v136
	v_add_f32_e32 v137, v120, v137
	v_exp_f32_e32 v127, v127
	v_fmamk_f32 v140, v140, 0x3e16c740, v136
	v_add_f32_e32 v137, v122, v137
	v_exp_f32_e32 v140, v140
	v_fmamk_f32 v141, v141, 0x3e16c740, v136
	v_add_f32_e32 v137, v124, v137
	v_exp_f32_e32 v141, v141
	v_fmamk_f32 v114, v114, 0x3e16c740, v136
	v_add_f32_e32 v137, v126, v137
	v_exp_f32_e32 v114, v114
	v_fmamk_f32 v115, v115, 0x3e16c740, v136
	v_add_f32_e32 v137, v127, v137
	v_exp_f32_e32 v115, v115
	v_fmamk_f32 v116, v116, 0x3e16c740, v136
	v_add_f32_e32 v137, v140, v137
	v_exp_f32_e32 v116, v116
	v_fmamk_f32 v117, v117, 0x3e16c740, v136
	v_add_f32_e32 v137, v141, v137
	v_exp_f32_e32 v117, v117
	v_fmamk_f32 v119, v119, 0x3e16c740, v136
	v_add_f32_e32 v137, v114, v137
	v_exp_f32_e32 v119, v119
	v_fmamk_f32 v121, v121, 0x3e16c740, v136
	v_add_f32_e32 v137, v115, v137
	v_exp_f32_e32 v121, v121
	v_fmamk_f32 v123, v123, 0x3e16c740, v136
	v_add_f32_e32 v137, v116, v137
	v_exp_f32_e32 v123, v123
	v_fmac_f32_e32 v136, 0x3e16c740, v125
	v_add_f32_e32 v137, v117, v137
	v_exp_f32_e32 v125, v136
	v_add_f32_e32 v136, v119, v137
	v_add_f32_e32 v136, v121, v136
	v_add_f32_e32 v136, v123, v136
	v_add_f32_e32 v143, v125, v136
	v_mov_b64_e32 v[136:137], v[144:145]
	s_branch .LBB0_1954

.LBB0_1954:
	v_cmp_lt_i32_e32 vcc, -1, v142
	v_add_f32_e32 v134, v134, v143
	s_nop 0
	v_cndmask_b32_e32 v150, v207, v96, vcc
	v_cmp_lt_i32_e32 vcc, 0, v142
	s_nop 1
	v_cndmask_b32_e32 v149, v207, v97, vcc
	v_cmp_lt_i32_e32 vcc, 1, v142
	s_nop 1
	v_cndmask_b32_e32 v148, v207, v98, vcc
	v_cmp_lt_i32_e32 vcc, 2, v142
	s_nop 1
	v_cndmask_b32_e32 v147, v207, v99, vcc
	v_cmp_lt_i32_e32 vcc, 3, v142
	s_nop 1
	v_cndmask_b32_e32 v146, v207, v100, vcc
	v_cmp_lt_i32_e32 vcc, 4, v142
	s_nop 1
	v_cndmask_b32_e32 v145, v207, v101, vcc
	v_cmp_lt_i32_e32 vcc, 5, v142
	v_max_f32_e32 v101, v149, v149
	s_nop 0
	v_cndmask_b32_e32 v144, v207, v102, vcc
	v_cmp_lt_i32_e32 vcc, 6, v142
	s_nop 1
	v_cndmask_b32_e32 v143, v207, v103, vcc
	v_cmp_lt_i32_e32 vcc, 31, v142
	v_max_f32_e32 v103, v150, v150
	v_max_f32_e32 v101, v103, v101
	v_cndmask_b32_e32 v97, v207, v104, vcc
	v_cmp_lt_i32_e32 vcc, 32, v142
	v_max3_f32 v101, v101, v148, v147
	v_max3_f32 v101, v101, v146, v145
	v_cndmask_b32_e32 v98, v207, v105, vcc
	v_cmp_lt_i32_e32 vcc, 33, v142
	v_max3_f32 v101, v101, v144, v143
	v_max3_f32 v101, v101, v97, v98
	v_cndmask_b32_e32 v99, v207, v106, vcc
	v_cmp_lt_i32_e32 vcc, 34, v142
	s_nop 1
	v_cndmask_b32_e32 v100, v207, v107, vcc
	v_cmp_lt_i32_e32 vcc, 35, v142
	v_max3_f32 v101, v101, v99, v100
	s_nop 0
	v_cndmask_b32_e32 v102, v207, v108, vcc
	v_cmp_lt_i32_e32 vcc, 36, v142
	s_nop 1
	v_cndmask_b32_e32 v104, v207, v109, vcc
	v_cmp_lt_i32_e32 vcc, 37, v142
	v_max3_f32 v101, v101, v102, v104
	s_nop 0
	v_cndmask_b32_e32 v106, v207, v110, vcc
	v_cmp_lt_i32_e32 vcc, 38, v142
	s_nop 1
	v_cndmask_b32_e32 v96, v207, v111, vcc
	v_max3_f32 v101, v101, v106, v96
	v_sub_f32_e32 v103, v101, v137
	v_mul_f32_e32 v103, 0x3e16c740, v103
	v_cmp_lt_f32_e32 vcc, s42, v103
	s_cbranch_vccz .LBB0_1956
	v_mov_b32_e32 v103, v101
	s_nop 1
	v_permlane16_swap_b32_e32 v101, v103
	v_max_f32_e32 v101, v103, v101
	v_mov_b32_e32 v103, v101
	s_nop 1
	v_permlane32_swap_b32_e32 v101, v103
	v_max3_f32 v101, v137, v101, v103
	v_sub_f32_e32 v103, v137, v101
	v_mul_f32_e32 v103, 0x3e16c740, v103
	v_exp_f32_e32 v108, v103
	v_mov_b32_e32 v137, v101
	v_mul_f32_e32 v135, v135, v108
	v_pk_mul_f32 v[42:43], v[42:43], v[108:109] op_sel_hi:[1,0]
	v_pk_mul_f32 v[40:41], v[40:41], v[108:109] op_sel_hi:[1,0]
	v_pk_mul_f32 v[74:75], v[74:75], v[108:109] op_sel_hi:[1,0]
	v_pk_mul_f32 v[72:73], v[72:73], v[108:109] op_sel_hi:[1,0]
	v_pk_mul_f32 v[82:83], v[82:83], v[108:109] op_sel_hi:[1,0]
	v_pk_mul_f32 v[80:81], v[80:81], v[108:109] op_sel_hi:[1,0]
	v_pk_mul_f32 v[90:91], v[90:91], v[108:109] op_sel_hi:[1,0]
	v_pk_mul_f32 v[88:89], v[88:89], v[108:109] op_sel_hi:[1,0]
	v_mul_f32_e32 v108, 0xbe16c740, v101
	v_fmamk_f32 v101, v150, 0x3e16c740, v108
	v_exp_f32_e32 v101, v101
	v_fmamk_f32 v103, v149, 0x3e16c740, v108
	v_exp_f32_e32 v103, v103
	v_fmamk_f32 v105, v148, 0x3e16c740, v108
	v_exp_f32_e32 v105, v105
	v_fmamk_f32 v107, v147, 0x3e16c740, v108
	v_exp_f32_e32 v107, v107
	v_add_f32_e32 v109, v103, v101
	v_add_f32_e32 v109, v105, v109
	v_add_f32_e32 v147, v107, v109
	v_fmamk_f32 v109, v146, 0x3e16c740, v108
	v_exp_f32_e32 v109, v109
	v_fmamk_f32 v110, v145, 0x3e16c740, v108
	v_exp_f32_e32 v110, v110
	v_fmamk_f32 v111, v144, 0x3e16c740, v108
	v_exp_f32_e32 v111, v111
	v_fmamk_f32 v142, v143, 0x3e16c740, v108
	v_exp_f32_e32 v142, v142
	v_fmamk_f32 v97, v97, 0x3e16c740, v108
	v_add_f32_e32 v143, v109, v147
	v_exp_f32_e32 v97, v97
	v_fmamk_f32 v98, v98, 0x3e16c740, v108
	v_add_f32_e32 v143, v110, v143
	v_exp_f32_e32 v98, v98
	v_fmamk_f32 v99, v99, 0x3e16c740, v108
	v_add_f32_e32 v143, v111, v143
	v_exp_f32_e32 v99, v99
	v_fmamk_f32 v100, v100, 0x3e16c740, v108
	v_add_f32_e32 v143, v142, v143
	v_exp_f32_e32 v100, v100
	v_fmamk_f32 v102, v102, 0x3e16c740, v108
	v_add_f32_e32 v143, v97, v143
	v_exp_f32_e32 v102, v102
	v_fmamk_f32 v104, v104, 0x3e16c740, v108
	v_fmamk_f32 v106, v106, 0x3e16c740, v108
	v_fmac_f32_e32 v108, 0x3e16c740, v96
	v_add_f32_e32 v143, v98, v143
	v_exp_f32_e32 v104, v104
	v_exp_f32_e32 v106, v106
	v_exp_f32_e32 v108, v108
	v_add_f32_e32 v143, v99, v143
	v_add_f32_e32 v143, v100, v143
	v_add_f32_e32 v96, v102, v143
	s_branch .LBB0_1957

.LBB0_1959:
	s_or_b64 exec, exec, s[8:9]
	s_add_i32 s3, s2, 0xffffff80
	v_cmp_le_i32_e32 vcc, s3, v133
	s_and_saveexec_b64 s[8:9], vcc
	s_cbranch_execz .LBB0_1938
	s_add_i32 s3, s2, 0xffffffbf
	v_cmp_le_i32_e32 vcc, s3, v139
	s_and_saveexec_b64 s[10:11], vcc
	s_xor_b64 s[10:11], exec, s[10:11]
	s_cbranch_execz .LBB0_1968
	v_mov_b32_e32 v96, v186
	s_nop 0
	v_and_b32_e32 v141, 15, v96
	v_and_b32_e32 v140, 48, v96
	v_mad_u32_u24 v146, v141, s36, v140
	ds_read_b128 v[96:99], v146 offset:22528
	ds_read_b128 v[104:107], v146 offset:22592
	ds_read_b128 v[108:111], v146 offset:25920
	ds_read_b128 v[116:119], v146 offset:29248
	ds_read_b128 v[124:127], v146 offset:29312
	ds_read_b128 v[142:145], v146 offset:32576
	s_waitcnt lgkmcnt(5)
	v_mfma_f32_16x16x32_bf16 v[100:103], v[96:99], v[16:19], 0
	v_mfma_f32_16x16x32_bf16 v[96:99], v[96:99], v[8:11], 0
	s_waitcnt lgkmcnt(4)
	v_mfma_f32_16x16x32_bf16 v[100:103], v[104:107], v[0:3], v[100:103]
	v_mfma_f32_16x16x32_bf16 v[96:99], v[104:107], v[12:15], v[96:99]
	ds_read_b128 v[104:107], v146 offset:22656
	s_waitcnt lgkmcnt(0)
	v_mfma_f32_16x16x32_bf16 v[112:115], v[104:107], v[4:7], v[100:103]
	s_nop 3
	ds_read_b128 v[100:103], v146 offset:25856
	v_mfma_f32_16x16x32_bf16 v[96:99], v[104:107], v[20:23], v[96:99]
	s_waitcnt lgkmcnt(0)
	v_mfma_f32_16x16x32_bf16 v[104:107], v[100:103], v[16:19], 0
	v_mfma_f32_16x16x32_bf16 v[100:103], v[100:103], v[8:11], 0
	v_mfma_f32_16x16x32_bf16 v[104:107], v[108:111], v[0:3], v[104:107]
	v_mfma_f32_16x16x32_bf16 v[100:103], v[108:111], v[12:15], v[100:103]
	ds_read_b128 v[108:111], v146 offset:25984
	s_waitcnt lgkmcnt(0)
	v_mfma_f32_16x16x32_bf16 v[120:123], v[108:111], v[4:7], v[104:107]
	v_mfma_f32_16x16x32_bf16 v[104:107], v[108:111], v[20:23], v[100:103]
	s_nop 3
	ds_read_b128 v[100:103], v146 offset:29184
	s_waitcnt lgkmcnt(0)
	v_mfma_f32_16x16x32_bf16 v[108:111], v[100:103], v[16:19], 0
	v_mfma_f32_16x16x32_bf16 v[100:103], v[100:103], v[8:11], 0
	v_mfma_f32_16x16x32_bf16 v[108:111], v[116:119], v[0:3], v[108:111]
	v_mfma_f32_16x16x32_bf16 v[100:103], v[116:119], v[12:15], v[100:103]
	v_mfma_f32_16x16x32_bf16 v[116:119], v[124:127], v[4:7], v[108:111]
	s_nop 5
	ds_read_b128 v[108:111], v146 offset:32512
	v_mfma_f32_16x16x32_bf16 v[100:103], v[124:127], v[20:23], v[100:103]
	s_waitcnt lgkmcnt(0)
	v_mfma_f32_16x16x32_bf16 v[124:127], v[108:111], v[16:19], 0
	v_mfma_f32_16x16x32_bf16 v[108:111], v[108:111], v[8:11], 0
	v_mfma_f32_16x16x32_bf16 v[124:127], v[142:145], v[0:3], v[124:127]
	v_mfma_f32_16x16x32_bf16 v[108:111], v[142:145], v[12:15], v[108:111]
	ds_read_b128 v[142:145], v146 offset:32640
	s_waitcnt lgkmcnt(0)
	v_mfma_f32_16x16x32_bf16 v[124:127], v[142:145], v[4:7], v[124:127]
	v_mfma_f32_16x16x32_bf16 v[108:111], v[142:145], v[20:23], v[108:111]
	v_max_f32_e32 v142, v113, v112
	v_max3_f32 v142, v142, v114, v115
	v_max3_f32 v142, v142, v120, v121
	v_max3_f32 v142, v142, v122, v123
	v_max3_f32 v142, v142, v116, v117
	v_max3_f32 v142, v142, v118, v119
	s_nop 0
	v_max3_f32 v142, v142, v124, v125
	v_max3_f32 v142, v142, v126, v127
	v_sub_f32_e32 v143, v142, v136
	v_mul_f32_e32 v143, 0x3e16c740, v143
	v_cmp_lt_f32_e32 vcc, s42, v143
	s_cbranch_vccz .LBB0_1963
	v_mov_b32_e32 v143, v142
	s_nop 1
	v_permlane16_swap_b32_e32 v142, v143
	v_max_f32_e32 v142, v143, v142
	v_mov_b32_e32 v143, v142
	s_nop 1
	v_permlane32_swap_b32_e32 v142, v143
	v_max3_f32 v146, v136, v142, v143
	v_sub_f32_e32 v136, v136, v146
	v_mul_f32_e32 v136, 0x3e16c740, v136
	v_exp_f32_e32 v136, v136
	v_mov_b32_e32 v147, v137
	v_mul_f32_e32 v134, v134, v136
	v_pk_mul_f32 v[50:51], v[50:51], v[136:137] op_sel_hi:[1,0]
	v_pk_mul_f32 v[48:49], v[48:49], v[136:137] op_sel_hi:[1,0]
	v_pk_mul_f32 v[78:79], v[78:79], v[136:137] op_sel_hi:[1,0]
	v_pk_mul_f32 v[76:77], v[76:77], v[136:137] op_sel_hi:[1,0]
	v_pk_mul_f32 v[86:87], v[86:87], v[136:137] op_sel_hi:[1,0]
	v_pk_mul_f32 v[84:85], v[84:85], v[136:137] op_sel_hi:[1,0]
	v_pk_mul_f32 v[94:95], v[94:95], v[136:137] op_sel_hi:[1,0]
	v_pk_mul_f32 v[92:93], v[92:93], v[136:137] op_sel_hi:[1,0]
	v_mul_f32_e32 v136, 0xbe16c740, v146
	v_fmamk_f32 v112, v112, 0x3e16c740, v136
	v_exp_f32_e32 v142, v112
	v_fmamk_f32 v112, v113, 0x3e16c740, v136
	v_exp_f32_e32 v143, v112
	v_fmamk_f32 v112, v114, 0x3e16c740, v136
	v_exp_f32_e32 v144, v112
	v_fmamk_f32 v112, v115, 0x3e16c740, v136
	v_exp_f32_e32 v145, v112
	v_fmamk_f32 v113, v120, 0x3e16c740, v136
	v_add_f32_e32 v112, 0, v142
	v_exp_f32_e32 v120, v113
	v_fmamk_f32 v113, v121, 0x3e16c740, v136
	v_add_f32_e32 v112, v143, v112
	v_exp_f32_e32 v121, v113
	v_fmamk_f32 v113, v122, 0x3e16c740, v136
	v_add_f32_e32 v112, v144, v112
	v_exp_f32_e32 v122, v113
	v_fmamk_f32 v113, v123, 0x3e16c740, v136
	v_add_f32_e32 v112, v145, v112
	v_exp_f32_e32 v123, v113
	v_add_f32_e32 v112, v120, v112
	v_add_f32_e32 v112, v121, v112
	v_add_f32_e32 v112, v122, v112
	v_add_f32_e32 v137, v123, v112
	v_fmamk_f32 v112, v116, 0x3e16c740, v136
	v_exp_f32_e32 v112, v112
	v_fmamk_f32 v113, v117, 0x3e16c740, v136
	v_exp_f32_e32 v113, v113
	v_fmamk_f32 v114, v118, 0x3e16c740, v136
	v_exp_f32_e32 v114, v114
	v_fmamk_f32 v115, v119, 0x3e16c740, v136
	v_exp_f32_e32 v115, v115
	v_add_f32_e32 v116, v112, v137
	v_add_f32_e32 v116, v113, v116
	v_add_f32_e32 v116, v114, v116
	v_add_f32_e32 v137, v115, v116
	v_fmamk_f32 v116, v124, 0x3e16c740, v136
	v_exp_f32_e32 v116, v116
	v_fmamk_f32 v117, v125, 0x3e16c740, v136
	v_exp_f32_e32 v117, v117
	v_fmamk_f32 v118, v126, 0x3e16c740, v136
	v_exp_f32_e32 v118, v118
	v_fmac_f32_e32 v136, 0x3e16c740, v127
	v_exp_f32_e32 v119, v136
	v_add_f32_e32 v124, v116, v137
	v_add_f32_e32 v124, v117, v124
	v_add_f32_e32 v124, v118, v124
	v_add_f32_e32 v124, v119, v124
	v_mov_b64_e32 v[136:137], v[146:147]
	s_branch .LBB0_1964

.LBB0_1968:
	s_andn2_saveexec_b64 s[10:11], s[10:11]
	s_cbranch_execz .LBB0_1937
	v_mov_b32_e32 v96, v186
	s_nop 0
	v_bfe_u32 v126, v96, 4, 2
	v_and_b32_e32 v113, 15, v96
	v_lshlrev_b32_e32 v112, 4, v126
	v_mad_u32_u24 v127, v113, s36, v112
	ds_read_b128 v[96:99], v127 offset:22528
	ds_read_b128 v[104:107], v127 offset:22592
	ds_read_b128 v[108:111], v127 offset:25920
	ds_read_b128 v[118:121], v127 offset:29248
	ds_read_b128 v[122:125], v127 offset:32576
	s_waitcnt lgkmcnt(4)
	v_mfma_f32_16x16x32_bf16 v[100:103], v[96:99], v[16:19], 0
	v_mfma_f32_16x16x32_bf16 v[96:99], v[96:99], v[8:11], 0
	s_waitcnt lgkmcnt(3)
	v_mfma_f32_16x16x32_bf16 v[100:103], v[104:107], v[0:3], v[100:103]
	v_mfma_f32_16x16x32_bf16 v[96:99], v[104:107], v[12:15], v[96:99]
	ds_read_b128 v[104:107], v127 offset:22656
	s_waitcnt lgkmcnt(0)
	v_mfma_f32_16x16x32_bf16 v[114:117], v[104:107], v[4:7], v[100:103]
	s_nop 3
	ds_read_b128 v[100:103], v127 offset:25856
	v_mfma_f32_16x16x32_bf16 v[96:99], v[104:107], v[20:23], v[96:99]
	s_waitcnt lgkmcnt(0)
	v_mfma_f32_16x16x32_bf16 v[104:107], v[100:103], v[16:19], 0
	v_mfma_f32_16x16x32_bf16 v[100:103], v[100:103], v[8:11], 0
	v_mfma_f32_16x16x32_bf16 v[104:107], v[108:111], v[0:3], v[104:107]
	v_mfma_f32_16x16x32_bf16 v[100:103], v[108:111], v[12:15], v[100:103]
	ds_read_b128 v[108:111], v127 offset:25984
	s_waitcnt lgkmcnt(0)
	v_mfma_f32_16x16x32_bf16 v[144:147], v[108:111], v[4:7], v[104:107]
	s_nop 3
	ds_read_b128 v[104:107], v127 offset:29184
	v_mfma_f32_16x16x32_bf16 v[100:103], v[108:111], v[20:23], v[100:103]
	s_waitcnt lgkmcnt(0)
	v_mfma_f32_16x16x32_bf16 v[108:111], v[104:107], v[16:19], 0
	v_mfma_f32_16x16x32_bf16 v[104:107], v[104:107], v[8:11], 0
	v_mfma_f32_16x16x32_bf16 v[108:111], v[118:121], v[0:3], v[108:111]
	v_mfma_f32_16x16x32_bf16 v[104:107], v[118:121], v[12:15], v[104:107]
	ds_read_b128 v[118:121], v127 offset:29312
	s_waitcnt lgkmcnt(0)
	v_mfma_f32_16x16x32_bf16 v[148:151], v[118:121], v[4:7], v[108:111]
	s_nop 3
	ds_read_b128 v[108:111], v127 offset:32512
	v_mfma_f32_16x16x32_bf16 v[104:107], v[118:121], v[20:23], v[104:107]
	s_waitcnt lgkmcnt(0)
	v_mfma_f32_16x16x32_bf16 v[118:121], v[108:111], v[16:19], 0
	v_mfma_f32_16x16x32_bf16 v[108:111], v[108:111], v[8:11], 0
	v_mfma_f32_16x16x32_bf16 v[118:121], v[122:125], v[0:3], v[118:121]
	v_mfma_f32_16x16x32_bf16 v[108:111], v[122:125], v[12:15], v[108:111]
	ds_read_b128 v[122:125], v127 offset:32640
	s_waitcnt lgkmcnt(0)
	v_mfma_f32_16x16x32_bf16 v[152:155], v[122:125], v[4:7], v[118:121]
	s_nop 3
	v_lshlrev_b32_e32 v118, 3, v126
	v_sub_u32_e32 v142, v132, v118
	v_mfma_f32_16x16x32_bf16 v[108:111], v[122:125], v[20:23], v[108:111]
	v_add_u32_e32 v125, 0xffffffb0, v142
	v_cmp_lt_i32_e32 vcc, -1, v125
	s_nop 1
	v_cndmask_b32_e32 v118, v207, v114, vcc
	v_cmp_lt_i32_e32 vcc, 0, v125
	s_nop 1
	v_cndmask_b32_e32 v120, v207, v115, vcc
	v_cmp_lt_i32_e32 vcc, 1, v125
	v_max_f32_e32 v143, v120, v120
	s_nop 0
	v_cndmask_b32_e32 v122, v207, v116, vcc
	v_cmp_lt_i32_e32 vcc, 2, v125
	s_nop 1
	v_cndmask_b32_e32 v124, v207, v117, vcc
	v_cmp_lt_i32_e32 vcc, 3, v125
	s_nop 1
	v_cndmask_b32_e32 v126, v207, v144, vcc
	v_cmp_lt_i32_e32 vcc, 4, v125
	v_max_f32_e32 v144, v118, v118
	v_max_f32_e32 v143, v144, v143
	v_cndmask_b32_e32 v127, v207, v145, vcc
	v_cmp_lt_i32_e32 vcc, 5, v125
	v_max3_f32 v143, v143, v122, v124
	v_max3_f32 v143, v143, v126, v127
	v_cndmask_b32_e32 v140, v207, v146, vcc
	v_cmp_lt_i32_e32 vcc, 6, v125
	s_nop 1
	v_cndmask_b32_e32 v141, v207, v147, vcc
	v_cmp_lt_i32_e32 vcc, 31, v125
	v_max3_f32 v143, v143, v140, v141
	s_nop 0
	v_cndmask_b32_e32 v114, v207, v148, vcc
	v_cmp_lt_i32_e32 vcc, 32, v125
	s_nop 1
	v_cndmask_b32_e32 v115, v207, v149, vcc
	v_cmp_lt_i32_e32 vcc, 33, v125
	v_max3_f32 v143, v143, v114, v115
	s_nop 0
	v_cndmask_b32_e32 v116, v207, v150, vcc
	v_cmp_lt_i32_e32 vcc, 34, v125
	s_nop 1
	v_cndmask_b32_e32 v117, v207, v151, vcc
	v_cmp_lt_i32_e32 vcc, 35, v125
	v_max3_f32 v143, v143, v116, v117
	s_nop 0
	v_cndmask_b32_e32 v119, v207, v152, vcc
	v_cmp_lt_i32_e32 vcc, 36, v125
	s_nop 1
	v_cndmask_b32_e32 v121, v207, v153, vcc
	v_cmp_lt_i32_e32 vcc, 37, v125
	v_max3_f32 v143, v143, v119, v121
	s_nop 0
	v_cndmask_b32_e32 v123, v207, v154, vcc
	v_cmp_lt_i32_e32 vcc, 38, v125
	s_nop 1
	v_cndmask_b32_e32 v125, v207, v155, vcc
	v_max3_f32 v143, v143, v123, v125
	v_sub_f32_e32 v144, v143, v136
	v_mul_f32_e32 v144, 0x3e16c740, v144
	v_cmp_lt_f32_e32 vcc, s42, v144
	s_cbranch_vccz .LBB0_1971
	v_mov_b32_e32 v144, v143
	s_nop 1
	v_permlane16_swap_b32_e32 v143, v144
	v_max_f32_e32 v143, v144, v143
	v_mov_b32_e32 v144, v143
	s_nop 1
	v_permlane32_swap_b32_e32 v143, v144
	v_max3_f32 v144, v136, v143, v144
	v_sub_f32_e32 v136, v136, v144
	v_mul_f32_e32 v136, 0x3e16c740, v136
	v_exp_f32_e32 v136, v136
	v_mov_b32_e32 v145, v137
	v_mul_f32_e32 v134, v134, v136
	v_pk_mul_f32 v[50:51], v[50:51], v[136:137] op_sel_hi:[1,0]
	v_pk_mul_f32 v[48:49], v[48:49], v[136:137] op_sel_hi:[1,0]
	v_pk_mul_f32 v[78:79], v[78:79], v[136:137] op_sel_hi:[1,0]
	v_pk_mul_f32 v[76:77], v[76:77], v[136:137] op_sel_hi:[1,0]
	v_pk_mul_f32 v[86:87], v[86:87], v[136:137] op_sel_hi:[1,0]
	v_pk_mul_f32 v[84:85], v[84:85], v[136:137] op_sel_hi:[1,0]
	v_pk_mul_f32 v[94:95], v[94:95], v[136:137] op_sel_hi:[1,0]
	v_pk_mul_f32 v[92:93], v[92:93], v[136:137] op_sel_hi:[1,0]
	v_mul_f32_e32 v136, 0xbe16c740, v144
	v_fmamk_f32 v118, v118, 0x3e16c740, v136
	v_exp_f32_e32 v118, v118
	v_fmamk_f32 v120, v120, 0x3e16c740, v136
	v_exp_f32_e32 v120, v120
	v_fmamk_f32 v122, v122, 0x3e16c740, v136
	v_exp_f32_e32 v122, v122
	v_fmamk_f32 v124, v124, 0x3e16c740, v136
	v_exp_f32_e32 v124, v124
	v_fmamk_f32 v126, v126, 0x3e16c740, v136
	v_add_f32_e32 v137, 0, v118
	v_exp_f32_e32 v126, v126
	v_fmamk_f32 v127, v127, 0x3e16c740, v136
	v_add_f32_e32 v137, v120, v137
	v_exp_f32_e32 v127, v127
	v_fmamk_f32 v140, v140, 0x3e16c740, v136
	v_add_f32_e32 v137, v122, v137
	v_exp_f32_e32 v140, v140
	v_fmamk_f32 v141, v141, 0x3e16c740, v136
	v_add_f32_e32 v137, v124, v137
	v_exp_f32_e32 v141, v141
	v_fmamk_f32 v114, v114, 0x3e16c740, v136
	v_add_f32_e32 v137, v126, v137
	v_exp_f32_e32 v114, v114
	v_fmamk_f32 v115, v115, 0x3e16c740, v136
	v_add_f32_e32 v137, v127, v137
	v_exp_f32_e32 v115, v115
	v_fmamk_f32 v116, v116, 0x3e16c740, v136
	v_add_f32_e32 v137, v140, v137
	v_exp_f32_e32 v116, v116
	v_fmamk_f32 v117, v117, 0x3e16c740, v136
	v_add_f32_e32 v137, v141, v137
	v_exp_f32_e32 v117, v117
	v_fmamk_f32 v119, v119, 0x3e16c740, v136
	v_add_f32_e32 v137, v114, v137
	v_exp_f32_e32 v119, v119
	v_fmamk_f32 v121, v121, 0x3e16c740, v136
	v_add_f32_e32 v137, v115, v137
	v_exp_f32_e32 v121, v121
	v_fmamk_f32 v123, v123, 0x3e16c740, v136
	v_add_f32_e32 v137, v116, v137
	v_exp_f32_e32 v123, v123
	v_fmac_f32_e32 v136, 0x3e16c740, v125
	v_add_f32_e32 v137, v117, v137
	v_exp_f32_e32 v125, v136
	v_add_f32_e32 v136, v119, v137
	v_add_f32_e32 v136, v121, v136
	v_add_f32_e32 v136, v123, v136
	v_add_f32_e32 v143, v125, v136
	v_mov_b64_e32 v[136:137], v[144:145]
	s_branch .LBB0_1972

.LBB0_1997:
	s_lshr_b32 s0, s2, 5
	s_cmp_eq_u32 s0, 1
	s_cselect_b64 vcc, -1, 0
	s_cmp_eq_u32 s0, 2
	v_cndmask_b32_e32 v100, v80, v81, vcc
	s_cselect_b64 vcc, -1, 0
	s_cmp_eq_u32 s0, 3
	v_cndmask_b32_e32 v100, v100, v82, vcc
	s_cselect_b64 vcc, -1, 0
	v_cndmask_b32_e32 v100, v100, v83, vcc
	s_and_b32 s3, s2, 31
	v_lshrrev_b32_e32 v101, s2, v100
	v_and_b32_e32 v101, 1, v101
	v_bfe_u32 v100, v100, s3, 1
	v_cmp_eq_u32_e64 s[0:1], 1, v101
	v_cmp_ne_u32_e32 vcc, 0, v100
	s_cbranch_vccz .LBB0_1992
	v_mov_b32_e32 v100, v186
	s_lshl_b32 s2, s2, 6
	v_bfe_u32 v123, v100, 4, 2
	v_and_b32_e32 v122, 15, v100
	v_lshlrev_b32_e32 v121, 4, v123
	v_mad_u32_u24 v130, v122, s43, v121
	ds_read_b128 v[100:103], v130
	ds_read_b128 v[104:107], v130 offset:64
	s_waitcnt lgkmcnt(1)
	v_mfma_f32_16x16x32_bf16 v[108:111], v[100:103], v[20:23], 0
	v_lshlrev_b32_e32 v123, 3, v123
	v_mfma_f32_16x16x32_bf16 v[100:103], v[100:103], v[28:31], 0
	s_waitcnt lgkmcnt(0)
	v_mfma_f32_16x16x32_bf16 v[108:111], v[104:107], v[24:27], v[108:111]
	v_mfma_f32_16x16x32_bf16 v[100:103], v[104:107], v[32:35], v[100:103]
	ds_read_b128 v[104:107], v130 offset:2304
	ds_read_b128 v[112:115], v130 offset:2368
	ds_read_b128 v[132:135], v130 offset:4608
	ds_read_b128 v[152:155], v130 offset:4672
	s_waitcnt lgkmcnt(3)
	v_mfma_f32_16x16x32_bf16 v[124:127], v[104:107], v[20:23], 0
	v_mfma_f32_16x16x32_bf16 v[104:107], v[104:107], v[28:31], 0
	s_waitcnt lgkmcnt(2)
	v_mfma_f32_16x16x32_bf16 v[138:141], v[112:115], v[24:27], v[124:127]
	s_nop 4
	v_subrev_u32_e32 v124, s2, v120
	v_mfma_f32_16x16x32_bf16 v[104:107], v[112:115], v[32:35], v[104:107]
	ds_read_b128 v[112:115], v130 offset:6912
	ds_read_b128 v[156:159], v130 offset:6976
	v_cndmask_b32_e64 v124, -1, v124, s[0:1]
	v_sub_u32_e32 v136, v124, v123
	s_waitcnt lgkmcnt(3)
	v_mfma_f32_16x16x32_bf16 v[164:167], v[132:135], v[20:23], 0
	v_cmp_gt_i32_e64 s[0:1], 0, v136
	v_cmp_gt_i32_e64 s[2:3], 1, v136
	v_cmp_gt_i32_e64 s[4:5], 2, v136
	v_mfma_f32_16x16x32_bf16 v[168:171], v[132:135], v[28:31], 0
	v_cmp_gt_i32_e64 s[6:7], 3, v136
	v_cndmask_b32_e64 v127, v108, v207, s[0:1]
	v_cndmask_b32_e64 v131, v109, v207, s[2:3]
	v_cndmask_b32_e64 v133, v110, v207, s[4:5]
	v_cndmask_b32_e64 v135, v111, v207, s[6:7]
	s_waitcnt lgkmcnt(2)
	v_mfma_f32_16x16x32_bf16 v[164:167], v[152:155], v[24:27], v[164:167]
	v_cmp_gt_i32_e64 s[8:9], 4, v136
	v_cmp_gt_i32_e64 s[10:11], 5, v136
	v_cmp_gt_i32_e64 s[14:15], 6, v136
	v_mfma_f32_16x16x32_bf16 v[108:111], v[152:155], v[32:35], v[168:171]
	v_cmp_gt_i32_e64 s[16:17], 7, v136
	v_cndmask_b32_e64 v137, v138, v207, s[8:9]
	v_cndmask_b32_e64 v138, v139, v207, s[10:11]
	s_waitcnt lgkmcnt(1)
	v_mfma_f32_16x16x32_bf16 v[152:155], v[112:115], v[20:23], 0
	v_cndmask_b32_e64 v139, v140, v207, s[14:15]
	v_cndmask_b32_e64 v140, v141, v207, s[16:17]
	v_max_f32_e32 v141, v131, v127
	s_waitcnt lgkmcnt(0)
	v_mfma_f32_16x16x32_bf16 v[152:155], v[156:159], v[24:27], v[152:155]
	v_max3_f32 v141, v141, v133, v135
	v_cmp_gt_i32_e64 s[18:19], 32, v136
	v_cmp_gt_i32_e64 s[20:21], 33, v136
	v_max3_f32 v141, v141, v137, v138
	v_cndmask_b32_e64 v123, v164, v207, s[18:19]
	v_cndmask_b32_e64 v124, v165, v207, s[20:21]
	v_mfma_f32_16x16x32_bf16 v[112:115], v[112:115], v[28:31], 0
	v_cmp_gt_i32_e64 s[22:23], 34, v136
	v_cmp_gt_i32_e64 s[24:25], 35, v136
	v_max3_f32 v141, v141, v139, v140
	v_cndmask_b32_e64 v125, v166, v207, s[22:23]
	v_cndmask_b32_e64 v126, v167, v207, s[24:25]
	v_cmp_gt_i32_e64 s[26:27], 36, v136
	v_cmp_gt_i32_e64 s[28:29], 37, v136
	v_max3_f32 v141, v141, v123, v124
	v_cndmask_b32_e64 v130, v152, v207, s[26:27]
	v_cndmask_b32_e64 v132, v153, v207, s[28:29]
	v_cmp_gt_i32_e64 s[30:31], 38, v136
	v_cmp_gt_i32_e64 s[34:35], 39, v136
	v_max3_f32 v141, v141, v125, v126
	v_cndmask_b32_e64 v134, v154, v207, s[30:31]
	v_cndmask_b32_e64 v136, v155, v207, s[34:35]
	v_max3_f32 v141, v141, v130, v132
	v_mfma_f32_16x16x32_bf16 v[112:115], v[156:159], v[32:35], v[112:115]
	v_max3_f32 v141, v141, v134, v136
	v_sub_f32_e32 v142, v141, v116
	v_mul_f32_e32 v142, 0x3e38aa3b, v142
	v_cmp_lt_f32_e32 vcc, s42, v142
	s_cbranch_vccz .LBB0_2003
	v_mov_b32_e32 v142, v141
	s_nop 1
	v_permlane16_swap_b32_e32 v141, v142
	v_max_f32_e32 v141, v142, v141
	v_mov_b32_e32 v142, v141
	s_nop 1
	v_permlane32_swap_b32_e32 v141, v142
	v_max3_f32 v142, v116, v141, v142
	v_sub_f32_e32 v116, v116, v142
	v_mul_f32_e32 v116, 0x3e38aa3b, v116
	v_exp_f32_e32 v116, v116
	v_mov_b32_e32 v143, v117
	v_mul_f32_e32 v118, v118, v116
	v_pk_mul_f32 v[50:51], v[50:51], v[116:117] op_sel_hi:[1,0]
	v_pk_mul_f32 v[48:49], v[48:49], v[116:117] op_sel_hi:[1,0]
	v_pk_mul_f32 v[54:55], v[54:55], v[116:117] op_sel_hi:[1,0]
	v_pk_mul_f32 v[52:53], v[52:53], v[116:117] op_sel_hi:[1,0]
	v_pk_mul_f32 v[58:59], v[58:59], v[116:117] op_sel_hi:[1,0]
	v_pk_mul_f32 v[56:57], v[56:57], v[116:117] op_sel_hi:[1,0]
	v_pk_mul_f32 v[62:63], v[62:63], v[116:117] op_sel_hi:[1,0]
	v_pk_mul_f32 v[60:61], v[60:61], v[116:117] op_sel_hi:[1,0]
	v_mul_f32_e32 v116, 0xbe38aa3b, v142
	v_fmamk_f32 v117, v127, 0x3e38aa3b, v116
	v_exp_f32_e32 v127, v117
	v_fmamk_f32 v117, v131, 0x3e38aa3b, v116
	v_exp_f32_e32 v131, v117
	v_fmamk_f32 v117, v133, 0x3e38aa3b, v116
	v_exp_f32_e32 v133, v117
	v_fmamk_f32 v117, v135, 0x3e38aa3b, v116
	v_exp_f32_e32 v135, v117
	v_fmamk_f32 v137, v137, 0x3e38aa3b, v116
	v_add_f32_e32 v117, 0, v127
	v_exp_f32_e32 v137, v137
	v_fmamk_f32 v138, v138, 0x3e38aa3b, v116
	v_add_f32_e32 v117, v131, v117
	v_exp_f32_e32 v138, v138
	v_fmamk_f32 v139, v139, 0x3e38aa3b, v116
	v_add_f32_e32 v117, v133, v117
	v_exp_f32_e32 v139, v139
	v_fmamk_f32 v140, v140, 0x3e38aa3b, v116
	v_add_f32_e32 v117, v135, v117
	v_exp_f32_e32 v140, v140
	v_fmamk_f32 v123, v123, 0x3e38aa3b, v116
	v_add_f32_e32 v117, v137, v117
	v_exp_f32_e32 v123, v123
	v_fmamk_f32 v124, v124, 0x3e38aa3b, v116
	v_add_f32_e32 v117, v138, v117
	v_exp_f32_e32 v124, v124
	v_fmamk_f32 v125, v125, 0x3e38aa3b, v116
	v_add_f32_e32 v117, v139, v117
	v_exp_f32_e32 v125, v125
	v_fmamk_f32 v126, v126, 0x3e38aa3b, v116
	v_add_f32_e32 v117, v140, v117
	v_exp_f32_e32 v126, v126
	v_fmamk_f32 v130, v130, 0x3e38aa3b, v116
	v_add_f32_e32 v117, v123, v117
	v_exp_f32_e32 v130, v130
	v_fmamk_f32 v132, v132, 0x3e38aa3b, v116
	v_add_f32_e32 v117, v124, v117
	v_exp_f32_e32 v132, v132
	v_fmamk_f32 v134, v134, 0x3e38aa3b, v116
	v_add_f32_e32 v117, v125, v117
	v_exp_f32_e32 v134, v134
	v_fmac_f32_e32 v116, 0x3e38aa3b, v136
	v_add_f32_e32 v117, v126, v117
	v_exp_f32_e32 v136, v116
	v_add_f32_e32 v116, v130, v117
	v_add_f32_e32 v116, v132, v116
	v_add_f32_e32 v116, v134, v116
	v_add_f32_e32 v141, v136, v116
	v_mov_b64_e32 v[116:117], v[142:143]
	s_branch .LBB0_2004

.LBB0_2004:
	v_cndmask_b32_e64 v155, v100, v207, s[0:1]
	v_cndmask_b32_e64 v154, v101, v207, s[2:3]
	v_add_f32_e32 v118, v118, v141
	v_cndmask_b32_e64 v143, v105, v207, s[10:11]
	v_cndmask_b32_e64 v141, v107, v207, s[16:17]
	v_max_f32_e32 v105, v154, v154
	v_max_f32_e32 v107, v155, v155
	v_cndmask_b32_e64 v153, v102, v207, s[4:5]
	v_cndmask_b32_e64 v152, v103, v207, s[6:7]
	v_max_f32_e32 v105, v107, v105
	v_cndmask_b32_e64 v151, v104, v207, s[8:9]
	v_max3_f32 v105, v105, v153, v152
	v_cndmask_b32_e64 v142, v106, v207, s[14:15]
	v_max3_f32 v105, v105, v151, v143
	v_cndmask_b32_e64 v101, v108, v207, s[18:19]
	v_cndmask_b32_e64 v102, v109, v207, s[20:21]
	v_max3_f32 v105, v105, v142, v141
	v_cndmask_b32_e64 v103, v110, v207, s[22:23]
	v_cndmask_b32_e64 v104, v111, v207, s[24:25]
	v_max3_f32 v105, v105, v101, v102
	v_cndmask_b32_e64 v106, v112, v207, s[26:27]
	v_cndmask_b32_e64 v108, v113, v207, s[28:29]
	v_max3_f32 v105, v105, v103, v104
	v_cndmask_b32_e64 v110, v114, v207, s[30:31]
	v_cndmask_b32_e64 v100, v115, v207, s[34:35]
	v_max3_f32 v105, v105, v106, v108
	v_max3_f32 v105, v105, v110, v100
	v_sub_f32_e32 v107, v105, v117
	v_mul_f32_e32 v107, 0x3e38aa3b, v107
	v_cmp_lt_f32_e32 vcc, s42, v107
	s_cbranch_vccz .LBB0_2006
	v_mov_b32_e32 v107, v105
	s_nop 1
	v_permlane16_swap_b32_e32 v105, v107
	v_max_f32_e32 v105, v107, v105
	v_mov_b32_e32 v107, v105
	s_nop 1
	v_permlane32_swap_b32_e32 v105, v107
	v_max3_f32 v105, v117, v105, v107
	v_sub_f32_e32 v107, v117, v105
	v_mul_f32_e32 v107, 0x3e38aa3b, v107
	v_exp_f32_e32 v112, v107
	v_mov_b32_e32 v117, v105
	v_mul_f32_e32 v119, v119, v112
	v_pk_mul_f32 v[66:67], v[66:67], v[112:113] op_sel_hi:[1,0]
	v_pk_mul_f32 v[64:65], v[64:65], v[112:113] op_sel_hi:[1,0]
	v_pk_mul_f32 v[70:71], v[70:71], v[112:113] op_sel_hi:[1,0]
	v_pk_mul_f32 v[68:69], v[68:69], v[112:113] op_sel_hi:[1,0]
	v_pk_mul_f32 v[74:75], v[74:75], v[112:113] op_sel_hi:[1,0]
	v_pk_mul_f32 v[72:73], v[72:73], v[112:113] op_sel_hi:[1,0]
	v_pk_mul_f32 v[78:79], v[78:79], v[112:113] op_sel_hi:[1,0]
	v_pk_mul_f32 v[76:77], v[76:77], v[112:113] op_sel_hi:[1,0]
	v_mul_f32_e32 v112, 0xbe38aa3b, v105
	v_fmamk_f32 v105, v155, 0x3e38aa3b, v112
	v_exp_f32_e32 v105, v105
	v_fmamk_f32 v107, v154, 0x3e38aa3b, v112
	v_exp_f32_e32 v107, v107
	v_fmamk_f32 v109, v153, 0x3e38aa3b, v112
	v_exp_f32_e32 v109, v109
	v_fmamk_f32 v111, v152, 0x3e38aa3b, v112
	v_exp_f32_e32 v111, v111
	v_add_f32_e32 v113, v107, v105
	v_add_f32_e32 v113, v109, v113
	v_add_f32_e32 v152, v111, v113
	v_fmamk_f32 v113, v151, 0x3e38aa3b, v112
	v_exp_f32_e32 v113, v113
	v_fmamk_f32 v114, v143, 0x3e38aa3b, v112
	v_exp_f32_e32 v114, v114
	v_fmamk_f32 v115, v142, 0x3e38aa3b, v112
	v_exp_f32_e32 v115, v115
	v_fmamk_f32 v141, v141, 0x3e38aa3b, v112
	v_exp_f32_e32 v141, v141
	v_fmamk_f32 v101, v101, 0x3e38aa3b, v112
	v_add_f32_e32 v142, v113, v152
	v_exp_f32_e32 v101, v101
	v_fmamk_f32 v102, v102, 0x3e38aa3b, v112
	v_add_f32_e32 v142, v114, v142
	v_exp_f32_e32 v102, v102
	v_fmamk_f32 v103, v103, 0x3e38aa3b, v112
	v_add_f32_e32 v142, v115, v142
	v_exp_f32_e32 v103, v103
	v_fmamk_f32 v104, v104, 0x3e38aa3b, v112
	v_add_f32_e32 v142, v141, v142
	v_exp_f32_e32 v104, v104
	v_fmamk_f32 v106, v106, 0x3e38aa3b, v112
	v_add_f32_e32 v142, v101, v142
	v_exp_f32_e32 v106, v106
	v_fmamk_f32 v108, v108, 0x3e38aa3b, v112
	v_fmamk_f32 v110, v110, 0x3e38aa3b, v112
	v_fmac_f32_e32 v112, 0x3e38aa3b, v100
	v_add_f32_e32 v142, v102, v142
	v_exp_f32_e32 v108, v108
	v_exp_f32_e32 v110, v110
	v_exp_f32_e32 v112, v112
	v_add_f32_e32 v142, v103, v142
	v_add_f32_e32 v142, v104, v142
	v_add_f32_e32 v100, v106, v142
	s_branch .LBB0_2007

.LBB0_2011:
	v_mov_b32_e32 v135, v133
	s_nop 1
	v_permlane16_swap_b32_e32 v133, v135
	v_max_f32_e32 v133, v135, v133
	v_mov_b32_e32 v135, v133
	s_nop 1
	v_permlane32_swap_b32_e32 v133, v135
	v_max3_f32 v133, v159, v133, v135
	v_sub_f32_e32 v135, v159, v133
	v_mul_f32_e32 v135, 0x3e38aa3b, v135
	v_exp_f32_e32 v140, v135
	v_mov_b32_e32 v159, v133
	v_mul_f32_e32 v153, v153, v140
	v_pk_mul_f32 v[82:83], v[82:83], v[140:141] op_sel_hi:[1,0]
	v_pk_mul_f32 v[80:81], v[80:81], v[140:141] op_sel_hi:[1,0]
	v_pk_mul_f32 v[90:91], v[90:91], v[140:141] op_sel_hi:[1,0]
	v_pk_mul_f32 v[88:89], v[88:89], v[140:141] op_sel_hi:[1,0]
	v_pk_mul_f32 v[106:107], v[106:107], v[140:141] op_sel_hi:[1,0]
	v_pk_mul_f32 v[104:105], v[104:105], v[140:141] op_sel_hi:[1,0]
	v_pk_mul_f32 v[102:103], v[102:103], v[140:141] op_sel_hi:[1,0]
	v_pk_mul_f32 v[100:101], v[100:101], v[140:141] op_sel_hi:[1,0]
	v_mul_f32_e32 v140, 0xbe38aa3b, v133
	v_fmamk_f32 v133, v195, 0x3e38aa3b, v140
	v_exp_f32_e32 v133, v133
	v_fmamk_f32 v135, v192, 0x3e38aa3b, v140
	v_exp_f32_e32 v135, v135
	v_fmamk_f32 v137, v189, 0x3e38aa3b, v140
	v_exp_f32_e32 v137, v137
	v_fmamk_f32 v139, v188, 0x3e38aa3b, v140
	v_exp_f32_e32 v139, v139
	v_add_f32_e32 v141, v135, v133
	v_add_f32_e32 v141, v137, v141
	v_add_f32_e32 v188, v139, v141
	v_fmamk_f32 v141, v185, 0x3e38aa3b, v140
	v_exp_f32_e32 v141, v141
	v_fmamk_f32 v142, v184, 0x3e38aa3b, v140
	v_exp_f32_e32 v142, v142
	v_fmamk_f32 v143, v183, 0x3e38aa3b, v140
	v_exp_f32_e32 v143, v143
	v_fmamk_f32 v182, v182, 0x3e38aa3b, v140
	v_exp_f32_e32 v182, v182
	v_fmamk_f32 v129, v129, 0x3e38aa3b, v140
	v_add_f32_e32 v183, v141, v188
	v_exp_f32_e32 v129, v129
	v_fmamk_f32 v130, v130, 0x3e38aa3b, v140
	v_add_f32_e32 v183, v142, v183
	v_exp_f32_e32 v130, v130
	v_fmamk_f32 v131, v131, 0x3e38aa3b, v140
	v_add_f32_e32 v183, v143, v183
	v_exp_f32_e32 v131, v131
	v_fmamk_f32 v132, v132, 0x3e38aa3b, v140
	v_add_f32_e32 v183, v182, v183
	v_exp_f32_e32 v132, v132
	v_fmamk_f32 v134, v134, 0x3e38aa3b, v140
	v_add_f32_e32 v183, v129, v183
	v_exp_f32_e32 v134, v134
	v_fmamk_f32 v136, v136, 0x3e38aa3b, v140
	v_fmamk_f32 v138, v138, 0x3e38aa3b, v140
	v_fmac_f32_e32 v140, 0x3e38aa3b, v128
	v_add_f32_e32 v183, v130, v183
	v_exp_f32_e32 v136, v136
	v_exp_f32_e32 v138, v138
	v_exp_f32_e32 v140, v140
	v_add_f32_e32 v183, v131, v183
	v_add_f32_e32 v183, v132, v183
	v_add_f32_e32 v128, v134, v183

.LBB0_2015:
	v_mov_b32_e32 v128, v186
	s_nop 0
	v_bfe_u32 v182, v128, 4, 2
	v_and_b32_e32 v165, 15, v128
	v_lshlrev_b32_e32 v160, 4, v182
	v_mad_u32_u24 v178, v165, s43, v160
	ds_read_b128 v[128:131], v178
	ds_read_b128 v[136:139], v178 offset:64
	ds_read_b128 v[140:143], v178 offset:2368
	ds_read_b128 v[174:177], v178 offset:4672
	s_waitcnt lgkmcnt(3)
	v_mfma_f32_16x16x32_bf16 v[132:135], v[128:131], v[20:23], 0
	s_waitcnt lgkmcnt(2)
	v_mfma_f32_16x16x32_bf16 v[166:169], v[136:139], v[24:27], v[132:135]
	s_nop 5
	ds_read_b128 v[132:135], v178 offset:2304
	v_mfma_f32_16x16x32_bf16 v[128:131], v[128:131], v[28:31], 0
	v_mfma_f32_16x16x32_bf16 v[128:131], v[136:139], v[32:35], v[128:131]
	s_waitcnt lgkmcnt(0)
	v_mfma_f32_16x16x32_bf16 v[136:139], v[132:135], v[20:23], 0
	v_mfma_f32_16x16x32_bf16 v[170:173], v[140:143], v[24:27], v[136:139]
	v_mfma_f32_16x16x32_bf16 v[132:135], v[132:135], v[28:31], 0
	s_nop 5
	ds_read_b128 v[136:139], v178 offset:4608
	v_mfma_f32_16x16x32_bf16 v[132:135], v[140:143], v[32:35], v[132:135]
	s_waitcnt lgkmcnt(0)
	v_mfma_f32_16x16x32_bf16 v[140:143], v[136:139], v[20:23], 0
	v_mfma_f32_16x16x32_bf16 v[200:203], v[174:177], v[24:27], v[140:143]
	s_nop 6
	ds_read_b128 v[140:143], v178 offset:6912
	ds_read_b128 v[178:181], v178 offset:6976
	v_mfma_f32_16x16x32_bf16 v[136:139], v[136:139], v[28:31], 0
	v_mfma_f32_16x16x32_bf16 v[136:139], v[174:177], v[32:35], v[136:139]
	s_waitcnt lgkmcnt(1)
	v_mfma_f32_16x16x32_bf16 v[174:177], v[140:143], v[20:23], 0
	v_mfma_f32_16x16x32_bf16 v[140:143], v[140:143], v[28:31], 0
	s_waitcnt lgkmcnt(0)
	v_mfma_f32_16x16x32_bf16 v[174:177], v[178:181], v[24:27], v[174:177]
	v_mfma_f32_16x16x32_bf16 v[140:143], v[178:181], v[32:35], v[140:143]
	v_lshlrev_b32_e32 v178, 3, v182
	v_sub_u32_e32 v188, v164, v178
	v_add_u32_e32 v189, 0x1ff, v188
	v_cmp_gt_i32_e32 vcc, 0, v189
	v_cmp_lt_i32_e64 s[0:1], 0, v188
	s_or_b64 s[0:1], s[0:1], vcc
	v_cmp_gt_i32_e32 vcc, 1, v189
	v_cmp_lt_i32_e64 s[2:3], 1, v188
	s_or_b64 s[2:3], s[2:3], vcc
	v_cmp_gt_i32_e32 vcc, 2, v189
	v_cmp_lt_i32_e64 s[4:5], 2, v188
	s_or_b64 s[4:5], s[4:5], vcc
	v_cmp_gt_i32_e32 vcc, 3, v189
	v_cmp_lt_i32_e64 s[6:7], 3, v188
	s_or_b64 s[6:7], s[6:7], vcc
	v_cmp_gt_i32_e32 vcc, 4, v189
	v_cmp_lt_i32_e64 s[8:9], 4, v188
	s_or_b64 s[8:9], s[8:9], vcc
	v_cmp_gt_i32_e32 vcc, 5, v189
	v_cmp_lt_i32_e64 s[10:11], 5, v188
	s_or_b64 s[10:11], s[10:11], vcc
	v_cmp_gt_i32_e32 vcc, 6, v189
	v_cmp_lt_i32_e64 s[14:15], 6, v188
	s_or_b64 s[14:15], s[14:15], vcc
	v_cmp_gt_i32_e32 vcc, 7, v189
	v_cmp_lt_i32_e64 s[16:17], 7, v188
	s_or_b64 s[16:17], s[16:17], vcc
	v_cmp_gt_i32_e32 vcc, 32, v189
	v_cmp_lt_i32_e64 s[18:19], 32, v188
	v_cndmask_b32_e64 v166, v166, v207, s[0:1]
	v_cndmask_b32_e64 v167, v167, v207, s[2:3]
	s_or_b64 s[18:19], s[18:19], vcc
	v_cmp_gt_i32_e32 vcc, 33, v189
	v_cmp_lt_i32_e64 s[20:21], 33, v188
	v_cndmask_b32_e64 v178, v170, v207, s[8:9]
	v_cndmask_b32_e64 v180, v172, v207, s[14:15]
	s_or_b64 s[20:21], s[20:21], vcc
	v_cmp_gt_i32_e32 vcc, 34, v189
	v_cmp_lt_i32_e64 s[22:23], 34, v188
	v_max_f32_e32 v170, v167, v167
	v_max_f32_e32 v172, v166, v166
	v_cndmask_b32_e64 v168, v168, v207, s[4:5]
	v_cndmask_b32_e64 v169, v169, v207, s[6:7]
	s_or_b64 s[22:23], s[22:23], vcc
	v_cmp_gt_i32_e32 vcc, 35, v189
	v_cmp_lt_i32_e64 s[24:25], 35, v188
	v_max_f32_e32 v170, v172, v170
	v_cndmask_b32_e64 v179, v171, v207, s[10:11]
	s_or_b64 s[24:25], s[24:25], vcc
	v_cmp_gt_i32_e32 vcc, 36, v189
	v_cmp_lt_i32_e64 s[26:27], 36, v188
	v_max3_f32 v170, v170, v168, v169
	v_cndmask_b32_e64 v181, v173, v207, s[16:17]
	s_or_b64 s[26:27], s[26:27], vcc
	v_cmp_gt_i32_e32 vcc, 37, v189
	v_cmp_lt_i32_e64 s[28:29], 37, v188
	v_max3_f32 v170, v170, v178, v179
	v_cndmask_b32_e64 v185, v200, v207, s[18:19]
	v_cndmask_b32_e64 v184, v201, v207, s[20:21]
	s_or_b64 s[28:29], s[28:29], vcc
	v_cmp_gt_i32_e32 vcc, 38, v189
	v_cmp_lt_i32_e64 s[30:31], 38, v188
	v_max3_f32 v170, v170, v180, v181
	v_cndmask_b32_e64 v183, v202, v207, s[22:23]
	v_cndmask_b32_e64 v182, v203, v207, s[24:25]
	s_or_b64 s[30:31], s[30:31], vcc
	v_cmp_gt_i32_e32 vcc, 39, v189
	v_cmp_lt_i32_e64 s[34:35], 39, v188
	v_max3_f32 v170, v170, v185, v184
	v_cndmask_b32_e64 v171, v174, v207, s[26:27]
	v_cndmask_b32_e64 v173, v175, v207, s[28:29]
	s_or_b64 s[34:35], s[34:35], vcc
	v_max3_f32 v170, v170, v183, v182
	v_cndmask_b32_e64 v175, v176, v207, s[30:31]
	v_cndmask_b32_e64 v177, v177, v207, s[34:35]
	v_max3_f32 v170, v170, v171, v173
	v_max3_f32 v170, v170, v175, v177
	v_sub_f32_e32 v172, v170, v158
	v_mul_f32_e32 v172, 0x3e38aa3b, v172
	v_cmp_lt_f32_e32 vcc, s42, v172
	s_cbranch_vccz .LBB0_2017
	v_mov_b32_e32 v172, v170
	s_nop 1
	v_permlane16_swap_b32_e32 v170, v172
	v_max_f32_e32 v170, v172, v170
	v_mov_b32_e32 v172, v170
	s_nop 1
	v_permlane32_swap_b32_e32 v170, v172
	v_max3_f32 v188, v158, v170, v172
	v_sub_f32_e32 v158, v158, v188
	v_mul_f32_e32 v158, 0x3e38aa3b, v158
	v_exp_f32_e32 v158, v158
	v_mov_b32_e32 v189, v159
	v_mul_f32_e32 v152, v152, v158
	v_pk_mul_f32 v[86:87], v[86:87], v[158:159] op_sel_hi:[1,0]
	v_pk_mul_f32 v[84:85], v[84:85], v[158:159] op_sel_hi:[1,0]
	v_pk_mul_f32 v[94:95], v[94:95], v[158:159] op_sel_hi:[1,0]
	v_pk_mul_f32 v[92:93], v[92:93], v[158:159] op_sel_hi:[1,0]
	v_pk_mul_f32 v[98:99], v[98:99], v[158:159] op_sel_hi:[1,0]
	v_pk_mul_f32 v[96:97], v[96:97], v[158:159] op_sel_hi:[1,0]
	v_pk_mul_f32 v[110:111], v[110:111], v[158:159] op_sel_hi:[1,0]
	v_pk_mul_f32 v[108:109], v[108:109], v[158:159] op_sel_hi:[1,0]
	v_mul_f32_e32 v158, 0xbe38aa3b, v188
	v_fmamk_f32 v159, v166, 0x3e38aa3b, v158
	v_exp_f32_e32 v170, v159
	v_fmamk_f32 v159, v167, 0x3e38aa3b, v158
	v_exp_f32_e32 v172, v159
	v_fmamk_f32 v159, v168, 0x3e38aa3b, v158
	v_exp_f32_e32 v174, v159
	v_fmamk_f32 v159, v169, 0x3e38aa3b, v158
	v_exp_f32_e32 v176, v159
	v_fmamk_f32 v166, v178, 0x3e38aa3b, v158
	v_add_f32_e32 v159, 0, v170
	v_exp_f32_e32 v178, v166
	v_fmamk_f32 v166, v179, 0x3e38aa3b, v158
	v_add_f32_e32 v159, v172, v159
	v_exp_f32_e32 v179, v166
	v_fmamk_f32 v166, v180, 0x3e38aa3b, v158
	v_add_f32_e32 v159, v174, v159
	v_exp_f32_e32 v180, v166
	v_fmamk_f32 v166, v181, 0x3e38aa3b, v158
	v_add_f32_e32 v159, v176, v159
	v_exp_f32_e32 v181, v166
	v_fmamk_f32 v166, v185, 0x3e38aa3b, v158
	v_add_f32_e32 v159, v178, v159
	v_exp_f32_e32 v166, v166
	v_fmamk_f32 v167, v184, 0x3e38aa3b, v158
	v_add_f32_e32 v159, v179, v159
	v_exp_f32_e32 v167, v167
	v_fmamk_f32 v168, v183, 0x3e38aa3b, v158
	v_add_f32_e32 v159, v180, v159
	v_exp_f32_e32 v168, v168
	v_fmamk_f32 v169, v182, 0x3e38aa3b, v158
	v_add_f32_e32 v159, v181, v159
	v_exp_f32_e32 v169, v169
	v_fmamk_f32 v171, v171, 0x3e38aa3b, v158
	v_add_f32_e32 v159, v166, v159
	v_exp_f32_e32 v171, v171
	v_fmamk_f32 v173, v173, 0x3e38aa3b, v158
	v_add_f32_e32 v159, v167, v159
	v_exp_f32_e32 v173, v173
	v_fmamk_f32 v175, v175, 0x3e38aa3b, v158
	v_add_f32_e32 v159, v168, v159
	v_exp_f32_e32 v175, v175
	v_fmac_f32_e32 v158, 0x3e38aa3b, v177
	v_add_f32_e32 v159, v169, v159
	v_exp_f32_e32 v177, v158
	v_add_f32_e32 v158, v171, v159
	v_add_f32_e32 v158, v173, v158
	v_add_f32_e32 v158, v175, v158
	v_add_f32_e32 v182, v177, v158
	v_mov_b64_e32 v[158:159], v[188:189]
	s_branch .LBB0_2018

.LBB0_2022:
	v_pk_add_f32 v[24:25], v[154:155], v[156:157]
	v_lshlrev_b32_e32 v160, 3, v147
	v_rcp_f32_e32 v20, v25
	s_nop 0
	v_cmp_lt_f32_e32 vcc, 0, v25
	v_div_scale_f32 v25, s[0:1], v24, v24, 1.0
	s_nop 0
	v_cndmask_b32_e32 v20, 0, v20, vcc
	s_waitcnt vmcnt(0)
	v_mul_f32_e32 v26, v163, v20
	v_pk_mul_f32 v[30:31], v[72:73], v[26:27] op_sel_hi:[1,0]
	v_pk_mul_f32 v[32:33], v[70:71], v[26:27] op_sel_hi:[1,0]
	v_pk_fma_f32 v[30:31], v[40:41], v[150:151], v[30:31] op_sel_hi:[1,0,1]
	global_load_dword v40, v[148:149], off offset:8
	global_load_dword v41, v[148:149], off offset:20
	v_pk_fma_f32 v[32:33], v[38:39], v[150:151], v[32:33] op_sel_hi:[1,0,1]
	v_rcp_f32_e32 v38, v25
	v_pk_mul_f32 v[34:35], v[68:69], v[26:27] op_sel_hi:[1,0]
	v_pk_mul_f32 v[22:23], v[78:79], v[26:27] op_sel_hi:[1,0]
	v_pk_mul_f32 v[20:21], v[76:77], v[26:27] op_sel_hi:[1,0]
	v_pk_mul_f32 v[28:29], v[74:75], v[26:27] op_sel_hi:[1,0]
	v_pk_fma_f32 v[34:35], v[36:37], v[150:151], v[34:35] op_sel_hi:[1,0,1]
	v_pk_mul_f32 v[36:37], v[66:67], v[26:27] op_sel_hi:[1,0]
	v_pk_mul_f32 v[26:27], v[64:65], v[26:27] op_sel_hi:[1,0]
	v_pk_fma_f32 v[14:15], v[14:15], v[150:151], v[36:37] op_sel_hi:[1,0,1]
	v_pk_fma_f32 v[12:13], v[12:13], v[150:151], v[26:27] op_sel_hi:[1,0,1]
	v_fma_f32 v26, -v25, v38, 1.0
	v_fmac_f32_e32 v38, v26, v38
	v_div_scale_f32 v26, vcc, 1.0, v24, 1.0
	v_mul_f32_e32 v27, v26, v38
	v_fma_f32 v36, -v25, v27, v26
	v_fmac_f32_e32 v27, v36, v38
	v_fma_f32 v25, -v25, v27, v26
	v_div_fmas_f32 v25, v25, v38, v27
	v_div_fixup_f32 v25, v25, v24, 1.0
	v_cmp_lt_f32_e32 vcc, 0, v24
	v_pk_fma_f32 v[20:21], v[44:45], v[150:151], v[20:21] op_sel_hi:[1,0,1]
	v_pk_fma_f32 v[22:23], v[46:47], v[150:151], v[22:23] op_sel_hi:[1,0,1]
	v_cndmask_b32_e32 v24, 0, v25, vcc
	v_mul_f32_e32 v24, v151, v24
	v_pk_mul_f32 v[26:27], v[62:63], v[24:25] op_sel_hi:[1,0]
	v_pk_mul_f32 v[36:37], v[60:61], v[24:25] op_sel_hi:[1,0]
	v_pk_fma_f32 v[18:19], v[18:19], v[146:147], v[26:27] op_sel_hi:[1,0,1]
	v_pk_mul_f32 v[26:27], v[58:59], v[24:25] op_sel_hi:[1,0]
	v_pk_fma_f32 v[16:17], v[16:17], v[146:147], v[36:37] op_sel_hi:[1,0,1]
	v_pk_mul_f32 v[36:37], v[56:57], v[24:25] op_sel_hi:[1,0]
	v_pk_fma_f32 v[10:11], v[10:11], v[146:147], v[26:27] op_sel_hi:[1,0,1]
	v_pk_mul_f32 v[26:27], v[54:55], v[24:25] op_sel_hi:[1,0]
	v_pk_fma_f32 v[8:9], v[8:9], v[146:147], v[36:37] op_sel_hi:[1,0,1]
	v_pk_mul_f32 v[36:37], v[52:53], v[24:25] op_sel_hi:[1,0]
	v_pk_fma_f32 v[6:7], v[6:7], v[146:147], v[26:27] op_sel_hi:[1,0,1]
	v_pk_mul_f32 v[26:27], v[50:51], v[24:25] op_sel_hi:[1,0]
	v_mov_b32_e32 v25, v152
	s_nop 1
	v_permlane16_swap_b32_e32 v152, v25
	v_pk_fma_f32 v[4:5], v[4:5], v[146:147], v[36:37] op_sel_hi:[1,0,1]
	v_add_f32_e32 v37, v152, v25
	v_mov_b32_e32 v25, v153
	s_nop 1
	v_permlane16_swap_b32_e32 v153, v25
	v_add_f32_e32 v36, v153, v25
	v_mov_b32_e32 v39, v37
	v_mov_b32_e32 v38, v36
	s_nop 0
	v_permlane32_swap_b32_e32 v37, v39
	v_permlane32_swap_b32_e32 v36, v38
	v_pk_add_f32 v[36:37], v[36:37], v[38:39]
	v_pk_mul_f32 v[24:25], v[48:49], v[24:25] op_sel_hi:[1,0]
	v_div_scale_f32 v38, s[0:1], v37, v37, 1.0
	v_rcp_f32_e32 v39, v38
	v_pk_fma_f32 v[0:1], v[0:1], v[146:147], v[24:25] op_sel_hi:[1,0,1]
	v_pk_fma_f32 v[2:3], v[2:3], v[146:147], v[26:27] op_sel_hi:[1,0,1]
	v_pk_fma_f32 v[28:29], v[42:43], v[150:151], v[28:29] op_sel_hi:[1,0,1]
	v_fma_f32 v24, -v38, v39, 1.0
	v_fmac_f32_e32 v39, v24, v39
	v_div_scale_f32 v24, vcc, 1.0, v37, 1.0
	v_mul_f32_e32 v25, v24, v39
	v_fma_f32 v26, -v38, v25, v24
	v_fmac_f32_e32 v25, v26, v39
	v_fma_f32 v24, -v38, v25, v24
	v_div_fmas_f32 v24, v24, v39, v25
	v_div_scale_f32 v25, s[0:1], v36, v36, 1.0
	v_rcp_f32_e32 v26, v25
	v_div_fixup_f32 v24, v24, v37, 1.0
	v_cmp_lt_f32_e32 vcc, 0, v37
	v_readlane_b32 s0, v254, 30
	v_fma_f32 v27, -v25, v26, 1.0
	v_cndmask_b32_e32 v24, 0, v24, vcc
	v_fmac_f32_e32 v26, v27, v26
	v_div_scale_f32 v27, vcc, 1.0, v36, 1.0
	v_mul_f32_e32 v37, v27, v26
	v_fma_f32 v38, -v25, v37, v27
	v_fmac_f32_e32 v37, v38, v26
	v_fma_f32 v25, -v25, v37, v27
	v_div_fmas_f32 v25, v25, v26, v37
	v_div_fixup_f32 v25, v25, v36, 1.0
	v_cmp_lt_f32_e32 vcc, 0, v36
	s_waitcnt vmcnt(1)
	v_mul_f32_e32 v24, v40, v24
	v_readlane_b32 s1, v254, 31
	v_cndmask_b32_e32 v25, 0, v25, vcc
	v_pk_fma_f32 v[2:3], v[86:87], v[24:25], v[2:3] op_sel_hi:[1,0,1]
	v_pk_fma_f32 v[0:1], v[84:85], v[24:25], v[0:1] op_sel_hi:[1,0,1]
	v_pk_fma_f32 v[6:7], v[94:95], v[24:25], v[6:7] op_sel_hi:[1,0,1]
	v_pk_fma_f32 v[4:5], v[92:93], v[24:25], v[4:5] op_sel_hi:[1,0,1]
	v_pk_fma_f32 v[10:11], v[98:99], v[24:25], v[10:11] op_sel_hi:[1,0,1]
	v_pk_fma_f32 v[8:9], v[96:97], v[24:25], v[8:9] op_sel_hi:[1,0,1]
	v_pk_fma_f32 v[18:19], v[110:111], v[24:25], v[18:19] op_sel_hi:[1,0,1]
	v_pk_fma_f32 v[16:17], v[108:109], v[24:25], v[16:17] op_sel_hi:[1,0,1]
	s_waitcnt vmcnt(0)
	v_mul_f32_e32 v24, v41, v25
	v_pk_fma_f32 v[14:15], v[82:83], v[24:25], v[14:15] op_sel_hi:[1,0,1]
	v_pk_fma_f32 v[12:13], v[80:81], v[24:25], v[12:13] op_sel_hi:[1,0,1]
	v_pk_fma_f32 v[26:27], v[90:91], v[24:25], v[32:33] op_sel_hi:[1,0,1]
	v_pk_fma_f32 v[32:33], v[88:89], v[24:25], v[34:35] op_sel_hi:[1,0,1]
	v_pk_fma_f32 v[28:29], v[106:107], v[24:25], v[28:29] op_sel_hi:[1,0,1]
	v_pk_fma_f32 v[30:31], v[104:105], v[24:25], v[30:31] op_sel_hi:[1,0,1]
	v_pk_fma_f32 v[22:23], v[102:103], v[24:25], v[22:23] op_sel_hi:[1,0,1]
	v_pk_fma_f32 v[20:21], v[100:101], v[24:25], v[20:21] op_sel_hi:[1,0,1]
	v_lshl_add_u64 v[24:25], s[0:1], 0, v[160:161]
	v_lshl_add_u64 v[24:25], v[24:25], 0, v[144:145]
	v_cvt_pk_bf16_f32 v0, v0, v1
	v_cvt_pk_bf16_f32 v1, v2, v3
	global_store_dwordx2 v[24:25], v[0:1], off
	v_cvt_pk_bf16_f32 v0, v4, v5
	v_cvt_pk_bf16_f32 v1, v6, v7
	global_store_dwordx2 v[24:25], v[0:1], off offset:32
	v_cvt_pk_bf16_f32 v0, v8, v9
	v_cvt_pk_bf16_f32 v1, v10, v11
	global_store_dwordx2 v[24:25], v[0:1], off offset:64
	v_cvt_pk_bf16_f32 v0, v16, v17
	v_cvt_pk_bf16_f32 v1, v18, v19
	global_store_dwordx2 v[24:25], v[0:1], off offset:96
	v_cvt_pk_bf16_f32 v0, v12, v13
	v_cvt_pk_bf16_f32 v1, v14, v15
	global_store_dwordx2 v[24:25], v[0:1], off offset:128
	v_cvt_pk_bf16_f32 v0, v32, v33
	v_cvt_pk_bf16_f32 v1, v26, v27
	global_store_dwordx2 v[24:25], v[0:1], off offset:160
	v_cvt_pk_bf16_f32 v0, v30, v31
	v_cvt_pk_bf16_f32 v1, v28, v29
	global_store_dwordx2 v[24:25], v[0:1], off offset:192
	v_cvt_pk_bf16_f32 v0, v20, v21
	v_cvt_pk_bf16_f32 v1, v22, v23
	global_store_dwordx2 v[24:25], v[0:1], off offset:224
	s_cbranch_execnz .LBB0_1893
	s_branch .LBB0_1934

.LBB0_2087:
	s_cmp_eq_u32 s5, 1
	s_mov_b32 s12, 0x7000000
	s_cselect_b32 s12, s12, 0x8800000
	s_cmp_lg_u32 s5, 0
	s_cselect_b32 s12, s12, 0x4800000
	v_mov_b32_e32 v0, 0
	s_add_u32 s12, s19, s12
	s_waitcnt vmcnt(8)
	v_mov_b32_e32 v49, v186
	s_addc_u32 s13, s20, 0
	s_add_u32 s22, s0, s8
	v_lshlrev_b32_e32 v16, 4, v49
	v_ashrrev_i32_e32 v50, 3, v49
	v_and_b32_e32 v48, 0x70, v16
	v_lshl_or_b32 v160, v50, 10, v48
	s_addc_u32 s23, s1, s9
	v_lshl_add_u64 v[32:33], s[22:23], 0, v[160:161]
	s_barrier
	global_load_dwordx4 v[16:19], v160, s[12:13]
	v_add_u32_e32 v148, 0x8000, v160
	v_mov_b32_e32 v149, v161
	v_add_co_u32_e32 v156, vcc, s94, v32
	global_load_dwordx4 v[20:23], v148, s[12:13]
	v_add_u32_e32 v152, 0x10000, v160
	v_addc_co_u32_e32 v157, vcc, 0, v33, vcc
	v_lshl_add_u64 v[36:37], s[22:23], 0, v[148:149]
	v_mov_b32_e32 v153, v161
	global_load_dwordx4 v[24:27], v152, s[12:13]
	v_add_u32_e32 v154, 0x18000, v160
	v_add_co_u32_e32 v158, vcc, s94, v36
	global_load_dwordx4 v[28:31], v154, s[12:13]
	s_nop 0
	v_addc_co_u32_e32 v159, vcc, 0, v37, vcc
	v_lshl_add_u64 v[40:41], s[22:23], 0, v[152:153]
	v_mov_b32_e32 v155, v161
	global_load_dwordx4 v[32:35], v[156:157], off
	v_add_co_u32_e32 v164, vcc, s94, v40
	global_load_dwordx4 v[36:39], v[158:159], off
	s_nop 0
	v_addc_co_u32_e32 v165, vcc, 0, v41, vcc
	v_lshl_add_u64 v[44:45], s[22:23], 0, v[154:155]
	global_load_dwordx4 v[40:43], v[164:165], off
	v_add_co_u32_e32 v166, vcc, s94, v44
	v_mad_u64_u32 v[146:147], s[22:23], v50, s43, v[48:49]
	s_nop 0
	v_addc_co_u32_e32 v167, vcc, 0, v45, vcc
	global_load_dwordx4 v[44:47], v[166:167], off
	global_load_dwordx4 v[80:83], v160, s[12:13] offset:128
	global_load_dwordx4 v[84:87], v148, s[12:13] offset:128
	global_load_dwordx4 v[88:91], v152, s[12:13] offset:128
	global_load_dwordx4 v[92:95], v154, s[12:13] offset:128
	global_load_dwordx4 v[64:67], v[156:157], off offset:128
	global_load_dwordx4 v[68:71], v[158:159], off offset:128
	global_load_dwordx4 v[72:75], v[164:165], off offset:128
	global_load_dwordx4 v[76:79], v[166:167], off offset:128
	v_mov_b32_e32 v1, v0
	v_mov_b32_e32 v2, v0
	v_mov_b32_e32 v3, v0
	v_mov_b32_e32 v4, v0
	v_mov_b32_e32 v5, v0
	v_mov_b32_e32 v6, v0
	v_mov_b32_e32 v7, v0
	s_waitcnt vmcnt(16)
	v_mov_b32_e32 v8, v0
	v_mov_b32_e32 v9, v0
	v_mov_b32_e32 v10, v0
	v_mov_b32_e32 v11, v0
	v_mov_b32_e32 v12, v0
	v_mov_b32_e32 v13, v0
	v_mov_b32_e32 v14, v0
	v_mov_b32_e32 v15, v0
	v_add_u32_e32 v149, 0xd800, v146
	s_waitcnt vmcnt(15)
	ds_write_b128 v146, v[16:19]
	s_waitcnt vmcnt(14)
	ds_write_b128 v146, v[20:23] offset:4608
	s_waitcnt vmcnt(13)
	ds_write_b128 v146, v[24:27] offset:9216
	s_waitcnt vmcnt(12)
	ds_write_b128 v146, v[28:31] offset:13824
	s_waitcnt vmcnt(11)
	ds_write_b128 v146, v[32:35] offset:36864
	s_waitcnt vmcnt(10)
	ds_write_b128 v146, v[36:39] offset:41472
	s_waitcnt vmcnt(9)
	ds_write_b128 v146, v[40:43] offset:46080
	s_waitcnt vmcnt(8)
	ds_write_b128 v146, v[44:47] offset:50688
	v_lshrrev_b32_e32 v18, 1, v49
	s_waitcnt lgkmcnt(0)
	s_barrier
	v_and_b32_e32 v17, 0x5f, v49
	v_and_b32_e32 v16, 16, v18
	global_load_dwordx4 v[112:115], v160, s[12:13] offset:256
	global_load_dwordx4 v[116:119], v148, s[12:13] offset:256
	global_load_dwordx4 v[120:123], v152, s[12:13] offset:256
	global_load_dwordx4 v[124:127], v154, s[12:13] offset:256
	global_load_dwordx4 v[96:99], v[156:157], off offset:256
	global_load_dwordx4 v[100:103], v[158:159], off offset:256
	global_load_dwordx4 v[104:107], v[164:165], off offset:256
	global_load_dwordx4 v[108:111], v[166:167], off offset:256
	v_mad_u32_u24 v147, v17, s43, v16
	v_and_b32_e32 v17, 31, v49
	v_and_or_b32 v17, v18, s44, v17
	v_mad_u64_u32 v[150:151], s[22:23], v17, s43, v[16:17]
	ds_read_b128 v[128:131], v150 offset:4608
	ds_read_b128 v[132:135], v147 offset:41472
	ds_read_b128 v[16:19], v150
	ds_read_b128 v[136:139], v150 offset:32
	ds_read_b128 v[140:143], v147 offset:36864
	ds_read_b128 v[200:203], v147 offset:36896
	s_waitcnt lgkmcnt(1)
	v_mfma_f32_32x32x16_bf16 v[48:63], v[16:19], v[140:143], v[0:15]
	v_mov_b32_e32 v151, v161
	v_mfma_f32_32x32x16_bf16 v[32:47], v[16:19], v[132:135], v[0:15]
	v_mfma_f32_32x32x16_bf16 v[16:31], v[128:131], v[140:143], v[0:15]
	v_mfma_f32_32x32x16_bf16 v[0:15], v[128:131], v[132:135], v[0:15]
	ds_read_b128 v[128:131], v150 offset:4640
	ds_read_b128 v[132:135], v147 offset:41504
	s_waitcnt vmcnt(15)
	ds_write_b128 v146, v[80:83] offset:18432
	s_waitcnt vmcnt(14)
	ds_write_b128 v146, v[84:87] offset:23040
	s_waitcnt vmcnt(13)
	ds_write_b128 v146, v[88:91] offset:27648
	s_waitcnt vmcnt(12)
	ds_write_b128 v146, v[92:95] offset:32256
	ds_read_b128 v[80:83], v150 offset:64
	ds_read_b128 v[84:87], v150 offset:4672
	ds_read_b128 v[88:91], v147 offset:36928
	ds_read_b128 v[92:95], v147 offset:41536
	s_waitcnt vmcnt(11)
	ds_write_b128 v146, v[64:67] offset:55296
	s_waitcnt vmcnt(10)
	ds_write_b128 v146, v[68:71] offset:59904
	s_waitcnt vmcnt(9)
	ds_write_b128 v146, v[72:75] offset:64512
	s_waitcnt vmcnt(8)
	ds_write_b128 v149, v[76:79] offset:13824
	ds_read_b128 v[64:67], v150 offset:96
	ds_read_b128 v[68:71], v150 offset:4704
	ds_read_b128 v[72:75], v147 offset:36960
	ds_read_b128 v[76:79], v147 offset:41568
	s_waitcnt lgkmcnt(0)
	s_barrier
	v_mfma_f32_32x32x16_bf16 v[48:63], v[136:139], v[200:203], v[48:63]
	v_mfma_f32_32x32x16_bf16 v[32:47], v[136:139], v[132:135], v[32:47]
	v_mfma_f32_32x32x16_bf16 v[16:31], v[128:131], v[200:203], v[16:31]
	v_mfma_f32_32x32x16_bf16 v[0:15], v[128:131], v[132:135], v[0:15]
	v_mfma_f32_32x32x16_bf16 v[48:63], v[80:83], v[88:91], v[48:63]
	v_mfma_f32_32x32x16_bf16 v[32:47], v[80:83], v[92:95], v[32:47]
	v_mfma_f32_32x32x16_bf16 v[16:31], v[84:87], v[88:91], v[16:31]
	v_mfma_f32_32x32x16_bf16 v[0:15], v[84:87], v[92:95], v[0:15]
	v_mfma_f32_32x32x16_bf16 v[48:63], v[64:67], v[72:75], v[48:63]
	v_mfma_f32_32x32x16_bf16 v[32:47], v[64:67], v[76:79], v[32:47]
	v_mfma_f32_32x32x16_bf16 v[16:31], v[68:71], v[72:75], v[16:31]
	v_mfma_f32_32x32x16_bf16 v[0:15], v[68:71], v[76:79], v[0:15]
	global_load_dwordx4 v[128:131], v160, s[12:13] offset:384
	global_load_dwordx4 v[132:135], v148, s[12:13] offset:384
	global_load_dwordx4 v[136:139], v152, s[12:13] offset:384
	global_load_dwordx4 v[140:143], v154, s[12:13] offset:384
	global_load_dwordx4 v[64:67], v[156:157], off offset:384
	global_load_dwordx4 v[68:71], v[158:159], off offset:384
	global_load_dwordx4 v[72:75], v[164:165], off offset:384
	global_load_dwordx4 v[76:79], v[166:167], off offset:384
	ds_read_b128 v[80:83], v150 offset:23040
	ds_read_b128 v[84:87], v147 offset:59904
	ds_read_b128 v[88:91], v150 offset:18432
	ds_read_b128 v[92:95], v150 offset:18464
	ds_read_b128 v[200:203], v147 offset:55296
	ds_read_b128 v[226:229], v147 offset:55328
	s_waitcnt lgkmcnt(1)
	v_mfma_f32_32x32x16_bf16 v[48:63], v[88:91], v[200:203], v[48:63]
	v_mfma_f32_32x32x16_bf16 v[32:47], v[88:91], v[84:87], v[32:47]
	v_mfma_f32_32x32x16_bf16 v[16:31], v[80:83], v[200:203], v[16:31]
	v_mfma_f32_32x32x16_bf16 v[0:15], v[80:83], v[84:87], v[0:15]
	ds_read_b128 v[80:83], v150 offset:23072
	ds_read_b128 v[84:87], v147 offset:59936
	s_waitcnt vmcnt(15)
	ds_write_b128 v146, v[112:115]
	s_waitcnt vmcnt(14)
	ds_write_b128 v146, v[116:119] offset:4608
	s_waitcnt vmcnt(13)
	ds_write_b128 v146, v[120:123] offset:9216
	s_waitcnt vmcnt(12)
	ds_write_b128 v146, v[124:127] offset:13824
	s_waitcnt lgkmcnt(6)
	v_mfma_f32_32x32x16_bf16 v[48:63], v[92:95], v[226:229], v[48:63]
	s_waitcnt lgkmcnt(4)
	v_mfma_f32_32x32x16_bf16 v[32:47], v[92:95], v[84:87], v[32:47]
	v_mfma_f32_32x32x16_bf16 v[16:31], v[80:83], v[226:229], v[16:31]
	v_mfma_f32_32x32x16_bf16 v[0:15], v[80:83], v[84:87], v[0:15]
	ds_read_b128 v[80:83], v150 offset:18496
	ds_read_b128 v[84:87], v150 offset:23104
	ds_read_b128 v[88:91], v147 offset:55360
	ds_read_b128 v[92:95], v147 offset:59968
	s_waitcnt vmcnt(11)
	ds_write_b128 v146, v[96:99] offset:36864
	s_waitcnt vmcnt(10)
	ds_write_b128 v146, v[100:103] offset:41472
	s_waitcnt vmcnt(9)
	ds_write_b128 v146, v[104:107] offset:46080
	s_waitcnt vmcnt(8)
	ds_write_b128 v146, v[108:111] offset:50688
	s_waitcnt lgkmcnt(5)
	v_mfma_f32_32x32x16_bf16 v[48:63], v[80:83], v[88:91], v[48:63]
	s_waitcnt lgkmcnt(4)
	v_mfma_f32_32x32x16_bf16 v[32:47], v[80:83], v[92:95], v[32:47]
	v_mfma_f32_32x32x16_bf16 v[16:31], v[84:87], v[88:91], v[16:31]
	v_mfma_f32_32x32x16_bf16 v[0:15], v[84:87], v[92:95], v[0:15]
	ds_read_b128 v[80:83], v150 offset:18528
	ds_read_b128 v[84:87], v150 offset:23136
	ds_read_b128 v[88:91], v147 offset:55392
	ds_read_b128 v[92:95], v147 offset:60000
	s_waitcnt lgkmcnt(0)
	s_barrier
	v_mfma_f32_32x32x16_bf16 v[48:63], v[80:83], v[88:91], v[48:63]
	v_mfma_f32_32x32x16_bf16 v[32:47], v[80:83], v[92:95], v[32:47]
	v_mfma_f32_32x32x16_bf16 v[16:31], v[84:87], v[88:91], v[16:31]
	v_mfma_f32_32x32x16_bf16 v[0:15], v[84:87], v[92:95], v[0:15]
	global_load_dwordx4 v[96:99], v160, s[12:13] offset:512
	global_load_dwordx4 v[100:103], v148, s[12:13] offset:512
	global_load_dwordx4 v[104:107], v152, s[12:13] offset:512
	global_load_dwordx4 v[108:111], v154, s[12:13] offset:512
	global_load_dwordx4 v[80:83], v[156:157], off offset:512
	global_load_dwordx4 v[84:87], v[158:159], off offset:512
	global_load_dwordx4 v[88:91], v[164:165], off offset:512
	global_load_dwordx4 v[92:95], v[166:167], off offset:512
	ds_read_b128 v[112:115], v150 offset:4608
	ds_read_b128 v[116:119], v147 offset:41472
	ds_read_b128 v[120:123], v150
	ds_read_b128 v[124:127], v150 offset:32
	ds_read_b128 v[200:203], v147 offset:36864
	ds_read_b128 v[226:229], v147 offset:36896
	s_waitcnt lgkmcnt(1)
	v_mfma_f32_32x32x16_bf16 v[48:63], v[120:123], v[200:203], v[48:63]
	v_mfma_f32_32x32x16_bf16 v[32:47], v[120:123], v[116:119], v[32:47]
	v_mfma_f32_32x32x16_bf16 v[16:31], v[112:115], v[200:203], v[16:31]
	v_mfma_f32_32x32x16_bf16 v[0:15], v[112:115], v[116:119], v[0:15]
	ds_read_b128 v[112:115], v150 offset:4640
	ds_read_b128 v[116:119], v147 offset:41504
	s_waitcnt vmcnt(15)
	ds_write_b128 v146, v[128:131] offset:18432
	s_waitcnt vmcnt(14)
	ds_write_b128 v146, v[132:135] offset:23040
	s_waitcnt vmcnt(13)
	ds_write_b128 v146, v[136:139] offset:27648
	s_waitcnt vmcnt(12)
	ds_write_b128 v146, v[140:143] offset:32256
	s_waitcnt lgkmcnt(6)
	v_mfma_f32_32x32x16_bf16 v[48:63], v[124:127], v[226:229], v[48:63]
	s_waitcnt lgkmcnt(4)
	v_mfma_f32_32x32x16_bf16 v[32:47], v[124:127], v[116:119], v[32:47]
	v_mfma_f32_32x32x16_bf16 v[16:31], v[112:115], v[226:229], v[16:31]
	v_mfma_f32_32x32x16_bf16 v[0:15], v[112:115], v[116:119], v[0:15]
	ds_read_b128 v[112:115], v150 offset:64
	ds_read_b128 v[116:119], v150 offset:4672
	ds_read_b128 v[120:123], v147 offset:36928
	ds_read_b128 v[124:127], v147 offset:41536
	s_waitcnt vmcnt(11)
	ds_write_b128 v146, v[64:67] offset:55296
	s_waitcnt vmcnt(10)
	ds_write_b128 v146, v[68:71] offset:59904
	s_waitcnt vmcnt(9)
	ds_write_b128 v146, v[72:75] offset:64512
	s_waitcnt vmcnt(8)
	ds_write_b128 v149, v[76:79] offset:13824
	ds_read_b128 v[64:67], v150 offset:96
	ds_read_b128 v[68:71], v150 offset:4704
	ds_read_b128 v[72:75], v147 offset:36960
	ds_read_b128 v[76:79], v147 offset:41568
	s_waitcnt lgkmcnt(0)
	s_barrier
	v_mfma_f32_32x32x16_bf16 v[48:63], v[112:115], v[120:123], v[48:63]
	v_mfma_f32_32x32x16_bf16 v[32:47], v[112:115], v[124:127], v[32:47]
	v_mfma_f32_32x32x16_bf16 v[16:31], v[116:119], v[120:123], v[16:31]
	v_mfma_f32_32x32x16_bf16 v[0:15], v[116:119], v[124:127], v[0:15]
	v_mfma_f32_32x32x16_bf16 v[48:63], v[64:67], v[72:75], v[48:63]
	v_mfma_f32_32x32x16_bf16 v[32:47], v[64:67], v[76:79], v[32:47]
	v_mfma_f32_32x32x16_bf16 v[16:31], v[68:71], v[72:75], v[16:31]
	v_mfma_f32_32x32x16_bf16 v[0:15], v[68:71], v[76:79], v[0:15]
	global_load_dwordx4 v[112:115], v160, s[12:13] offset:640
	global_load_dwordx4 v[116:119], v148, s[12:13] offset:640
	global_load_dwordx4 v[120:123], v152, s[12:13] offset:640
	global_load_dwordx4 v[124:127], v154, s[12:13] offset:640
	global_load_dwordx4 v[64:67], v[156:157], off offset:640
	global_load_dwordx4 v[68:71], v[158:159], off offset:640
	global_load_dwordx4 v[72:75], v[164:165], off offset:640
	global_load_dwordx4 v[76:79], v[166:167], off offset:640
	ds_read_b128 v[128:131], v150 offset:23040
	ds_read_b128 v[132:135], v147 offset:59904
	ds_read_b128 v[136:139], v150 offset:18432
	ds_read_b128 v[140:143], v150 offset:18464
	ds_read_b128 v[200:203], v147 offset:55296
	ds_read_b128 v[226:229], v147 offset:55328
	s_waitcnt lgkmcnt(1)
	v_mfma_f32_32x32x16_bf16 v[48:63], v[136:139], v[200:203], v[48:63]
	v_mfma_f32_32x32x16_bf16 v[32:47], v[136:139], v[132:135], v[32:47]
	v_mfma_f32_32x32x16_bf16 v[16:31], v[128:131], v[200:203], v[16:31]
	v_mfma_f32_32x32x16_bf16 v[0:15], v[128:131], v[132:135], v[0:15]
	ds_read_b128 v[128:131], v150 offset:23072
	ds_read_b128 v[132:135], v147 offset:59936
	s_waitcnt vmcnt(15)
	ds_write_b128 v146, v[96:99]
	s_waitcnt vmcnt(14)
	ds_write_b128 v146, v[100:103] offset:4608
	s_waitcnt vmcnt(13)
	ds_write_b128 v146, v[104:107] offset:9216
	s_waitcnt vmcnt(12)
	ds_write_b128 v146, v[108:111] offset:13824
	ds_read_b128 v[96:99], v150 offset:18496
	ds_read_b128 v[100:103], v150 offset:23104
	ds_read_b128 v[104:107], v147 offset:55360
	ds_read_b128 v[108:111], v147 offset:59968
	s_waitcnt vmcnt(11)
	ds_write_b128 v146, v[80:83] offset:36864
	s_waitcnt vmcnt(10)
	ds_write_b128 v146, v[84:87] offset:41472
	s_waitcnt vmcnt(9)
	ds_write_b128 v146, v[88:91] offset:46080
	s_waitcnt vmcnt(8)
	ds_write_b128 v146, v[92:95] offset:50688
	ds_read_b128 v[80:83], v150 offset:18528
	ds_read_b128 v[84:87], v150 offset:23136
	ds_read_b128 v[88:91], v147 offset:55392
	ds_read_b128 v[92:95], v147 offset:60000
	s_waitcnt lgkmcnt(0)
	s_barrier
	v_mfma_f32_32x32x16_bf16 v[48:63], v[140:143], v[226:229], v[48:63]
	v_mfma_f32_32x32x16_bf16 v[32:47], v[140:143], v[132:135], v[32:47]
	v_mfma_f32_32x32x16_bf16 v[16:31], v[128:131], v[226:229], v[16:31]
	v_mfma_f32_32x32x16_bf16 v[0:15], v[128:131], v[132:135], v[0:15]
	v_mfma_f32_32x32x16_bf16 v[48:63], v[96:99], v[104:107], v[48:63]
	v_mfma_f32_32x32x16_bf16 v[32:47], v[96:99], v[108:111], v[32:47]
	v_mfma_f32_32x32x16_bf16 v[16:31], v[100:103], v[104:107], v[16:31]
	v_mfma_f32_32x32x16_bf16 v[0:15], v[100:103], v[108:111], v[0:15]
	v_mfma_f32_32x32x16_bf16 v[48:63], v[80:83], v[88:91], v[48:63]
	v_mfma_f32_32x32x16_bf16 v[32:47], v[80:83], v[92:95], v[32:47]
	v_mfma_f32_32x32x16_bf16 v[16:31], v[84:87], v[88:91], v[16:31]
	v_mfma_f32_32x32x16_bf16 v[0:15], v[84:87], v[92:95], v[0:15]
	global_load_dwordx4 v[96:99], v160, s[12:13] offset:768
	global_load_dwordx4 v[100:103], v148, s[12:13] offset:768
	global_load_dwordx4 v[104:107], v152, s[12:13] offset:768
	global_load_dwordx4 v[108:111], v154, s[12:13] offset:768
	global_load_dwordx4 v[80:83], v[156:157], off offset:768
	global_load_dwordx4 v[84:87], v[158:159], off offset:768
	global_load_dwordx4 v[88:91], v[164:165], off offset:768
	global_load_dwordx4 v[92:95], v[166:167], off offset:768
	ds_read_b128 v[128:131], v150 offset:4608
	ds_read_b128 v[132:135], v147 offset:41472
	ds_read_b128 v[136:139], v150
	ds_read_b128 v[140:143], v150 offset:32
	ds_read_b128 v[200:203], v147 offset:36864
	ds_read_b128 v[226:229], v147 offset:36896
	s_waitcnt lgkmcnt(1)
	v_mfma_f32_32x32x16_bf16 v[48:63], v[136:139], v[200:203], v[48:63]
	v_mfma_f32_32x32x16_bf16 v[32:47], v[136:139], v[132:135], v[32:47]
	v_mfma_f32_32x32x16_bf16 v[16:31], v[128:131], v[200:203], v[16:31]
	v_mfma_f32_32x32x16_bf16 v[0:15], v[128:131], v[132:135], v[0:15]
	ds_read_b128 v[128:131], v150 offset:4640
	ds_read_b128 v[132:135], v147 offset:41504
	s_waitcnt vmcnt(15)
	ds_write_b128 v146, v[112:115] offset:18432
	s_waitcnt vmcnt(14)
	ds_write_b128 v146, v[116:119] offset:23040
	s_waitcnt vmcnt(13)
	ds_write_b128 v146, v[120:123] offset:27648
	s_waitcnt vmcnt(12)
	ds_write_b128 v146, v[124:127] offset:32256
	ds_read_b128 v[112:115], v150 offset:64
	ds_read_b128 v[116:119], v150 offset:4672
	ds_read_b128 v[120:123], v147 offset:36928
	ds_read_b128 v[124:127], v147 offset:41536
	s_waitcnt vmcnt(11)
	ds_write_b128 v146, v[64:67] offset:55296
	s_waitcnt vmcnt(10)
	ds_write_b128 v146, v[68:71] offset:59904
	s_waitcnt vmcnt(9)
	ds_write_b128 v146, v[72:75] offset:64512
	s_waitcnt vmcnt(8)
	ds_write_b128 v149, v[76:79] offset:13824
	ds_read_b128 v[64:67], v150 offset:96
	ds_read_b128 v[68:71], v150 offset:4704
	ds_read_b128 v[72:75], v147 offset:36960
	ds_read_b128 v[76:79], v147 offset:41568
	s_waitcnt lgkmcnt(0)
	s_barrier
	v_mfma_f32_32x32x16_bf16 v[48:63], v[140:143], v[226:229], v[48:63]
	v_mfma_f32_32x32x16_bf16 v[32:47], v[140:143], v[132:135], v[32:47]
	v_mfma_f32_32x32x16_bf16 v[16:31], v[128:131], v[226:229], v[16:31]
	v_mfma_f32_32x32x16_bf16 v[0:15], v[128:131], v[132:135], v[0:15]
	v_mfma_f32_32x32x16_bf16 v[48:63], v[112:115], v[120:123], v[48:63]
	v_mfma_f32_32x32x16_bf16 v[32:47], v[112:115], v[124:127], v[32:47]
	v_mfma_f32_32x32x16_bf16 v[16:31], v[116:119], v[120:123], v[16:31]
	v_mfma_f32_32x32x16_bf16 v[0:15], v[116:119], v[124:127], v[0:15]
	v_mfma_f32_32x32x16_bf16 v[48:63], v[64:67], v[72:75], v[48:63]
	v_mfma_f32_32x32x16_bf16 v[32:47], v[64:67], v[76:79], v[32:47]
	v_mfma_f32_32x32x16_bf16 v[16:31], v[68:71], v[72:75], v[16:31]
	v_mfma_f32_32x32x16_bf16 v[0:15], v[68:71], v[76:79], v[0:15]
	global_load_dwordx4 v[112:115], v160, s[12:13] offset:896
	global_load_dwordx4 v[116:119], v148, s[12:13] offset:896
	global_load_dwordx4 v[120:123], v152, s[12:13] offset:896
	global_load_dwordx4 v[124:127], v154, s[12:13] offset:896
	global_load_dwordx4 v[64:67], v[156:157], off offset:896
	global_load_dwordx4 v[68:71], v[158:159], off offset:896
	global_load_dwordx4 v[72:75], v[164:165], off offset:896
	global_load_dwordx4 v[76:79], v[166:167], off offset:896
	ds_read_b128 v[128:131], v150 offset:23040
	ds_read_b128 v[132:135], v147 offset:59904
	ds_read_b128 v[136:139], v150 offset:18432
	ds_read_b128 v[140:143], v150 offset:18464
	ds_read_b128 v[152:155], v147 offset:55296
	ds_read_b128 v[156:159], v147 offset:55328
	s_add_u32 s12, s0, s14
	s_addc_u32 s13, s1, s15
	s_add_i32 s5, s5, 1
	s_add_u32 s8, s8, 0x100000
	s_addc_u32 s9, s9, 0
	s_waitcnt lgkmcnt(1)
	v_mfma_f32_32x32x16_bf16 v[48:63], v[136:139], v[152:155], v[48:63]
	s_add_u32 s14, s14, 0x200000
	s_addc_u32 s15, s15, 0
	s_cmp_eq_u32 s5, 3
	v_mfma_f32_32x32x16_bf16 v[0:15], v[128:131], v[132:135], v[0:15]
	v_mfma_f32_32x32x16_bf16 v[16:31], v[128:131], v[152:155], v[16:31]
	v_mov_b32_e32 v153, v161
	v_mfma_f32_32x32x16_bf16 v[32:47], v[136:139], v[132:135], v[32:47]
	ds_read_b128 v[128:131], v150 offset:23072
	ds_read_b128 v[132:135], v147 offset:59936
	s_waitcnt vmcnt(15)
	ds_write_b128 v146, v[96:99]
	s_waitcnt vmcnt(14)
	ds_write_b128 v146, v[100:103] offset:4608
	s_waitcnt vmcnt(13)
	ds_write_b128 v146, v[104:107] offset:9216
	s_waitcnt vmcnt(12)
	ds_write_b128 v146, v[108:111] offset:13824
	ds_read_b128 v[96:99], v150 offset:18496
	ds_read_b128 v[100:103], v150 offset:23104
	ds_read_b128 v[104:107], v147 offset:55360
	ds_read_b128 v[108:111], v147 offset:59968
	s_waitcnt vmcnt(11)
	ds_write_b128 v146, v[80:83] offset:36864
	s_waitcnt vmcnt(10)
	ds_write_b128 v146, v[84:87] offset:41472
	s_waitcnt vmcnt(9)
	ds_write_b128 v146, v[88:91] offset:46080
	s_waitcnt vmcnt(8)
	ds_write_b128 v146, v[92:95] offset:50688
	ds_read_b128 v[80:83], v150 offset:18528
	ds_read_b128 v[84:87], v150 offset:23136
	ds_read_b128 v[88:91], v147 offset:55392
	ds_read_b128 v[92:95], v147 offset:60000
	s_waitcnt lgkmcnt(0)
	s_barrier
	v_mfma_f32_32x32x16_bf16 v[48:63], v[140:143], v[156:159], v[48:63]
	v_mfma_f32_32x32x16_bf16 v[0:15], v[128:131], v[132:135], v[0:15]
	v_mfma_f32_32x32x16_bf16 v[16:31], v[128:131], v[156:159], v[16:31]
	v_mfma_f32_32x32x16_bf16 v[32:47], v[140:143], v[132:135], v[32:47]
	v_mfma_f32_32x32x16_bf16 v[48:63], v[96:99], v[104:107], v[48:63]
	v_mfma_f32_32x32x16_bf16 v[0:15], v[100:103], v[108:111], v[0:15]
	v_mfma_f32_32x32x16_bf16 v[16:31], v[100:103], v[104:107], v[16:31]
	v_mfma_f32_32x32x16_bf16 v[32:47], v[96:99], v[108:111], v[32:47]
	v_mfma_f32_32x32x16_bf16 v[48:63], v[80:83], v[88:91], v[48:63]
	v_mfma_f32_32x32x16_bf16 v[0:15], v[84:87], v[92:95], v[0:15]
	v_mfma_f32_32x32x16_bf16 v[16:31], v[84:87], v[88:91], v[16:31]
	v_mfma_f32_32x32x16_bf16 v[32:47], v[80:83], v[92:95], v[32:47]
	ds_read_b128 v[80:83], v150 offset:4608
	ds_read_b128 v[84:87], v147 offset:41472
	ds_read_b128 v[88:91], v150
	ds_read_b128 v[92:95], v150 offset:32
	ds_read_b128 v[96:99], v147 offset:36864
	ds_read_b128 v[100:103], v147 offset:36896
	s_waitcnt lgkmcnt(1)
	v_mfma_f32_32x32x16_bf16 v[48:63], v[88:91], v[96:99], v[48:63]
	v_mfma_f32_32x32x16_bf16 v[0:15], v[80:83], v[84:87], v[0:15]
	v_mfma_f32_32x32x16_bf16 v[16:31], v[80:83], v[96:99], v[16:31]
	v_mfma_f32_32x32x16_bf16 v[32:47], v[88:91], v[84:87], v[32:47]
	ds_read_b128 v[80:83], v150 offset:4640
	ds_read_b128 v[84:87], v147 offset:41504
	s_waitcnt vmcnt(7)
	ds_write_b128 v146, v[112:115] offset:18432
	s_waitcnt vmcnt(6)
	ds_write_b128 v146, v[116:119] offset:23040
	s_waitcnt vmcnt(5)
	ds_write_b128 v146, v[120:123] offset:27648
	s_waitcnt vmcnt(4)
	ds_write_b128 v146, v[124:127] offset:32256
	s_waitcnt lgkmcnt(6)
	v_mfma_f32_32x32x16_bf16 v[48:63], v[92:95], v[100:103], v[48:63]
	s_waitcnt lgkmcnt(4)
	v_mfma_f32_32x32x16_bf16 v[0:15], v[80:83], v[84:87], v[0:15]
	v_mfma_f32_32x32x16_bf16 v[16:31], v[80:83], v[100:103], v[16:31]
	v_mfma_f32_32x32x16_bf16 v[32:47], v[92:95], v[84:87], v[32:47]
	ds_read_b128 v[80:83], v150 offset:64
	ds_read_b128 v[84:87], v150 offset:4672
	ds_read_b128 v[88:91], v147 offset:36928
	ds_read_b128 v[92:95], v147 offset:41536
	s_waitcnt vmcnt(3)
	ds_write_b128 v146, v[64:67] offset:55296
	s_waitcnt vmcnt(2)
	ds_write_b128 v146, v[68:71] offset:59904
	s_waitcnt vmcnt(1)
	ds_write_b128 v146, v[72:75] offset:64512
	s_waitcnt vmcnt(0)
	ds_write_b128 v149, v[76:79] offset:13824
	ds_read_b128 v[64:67], v150 offset:96
	ds_read_b128 v[68:71], v150 offset:4704
	ds_read_b128 v[72:75], v147 offset:36960
	ds_read_b128 v[76:79], v147 offset:41568
	s_waitcnt lgkmcnt(0)
	s_barrier
	v_mov_b32_e32 v149, v161
	v_mfma_f32_32x32x16_bf16 v[48:63], v[80:83], v[88:91], v[48:63]
	v_mfma_f32_32x32x16_bf16 v[0:15], v[84:87], v[92:95], v[0:15]
	v_mfma_f32_32x32x16_bf16 v[16:31], v[84:87], v[88:91], v[16:31]
	v_mfma_f32_32x32x16_bf16 v[32:47], v[80:83], v[92:95], v[32:47]
	v_mfma_f32_32x32x16_bf16 v[48:63], v[64:67], v[72:75], v[48:63]
	v_mfma_f32_32x32x16_bf16 v[0:15], v[68:71], v[76:79], v[0:15]
	v_mfma_f32_32x32x16_bf16 v[16:31], v[68:71], v[72:75], v[16:31]
	v_mfma_f32_32x32x16_bf16 v[32:47], v[64:67], v[76:79], v[32:47]
	ds_read_b128 v[64:67], v150 offset:23040
	ds_read_b128 v[68:71], v147 offset:59904
	ds_read_b128 v[72:75], v150 offset:18432
	ds_read_b128 v[76:79], v150 offset:18464
	ds_read_b128 v[80:83], v147 offset:55296
	ds_read_b128 v[84:87], v147 offset:55328
	s_waitcnt lgkmcnt(1)
	v_mfma_f32_32x32x16_bf16 v[48:63], v[72:75], v[80:83], v[48:63]
	v_mfma_f32_32x32x16_bf16 v[0:15], v[64:67], v[68:71], v[0:15]
	v_mfma_f32_32x32x16_bf16 v[16:31], v[64:67], v[80:83], v[16:31]
	v_mfma_f32_32x32x16_bf16 v[32:47], v[72:75], v[68:71], v[32:47]
	ds_read_b128 v[64:67], v150 offset:23072
	ds_read_b128 v[68:71], v147 offset:59936
	s_waitcnt lgkmcnt(2)
	v_mfma_f32_32x32x16_bf16 v[48:63], v[76:79], v[84:87], v[48:63]
	s_waitcnt lgkmcnt(0)
	v_mfma_f32_32x32x16_bf16 v[0:15], v[64:67], v[68:71], v[0:15]
	v_mfma_f32_32x32x16_bf16 v[16:31], v[64:67], v[84:87], v[16:31]
	v_mfma_f32_32x32x16_bf16 v[32:47], v[76:79], v[68:71], v[32:47]
	ds_read_b128 v[64:67], v147 offset:59968
	ds_read_b128 v[68:71], v147 offset:55360
	ds_read_b128 v[72:75], v150 offset:23104
	ds_read_b128 v[76:79], v150 offset:18496
	s_waitcnt lgkmcnt(0)
	v_mfma_f32_32x32x16_bf16 v[48:63], v[76:79], v[68:71], v[48:63]
	v_mfma_f32_32x32x16_bf16 v[0:15], v[72:75], v[64:67], v[0:15]
	v_mfma_f32_32x32x16_bf16 v[16:31], v[72:75], v[68:71], v[16:31]
	v_mfma_f32_32x32x16_bf16 v[32:47], v[76:79], v[64:67], v[32:47]
	ds_read_b128 v[64:67], v147 offset:60000
	ds_read_b128 v[68:71], v147 offset:55392
	ds_read_b128 v[72:75], v150 offset:23136
	ds_read_b128 v[76:79], v150 offset:18528
	s_waitcnt lgkmcnt(0)
	s_barrier
	v_mfma_f32_32x32x16_bf16 v[48:63], v[76:79], v[68:71], v[48:63]
	v_mfma_f32_32x32x16_bf16 v[0:15], v[72:75], v[64:67], v[0:15]
	s_nop 10
	v_cvt_pk_bf16_f32 v200, v48, v49
	v_mov_b32_e32 v49, v186
	v_cvt_pk_bf16_f32 v189, v50, v51
	v_cvt_pk_bf16_f32 v188, v52, v53
	v_cvt_pk_bf16_f32 v208, v54, v55
	v_cvt_pk_bf16_f32 v195, v56, v57
	v_cvt_pk_bf16_f32 v192, v58, v59
	v_mfma_f32_32x32x16_bf16 v[16:31], v[72:75], v[68:71], v[16:31]
	v_cvt_pk_bf16_f32 v232, v0, v1
	v_mov_b32_e32 v0, v161
	s_nop 0
	v_ashrrev_i32_e32 v50, 3, v49
	s_barrier
	v_mfma_f32_32x32x16_bf16 v[32:47], v[76:79], v[64:67], v[32:47]
	s_nop 5
	v_cvt_pk_bf16_f32 v240, v16, v17
	v_lshlrev_b32_e32 v16, 4, v49
	v_and_b32_e32 v48, 0x70, v16
	v_lshl_or_b32 v160, v50, 11, v48
	v_cvt_pk_bf16_f32 v239, v18, v19
	global_load_dwordx4 v[16:19], v160, s[10:11]
	v_cvt_pk_bf16_f32 v248, v32, v33
	v_lshl_add_u64 v[32:33], s[12:13], 0, v[160:161]
	v_add_u32_e32 v148, 0x10000, v160
	v_add_co_u32_e32 v154, vcc, s95, v32
	v_cvt_pk_bf16_f32 v246, v36, v37
	v_cvt_pk_bf16_f32 v238, v20, v21
	v_cvt_pk_bf16_f32 v237, v22, v23
	global_load_dwordx4 v[20:23], v148, s[10:11]
	v_add_u32_e32 v150, 0x20000, v160
	v_addc_co_u32_e32 v155, vcc, 0, v33, vcc
	v_lshl_add_u64 v[36:37], s[12:13], 0, v[148:149]
	v_cvt_pk_bf16_f32 v236, v24, v25
	v_cvt_pk_bf16_f32 v235, v26, v27
	global_load_dwordx4 v[24:27], v150, s[10:11]
	v_add_u32_e32 v152, 0x30000, v160
	v_add_co_u32_e32 v156, vcc, s95, v36
	v_cvt_pk_bf16_f32 v244, v40, v41
	v_cvt_pk_bf16_f32 v234, v28, v29
	v_cvt_pk_bf16_f32 v233, v30, v31
	global_load_dwordx4 v[28:31], v152, s[10:11]
	v_addc_co_u32_e32 v157, vcc, 0, v37, vcc
	v_lshl_add_u64 v[40:41], s[12:13], 0, v[150:151]
	v_cvt_pk_bf16_f32 v247, v34, v35
	global_load_dwordx4 v[32:35], v[154:155], off
	v_add_co_u32_e32 v158, vcc, s95, v40
	v_cvt_pk_bf16_f32 v245, v38, v39
	v_cvt_pk_bf16_f32 v242, v44, v45
	global_load_dwordx4 v[36:39], v[156:157], off
	v_addc_co_u32_e32 v159, vcc, 0, v41, vcc
	v_lshl_add_u64 v[44:45], s[12:13], 0, v[152:153]
	v_cvt_pk_bf16_f32 v243, v42, v43
	global_load_dwordx4 v[40:43], v[158:159], off
	v_add_co_u32_e32 v164, vcc, s95, v44
	v_cvt_pk_bf16_f32 v241, v46, v47
	s_nop 0
	v_addc_co_u32_e32 v165, vcc, 0, v45, vcc
	global_load_dwordx4 v[44:47], v[164:165], off
	global_load_dwordx4 v[80:83], v160, s[10:11] offset:128
	global_load_dwordx4 v[84:87], v148, s[10:11] offset:128
	global_load_dwordx4 v[88:91], v150, s[10:11] offset:128
	global_load_dwordx4 v[92:95], v152, s[10:11] offset:128
	global_load_dwordx4 v[64:67], v[154:155], off offset:128
	global_load_dwordx4 v[68:71], v[156:157], off offset:128
	global_load_dwordx4 v[72:75], v[158:159], off offset:128
	global_load_dwordx4 v[76:79], v[164:165], off offset:128
	v_mad_u64_u32 v[146:147], s[12:13], v50, s43, v[48:49]
	s_waitcnt vmcnt(15)
	ds_write_b128 v146, v[16:19]
	s_waitcnt vmcnt(14)
	ds_write_b128 v146, v[20:23] offset:4608
	s_waitcnt vmcnt(13)
	ds_write_b128 v146, v[24:27] offset:9216
	s_waitcnt vmcnt(12)
	ds_write_b128 v146, v[28:31] offset:13824
	s_waitcnt vmcnt(11)
	ds_write_b128 v146, v[32:35] offset:36864
	s_waitcnt vmcnt(10)
	ds_write_b128 v146, v[36:39] offset:41472
	s_waitcnt vmcnt(9)
	ds_write_b128 v146, v[40:43] offset:46080
	s_waitcnt vmcnt(8)
	ds_write_b128 v146, v[44:47] offset:50688
	v_lshrrev_b32_e32 v18, 1, v49
	s_waitcnt lgkmcnt(0)
	s_barrier
	v_and_b32_e32 v17, 0x5f, v49
	v_and_b32_e32 v16, 16, v18
	global_load_dwordx4 v[112:115], v160, s[10:11] offset:256
	global_load_dwordx4 v[116:119], v148, s[10:11] offset:256
	global_load_dwordx4 v[120:123], v150, s[10:11] offset:256
	global_load_dwordx4 v[124:127], v152, s[10:11] offset:256
	global_load_dwordx4 v[96:99], v[154:155], off offset:256
	global_load_dwordx4 v[100:103], v[156:157], off offset:256
	global_load_dwordx4 v[104:107], v[158:159], off offset:256
	global_load_dwordx4 v[108:111], v[164:165], off offset:256
	v_mad_u32_u24 v147, v17, s43, v16
	v_and_b32_e32 v17, 31, v49
	v_and_or_b32 v17, v18, s44, v17
	v_mad_u64_u32 v[166:167], s[12:13], v17, s43, v[16:17]
	ds_read_b128 v[128:131], v166 offset:4608
	ds_read_b128 v[132:135], v147 offset:41472
	ds_read_b128 v[16:19], v166
	ds_read_b128 v[136:139], v166 offset:32
	ds_read_b128 v[140:143], v147 offset:36864
	ds_read_b128 v[202:205], v147 offset:36896
	v_cvt_pk_bf16_f32 v231, v2, v3
	v_cvt_pk_bf16_f32 v230, v4, v5
	v_cvt_pk_bf16_f32 v229, v6, v7
	v_cvt_pk_bf16_f32 v228, v8, v9
	v_cvt_pk_bf16_f32 v227, v10, v11
	v_cvt_pk_bf16_f32 v226, v12, v13
	v_cvt_pk_bf16_f32 v225, v14, v15
	v_mov_b32_e32 v1, v0
	v_mov_b32_e32 v2, v0
	v_mov_b32_e32 v3, v0
	v_mov_b32_e32 v4, v0
	v_mov_b32_e32 v5, v0
	v_mov_b32_e32 v6, v0
	v_mov_b32_e32 v7, v0
	v_mov_b32_e32 v8, v0
	v_mov_b32_e32 v9, v0
	v_mov_b32_e32 v10, v0
	v_mov_b32_e32 v11, v0
	v_mov_b32_e32 v12, v0
	v_mov_b32_e32 v13, v0
	v_mov_b32_e32 v14, v0
	v_mov_b32_e32 v15, v0
	v_cvt_pk_bf16_f32 v250, v60, v61
	v_cvt_pk_bf16_f32 v249, v62, v63
	s_waitcnt lgkmcnt(1)
	v_mfma_f32_32x32x16_bf16 v[48:63], v[16:19], v[140:143], v[0:15]
	v_add_u32_e32 v149, 0xd800, v146
	v_mfma_f32_32x32x16_bf16 v[32:47], v[16:19], v[132:135], v[0:15]
	v_mfma_f32_32x32x16_bf16 v[16:31], v[128:131], v[140:143], v[0:15]
	v_mfma_f32_32x32x16_bf16 v[0:15], v[128:131], v[132:135], v[0:15]
	ds_read_b128 v[128:131], v166 offset:4640
	ds_read_b128 v[132:135], v147 offset:41504
	s_waitcnt vmcnt(15)
	ds_write_b128 v146, v[80:83] offset:18432
	s_waitcnt vmcnt(14)
	ds_write_b128 v146, v[84:87] offset:23040
	s_waitcnt vmcnt(13)
	ds_write_b128 v146, v[88:91] offset:27648
	s_waitcnt vmcnt(12)
	ds_write_b128 v146, v[92:95] offset:32256
	ds_read_b128 v[80:83], v166 offset:64
	ds_read_b128 v[84:87], v166 offset:4672
	ds_read_b128 v[88:91], v147 offset:36928
	ds_read_b128 v[92:95], v147 offset:41536
	s_waitcnt vmcnt(11)
	ds_write_b128 v146, v[64:67] offset:55296
	s_waitcnt vmcnt(10)
	ds_write_b128 v146, v[68:71] offset:59904
	s_waitcnt vmcnt(9)
	ds_write_b128 v146, v[72:75] offset:64512
	s_waitcnt vmcnt(8)
	ds_write_b128 v149, v[76:79] offset:13824
	ds_read_b128 v[64:67], v166 offset:96
	ds_read_b128 v[68:71], v166 offset:4704
	ds_read_b128 v[72:75], v147 offset:36960
	ds_read_b128 v[76:79], v147 offset:41568
	s_waitcnt lgkmcnt(0)
	s_barrier
	v_mfma_f32_32x32x16_bf16 v[48:63], v[136:139], v[202:205], v[48:63]
	v_mfma_f32_32x32x16_bf16 v[32:47], v[136:139], v[132:135], v[32:47]
	v_mfma_f32_32x32x16_bf16 v[16:31], v[128:131], v[202:205], v[16:31]
	v_mfma_f32_32x32x16_bf16 v[0:15], v[128:131], v[132:135], v[0:15]
	v_mfma_f32_32x32x16_bf16 v[48:63], v[80:83], v[88:91], v[48:63]
	v_mfma_f32_32x32x16_bf16 v[32:47], v[80:83], v[92:95], v[32:47]
	v_mfma_f32_32x32x16_bf16 v[16:31], v[84:87], v[88:91], v[16:31]
	v_mfma_f32_32x32x16_bf16 v[0:15], v[84:87], v[92:95], v[0:15]
	v_mfma_f32_32x32x16_bf16 v[48:63], v[64:67], v[72:75], v[48:63]
	v_mfma_f32_32x32x16_bf16 v[32:47], v[64:67], v[76:79], v[32:47]
	v_mfma_f32_32x32x16_bf16 v[16:31], v[68:71], v[72:75], v[16:31]
	v_mfma_f32_32x32x16_bf16 v[0:15], v[68:71], v[76:79], v[0:15]
	global_load_dwordx4 v[128:131], v160, s[10:11] offset:384
	global_load_dwordx4 v[132:135], v148, s[10:11] offset:384
	global_load_dwordx4 v[136:139], v150, s[10:11] offset:384
	global_load_dwordx4 v[140:143], v152, s[10:11] offset:384
	global_load_dwordx4 v[64:67], v[154:155], off offset:384
	global_load_dwordx4 v[68:71], v[156:157], off offset:384
	global_load_dwordx4 v[72:75], v[158:159], off offset:384
	global_load_dwordx4 v[76:79], v[164:165], off offset:384
	ds_read_b128 v[80:83], v166 offset:23040
	ds_read_b128 v[84:87], v147 offset:59904
	ds_read_b128 v[88:91], v166 offset:18432
	ds_read_b128 v[92:95], v166 offset:18464
	ds_read_b128 v[202:205], v147 offset:55296
	ds_read_b128 v[196:199], v147 offset:55328
	s_waitcnt lgkmcnt(1)
	v_mfma_f32_32x32x16_bf16 v[48:63], v[88:91], v[202:205], v[48:63]
	v_mfma_f32_32x32x16_bf16 v[32:47], v[88:91], v[84:87], v[32:47]
	v_mfma_f32_32x32x16_bf16 v[16:31], v[80:83], v[202:205], v[16:31]
	v_mfma_f32_32x32x16_bf16 v[0:15], v[80:83], v[84:87], v[0:15]
	ds_read_b128 v[80:83], v166 offset:23072
	ds_read_b128 v[84:87], v147 offset:59936
	s_waitcnt vmcnt(15)
	ds_write_b128 v146, v[112:115]
	s_waitcnt vmcnt(14)
	ds_write_b128 v146, v[116:119] offset:4608
	s_waitcnt vmcnt(13)
	ds_write_b128 v146, v[120:123] offset:9216
	s_waitcnt vmcnt(12)
	ds_write_b128 v146, v[124:127] offset:13824
	s_waitcnt lgkmcnt(6)
	v_mfma_f32_32x32x16_bf16 v[48:63], v[92:95], v[196:199], v[48:63]
	s_waitcnt lgkmcnt(4)
	v_mfma_f32_32x32x16_bf16 v[32:47], v[92:95], v[84:87], v[32:47]
	v_mfma_f32_32x32x16_bf16 v[16:31], v[80:83], v[196:199], v[16:31]
	v_mfma_f32_32x32x16_bf16 v[0:15], v[80:83], v[84:87], v[0:15]
	ds_read_b128 v[80:83], v166 offset:18496
	ds_read_b128 v[84:87], v166 offset:23104
	ds_read_b128 v[88:91], v147 offset:55360
	ds_read_b128 v[92:95], v147 offset:59968
	s_waitcnt vmcnt(11)
	ds_write_b128 v146, v[96:99] offset:36864
	s_waitcnt vmcnt(10)
	ds_write_b128 v146, v[100:103] offset:41472
	s_waitcnt vmcnt(9)
	ds_write_b128 v146, v[104:107] offset:46080
	s_waitcnt vmcnt(8)
	ds_write_b128 v146, v[108:111] offset:50688
	s_waitcnt lgkmcnt(5)
	v_mfma_f32_32x32x16_bf16 v[48:63], v[80:83], v[88:91], v[48:63]
	s_waitcnt lgkmcnt(4)
	v_mfma_f32_32x32x16_bf16 v[32:47], v[80:83], v[92:95], v[32:47]
	v_mfma_f32_32x32x16_bf16 v[16:31], v[84:87], v[88:91], v[16:31]
	v_mfma_f32_32x32x16_bf16 v[0:15], v[84:87], v[92:95], v[0:15]
	ds_read_b128 v[80:83], v166 offset:18528
	ds_read_b128 v[84:87], v166 offset:23136
	ds_read_b128 v[88:91], v147 offset:55392
	ds_read_b128 v[92:95], v147 offset:60000
	s_waitcnt lgkmcnt(0)
	s_barrier
	v_mfma_f32_32x32x16_bf16 v[48:63], v[80:83], v[88:91], v[48:63]
	v_mfma_f32_32x32x16_bf16 v[32:47], v[80:83], v[92:95], v[32:47]
	v_mfma_f32_32x32x16_bf16 v[16:31], v[84:87], v[88:91], v[16:31]
	v_mfma_f32_32x32x16_bf16 v[0:15], v[84:87], v[92:95], v[0:15]
	global_load_dwordx4 v[96:99], v160, s[10:11] offset:512
	global_load_dwordx4 v[100:103], v148, s[10:11] offset:512
	global_load_dwordx4 v[104:107], v150, s[10:11] offset:512
	global_load_dwordx4 v[108:111], v152, s[10:11] offset:512
	global_load_dwordx4 v[80:83], v[154:155], off offset:512
	global_load_dwordx4 v[84:87], v[156:157], off offset:512
	global_load_dwordx4 v[88:91], v[158:159], off offset:512
	global_load_dwordx4 v[92:95], v[164:165], off offset:512
	ds_read_b128 v[112:115], v166 offset:4608
	ds_read_b128 v[116:119], v147 offset:41472
	ds_read_b128 v[120:123], v166
	ds_read_b128 v[124:127], v166 offset:32
	ds_read_b128 v[196:199], v147 offset:36864
	ds_read_b128 v[202:205], v147 offset:36896
	s_waitcnt lgkmcnt(1)
	v_mfma_f32_32x32x16_bf16 v[48:63], v[120:123], v[196:199], v[48:63]
	v_mfma_f32_32x32x16_bf16 v[32:47], v[120:123], v[116:119], v[32:47]
	v_mfma_f32_32x32x16_bf16 v[16:31], v[112:115], v[196:199], v[16:31]
	v_mfma_f32_32x32x16_bf16 v[0:15], v[112:115], v[116:119], v[0:15]
	ds_read_b128 v[112:115], v166 offset:4640
	ds_read_b128 v[116:119], v147 offset:41504
	s_waitcnt vmcnt(15)
	ds_write_b128 v146, v[128:131] offset:18432
	s_waitcnt vmcnt(14)
	ds_write_b128 v146, v[132:135] offset:23040
	s_waitcnt vmcnt(13)
	ds_write_b128 v146, v[136:139] offset:27648
	s_waitcnt vmcnt(12)
	ds_write_b128 v146, v[140:143] offset:32256
	s_waitcnt lgkmcnt(6)
	v_mfma_f32_32x32x16_bf16 v[48:63], v[124:127], v[202:205], v[48:63]
	s_waitcnt lgkmcnt(4)
	v_mfma_f32_32x32x16_bf16 v[32:47], v[124:127], v[116:119], v[32:47]
	v_mfma_f32_32x32x16_bf16 v[16:31], v[112:115], v[202:205], v[16:31]
	v_mfma_f32_32x32x16_bf16 v[0:15], v[112:115], v[116:119], v[0:15]
	ds_read_b128 v[112:115], v166 offset:64
	ds_read_b128 v[116:119], v166 offset:4672
	ds_read_b128 v[120:123], v147 offset:36928
	ds_read_b128 v[124:127], v147 offset:41536
	s_waitcnt vmcnt(11)
	ds_write_b128 v146, v[64:67] offset:55296
	s_waitcnt vmcnt(10)
	ds_write_b128 v146, v[68:71] offset:59904
	s_waitcnt vmcnt(9)
	ds_write_b128 v146, v[72:75] offset:64512
	s_waitcnt vmcnt(8)
	ds_write_b128 v149, v[76:79] offset:13824
	ds_read_b128 v[64:67], v166 offset:96
	ds_read_b128 v[68:71], v166 offset:4704
	ds_read_b128 v[72:75], v147 offset:36960
	ds_read_b128 v[76:79], v147 offset:41568
	s_waitcnt lgkmcnt(0)
	s_barrier
	v_mfma_f32_32x32x16_bf16 v[48:63], v[112:115], v[120:123], v[48:63]
	v_mfma_f32_32x32x16_bf16 v[32:47], v[112:115], v[124:127], v[32:47]
	v_mfma_f32_32x32x16_bf16 v[16:31], v[116:119], v[120:123], v[16:31]
	v_mfma_f32_32x32x16_bf16 v[0:15], v[116:119], v[124:127], v[0:15]
	v_mfma_f32_32x32x16_bf16 v[48:63], v[64:67], v[72:75], v[48:63]
	v_mfma_f32_32x32x16_bf16 v[32:47], v[64:67], v[76:79], v[32:47]
	v_mfma_f32_32x32x16_bf16 v[16:31], v[68:71], v[72:75], v[16:31]
	v_mfma_f32_32x32x16_bf16 v[0:15], v[68:71], v[76:79], v[0:15]
	global_load_dwordx4 v[112:115], v160, s[10:11] offset:640
	global_load_dwordx4 v[116:119], v148, s[10:11] offset:640
	global_load_dwordx4 v[120:123], v150, s[10:11] offset:640
	global_load_dwordx4 v[124:127], v152, s[10:11] offset:640
	global_load_dwordx4 v[64:67], v[154:155], off offset:640
	global_load_dwordx4 v[68:71], v[156:157], off offset:640
	global_load_dwordx4 v[72:75], v[158:159], off offset:640
	global_load_dwordx4 v[76:79], v[164:165], off offset:640
	ds_read_b128 v[128:131], v166 offset:23040
	ds_read_b128 v[132:135], v147 offset:59904
	ds_read_b128 v[136:139], v166 offset:18432
	ds_read_b128 v[140:143], v166 offset:18464
	ds_read_b128 v[196:199], v147 offset:55296
	ds_read_b128 v[202:205], v147 offset:55328
	s_waitcnt lgkmcnt(1)
	v_mfma_f32_32x32x16_bf16 v[48:63], v[136:139], v[196:199], v[48:63]
	v_mfma_f32_32x32x16_bf16 v[32:47], v[136:139], v[132:135], v[32:47]
	v_mfma_f32_32x32x16_bf16 v[16:31], v[128:131], v[196:199], v[16:31]
	v_mfma_f32_32x32x16_bf16 v[0:15], v[128:131], v[132:135], v[0:15]
	ds_read_b128 v[128:131], v166 offset:23072
	ds_read_b128 v[132:135], v147 offset:59936
	s_waitcnt vmcnt(15)
	ds_write_b128 v146, v[96:99]
	s_waitcnt vmcnt(14)
	ds_write_b128 v146, v[100:103] offset:4608
	s_waitcnt vmcnt(13)
	ds_write_b128 v146, v[104:107] offset:9216
	s_waitcnt vmcnt(12)
	ds_write_b128 v146, v[108:111] offset:13824
	ds_read_b128 v[96:99], v166 offset:18496
	ds_read_b128 v[100:103], v166 offset:23104
	ds_read_b128 v[104:107], v147 offset:55360
	ds_read_b128 v[108:111], v147 offset:59968
	s_waitcnt vmcnt(11)
	ds_write_b128 v146, v[80:83] offset:36864
	s_waitcnt vmcnt(10)
	ds_write_b128 v146, v[84:87] offset:41472
	s_waitcnt vmcnt(9)
	ds_write_b128 v146, v[88:91] offset:46080
	s_waitcnt vmcnt(8)
	ds_write_b128 v146, v[92:95] offset:50688
	ds_read_b128 v[80:83], v166 offset:18528
	ds_read_b128 v[84:87], v166 offset:23136
	ds_read_b128 v[88:91], v147 offset:55392
	ds_read_b128 v[92:95], v147 offset:60000
	s_waitcnt lgkmcnt(0)
	s_barrier
	v_mfma_f32_32x32x16_bf16 v[48:63], v[140:143], v[202:205], v[48:63]
	v_mfma_f32_32x32x16_bf16 v[32:47], v[140:143], v[132:135], v[32:47]
	v_mfma_f32_32x32x16_bf16 v[16:31], v[128:131], v[202:205], v[16:31]
	v_mfma_f32_32x32x16_bf16 v[0:15], v[128:131], v[132:135], v[0:15]
	v_mfma_f32_32x32x16_bf16 v[48:63], v[96:99], v[104:107], v[48:63]
	v_mfma_f32_32x32x16_bf16 v[32:47], v[96:99], v[108:111], v[32:47]
	v_mfma_f32_32x32x16_bf16 v[16:31], v[100:103], v[104:107], v[16:31]
	v_mfma_f32_32x32x16_bf16 v[0:15], v[100:103], v[108:111], v[0:15]
	v_mfma_f32_32x32x16_bf16 v[48:63], v[80:83], v[88:91], v[48:63]
	v_mfma_f32_32x32x16_bf16 v[32:47], v[80:83], v[92:95], v[32:47]
	v_mfma_f32_32x32x16_bf16 v[16:31], v[84:87], v[88:91], v[16:31]
	v_mfma_f32_32x32x16_bf16 v[0:15], v[84:87], v[92:95], v[0:15]
	global_load_dwordx4 v[96:99], v160, s[10:11] offset:768
	global_load_dwordx4 v[100:103], v148, s[10:11] offset:768
	global_load_dwordx4 v[104:107], v150, s[10:11] offset:768
	global_load_dwordx4 v[108:111], v152, s[10:11] offset:768
	global_load_dwordx4 v[80:83], v[154:155], off offset:768
	global_load_dwordx4 v[84:87], v[156:157], off offset:768
	global_load_dwordx4 v[88:91], v[158:159], off offset:768
	global_load_dwordx4 v[92:95], v[164:165], off offset:768
	ds_read_b128 v[128:131], v166 offset:4608
	ds_read_b128 v[132:135], v147 offset:41472
	ds_read_b128 v[136:139], v166
	ds_read_b128 v[140:143], v166 offset:32
	ds_read_b128 v[196:199], v147 offset:36864
	ds_read_b128 v[202:205], v147 offset:36896
	s_waitcnt lgkmcnt(1)
	v_mfma_f32_32x32x16_bf16 v[48:63], v[136:139], v[196:199], v[48:63]
	v_mfma_f32_32x32x16_bf16 v[32:47], v[136:139], v[132:135], v[32:47]
	v_mfma_f32_32x32x16_bf16 v[16:31], v[128:131], v[196:199], v[16:31]
	v_mfma_f32_32x32x16_bf16 v[0:15], v[128:131], v[132:135], v[0:15]
	ds_read_b128 v[128:131], v166 offset:4640
	ds_read_b128 v[132:135], v147 offset:41504
	s_waitcnt vmcnt(15)
	ds_write_b128 v146, v[112:115] offset:18432
	s_waitcnt vmcnt(14)
	ds_write_b128 v146, v[116:119] offset:23040
	s_waitcnt vmcnt(13)
	ds_write_b128 v146, v[120:123] offset:27648
	s_waitcnt vmcnt(12)
	ds_write_b128 v146, v[124:127] offset:32256
	ds_read_b128 v[112:115], v166 offset:64
	ds_read_b128 v[116:119], v166 offset:4672
	ds_read_b128 v[120:123], v147 offset:36928
	ds_read_b128 v[124:127], v147 offset:41536
	s_waitcnt vmcnt(11)
	ds_write_b128 v146, v[64:67] offset:55296
	s_waitcnt vmcnt(10)
	ds_write_b128 v146, v[68:71] offset:59904
	s_waitcnt vmcnt(9)
	ds_write_b128 v146, v[72:75] offset:64512
	s_waitcnt vmcnt(8)
	ds_write_b128 v149, v[76:79] offset:13824
	ds_read_b128 v[64:67], v166 offset:96
	ds_read_b128 v[68:71], v166 offset:4704
	ds_read_b128 v[72:75], v147 offset:36960
	ds_read_b128 v[76:79], v147 offset:41568
	s_waitcnt lgkmcnt(0)
	s_barrier
	v_mfma_f32_32x32x16_bf16 v[48:63], v[140:143], v[202:205], v[48:63]
	v_mfma_f32_32x32x16_bf16 v[32:47], v[140:143], v[132:135], v[32:47]
	v_mfma_f32_32x32x16_bf16 v[16:31], v[128:131], v[202:205], v[16:31]
	v_mfma_f32_32x32x16_bf16 v[0:15], v[128:131], v[132:135], v[0:15]
	v_mfma_f32_32x32x16_bf16 v[48:63], v[112:115], v[120:123], v[48:63]
	v_mfma_f32_32x32x16_bf16 v[32:47], v[112:115], v[124:127], v[32:47]
	v_mfma_f32_32x32x16_bf16 v[16:31], v[116:119], v[120:123], v[16:31]
	v_mfma_f32_32x32x16_bf16 v[0:15], v[116:119], v[124:127], v[0:15]
	v_mfma_f32_32x32x16_bf16 v[48:63], v[64:67], v[72:75], v[48:63]
	v_mfma_f32_32x32x16_bf16 v[32:47], v[64:67], v[76:79], v[32:47]
	v_mfma_f32_32x32x16_bf16 v[16:31], v[68:71], v[72:75], v[16:31]
	v_mfma_f32_32x32x16_bf16 v[0:15], v[68:71], v[76:79], v[0:15]
	global_load_dwordx4 v[112:115], v160, s[10:11] offset:896
	global_load_dwordx4 v[116:119], v148, s[10:11] offset:896
	global_load_dwordx4 v[120:123], v150, s[10:11] offset:896
	global_load_dwordx4 v[124:127], v152, s[10:11] offset:896
	global_load_dwordx4 v[64:67], v[154:155], off offset:896
	global_load_dwordx4 v[68:71], v[156:157], off offset:896
	global_load_dwordx4 v[72:75], v[158:159], off offset:896
	global_load_dwordx4 v[76:79], v[164:165], off offset:896
	ds_read_b128 v[128:131], v166 offset:23040
	ds_read_b128 v[132:135], v147 offset:59904
	ds_read_b128 v[136:139], v166 offset:18432
	ds_read_b128 v[140:143], v166 offset:18464
	ds_read_b128 v[196:199], v147 offset:55296
	ds_read_b128 v[202:205], v147 offset:55328
	s_waitcnt lgkmcnt(1)
	v_mfma_f32_32x32x16_bf16 v[48:63], v[136:139], v[196:199], v[48:63]
	v_mfma_f32_32x32x16_bf16 v[32:47], v[136:139], v[132:135], v[32:47]
	v_mfma_f32_32x32x16_bf16 v[16:31], v[128:131], v[196:199], v[16:31]
	v_mfma_f32_32x32x16_bf16 v[0:15], v[128:131], v[132:135], v[0:15]
	ds_read_b128 v[128:131], v166 offset:23072
	ds_read_b128 v[132:135], v147 offset:59936
	s_waitcnt vmcnt(15)
	ds_write_b128 v146, v[96:99]
	s_waitcnt vmcnt(14)
	ds_write_b128 v146, v[100:103] offset:4608
	s_waitcnt vmcnt(13)
	ds_write_b128 v146, v[104:107] offset:9216
	s_waitcnt vmcnt(12)
	ds_write_b128 v146, v[108:111] offset:13824
	ds_read_b128 v[96:99], v166 offset:18496
	ds_read_b128 v[100:103], v166 offset:23104
	ds_read_b128 v[104:107], v147 offset:55360
	ds_read_b128 v[108:111], v147 offset:59968
	s_waitcnt vmcnt(11)
	ds_write_b128 v146, v[80:83] offset:36864
	s_waitcnt vmcnt(10)
	ds_write_b128 v146, v[84:87] offset:41472
	s_waitcnt vmcnt(9)
	ds_write_b128 v146, v[88:91] offset:46080
	s_waitcnt vmcnt(8)
	ds_write_b128 v146, v[92:95] offset:50688
	ds_read_b128 v[80:83], v166 offset:18528
	ds_read_b128 v[84:87], v166 offset:23136
	ds_read_b128 v[88:91], v147 offset:55392
	ds_read_b128 v[92:95], v147 offset:60000
	s_waitcnt lgkmcnt(0)
	s_barrier
	v_mfma_f32_32x32x16_bf16 v[48:63], v[140:143], v[202:205], v[48:63]
	v_mfma_f32_32x32x16_bf16 v[32:47], v[140:143], v[132:135], v[32:47]
	v_mfma_f32_32x32x16_bf16 v[16:31], v[128:131], v[202:205], v[16:31]
	v_mfma_f32_32x32x16_bf16 v[0:15], v[128:131], v[132:135], v[0:15]
	v_mfma_f32_32x32x16_bf16 v[48:63], v[96:99], v[104:107], v[48:63]
	v_mfma_f32_32x32x16_bf16 v[32:47], v[96:99], v[108:111], v[32:47]
	v_mfma_f32_32x32x16_bf16 v[16:31], v[100:103], v[104:107], v[16:31]
	v_mfma_f32_32x32x16_bf16 v[0:15], v[100:103], v[108:111], v[0:15]
	v_mfma_f32_32x32x16_bf16 v[48:63], v[80:83], v[88:91], v[48:63]
	v_mfma_f32_32x32x16_bf16 v[32:47], v[80:83], v[92:95], v[32:47]
	v_mfma_f32_32x32x16_bf16 v[16:31], v[84:87], v[88:91], v[16:31]
	v_mfma_f32_32x32x16_bf16 v[0:15], v[84:87], v[92:95], v[0:15]
	global_load_dwordx4 v[96:99], v160, s[10:11] offset:1024
	global_load_dwordx4 v[100:103], v148, s[10:11] offset:1024
	global_load_dwordx4 v[104:107], v150, s[10:11] offset:1024
	global_load_dwordx4 v[108:111], v152, s[10:11] offset:1024
	global_load_dwordx4 v[80:83], v[154:155], off offset:1024
	global_load_dwordx4 v[84:87], v[156:157], off offset:1024
	global_load_dwordx4 v[88:91], v[158:159], off offset:1024
	global_load_dwordx4 v[92:95], v[164:165], off offset:1024
	ds_read_b128 v[128:131], v166 offset:4608
	ds_read_b128 v[132:135], v147 offset:41472
	ds_read_b128 v[136:139], v166
	ds_read_b128 v[140:143], v166 offset:32
	ds_read_b128 v[196:199], v147 offset:36864
	ds_read_b128 v[202:205], v147 offset:36896
	s_waitcnt lgkmcnt(1)
	v_mfma_f32_32x32x16_bf16 v[48:63], v[136:139], v[196:199], v[48:63]
	v_mfma_f32_32x32x16_bf16 v[32:47], v[136:139], v[132:135], v[32:47]
	v_mfma_f32_32x32x16_bf16 v[16:31], v[128:131], v[196:199], v[16:31]
	v_mfma_f32_32x32x16_bf16 v[0:15], v[128:131], v[132:135], v[0:15]
	ds_read_b128 v[128:131], v166 offset:4640
	ds_read_b128 v[132:135], v147 offset:41504
	s_waitcnt vmcnt(15)
	ds_write_b128 v146, v[112:115] offset:18432
	s_waitcnt vmcnt(14)
	ds_write_b128 v146, v[116:119] offset:23040
	s_waitcnt vmcnt(13)
	ds_write_b128 v146, v[120:123] offset:27648
	s_waitcnt vmcnt(12)
	ds_write_b128 v146, v[124:127] offset:32256
	ds_read_b128 v[112:115], v166 offset:64
	ds_read_b128 v[116:119], v166 offset:4672
	ds_read_b128 v[120:123], v147 offset:36928
	ds_read_b128 v[124:127], v147 offset:41536
	s_waitcnt vmcnt(11)
	ds_write_b128 v146, v[64:67] offset:55296
	s_waitcnt vmcnt(10)
	ds_write_b128 v146, v[68:71] offset:59904
	s_waitcnt vmcnt(9)
	ds_write_b128 v146, v[72:75] offset:64512
	s_waitcnt vmcnt(8)
	ds_write_b128 v149, v[76:79] offset:13824
	ds_read_b128 v[64:67], v166 offset:96
	ds_read_b128 v[68:71], v166 offset:4704
	ds_read_b128 v[72:75], v147 offset:36960
	ds_read_b128 v[76:79], v147 offset:41568
	s_waitcnt lgkmcnt(0)
	s_barrier
	v_mfma_f32_32x32x16_bf16 v[48:63], v[140:143], v[202:205], v[48:63]
	v_mfma_f32_32x32x16_bf16 v[32:47], v[140:143], v[132:135], v[32:47]
	v_mfma_f32_32x32x16_bf16 v[16:31], v[128:131], v[202:205], v[16:31]
	v_mfma_f32_32x32x16_bf16 v[0:15], v[128:131], v[132:135], v[0:15]
	v_mfma_f32_32x32x16_bf16 v[48:63], v[112:115], v[120:123], v[48:63]
	v_mfma_f32_32x32x16_bf16 v[32:47], v[112:115], v[124:127], v[32:47]
	v_mfma_f32_32x32x16_bf16 v[16:31], v[116:119], v[120:123], v[16:31]
	v_mfma_f32_32x32x16_bf16 v[0:15], v[116:119], v[124:127], v[0:15]
	v_mfma_f32_32x32x16_bf16 v[48:63], v[64:67], v[72:75], v[48:63]
	v_mfma_f32_32x32x16_bf16 v[32:47], v[64:67], v[76:79], v[32:47]
	v_mfma_f32_32x32x16_bf16 v[16:31], v[68:71], v[72:75], v[16:31]
	v_mfma_f32_32x32x16_bf16 v[0:15], v[68:71], v[76:79], v[0:15]
	global_load_dwordx4 v[112:115], v160, s[10:11] offset:1152
	global_load_dwordx4 v[116:119], v148, s[10:11] offset:1152
	global_load_dwordx4 v[120:123], v150, s[10:11] offset:1152
	global_load_dwordx4 v[124:127], v152, s[10:11] offset:1152
	global_load_dwordx4 v[64:67], v[154:155], off offset:1152
	global_load_dwordx4 v[68:71], v[156:157], off offset:1152
	global_load_dwordx4 v[72:75], v[158:159], off offset:1152
	global_load_dwordx4 v[76:79], v[164:165], off offset:1152
	ds_read_b128 v[128:131], v166 offset:23040
	ds_read_b128 v[132:135], v147 offset:59904
	ds_read_b128 v[136:139], v166 offset:18432
	ds_read_b128 v[140:143], v166 offset:18464
	ds_read_b128 v[196:199], v147 offset:55296
	ds_read_b128 v[202:205], v147 offset:55328
	s_waitcnt lgkmcnt(1)
	v_mfma_f32_32x32x16_bf16 v[48:63], v[136:139], v[196:199], v[48:63]
	v_mfma_f32_32x32x16_bf16 v[32:47], v[136:139], v[132:135], v[32:47]
	v_mfma_f32_32x32x16_bf16 v[16:31], v[128:131], v[196:199], v[16:31]
	v_mfma_f32_32x32x16_bf16 v[0:15], v[128:131], v[132:135], v[0:15]
	ds_read_b128 v[128:131], v166 offset:23072
	ds_read_b128 v[132:135], v147 offset:59936
	s_waitcnt vmcnt(15)
	ds_write_b128 v146, v[96:99]
	s_waitcnt vmcnt(14)
	ds_write_b128 v146, v[100:103] offset:4608
	s_waitcnt vmcnt(13)
	ds_write_b128 v146, v[104:107] offset:9216
	s_waitcnt vmcnt(12)
	ds_write_b128 v146, v[108:111] offset:13824
	ds_read_b128 v[96:99], v166 offset:18496
	ds_read_b128 v[100:103], v166 offset:23104
	ds_read_b128 v[104:107], v147 offset:55360
	ds_read_b128 v[108:111], v147 offset:59968
	s_waitcnt vmcnt(11)
	ds_write_b128 v146, v[80:83] offset:36864
	s_waitcnt vmcnt(10)
	ds_write_b128 v146, v[84:87] offset:41472
	s_waitcnt vmcnt(9)
	ds_write_b128 v146, v[88:91] offset:46080
	s_waitcnt vmcnt(8)
	ds_write_b128 v146, v[92:95] offset:50688
	ds_read_b128 v[80:83], v166 offset:18528
	ds_read_b128 v[84:87], v166 offset:23136
	ds_read_b128 v[88:91], v147 offset:55392
	ds_read_b128 v[92:95], v147 offset:60000
	s_waitcnt lgkmcnt(0)
	s_barrier
	v_mfma_f32_32x32x16_bf16 v[48:63], v[140:143], v[202:205], v[48:63]
	v_mfma_f32_32x32x16_bf16 v[32:47], v[140:143], v[132:135], v[32:47]
	v_mfma_f32_32x32x16_bf16 v[16:31], v[128:131], v[202:205], v[16:31]
	v_mfma_f32_32x32x16_bf16 v[0:15], v[128:131], v[132:135], v[0:15]
	v_mfma_f32_32x32x16_bf16 v[48:63], v[96:99], v[104:107], v[48:63]
	v_mfma_f32_32x32x16_bf16 v[32:47], v[96:99], v[108:111], v[32:47]
	v_mfma_f32_32x32x16_bf16 v[16:31], v[100:103], v[104:107], v[16:31]
	v_mfma_f32_32x32x16_bf16 v[0:15], v[100:103], v[108:111], v[0:15]
	v_mfma_f32_32x32x16_bf16 v[48:63], v[80:83], v[88:91], v[48:63]
	v_mfma_f32_32x32x16_bf16 v[32:47], v[80:83], v[92:95], v[32:47]
	v_mfma_f32_32x32x16_bf16 v[16:31], v[84:87], v[88:91], v[16:31]
	v_mfma_f32_32x32x16_bf16 v[0:15], v[84:87], v[92:95], v[0:15]
	global_load_dwordx4 v[96:99], v160, s[10:11] offset:1280
	global_load_dwordx4 v[100:103], v148, s[10:11] offset:1280
	global_load_dwordx4 v[104:107], v150, s[10:11] offset:1280
	global_load_dwordx4 v[108:111], v152, s[10:11] offset:1280
	global_load_dwordx4 v[80:83], v[154:155], off offset:1280
	global_load_dwordx4 v[84:87], v[156:157], off offset:1280
	global_load_dwordx4 v[88:91], v[158:159], off offset:1280
	global_load_dwordx4 v[92:95], v[164:165], off offset:1280
	ds_read_b128 v[128:131], v166 offset:4608
	ds_read_b128 v[132:135], v147 offset:41472
	ds_read_b128 v[136:139], v166
	ds_read_b128 v[140:143], v166 offset:32
	ds_read_b128 v[196:199], v147 offset:36864
	ds_read_b128 v[202:205], v147 offset:36896
	s_waitcnt lgkmcnt(1)
	v_mfma_f32_32x32x16_bf16 v[48:63], v[136:139], v[196:199], v[48:63]
	v_mfma_f32_32x32x16_bf16 v[32:47], v[136:139], v[132:135], v[32:47]
	v_mfma_f32_32x32x16_bf16 v[16:31], v[128:131], v[196:199], v[16:31]
	v_mfma_f32_32x32x16_bf16 v[0:15], v[128:131], v[132:135], v[0:15]
	ds_read_b128 v[128:131], v166 offset:4640
	ds_read_b128 v[132:135], v147 offset:41504
	s_waitcnt vmcnt(15)
	ds_write_b128 v146, v[112:115] offset:18432
	s_waitcnt vmcnt(14)
	ds_write_b128 v146, v[116:119] offset:23040
	s_waitcnt vmcnt(13)
	ds_write_b128 v146, v[120:123] offset:27648
	s_waitcnt vmcnt(12)
	ds_write_b128 v146, v[124:127] offset:32256
	ds_read_b128 v[112:115], v166 offset:64
	ds_read_b128 v[116:119], v166 offset:4672
	ds_read_b128 v[120:123], v147 offset:36928
	ds_read_b128 v[124:127], v147 offset:41536
	s_waitcnt vmcnt(11)
	ds_write_b128 v146, v[64:67] offset:55296
	s_waitcnt vmcnt(10)
	ds_write_b128 v146, v[68:71] offset:59904
	s_waitcnt vmcnt(9)
	ds_write_b128 v146, v[72:75] offset:64512
	s_waitcnt vmcnt(8)
	ds_write_b128 v149, v[76:79] offset:13824
	ds_read_b128 v[64:67], v166 offset:96
	ds_read_b128 v[68:71], v166 offset:4704
	ds_read_b128 v[72:75], v147 offset:36960
	ds_read_b128 v[76:79], v147 offset:41568
	s_waitcnt lgkmcnt(0)
	s_barrier
	v_mfma_f32_32x32x16_bf16 v[48:63], v[140:143], v[202:205], v[48:63]
	v_mfma_f32_32x32x16_bf16 v[32:47], v[140:143], v[132:135], v[32:47]
	v_mfma_f32_32x32x16_bf16 v[16:31], v[128:131], v[202:205], v[16:31]
	v_mfma_f32_32x32x16_bf16 v[0:15], v[128:131], v[132:135], v[0:15]
	v_mfma_f32_32x32x16_bf16 v[48:63], v[112:115], v[120:123], v[48:63]
	v_mfma_f32_32x32x16_bf16 v[32:47], v[112:115], v[124:127], v[32:47]
	v_mfma_f32_32x32x16_bf16 v[16:31], v[116:119], v[120:123], v[16:31]
	v_mfma_f32_32x32x16_bf16 v[0:15], v[116:119], v[124:127], v[0:15]
	v_mfma_f32_32x32x16_bf16 v[48:63], v[64:67], v[72:75], v[48:63]
	v_mfma_f32_32x32x16_bf16 v[32:47], v[64:67], v[76:79], v[32:47]
	v_mfma_f32_32x32x16_bf16 v[16:31], v[68:71], v[72:75], v[16:31]
	v_mfma_f32_32x32x16_bf16 v[0:15], v[68:71], v[76:79], v[0:15]
	global_load_dwordx4 v[112:115], v160, s[10:11] offset:1408
	global_load_dwordx4 v[116:119], v148, s[10:11] offset:1408
	global_load_dwordx4 v[120:123], v150, s[10:11] offset:1408
	global_load_dwordx4 v[124:127], v152, s[10:11] offset:1408
	global_load_dwordx4 v[64:67], v[154:155], off offset:1408
	global_load_dwordx4 v[68:71], v[156:157], off offset:1408
	global_load_dwordx4 v[72:75], v[158:159], off offset:1408
	global_load_dwordx4 v[76:79], v[164:165], off offset:1408
	ds_read_b128 v[128:131], v166 offset:23040
	ds_read_b128 v[132:135], v147 offset:59904
	ds_read_b128 v[136:139], v166 offset:18432
	ds_read_b128 v[140:143], v166 offset:18464
	ds_read_b128 v[196:199], v147 offset:55296
	ds_read_b128 v[202:205], v147 offset:55328
	s_waitcnt lgkmcnt(1)
	v_mfma_f32_32x32x16_bf16 v[48:63], v[136:139], v[196:199], v[48:63]
	v_mfma_f32_32x32x16_bf16 v[32:47], v[136:139], v[132:135], v[32:47]
	v_mfma_f32_32x32x16_bf16 v[16:31], v[128:131], v[196:199], v[16:31]
	v_mfma_f32_32x32x16_bf16 v[0:15], v[128:131], v[132:135], v[0:15]
	ds_read_b128 v[128:131], v166 offset:23072
	ds_read_b128 v[132:135], v147 offset:59936
	s_waitcnt vmcnt(15)
	ds_write_b128 v146, v[96:99]
	s_waitcnt vmcnt(14)
	ds_write_b128 v146, v[100:103] offset:4608
	s_waitcnt vmcnt(13)
	ds_write_b128 v146, v[104:107] offset:9216
	s_waitcnt vmcnt(12)
	ds_write_b128 v146, v[108:111] offset:13824
	ds_read_b128 v[96:99], v166 offset:18496
	ds_read_b128 v[100:103], v166 offset:23104
	ds_read_b128 v[104:107], v147 offset:55360
	ds_read_b128 v[108:111], v147 offset:59968
	s_waitcnt vmcnt(11)
	ds_write_b128 v146, v[80:83] offset:36864
	s_waitcnt vmcnt(10)
	ds_write_b128 v146, v[84:87] offset:41472
	s_waitcnt vmcnt(9)
	ds_write_b128 v146, v[88:91] offset:46080
	s_waitcnt vmcnt(8)
	ds_write_b128 v146, v[92:95] offset:50688
	ds_read_b128 v[80:83], v166 offset:18528
	ds_read_b128 v[84:87], v166 offset:23136
	ds_read_b128 v[88:91], v147 offset:55392
	ds_read_b128 v[92:95], v147 offset:60000
	s_waitcnt lgkmcnt(0)
	s_barrier
	v_mfma_f32_32x32x16_bf16 v[48:63], v[140:143], v[202:205], v[48:63]
	v_mfma_f32_32x32x16_bf16 v[32:47], v[140:143], v[132:135], v[32:47]
	v_mfma_f32_32x32x16_bf16 v[16:31], v[128:131], v[202:205], v[16:31]
	v_mfma_f32_32x32x16_bf16 v[0:15], v[128:131], v[132:135], v[0:15]
	v_mfma_f32_32x32x16_bf16 v[48:63], v[96:99], v[104:107], v[48:63]
	v_mfma_f32_32x32x16_bf16 v[32:47], v[96:99], v[108:111], v[32:47]
	v_mfma_f32_32x32x16_bf16 v[16:31], v[100:103], v[104:107], v[16:31]
	v_mfma_f32_32x32x16_bf16 v[0:15], v[100:103], v[108:111], v[0:15]
	v_mfma_f32_32x32x16_bf16 v[48:63], v[80:83], v[88:91], v[48:63]
	v_mfma_f32_32x32x16_bf16 v[32:47], v[80:83], v[92:95], v[32:47]
	v_mfma_f32_32x32x16_bf16 v[16:31], v[84:87], v[88:91], v[16:31]
	v_mfma_f32_32x32x16_bf16 v[0:15], v[84:87], v[92:95], v[0:15]
	global_load_dwordx4 v[80:83], v160, s[10:11] offset:1536
	global_load_dwordx4 v[84:87], v148, s[10:11] offset:1536
	global_load_dwordx4 v[88:91], v150, s[10:11] offset:1536
	global_load_dwordx4 v[92:95], v152, s[10:11] offset:1536
	global_load_dwordx4 v[96:99], v[154:155], off offset:1536
	global_load_dwordx4 v[100:103], v[156:157], off offset:1536
	global_load_dwordx4 v[104:107], v[158:159], off offset:1536
	global_load_dwordx4 v[108:111], v[164:165], off offset:1536
	ds_read_b128 v[128:131], v166 offset:4608
	ds_read_b128 v[132:135], v147 offset:41472
	ds_read_b128 v[136:139], v166
	ds_read_b128 v[140:143], v166 offset:32
	ds_read_b128 v[196:199], v147 offset:36864
	ds_read_b128 v[202:205], v147 offset:36896
	s_waitcnt lgkmcnt(1)
	v_mfma_f32_32x32x16_bf16 v[48:63], v[136:139], v[196:199], v[48:63]
	v_mfma_f32_32x32x16_bf16 v[32:47], v[136:139], v[132:135], v[32:47]
	v_mfma_f32_32x32x16_bf16 v[16:31], v[128:131], v[196:199], v[16:31]
	v_mfma_f32_32x32x16_bf16 v[0:15], v[128:131], v[132:135], v[0:15]
	ds_read_b128 v[128:131], v166 offset:4640
	ds_read_b128 v[132:135], v147 offset:41504
	s_waitcnt vmcnt(15)
	ds_write_b128 v146, v[112:115] offset:18432
	s_waitcnt vmcnt(14)
	ds_write_b128 v146, v[116:119] offset:23040
	s_waitcnt vmcnt(13)
	ds_write_b128 v146, v[120:123] offset:27648
	s_waitcnt vmcnt(12)
	ds_write_b128 v146, v[124:127] offset:32256
	ds_read_b128 v[112:115], v166 offset:64
	ds_read_b128 v[116:119], v166 offset:4672
	ds_read_b128 v[120:123], v147 offset:36928
	ds_read_b128 v[124:127], v147 offset:41536
	s_waitcnt vmcnt(11)
	ds_write_b128 v146, v[64:67] offset:55296
	s_waitcnt vmcnt(10)
	ds_write_b128 v146, v[68:71] offset:59904
	s_waitcnt vmcnt(9)
	ds_write_b128 v146, v[72:75] offset:64512
	s_waitcnt vmcnt(8)
	ds_write_b128 v149, v[76:79] offset:13824
	ds_read_b128 v[64:67], v166 offset:96
	ds_read_b128 v[68:71], v166 offset:4704
	ds_read_b128 v[72:75], v147 offset:36960
	ds_read_b128 v[76:79], v147 offset:41568
	s_waitcnt lgkmcnt(0)
	s_barrier
	v_mfma_f32_32x32x16_bf16 v[48:63], v[140:143], v[202:205], v[48:63]
	v_mfma_f32_32x32x16_bf16 v[32:47], v[140:143], v[132:135], v[32:47]
	v_mfma_f32_32x32x16_bf16 v[16:31], v[128:131], v[202:205], v[16:31]
	v_mfma_f32_32x32x16_bf16 v[0:15], v[128:131], v[132:135], v[0:15]
	v_mfma_f32_32x32x16_bf16 v[48:63], v[112:115], v[120:123], v[48:63]
	v_mfma_f32_32x32x16_bf16 v[32:47], v[112:115], v[124:127], v[32:47]
	v_mfma_f32_32x32x16_bf16 v[16:31], v[116:119], v[120:123], v[16:31]
	v_mfma_f32_32x32x16_bf16 v[0:15], v[116:119], v[124:127], v[0:15]
	v_mfma_f32_32x32x16_bf16 v[48:63], v[64:67], v[72:75], v[48:63]
	v_mfma_f32_32x32x16_bf16 v[32:47], v[64:67], v[76:79], v[32:47]
	v_mfma_f32_32x32x16_bf16 v[16:31], v[68:71], v[72:75], v[16:31]
	v_mfma_f32_32x32x16_bf16 v[0:15], v[68:71], v[76:79], v[0:15]
	global_load_dwordx4 v[64:67], v160, s[10:11] offset:1664
	global_load_dwordx4 v[68:71], v148, s[10:11] offset:1664
	global_load_dwordx4 v[72:75], v150, s[10:11] offset:1664
	global_load_dwordx4 v[76:79], v152, s[10:11] offset:1664
	global_load_dwordx4 v[112:115], v[154:155], off offset:1664
	global_load_dwordx4 v[116:119], v[156:157], off offset:1664
	global_load_dwordx4 v[120:123], v[158:159], off offset:1664
	global_load_dwordx4 v[124:127], v[164:165], off offset:1664
	ds_read_b128 v[128:131], v166 offset:23040
	ds_read_b128 v[132:135], v147 offset:59904
	ds_read_b128 v[136:139], v166 offset:18432
	ds_read_b128 v[140:143], v166 offset:18464
	ds_read_b128 v[196:199], v147 offset:55296
	ds_read_b128 v[202:205], v147 offset:55328
	s_waitcnt lgkmcnt(1)
	v_mfma_f32_32x32x16_bf16 v[48:63], v[136:139], v[196:199], v[48:63]
	v_mfma_f32_32x32x16_bf16 v[32:47], v[136:139], v[132:135], v[32:47]
	v_mfma_f32_32x32x16_bf16 v[16:31], v[128:131], v[196:199], v[16:31]
	v_mfma_f32_32x32x16_bf16 v[0:15], v[128:131], v[132:135], v[0:15]
	ds_read_b128 v[128:131], v166 offset:23072
	ds_read_b128 v[132:135], v147 offset:59936
	s_waitcnt vmcnt(15)
	ds_write_b128 v146, v[80:83]
	s_waitcnt vmcnt(14)
	ds_write_b128 v146, v[84:87] offset:4608
	s_waitcnt vmcnt(13)
	ds_write_b128 v146, v[88:91] offset:9216
	s_waitcnt vmcnt(12)
	ds_write_b128 v146, v[92:95] offset:13824
	ds_read_b128 v[80:83], v166 offset:18496
	ds_read_b128 v[84:87], v166 offset:23104
	ds_read_b128 v[88:91], v147 offset:55360
	ds_read_b128 v[92:95], v147 offset:59968
	s_waitcnt vmcnt(11)
	ds_write_b128 v146, v[96:99] offset:36864
	s_waitcnt vmcnt(10)
	ds_write_b128 v146, v[100:103] offset:41472
	s_waitcnt vmcnt(9)
	ds_write_b128 v146, v[104:107] offset:46080
	s_waitcnt vmcnt(8)
	ds_write_b128 v146, v[108:111] offset:50688
	s_waitcnt lgkmcnt(14)
	v_mfma_f32_32x32x16_bf16 v[48:63], v[140:143], v[202:205], v[48:63]
	s_waitcnt lgkmcnt(12)
	v_mfma_f32_32x32x16_bf16 v[32:47], v[140:143], v[132:135], v[32:47]
	v_mfma_f32_32x32x16_bf16 v[16:31], v[128:131], v[202:205], v[16:31]
	v_mfma_f32_32x32x16_bf16 v[0:15], v[128:131], v[132:135], v[0:15]
	s_waitcnt lgkmcnt(5)
	v_mfma_f32_32x32x16_bf16 v[48:63], v[80:83], v[88:91], v[48:63]
	s_waitcnt lgkmcnt(4)
	v_mfma_f32_32x32x16_bf16 v[32:47], v[80:83], v[92:95], v[32:47]
	v_mfma_f32_32x32x16_bf16 v[16:31], v[84:87], v[88:91], v[16:31]
	v_mfma_f32_32x32x16_bf16 v[0:15], v[84:87], v[92:95], v[0:15]
	ds_read_b128 v[80:83], v166 offset:18528
	ds_read_b128 v[84:87], v166 offset:23136
	ds_read_b128 v[88:91], v147 offset:55392
	ds_read_b128 v[92:95], v147 offset:60000
	s_waitcnt lgkmcnt(0)
	s_barrier
	v_mfma_f32_32x32x16_bf16 v[48:63], v[80:83], v[88:91], v[48:63]
	v_mfma_f32_32x32x16_bf16 v[32:47], v[80:83], v[92:95], v[32:47]
	v_mfma_f32_32x32x16_bf16 v[16:31], v[84:87], v[88:91], v[16:31]
	v_mfma_f32_32x32x16_bf16 v[0:15], v[84:87], v[92:95], v[0:15]
	global_load_dwordx4 v[80:83], v160, s[10:11] offset:1792
	global_load_dwordx4 v[84:87], v148, s[10:11] offset:1792
	global_load_dwordx4 v[88:91], v150, s[10:11] offset:1792
	global_load_dwordx4 v[92:95], v152, s[10:11] offset:1792
	global_load_dwordx4 v[96:99], v[154:155], off offset:1792
	global_load_dwordx4 v[100:103], v[156:157], off offset:1792
	global_load_dwordx4 v[104:107], v[158:159], off offset:1792
	global_load_dwordx4 v[108:111], v[164:165], off offset:1792
	ds_read_b128 v[128:131], v166 offset:4608
	ds_read_b128 v[132:135], v147 offset:41472
	ds_read_b128 v[136:139], v166
	ds_read_b128 v[140:143], v166 offset:32
	ds_read_b128 v[196:199], v147 offset:36864
	ds_read_b128 v[202:205], v147 offset:36896
	s_waitcnt lgkmcnt(1)
	v_mfma_f32_32x32x16_bf16 v[48:63], v[136:139], v[196:199], v[48:63]
	v_mfma_f32_32x32x16_bf16 v[32:47], v[136:139], v[132:135], v[32:47]
	v_mfma_f32_32x32x16_bf16 v[16:31], v[128:131], v[196:199], v[16:31]
	v_mfma_f32_32x32x16_bf16 v[0:15], v[128:131], v[132:135], v[0:15]
	ds_read_b128 v[128:131], v166 offset:4640
	ds_read_b128 v[132:135], v147 offset:41504
	s_waitcnt vmcnt(15)
	ds_write_b128 v146, v[64:67] offset:18432
	s_waitcnt vmcnt(14)
	ds_write_b128 v146, v[68:71] offset:23040
	s_waitcnt vmcnt(13)
	ds_write_b128 v146, v[72:75] offset:27648
	s_waitcnt vmcnt(12)
	ds_write_b128 v146, v[76:79] offset:32256
	ds_read_b128 v[64:67], v166 offset:64
	ds_read_b128 v[68:71], v166 offset:4672
	ds_read_b128 v[72:75], v147 offset:36928
	ds_read_b128 v[76:79], v147 offset:41536
	s_waitcnt vmcnt(11)
	ds_write_b128 v146, v[112:115] offset:55296
	s_waitcnt vmcnt(10)
	ds_write_b128 v146, v[116:119] offset:59904
	s_waitcnt vmcnt(9)
	ds_write_b128 v146, v[120:123] offset:64512
	s_waitcnt vmcnt(8)
	ds_write_b128 v149, v[124:127] offset:13824
	s_waitcnt lgkmcnt(14)
	v_mfma_f32_32x32x16_bf16 v[48:63], v[140:143], v[202:205], v[48:63]
	s_waitcnt lgkmcnt(12)
	v_mfma_f32_32x32x16_bf16 v[32:47], v[140:143], v[132:135], v[32:47]
	v_mfma_f32_32x32x16_bf16 v[16:31], v[128:131], v[202:205], v[16:31]
	v_mfma_f32_32x32x16_bf16 v[0:15], v[128:131], v[132:135], v[0:15]
	s_waitcnt lgkmcnt(5)
	v_mfma_f32_32x32x16_bf16 v[48:63], v[64:67], v[72:75], v[48:63]
	s_waitcnt lgkmcnt(4)
	v_mfma_f32_32x32x16_bf16 v[32:47], v[64:67], v[76:79], v[32:47]
	v_mfma_f32_32x32x16_bf16 v[16:31], v[68:71], v[72:75], v[16:31]
	v_mfma_f32_32x32x16_bf16 v[0:15], v[68:71], v[76:79], v[0:15]
	ds_read_b128 v[64:67], v166 offset:96
	ds_read_b128 v[68:71], v166 offset:4704
	ds_read_b128 v[72:75], v147 offset:36960
	ds_read_b128 v[76:79], v147 offset:41568
	s_waitcnt lgkmcnt(0)
	s_barrier
	v_mfma_f32_32x32x16_bf16 v[48:63], v[64:67], v[72:75], v[48:63]
	v_mfma_f32_32x32x16_bf16 v[32:47], v[64:67], v[76:79], v[32:47]
	v_mfma_f32_32x32x16_bf16 v[16:31], v[68:71], v[72:75], v[16:31]
	v_mfma_f32_32x32x16_bf16 v[0:15], v[68:71], v[76:79], v[0:15]
	global_load_dwordx4 v[64:67], v160, s[10:11] offset:1920
	global_load_dwordx4 v[68:71], v148, s[10:11] offset:1920
	global_load_dwordx4 v[72:75], v150, s[10:11] offset:1920
	global_load_dwordx4 v[76:79], v152, s[10:11] offset:1920
	global_load_dwordx4 v[112:115], v[154:155], off offset:1920
	global_load_dwordx4 v[116:119], v[156:157], off offset:1920
	global_load_dwordx4 v[120:123], v[158:159], off offset:1920
	global_load_dwordx4 v[124:127], v[164:165], off offset:1920
	ds_read_b128 v[128:131], v166 offset:23040
	ds_read_b128 v[132:135], v147 offset:59904
	ds_read_b128 v[136:139], v166 offset:18432
	ds_read_b128 v[140:143], v166 offset:18464
	ds_read_b128 v[150:153], v147 offset:55296
	ds_read_b128 v[154:157], v147 offset:55328
	s_waitcnt lgkmcnt(1)
	v_mfma_f32_32x32x16_bf16 v[48:63], v[136:139], v[150:153], v[48:63]
	v_mfma_f32_32x32x16_bf16 v[32:47], v[136:139], v[132:135], v[32:47]
	v_mfma_f32_32x32x16_bf16 v[16:31], v[128:131], v[150:153], v[16:31]
	v_mfma_f32_32x32x16_bf16 v[0:15], v[128:131], v[132:135], v[0:15]
	ds_read_b128 v[128:131], v166 offset:23072
	ds_read_b128 v[132:135], v147 offset:59936
	s_waitcnt vmcnt(15)
	ds_write_b128 v146, v[80:83]
	s_waitcnt vmcnt(14)
	ds_write_b128 v146, v[84:87] offset:4608
	s_waitcnt vmcnt(13)
	ds_write_b128 v146, v[88:91] offset:9216
	s_waitcnt vmcnt(12)
	ds_write_b128 v146, v[92:95] offset:13824
	ds_read_b128 v[80:83], v166 offset:18496
	ds_read_b128 v[84:87], v166 offset:23104
	ds_read_b128 v[88:91], v147 offset:55360
	ds_read_b128 v[92:95], v147 offset:59968
	s_waitcnt vmcnt(11)
	ds_write_b128 v146, v[96:99] offset:36864
	s_waitcnt vmcnt(10)
	ds_write_b128 v146, v[100:103] offset:41472
	s_waitcnt vmcnt(9)
	ds_write_b128 v146, v[104:107] offset:46080
	s_waitcnt vmcnt(8)
	ds_write_b128 v146, v[108:111] offset:50688
	s_waitcnt lgkmcnt(14)
	v_mfma_f32_32x32x16_bf16 v[48:63], v[140:143], v[154:157], v[48:63]
	s_waitcnt lgkmcnt(12)
	v_mfma_f32_32x32x16_bf16 v[32:47], v[140:143], v[132:135], v[32:47]
	v_mfma_f32_32x32x16_bf16 v[16:31], v[128:131], v[154:157], v[16:31]
	v_mfma_f32_32x32x16_bf16 v[0:15], v[128:131], v[132:135], v[0:15]
	s_waitcnt lgkmcnt(5)
	v_mfma_f32_32x32x16_bf16 v[48:63], v[80:83], v[88:91], v[48:63]
	s_waitcnt lgkmcnt(4)
	v_mfma_f32_32x32x16_bf16 v[32:47], v[80:83], v[92:95], v[32:47]
	v_mfma_f32_32x32x16_bf16 v[16:31], v[84:87], v[88:91], v[16:31]
	v_mfma_f32_32x32x16_bf16 v[0:15], v[84:87], v[92:95], v[0:15]
	ds_read_b128 v[80:83], v166 offset:18528
	ds_read_b128 v[84:87], v166 offset:23136
	ds_read_b128 v[88:91], v147 offset:55392
	ds_read_b128 v[92:95], v147 offset:60000
	s_waitcnt lgkmcnt(0)
	s_barrier
	v_mfma_f32_32x32x16_bf16 v[48:63], v[80:83], v[88:91], v[48:63]
	v_mfma_f32_32x32x16_bf16 v[32:47], v[80:83], v[92:95], v[32:47]
	v_mfma_f32_32x32x16_bf16 v[16:31], v[84:87], v[88:91], v[16:31]
	v_mfma_f32_32x32x16_bf16 v[0:15], v[84:87], v[92:95], v[0:15]
	ds_read_b128 v[80:83], v166 offset:4608
	ds_read_b128 v[84:87], v147 offset:41472
	ds_read_b128 v[88:91], v166
	ds_read_b128 v[92:95], v166 offset:32
	ds_read_b128 v[96:99], v147 offset:36864
	ds_read_b128 v[100:103], v147 offset:36896
	s_waitcnt lgkmcnt(1)
	v_mfma_f32_32x32x16_bf16 v[48:63], v[88:91], v[96:99], v[48:63]
	v_mfma_f32_32x32x16_bf16 v[32:47], v[88:91], v[84:87], v[32:47]
	v_mfma_f32_32x32x16_bf16 v[16:31], v[80:83], v[96:99], v[16:31]
	v_mfma_f32_32x32x16_bf16 v[0:15], v[80:83], v[84:87], v[0:15]
	ds_read_b128 v[80:83], v166 offset:4640
	ds_read_b128 v[84:87], v147 offset:41504
	s_waitcnt vmcnt(7)
	ds_write_b128 v146, v[64:67] offset:18432
	s_waitcnt vmcnt(6)
	ds_write_b128 v146, v[68:71] offset:23040
	s_waitcnt vmcnt(5)
	ds_write_b128 v146, v[72:75] offset:27648
	s_waitcnt vmcnt(4)
	ds_write_b128 v146, v[76:79] offset:32256
	ds_read_b128 v[64:67], v166 offset:64
	ds_read_b128 v[68:71], v166 offset:4672
	ds_read_b128 v[72:75], v147 offset:36928
	ds_read_b128 v[76:79], v147 offset:41536
	s_waitcnt vmcnt(3)
	ds_write_b128 v146, v[112:115] offset:55296
	s_waitcnt vmcnt(2)
	ds_write_b128 v146, v[116:119] offset:59904
	s_waitcnt vmcnt(1)
	ds_write_b128 v146, v[120:123] offset:64512
	s_waitcnt vmcnt(0)
	ds_write_b128 v149, v[124:127] offset:13824
	s_waitcnt lgkmcnt(14)
	v_mfma_f32_32x32x16_bf16 v[48:63], v[92:95], v[100:103], v[48:63]
	s_waitcnt lgkmcnt(12)
	v_mfma_f32_32x32x16_bf16 v[32:47], v[92:95], v[84:87], v[32:47]
	v_mfma_f32_32x32x16_bf16 v[16:31], v[80:83], v[100:103], v[16:31]
	v_mfma_f32_32x32x16_bf16 v[0:15], v[80:83], v[84:87], v[0:15]
	s_waitcnt lgkmcnt(5)
	v_mfma_f32_32x32x16_bf16 v[48:63], v[64:67], v[72:75], v[48:63]
	s_waitcnt lgkmcnt(4)
	v_mfma_f32_32x32x16_bf16 v[32:47], v[64:67], v[76:79], v[32:47]
	v_mfma_f32_32x32x16_bf16 v[16:31], v[68:71], v[72:75], v[16:31]
	v_mfma_f32_32x32x16_bf16 v[0:15], v[68:71], v[76:79], v[0:15]
	ds_read_b128 v[64:67], v166 offset:96
	ds_read_b128 v[68:71], v166 offset:4704
	ds_read_b128 v[72:75], v147 offset:36960
	ds_read_b128 v[76:79], v147 offset:41568
	s_waitcnt lgkmcnt(0)
	s_barrier
	v_mfma_f32_32x32x16_bf16 v[48:63], v[64:67], v[72:75], v[48:63]
	v_mfma_f32_32x32x16_bf16 v[32:47], v[64:67], v[76:79], v[32:47]
	v_mfma_f32_32x32x16_bf16 v[16:31], v[68:71], v[72:75], v[16:31]
	v_mfma_f32_32x32x16_bf16 v[0:15], v[68:71], v[76:79], v[0:15]
	ds_read_b128 v[64:67], v166 offset:23040
	ds_read_b128 v[68:71], v147 offset:59904
	ds_read_b128 v[72:75], v166 offset:18432
	ds_read_b128 v[76:79], v166 offset:18464
	ds_read_b128 v[80:83], v147 offset:55296
	ds_read_b128 v[84:87], v147 offset:55328
	s_waitcnt lgkmcnt(1)
	v_mfma_f32_32x32x16_bf16 v[48:63], v[72:75], v[80:83], v[48:63]
	v_mfma_f32_32x32x16_bf16 v[32:47], v[72:75], v[68:71], v[32:47]
	v_mfma_f32_32x32x16_bf16 v[16:31], v[64:67], v[80:83], v[16:31]
	v_mfma_f32_32x32x16_bf16 v[0:15], v[64:67], v[68:71], v[0:15]
	ds_read_b128 v[64:67], v166 offset:23072
	ds_read_b128 v[68:71], v147 offset:59936
	s_waitcnt lgkmcnt(2)
	v_mfma_f32_32x32x16_bf16 v[48:63], v[76:79], v[84:87], v[48:63]
	s_waitcnt lgkmcnt(0)
	v_mfma_f32_32x32x16_bf16 v[32:47], v[76:79], v[68:71], v[32:47]
	v_mfma_f32_32x32x16_bf16 v[16:31], v[64:67], v[84:87], v[16:31]
	v_mfma_f32_32x32x16_bf16 v[0:15], v[64:67], v[68:71], v[0:15]
	ds_read_b128 v[64:67], v147 offset:59968
	ds_read_b128 v[68:71], v147 offset:55360
	ds_read_b128 v[72:75], v166 offset:23104
	ds_read_b128 v[76:79], v166 offset:18496
	s_waitcnt lgkmcnt(0)
	v_mfma_f32_32x32x16_bf16 v[48:63], v[76:79], v[68:71], v[48:63]
	v_mfma_f32_32x32x16_bf16 v[32:47], v[76:79], v[64:67], v[32:47]
	v_mfma_f32_32x32x16_bf16 v[16:31], v[72:75], v[68:71], v[16:31]
	v_mfma_f32_32x32x16_bf16 v[0:15], v[72:75], v[64:67], v[0:15]
	ds_read_b128 v[64:67], v147 offset:60000
	ds_read_b128 v[68:71], v147 offset:55392
	ds_read_b128 v[72:75], v166 offset:23136
	ds_read_b128 v[76:79], v166 offset:18528
	s_waitcnt lgkmcnt(0)
	s_barrier
	v_mfma_f32_32x32x16_bf16 v[48:63], v[76:79], v[68:71], v[48:63]
	v_mfma_f32_32x32x16_bf16 v[16:31], v[72:75], v[68:71], v[16:31]
	s_nop 10
	v_mul_f32_e32 v48, 0xbfb8aa3b, v48
	v_mul_f32_e32 v49, 0xbfb8aa3b, v49
	v_exp_f32_e32 v48, v48
	v_exp_f32_e32 v49, v49
	v_mul_f32_e32 v51, 0xbfb8aa3b, v51
	v_exp_f32_e32 v51, v51
	v_pk_add_f32 v[48:49], v[48:49], 1.0 op_sel_hi:[1,0]
	s_nop 0
	v_div_scale_f32 v68, s[12:13], v49, v49, 1.0
	v_rcp_f32_e32 v69, v68
	v_mfma_f32_32x32x16_bf16 v[0:15], v[72:75], v[64:67], v[0:15]
	v_mul_f32_e32 v16, 0xbfb8aa3b, v16
	v_mul_f32_e32 v17, 0xbfb8aa3b, v17
	v_fma_f32 v70, -v68, v69, 1.0
	v_fmac_f32_e32 v69, v70, v69
	v_div_scale_f32 v70, vcc, 1.0, v49, 1.0
	v_mul_f32_e32 v71, v70, v69
	v_fma_f32 v72, -v68, v71, v70
	v_fmac_f32_e32 v71, v72, v69
	v_fma_f32 v68, -v68, v71, v70
	v_div_fmas_f32 v68, v68, v69, v71
	v_div_fixup_f32 v49, v68, v49, 1.0
	v_mfma_f32_32x32x16_bf16 v[32:47], v[76:79], v[64:67], v[32:47]
	v_lshlrev_b32_e32 v64, 16, v223
	v_lshlrev_b32_e32 v66, 16, v200
	v_and_b32_e32 v65, 0xffff0000, v223
	v_and_b32_e32 v67, 0xffff0000, v200
	v_rcp_f32_e32 v48, v48
	s_nop 0
	v_pk_fma_f32 v[48:49], v[48:49], v[66:67], v[64:65]
	v_lshlrev_b32_e32 v64, 16, v189
	v_cvt_pk_bf16_f32 v223, v48, v49
	v_mul_f32_e32 v49, 0xbfb8aa3b, v50
	v_exp_f32_e32 v50, v49
	v_lshlrev_b32_e32 v48, 16, v222
	v_and_b32_e32 v49, 0xffff0000, v222
	v_and_b32_e32 v65, 0xffff0000, v189
	v_pk_add_f32 v[50:51], v[50:51], 1.0 op_sel_hi:[1,0]
	v_mul_f32_e32 v32, 0xbfb8aa3b, v32
	v_mul_f32_e32 v33, 0xbfb8aa3b, v33
	v_exp_f32_e32 v32, v32
	v_exp_f32_e32 v33, v33
	v_rcp_f32_e32 v51, v51
	s_nop 0
	v_pk_add_f32 v[32:33], v[32:33], 1.0 op_sel_hi:[1,0]
	v_mul_f32_e32 v35, 0xbfb8aa3b, v35
	v_exp_f32_e32 v35, v35
	v_rcp_f32_e32 v50, v50
	s_nop 0
	v_pk_fma_f32 v[48:49], v[50:51], v[64:65], v[48:49]
	v_mul_f32_e32 v51, 0xbfb8aa3b, v53
	v_cvt_pk_bf16_f32 v222, v48, v49
	v_mul_f32_e32 v49, 0xbfb8aa3b, v52
	v_exp_f32_e32 v50, v49
	v_exp_f32_e32 v51, v51
	v_lshlrev_b32_e32 v48, 16, v221
	v_lshlrev_b32_e32 v52, 16, v188
	v_and_b32_e32 v49, 0xffff0000, v221
	v_pk_add_f32 v[50:51], v[50:51], 1.0 op_sel_hi:[1,0]
	v_and_b32_e32 v53, 0xffff0000, v188
	v_exp_f32_e32 v16, v16
	v_exp_f32_e32 v17, v17
	v_mul_f32_e32 v19, 0xbfb8aa3b, v19
	v_rcp_f32_e32 v51, v51
	s_nop 0
	v_pk_add_f32 v[16:17], v[16:17], 1.0 op_sel_hi:[1,0]
	v_exp_f32_e32 v19, v19
	v_mul_f32_e32 v0, 0xbfb8aa3b, v0
	v_rcp_f32_e32 v50, v50
	s_nop 0
	v_pk_fma_f32 v[48:49], v[50:51], v[52:53], v[48:49]
	v_mul_f32_e32 v51, 0xbfb8aa3b, v55
	v_cvt_pk_bf16_f32 v221, v48, v49
	v_mul_f32_e32 v49, 0xbfb8aa3b, v54
	v_exp_f32_e32 v50, v49
	v_exp_f32_e32 v51, v51
	v_lshlrev_b32_e32 v48, 16, v220
	v_lshlrev_b32_e32 v52, 16, v208
	v_and_b32_e32 v49, 0xffff0000, v220
	v_pk_add_f32 v[50:51], v[50:51], 1.0 op_sel_hi:[1,0]
	v_and_b32_e32 v53, 0xffff0000, v208
	v_mul_f32_e32 v1, 0xbfb8aa3b, v1
	v_exp_f32_e32 v0, v0
	v_exp_f32_e32 v1, v1
	v_rcp_f32_e32 v51, v51
	s_nop 0
	v_pk_add_f32 v[0:1], v[0:1], 1.0 op_sel_hi:[1,0]
	v_mul_f32_e32 v3, 0xbfb8aa3b, v3
	v_exp_f32_e32 v3, v3
	v_rcp_f32_e32 v50, v50
	s_nop 0
	v_pk_fma_f32 v[48:49], v[50:51], v[52:53], v[48:49]
	v_mul_f32_e32 v51, 0xbfb8aa3b, v57
	v_cvt_pk_bf16_f32 v220, v48, v49
	v_mul_f32_e32 v49, 0xbfb8aa3b, v56
	v_exp_f32_e32 v50, v49
	v_exp_f32_e32 v51, v51
	v_lshlrev_b32_e32 v48, 16, v219
	v_lshlrev_b32_e32 v52, 16, v195
	v_and_b32_e32 v49, 0xffff0000, v219
	v_pk_add_f32 v[50:51], v[50:51], 1.0 op_sel_hi:[1,0]
	v_and_b32_e32 v53, 0xffff0000, v195
	v_rcp_f32_e32 v51, v51
	s_nop 0
	v_rcp_f32_e32 v50, v50
	s_nop 0
	v_pk_fma_f32 v[48:49], v[50:51], v[52:53], v[48:49]
	v_mul_f32_e32 v51, 0xbfb8aa3b, v59
	v_cvt_pk_bf16_f32 v219, v48, v49
	v_mul_f32_e32 v49, 0xbfb8aa3b, v58
	v_exp_f32_e32 v50, v49
	v_exp_f32_e32 v51, v51
	v_lshlrev_b32_e32 v48, 16, v218
	v_lshlrev_b32_e32 v52, 16, v192
	v_and_b32_e32 v49, 0xffff0000, v218
	v_pk_add_f32 v[50:51], v[50:51], 1.0 op_sel_hi:[1,0]
	v_and_b32_e32 v53, 0xffff0000, v192
	v_rcp_f32_e32 v51, v51
	s_nop 0
	v_rcp_f32_e32 v50, v50
	s_nop 0
	v_pk_fma_f32 v[48:49], v[50:51], v[52:53], v[48:49]
	v_mul_f32_e32 v51, 0xbfb8aa3b, v61
	v_cvt_pk_bf16_f32 v218, v48, v49
	v_mul_f32_e32 v49, 0xbfb8aa3b, v60
	v_exp_f32_e32 v50, v49
	v_exp_f32_e32 v51, v51
	v_lshlrev_b32_e32 v48, 16, v217
	v_lshlrev_b32_e32 v52, 16, v250
	v_and_b32_e32 v49, 0xffff0000, v217
	v_pk_add_f32 v[50:51], v[50:51], 1.0 op_sel_hi:[1,0]
	v_and_b32_e32 v53, 0xffff0000, v250
	v_rcp_f32_e32 v51, v51
	s_nop 0
	v_rcp_f32_e32 v50, v50
	s_nop 0
	v_pk_fma_f32 v[48:49], v[50:51], v[52:53], v[48:49]
	v_mul_f32_e32 v51, 0xbfb8aa3b, v63
	v_cvt_pk_bf16_f32 v217, v48, v49
	v_mul_f32_e32 v49, 0xbfb8aa3b, v62
	v_exp_f32_e32 v50, v49
	v_exp_f32_e32 v51, v51
	v_lshlrev_b32_e32 v48, 16, v216
	v_lshlrev_b32_e32 v52, 16, v249
	v_and_b32_e32 v49, 0xffff0000, v216
	v_pk_add_f32 v[50:51], v[50:51], 1.0 op_sel_hi:[1,0]
	v_and_b32_e32 v53, 0xffff0000, v249
	v_rcp_f32_e32 v51, v51
	s_nop 0
	v_rcp_f32_e32 v50, v50
	s_nop 0
	v_pk_fma_f32 v[48:49], v[50:51], v[52:53], v[48:49]
	v_cvt_pk_bf16_f32 v216, v48, v49
	v_lshlrev_b32_e32 v48, 16, v215
	v_lshlrev_b32_e32 v50, 16, v248
	v_rcp_f32_e32 v33, v33
	s_nop 0
	v_and_b32_e32 v49, 0xffff0000, v215
	v_and_b32_e32 v51, 0xffff0000, v248
	v_rcp_f32_e32 v32, v32
	s_nop 0
	v_pk_fma_f32 v[32:33], v[32:33], v[50:51], v[48:49]
	v_lshlrev_b32_e32 v48, 16, v247
	v_cvt_pk_bf16_f32 v215, v32, v33
	v_mul_f32_e32 v33, 0xbfb8aa3b, v34
	v_exp_f32_e32 v34, v33
	v_lshlrev_b32_e32 v32, 16, v214
	v_and_b32_e32 v33, 0xffff0000, v214
	v_and_b32_e32 v49, 0xffff0000, v247
	v_pk_add_f32 v[34:35], v[34:35], 1.0 op_sel_hi:[1,0]
	s_nop 0
	v_rcp_f32_e32 v35, v35
	s_nop 0
	v_rcp_f32_e32 v34, v34
	s_nop 0
	v_pk_fma_f32 v[32:33], v[34:35], v[48:49], v[32:33]
	v_mul_f32_e32 v35, 0xbfb8aa3b, v37
	v_cvt_pk_bf16_f32 v214, v32, v33
	v_mul_f32_e32 v33, 0xbfb8aa3b, v36
	v_exp_f32_e32 v34, v33
	v_exp_f32_e32 v35, v35
	v_lshlrev_b32_e32 v32, 16, v213
	v_lshlrev_b32_e32 v36, 16, v246
	v_and_b32_e32 v33, 0xffff0000, v213
	v_pk_add_f32 v[34:35], v[34:35], 1.0 op_sel_hi:[1,0]
	v_and_b32_e32 v37, 0xffff0000, v246
	v_rcp_f32_e32 v35, v35
	s_nop 0
	v_rcp_f32_e32 v34, v34
	s_nop 0
	v_pk_fma_f32 v[32:33], v[34:35], v[36:37], v[32:33]
	v_mul_f32_e32 v35, 0xbfb8aa3b, v39
	v_cvt_pk_bf16_f32 v213, v32, v33
	v_mul_f32_e32 v33, 0xbfb8aa3b, v38
	v_exp_f32_e32 v34, v33
	v_exp_f32_e32 v35, v35
	v_lshlrev_b32_e32 v32, 16, v212
	v_lshlrev_b32_e32 v36, 16, v245
	v_and_b32_e32 v33, 0xffff0000, v212
	v_pk_add_f32 v[34:35], v[34:35], 1.0 op_sel_hi:[1,0]
	v_and_b32_e32 v37, 0xffff0000, v245
	v_rcp_f32_e32 v35, v35
	s_nop 0
	v_rcp_f32_e32 v34, v34
	s_nop 0
	v_pk_fma_f32 v[32:33], v[34:35], v[36:37], v[32:33]
	v_mul_f32_e32 v35, 0xbfb8aa3b, v41
	v_cvt_pk_bf16_f32 v212, v32, v33
	v_mul_f32_e32 v33, 0xbfb8aa3b, v40
	v_exp_f32_e32 v34, v33
	v_exp_f32_e32 v35, v35
	v_lshlrev_b32_e32 v32, 16, v211
	v_lshlrev_b32_e32 v36, 16, v244
	v_and_b32_e32 v33, 0xffff0000, v211
	v_pk_add_f32 v[34:35], v[34:35], 1.0 op_sel_hi:[1,0]
	v_and_b32_e32 v37, 0xffff0000, v244
	v_rcp_f32_e32 v35, v35
	s_nop 0
	v_rcp_f32_e32 v34, v34
	s_nop 0
	v_pk_fma_f32 v[32:33], v[34:35], v[36:37], v[32:33]
	v_mul_f32_e32 v35, 0xbfb8aa3b, v43
	v_cvt_pk_bf16_f32 v211, v32, v33
	v_mul_f32_e32 v33, 0xbfb8aa3b, v42
	v_exp_f32_e32 v34, v33
	v_exp_f32_e32 v35, v35
	v_lshlrev_b32_e32 v32, 16, v210
	v_lshlrev_b32_e32 v36, 16, v243
	v_and_b32_e32 v33, 0xffff0000, v210
	v_pk_add_f32 v[34:35], v[34:35], 1.0 op_sel_hi:[1,0]
	v_and_b32_e32 v37, 0xffff0000, v243
	v_rcp_f32_e32 v35, v35
	s_nop 0
	v_rcp_f32_e32 v34, v34
	s_nop 0
	v_pk_fma_f32 v[32:33], v[34:35], v[36:37], v[32:33]
	v_mul_f32_e32 v35, 0xbfb8aa3b, v45
	v_cvt_pk_bf16_f32 v210, v32, v33
	v_mul_f32_e32 v33, 0xbfb8aa3b, v44
	v_exp_f32_e32 v34, v33
	v_exp_f32_e32 v35, v35
	v_lshlrev_b32_e32 v32, 16, v185
	v_lshlrev_b32_e32 v36, 16, v242
	v_and_b32_e32 v33, 0xffff0000, v185
	v_pk_add_f32 v[34:35], v[34:35], 1.0 op_sel_hi:[1,0]
	v_and_b32_e32 v37, 0xffff0000, v242
	v_rcp_f32_e32 v35, v35
	s_nop 0
	v_rcp_f32_e32 v34, v34
	s_nop 0
	v_pk_fma_f32 v[32:33], v[34:35], v[36:37], v[32:33]
	v_mul_f32_e32 v35, 0xbfb8aa3b, v47
	v_cvt_pk_bf16_f32 v185, v32, v33
	v_mul_f32_e32 v33, 0xbfb8aa3b, v46
	v_exp_f32_e32 v34, v33
	v_exp_f32_e32 v35, v35
	v_lshlrev_b32_e32 v32, 16, v184
	v_lshlrev_b32_e32 v36, 16, v241
	v_and_b32_e32 v33, 0xffff0000, v184
	v_pk_add_f32 v[34:35], v[34:35], 1.0 op_sel_hi:[1,0]
	v_and_b32_e32 v37, 0xffff0000, v241
	v_rcp_f32_e32 v35, v35
	s_nop 0
	v_rcp_f32_e32 v34, v34
	s_nop 0
	v_pk_fma_f32 v[32:33], v[34:35], v[36:37], v[32:33]
	v_cvt_pk_bf16_f32 v184, v32, v33
	v_lshlrev_b32_e32 v32, 16, v183
	v_lshlrev_b32_e32 v34, 16, v240
	v_rcp_f32_e32 v17, v17
	s_nop 0
	v_and_b32_e32 v33, 0xffff0000, v183
	v_and_b32_e32 v35, 0xffff0000, v240
	v_rcp_f32_e32 v16, v16
	s_nop 0
	v_pk_fma_f32 v[16:17], v[16:17], v[34:35], v[32:33]
	v_lshlrev_b32_e32 v32, 16, v239
	v_cvt_pk_bf16_f32 v183, v16, v17
	v_mul_f32_e32 v17, 0xbfb8aa3b, v18
	v_exp_f32_e32 v18, v17
	v_lshlrev_b32_e32 v16, 16, v182
	v_and_b32_e32 v17, 0xffff0000, v182
	v_and_b32_e32 v33, 0xffff0000, v239
	v_pk_add_f32 v[18:19], v[18:19], 1.0 op_sel_hi:[1,0]
	s_nop 0
	v_rcp_f32_e32 v19, v19
	s_nop 0
	v_rcp_f32_e32 v18, v18
	s_nop 0
	v_pk_fma_f32 v[16:17], v[18:19], v[32:33], v[16:17]
	v_mul_f32_e32 v19, 0xbfb8aa3b, v21
	v_cvt_pk_bf16_f32 v182, v16, v17
	v_mul_f32_e32 v17, 0xbfb8aa3b, v20
	v_exp_f32_e32 v18, v17
	v_exp_f32_e32 v19, v19
	v_lshlrev_b32_e32 v16, 16, v181
	v_lshlrev_b32_e32 v20, 16, v238
	v_and_b32_e32 v17, 0xffff0000, v181
	v_pk_add_f32 v[18:19], v[18:19], 1.0 op_sel_hi:[1,0]
	v_and_b32_e32 v21, 0xffff0000, v238
	v_rcp_f32_e32 v19, v19
	s_nop 0
	v_rcp_f32_e32 v18, v18
	s_nop 0
	v_pk_fma_f32 v[16:17], v[18:19], v[20:21], v[16:17]
	v_mul_f32_e32 v19, 0xbfb8aa3b, v23
	v_cvt_pk_bf16_f32 v181, v16, v17
	v_mul_f32_e32 v17, 0xbfb8aa3b, v22
	v_exp_f32_e32 v18, v17
	v_exp_f32_e32 v19, v19
	v_lshlrev_b32_e32 v16, 16, v180
	v_lshlrev_b32_e32 v20, 16, v237
	v_and_b32_e32 v17, 0xffff0000, v180
	v_pk_add_f32 v[18:19], v[18:19], 1.0 op_sel_hi:[1,0]
	v_and_b32_e32 v21, 0xffff0000, v237
	v_rcp_f32_e32 v19, v19
	s_nop 0
	v_rcp_f32_e32 v18, v18
	s_nop 0
	v_pk_fma_f32 v[16:17], v[18:19], v[20:21], v[16:17]
	v_mul_f32_e32 v19, 0xbfb8aa3b, v25
	v_cvt_pk_bf16_f32 v180, v16, v17
	v_mul_f32_e32 v17, 0xbfb8aa3b, v24
	v_exp_f32_e32 v18, v17
	v_exp_f32_e32 v19, v19
	v_lshlrev_b32_e32 v16, 16, v179
	v_lshlrev_b32_e32 v20, 16, v236
	v_and_b32_e32 v17, 0xffff0000, v179
	v_pk_add_f32 v[18:19], v[18:19], 1.0 op_sel_hi:[1,0]
	v_and_b32_e32 v21, 0xffff0000, v236
	v_rcp_f32_e32 v19, v19
	s_nop 0
	v_rcp_f32_e32 v18, v18
	s_nop 0
	v_pk_fma_f32 v[16:17], v[18:19], v[20:21], v[16:17]
	v_mul_f32_e32 v19, 0xbfb8aa3b, v27
	v_cvt_pk_bf16_f32 v179, v16, v17
	v_mul_f32_e32 v17, 0xbfb8aa3b, v26
	v_exp_f32_e32 v18, v17
	v_exp_f32_e32 v19, v19
	v_lshlrev_b32_e32 v16, 16, v178
	v_lshlrev_b32_e32 v20, 16, v235
	v_and_b32_e32 v17, 0xffff0000, v178
	v_pk_add_f32 v[18:19], v[18:19], 1.0 op_sel_hi:[1,0]
	v_and_b32_e32 v21, 0xffff0000, v235
	v_rcp_f32_e32 v19, v19
	s_nop 0
	v_rcp_f32_e32 v18, v18
	s_nop 0
	v_pk_fma_f32 v[16:17], v[18:19], v[20:21], v[16:17]
	v_mul_f32_e32 v19, 0xbfb8aa3b, v29
	v_cvt_pk_bf16_f32 v178, v16, v17
	v_mul_f32_e32 v17, 0xbfb8aa3b, v28
	v_exp_f32_e32 v18, v17
	v_exp_f32_e32 v19, v19
	v_lshlrev_b32_e32 v16, 16, v177
	v_lshlrev_b32_e32 v20, 16, v234
	v_and_b32_e32 v17, 0xffff0000, v177
	v_pk_add_f32 v[18:19], v[18:19], 1.0 op_sel_hi:[1,0]
	v_and_b32_e32 v21, 0xffff0000, v234
	v_rcp_f32_e32 v19, v19
	s_nop 0
	v_rcp_f32_e32 v18, v18
	s_nop 0
	v_pk_fma_f32 v[16:17], v[18:19], v[20:21], v[16:17]
	v_mul_f32_e32 v19, 0xbfb8aa3b, v31
	v_cvt_pk_bf16_f32 v177, v16, v17
	v_mul_f32_e32 v17, 0xbfb8aa3b, v30
	v_exp_f32_e32 v18, v17
	v_exp_f32_e32 v19, v19
	v_lshlrev_b32_e32 v16, 16, v176
	v_lshlrev_b32_e32 v20, 16, v233
	v_and_b32_e32 v17, 0xffff0000, v176
	v_pk_add_f32 v[18:19], v[18:19], 1.0 op_sel_hi:[1,0]
	v_and_b32_e32 v21, 0xffff0000, v233
	v_rcp_f32_e32 v19, v19
	s_nop 0
	v_rcp_f32_e32 v18, v18
	s_nop 0
	v_pk_fma_f32 v[16:17], v[18:19], v[20:21], v[16:17]
	v_cvt_pk_bf16_f32 v176, v16, v17
	v_lshlrev_b32_e32 v16, 16, v175
	v_lshlrev_b32_e32 v18, 16, v232
	v_rcp_f32_e32 v1, v1
	s_nop 0
	v_and_b32_e32 v17, 0xffff0000, v175
	v_and_b32_e32 v19, 0xffff0000, v232
	v_rcp_f32_e32 v0, v0
	s_nop 0
	v_pk_fma_f32 v[0:1], v[0:1], v[18:19], v[16:17]
	v_lshlrev_b32_e32 v16, 16, v231
	v_cvt_pk_bf16_f32 v175, v0, v1
	v_mul_f32_e32 v1, 0xbfb8aa3b, v2
	v_exp_f32_e32 v2, v1
	v_lshlrev_b32_e32 v0, 16, v174
	v_and_b32_e32 v1, 0xffff0000, v174
	v_and_b32_e32 v17, 0xffff0000, v231
	v_pk_add_f32 v[2:3], v[2:3], 1.0 op_sel_hi:[1,0]
	s_nop 0
	v_rcp_f32_e32 v3, v3
	s_nop 0
	v_rcp_f32_e32 v2, v2
	s_nop 0
	v_pk_fma_f32 v[0:1], v[2:3], v[16:17], v[0:1]
	v_mul_f32_e32 v3, 0xbfb8aa3b, v5
	v_cvt_pk_bf16_f32 v174, v0, v1
	v_mul_f32_e32 v1, 0xbfb8aa3b, v4
	v_exp_f32_e32 v2, v1
	v_exp_f32_e32 v3, v3
	v_lshlrev_b32_e32 v0, 16, v173
	v_lshlrev_b32_e32 v4, 16, v230
	v_and_b32_e32 v1, 0xffff0000, v173
	v_pk_add_f32 v[2:3], v[2:3], 1.0 op_sel_hi:[1,0]
	v_and_b32_e32 v5, 0xffff0000, v230
	v_rcp_f32_e32 v3, v3
	s_nop 0
	v_rcp_f32_e32 v2, v2
	s_nop 0
	v_pk_fma_f32 v[0:1], v[2:3], v[4:5], v[0:1]
	v_mul_f32_e32 v3, 0xbfb8aa3b, v7
	v_cvt_pk_bf16_f32 v173, v0, v1
	v_mul_f32_e32 v1, 0xbfb8aa3b, v6
	v_exp_f32_e32 v2, v1
	v_exp_f32_e32 v3, v3
	v_lshlrev_b32_e32 v0, 16, v172
	v_lshlrev_b32_e32 v4, 16, v229
	v_and_b32_e32 v1, 0xffff0000, v172
	v_pk_add_f32 v[2:3], v[2:3], 1.0 op_sel_hi:[1,0]
	v_and_b32_e32 v5, 0xffff0000, v229
	v_rcp_f32_e32 v3, v3
	s_nop 0
	v_rcp_f32_e32 v2, v2
	s_nop 0
	v_pk_fma_f32 v[0:1], v[2:3], v[4:5], v[0:1]
	v_mul_f32_e32 v3, 0xbfb8aa3b, v9
	v_cvt_pk_bf16_f32 v172, v0, v1
	v_mul_f32_e32 v1, 0xbfb8aa3b, v8
	v_exp_f32_e32 v2, v1
	v_exp_f32_e32 v3, v3
	v_lshlrev_b32_e32 v0, 16, v171
	v_lshlrev_b32_e32 v4, 16, v228
	v_and_b32_e32 v1, 0xffff0000, v171
	v_pk_add_f32 v[2:3], v[2:3], 1.0 op_sel_hi:[1,0]
	v_and_b32_e32 v5, 0xffff0000, v228
	v_rcp_f32_e32 v3, v3
	s_nop 0
	v_rcp_f32_e32 v2, v2
	s_nop 0
	v_pk_fma_f32 v[0:1], v[2:3], v[4:5], v[0:1]
	v_mul_f32_e32 v3, 0xbfb8aa3b, v11
	v_cvt_pk_bf16_f32 v171, v0, v1
	v_mul_f32_e32 v1, 0xbfb8aa3b, v10
	v_exp_f32_e32 v2, v1
	v_exp_f32_e32 v3, v3
	v_lshlrev_b32_e32 v0, 16, v170
	v_lshlrev_b32_e32 v4, 16, v227
	v_and_b32_e32 v1, 0xffff0000, v170
	v_pk_add_f32 v[2:3], v[2:3], 1.0 op_sel_hi:[1,0]
	v_and_b32_e32 v5, 0xffff0000, v227
	v_rcp_f32_e32 v3, v3
	s_nop 0
	v_rcp_f32_e32 v2, v2
	s_nop 0
	v_pk_fma_f32 v[0:1], v[2:3], v[4:5], v[0:1]
	v_mul_f32_e32 v3, 0xbfb8aa3b, v13
	v_cvt_pk_bf16_f32 v170, v0, v1
	v_mul_f32_e32 v1, 0xbfb8aa3b, v12
	v_exp_f32_e32 v2, v1
	v_exp_f32_e32 v3, v3
	v_lshlrev_b32_e32 v0, 16, v169
	v_lshlrev_b32_e32 v4, 16, v226
	v_and_b32_e32 v1, 0xffff0000, v169
	v_pk_add_f32 v[2:3], v[2:3], 1.0 op_sel_hi:[1,0]
	v_and_b32_e32 v5, 0xffff0000, v226
	v_rcp_f32_e32 v3, v3
	s_nop 0
	v_rcp_f32_e32 v2, v2
	s_nop 0
	v_pk_fma_f32 v[0:1], v[2:3], v[4:5], v[0:1]
	v_mul_f32_e32 v3, 0xbfb8aa3b, v15
	v_cvt_pk_bf16_f32 v169, v0, v1
	v_mul_f32_e32 v1, 0xbfb8aa3b, v14
	v_exp_f32_e32 v4, v1
	v_exp_f32_e32 v5, v3
	v_lshlrev_b32_e32 v0, 16, v224
	v_lshlrev_b32_e32 v2, 16, v225
	v_and_b32_e32 v1, 0xffff0000, v224
	v_pk_add_f32 v[4:5], v[4:5], 1.0 op_sel_hi:[1,0]
	v_and_b32_e32 v3, 0xffff0000, v225
	v_rcp_f32_e32 v5, v5
	s_nop 0
	v_rcp_f32_e32 v4, v4
	s_nop 0
	v_pk_fma_f32 v[0:1], v[4:5], v[2:3], v[0:1]
	s_nop 0
	v_cvt_pk_bf16_f32 v224, v0, v1
	s_cbranch_scc0 .LBB0_2087
	v_add_u32_e32 v18, s4, v163
	v_or_b32_e32 v4, 2, v168
	v_or_b32_e32 v6, 8, v168
	v_or_b32_e32 v8, 10, v168
	v_or_b32_e32 v10, 16, v168
	v_or_b32_e32 v12, 18, v168
	v_or_b32_e32 v14, 24, v168
	v_or_b32_e32 v16, 26, v168
	v_or_b32_e32 v2, v18, v168
	v_or_b32_e32 v4, v18, v4
	v_or_b32_e32 v6, v18, v6
	v_or_b32_e32 v8, v18, v8
	v_or_b32_e32 v10, v18, v10
	v_or_b32_e32 v12, v18, v12
	v_or_b32_e32 v14, v18, v14
	v_or_b32_e32 v16, v18, v16
	v_ashrrev_i32_e32 v3, 31, v2
	v_ashrrev_i32_e32 v5, 31, v4
	v_ashrrev_i32_e32 v7, 31, v6
	v_ashrrev_i32_e32 v9, 31, v8
	v_ashrrev_i32_e32 v11, 31, v10
	v_ashrrev_i32_e32 v13, 31, v12
	v_ashrrev_i32_e32 v15, 31, v14
	v_ashrrev_i32_e32 v17, 31, v16
	v_lshl_add_u64 v[0:1], s[6:7], 1, v[144:145]
	v_lshlrev_b64 v[2:3], 11, v[2:3]
	v_lshlrev_b64 v[4:5], 11, v[4:5]
	v_lshlrev_b64 v[6:7], 11, v[6:7]
	v_lshlrev_b64 v[8:9], 11, v[8:9]
	v_lshlrev_b64 v[10:11], 11, v[10:11]
	v_lshlrev_b64 v[12:13], 11, v[12:13]
	v_lshlrev_b64 v[14:15], 11, v[14:15]
	v_lshlrev_b64 v[16:17], 11, v[16:17]
	v_lshl_add_u64 v[2:3], v[0:1], 0, v[2:3]
	v_lshl_add_u64 v[4:5], v[0:1], 0, v[4:5]
	v_lshl_add_u64 v[6:7], v[0:1], 0, v[6:7]
	v_lshl_add_u64 v[8:9], v[0:1], 0, v[8:9]
	v_lshl_add_u64 v[10:11], v[0:1], 0, v[10:11]
	v_lshl_add_u64 v[12:13], v[0:1], 0, v[12:13]
	v_lshl_add_u64 v[14:15], v[0:1], 0, v[14:15]
	v_lshl_add_u64 v[16:17], v[0:1], 0, v[16:17]
	global_store_short v[2:3], v223, off
	global_store_short_d16_hi v[2:3], v223, off offset:2048
	global_store_short v[4:5], v222, off
	global_store_short_d16_hi v[4:5], v222, off offset:2048
	global_store_short v[6:7], v221, off
	global_store_short_d16_hi v[6:7], v221, off offset:2048
	global_store_short v[8:9], v220, off
	global_store_short_d16_hi v[8:9], v220, off offset:2048
	global_store_short v[10:11], v219, off
	global_store_short_d16_hi v[10:11], v219, off offset:2048
	global_store_short v[12:13], v218, off
	global_store_short_d16_hi v[12:13], v218, off offset:2048
	global_store_short v[14:15], v217, off
	global_store_short_d16_hi v[14:15], v217, off offset:2048
	global_store_short v[16:17], v216, off
	global_store_short_d16_hi v[16:17], v216, off offset:2048
	global_store_short v[2:3], v215, off offset:64
	global_store_short_d16_hi v[2:3], v215, off offset:2112
	global_store_short v[4:5], v214, off offset:64
	global_store_short_d16_hi v[4:5], v214, off offset:2112
	global_store_short v[6:7], v213, off offset:64
	global_store_short_d16_hi v[6:7], v213, off offset:2112
	global_store_short v[8:9], v212, off offset:64
	global_store_short_d16_hi v[8:9], v212, off offset:2112
	global_store_short v[10:11], v211, off offset:64
	global_store_short_d16_hi v[10:11], v211, off offset:2112
	global_store_short v[12:13], v210, off offset:64
	global_store_short_d16_hi v[12:13], v210, off offset:2112
	global_store_short v[14:15], v185, off offset:64
	global_store_short_d16_hi v[14:15], v185, off offset:2112
	global_store_short v[16:17], v184, off offset:64
	global_store_short_d16_hi v[16:17], v184, off offset:2112
	v_or_b32_e32 v2, 32, v168
	v_or_b32_e32 v4, 34, v168
	v_or_b32_e32 v6, 40, v168
	v_or_b32_e32 v8, 42, v168
	v_or_b32_e32 v10, 48, v168
	v_or_b32_e32 v12, 50, v168
	v_or_b32_e32 v14, 56, v168
	v_or_b32_e32 v16, 58, v168
	v_or_b32_e32 v2, v18, v2
	v_or_b32_e32 v4, v18, v4
	v_or_b32_e32 v6, v18, v6
	v_or_b32_e32 v8, v18, v8
	v_or_b32_e32 v10, v18, v10
	v_or_b32_e32 v12, v18, v12
	v_or_b32_e32 v14, v18, v14
	v_or_b32_e32 v16, v18, v16
	v_ashrrev_i32_e32 v3, 31, v2
	v_ashrrev_i32_e32 v5, 31, v4
	v_ashrrev_i32_e32 v7, 31, v6
	v_ashrrev_i32_e32 v9, 31, v8
	v_ashrrev_i32_e32 v11, 31, v10
	v_ashrrev_i32_e32 v13, 31, v12
	v_ashrrev_i32_e32 v15, 31, v14
	v_ashrrev_i32_e32 v17, 31, v16
	v_readlane_b32 s4, v252, 22
	v_lshlrev_b64 v[2:3], 11, v[2:3]
	v_lshlrev_b64 v[4:5], 11, v[4:5]
	v_lshlrev_b64 v[6:7], 11, v[6:7]
	v_lshlrev_b64 v[8:9], 11, v[8:9]
	v_lshlrev_b64 v[10:11], 11, v[10:11]
	v_lshlrev_b64 v[12:13], 11, v[12:13]
	v_lshlrev_b64 v[14:15], 11, v[14:15]
	v_lshlrev_b64 v[16:17], 11, v[16:17]
	s_add_i32 s18, s18, s4
	v_lshl_add_u64 v[2:3], v[0:1], 0, v[2:3]
	v_lshl_add_u64 v[4:5], v[0:1], 0, v[4:5]
	v_lshl_add_u64 v[6:7], v[0:1], 0, v[6:7]
	v_lshl_add_u64 v[8:9], v[0:1], 0, v[8:9]
	v_lshl_add_u64 v[10:11], v[0:1], 0, v[10:11]
	v_lshl_add_u64 v[12:13], v[0:1], 0, v[12:13]
	v_lshl_add_u64 v[14:15], v[0:1], 0, v[14:15]
	v_lshl_add_u64 v[0:1], v[0:1], 0, v[16:17]
	s_cmp_ge_i32 s18, s24
	global_store_short v[2:3], v183, off
	global_store_short_d16_hi v[2:3], v183, off offset:2048
	global_store_short v[4:5], v182, off
	global_store_short_d16_hi v[4:5], v182, off offset:2048
	global_store_short v[6:7], v181, off
	global_store_short_d16_hi v[6:7], v181, off offset:2048
	global_store_short v[8:9], v180, off
	global_store_short_d16_hi v[8:9], v180, off offset:2048
	global_store_short v[10:11], v179, off
	global_store_short_d16_hi v[10:11], v179, off offset:2048
	global_store_short v[12:13], v178, off
	global_store_short_d16_hi v[12:13], v178, off offset:2048
	global_store_short v[14:15], v177, off
	global_store_short_d16_hi v[14:15], v177, off offset:2048
	global_store_short v[0:1], v176, off
	global_store_short_d16_hi v[0:1], v176, off offset:2048
	global_store_short v[2:3], v175, off offset:64
	global_store_short_d16_hi v[2:3], v175, off offset:2112
	global_store_short v[4:5], v174, off offset:64
	global_store_short_d16_hi v[4:5], v174, off offset:2112
	global_store_short v[6:7], v173, off offset:64
	global_store_short_d16_hi v[6:7], v173, off offset:2112
	global_store_short v[8:9], v172, off offset:64
	global_store_short_d16_hi v[8:9], v172, off offset:2112
	global_store_short v[10:11], v171, off offset:64
	global_store_short_d16_hi v[10:11], v171, off offset:2112
	global_store_short v[12:13], v170, off offset:64
	global_store_short_d16_hi v[12:13], v170, off offset:2112
	global_store_short v[14:15], v169, off offset:64
	global_store_short_d16_hi v[14:15], v169, off offset:2112
	global_store_short v[0:1], v224, off offset:64
	global_store_short_d16_hi v[0:1], v224, off offset:2112
	s_cbranch_scc0 .LBB0_2078

.LBB0_2144:
	s_lshl_b32 s4, s5, 7
	s_ashr_i32 s5, s4, 31
	s_lshl_b32 s0, s6, 7
	s_lshl_b64 s[6:7], s[4:5], 11
	v_mov_b32_e32 v0, v161
	s_add_u32 s6, s10, s6
	s_waitcnt vmcnt(8)
	v_mov_b32_e32 v49, v186
	s_addc_u32 s7, s11, s7
	s_ashr_i32 s1, s0, 31
	s_lshl_b64 s[8:9], s[0:1], 11
	v_lshlrev_b32_e32 v16, 4, v49
	v_ashrrev_i32_e32 v50, 3, v49
	v_and_b32_e32 v48, 0x70, v16
	s_add_u32 s8, s12, s8
	v_lshl_or_b32 v168, v50, 11, v48
	s_addc_u32 s9, s13, s9
	v_add_u32_e32 v169, 0x10000, v168
	v_add_u32_e32 v170, 0x20000, v168
	v_add_u32_e32 v171, 0x30000, v168
	s_barrier
	global_load_dwordx4 v[16:19], v168, s[6:7]
	global_load_dwordx4 v[20:23], v169, s[6:7]
	global_load_dwordx4 v[24:27], v170, s[6:7]
	global_load_dwordx4 v[28:31], v171, s[6:7]
	global_load_dwordx4 v[32:35], v168, s[8:9]
	global_load_dwordx4 v[36:39], v169, s[8:9]
	global_load_dwordx4 v[40:43], v170, s[8:9]
	global_load_dwordx4 v[44:47], v171, s[8:9]
	v_mad_u64_u32 v[130:131], s[16:17], v50, s43, v[48:49]
	v_mov_b32_e32 v1, v0
	v_mov_b32_e32 v2, v0
	v_mov_b32_e32 v3, v0
	v_mov_b32_e32 v4, v0
	v_mov_b32_e32 v5, v0
	v_mov_b32_e32 v6, v0
	v_mov_b32_e32 v7, v0
	s_waitcnt vmcnt(8)
	v_mov_b32_e32 v8, v0
	v_mov_b32_e32 v9, v0
	v_mov_b32_e32 v10, v0
	v_mov_b32_e32 v11, v0
	v_mov_b32_e32 v12, v0
	v_mov_b32_e32 v13, v0
	v_mov_b32_e32 v14, v0
	v_mov_b32_e32 v15, v0
	s_waitcnt vmcnt(7)
	ds_write_b128 v130, v[16:19]
	s_waitcnt vmcnt(6)
	ds_write_b128 v130, v[20:23] offset:4608
	s_waitcnt vmcnt(5)
	ds_write_b128 v130, v[24:27] offset:9216
	s_waitcnt vmcnt(4)
	ds_write_b128 v130, v[28:31] offset:13824
	s_waitcnt vmcnt(3)
	ds_write_b128 v130, v[32:35] offset:36864
	s_waitcnt vmcnt(2)
	ds_write_b128 v130, v[36:39] offset:41472
	s_waitcnt vmcnt(1)
	ds_write_b128 v130, v[40:43] offset:46080
	s_waitcnt vmcnt(0)
	ds_write_b128 v130, v[44:47] offset:50688
	global_load_dwordx4 v[96:99], v168, s[6:7] offset:128
	global_load_dwordx4 v[100:103], v169, s[6:7] offset:128
	global_load_dwordx4 v[104:107], v170, s[6:7] offset:128
	global_load_dwordx4 v[108:111], v171, s[6:7] offset:128
	global_load_dwordx4 v[64:67], v168, s[8:9] offset:128
	global_load_dwordx4 v[68:71], v169, s[8:9] offset:128
	global_load_dwordx4 v[72:75], v170, s[8:9] offset:128
	global_load_dwordx4 v[76:79], v171, s[8:9] offset:128
	v_lshrrev_b32_e32 v18, 1, v49
	v_and_b32_e32 v17, 0x5f, v49
	v_and_b32_e32 v16, 16, v18
	v_mad_u32_u24 v131, v17, s43, v16
	v_and_b32_e32 v17, 31, v49
	v_and_or_b32 v17, v18, s44, v17
	v_mad_u64_u32 v[132:133], s[16:17], v17, s43, v[16:17]
	s_waitcnt lgkmcnt(0)
	s_barrier
	ds_read_b128 v[16:19], v132
	ds_read_b128 v[84:87], v131 offset:41472
	ds_read_b128 v[80:83], v132 offset:4608
	ds_read_b128 v[172:175], v132 offset:32
	s_waitcnt lgkmcnt(2)
	v_mfma_f32_32x32x16_bf16 v[32:47], v[84:87], v[16:19], v[0:15]
	ds_read_b128 v[88:91], v131 offset:36864
	ds_read_b128 v[176:179], v132 offset:4640
	ds_read_b128 v[180:183], v131 offset:36896
	ds_read_b128 v[196:199], v131 offset:41504
	v_add_u32_e32 v133, 0xd800, v130
	s_waitcnt lgkmcnt(3)
	v_mfma_f32_32x32x16_bf16 v[48:63], v[88:91], v[16:19], v[0:15]
	v_mfma_f32_32x32x16_bf16 v[16:31], v[88:91], v[80:83], v[0:15]
	v_mfma_f32_32x32x16_bf16 v[0:15], v[84:87], v[80:83], v[0:15]
	s_waitcnt lgkmcnt(1)
	v_mfma_f32_32x32x16_bf16 v[48:63], v[180:183], v[172:175], v[48:63]
	s_waitcnt lgkmcnt(0)
	v_mfma_f32_32x32x16_bf16 v[32:47], v[196:199], v[172:175], v[32:47]
	v_mfma_f32_32x32x16_bf16 v[16:31], v[180:183], v[176:179], v[16:31]
	v_mfma_f32_32x32x16_bf16 v[0:15], v[196:199], v[176:179], v[0:15]
	ds_read_b128 v[200:203], v132 offset:64
	ds_read_b128 v[210:213], v132 offset:4672
	ds_read_b128 v[214:217], v131 offset:36928
	ds_read_b128 v[218:221], v131 offset:41536
	s_waitcnt lgkmcnt(1)
	v_mfma_f32_32x32x16_bf16 v[48:63], v[214:217], v[200:203], v[48:63]
	s_waitcnt lgkmcnt(0)
	v_mfma_f32_32x32x16_bf16 v[32:47], v[218:221], v[200:203], v[32:47]
	v_mfma_f32_32x32x16_bf16 v[16:31], v[214:217], v[210:213], v[16:31]
	v_mfma_f32_32x32x16_bf16 v[0:15], v[218:221], v[210:213], v[0:15]
	global_load_dwordx4 v[112:115], v168, s[6:7] offset:256
	global_load_dwordx4 v[116:119], v169, s[6:7] offset:256
	global_load_dwordx4 v[120:123], v170, s[6:7] offset:256
	global_load_dwordx4 v[124:127], v171, s[6:7] offset:256
	global_load_dwordx4 v[80:83], v168, s[8:9] offset:256
	global_load_dwordx4 v[84:87], v169, s[8:9] offset:256
	global_load_dwordx4 v[88:91], v170, s[8:9] offset:256
	global_load_dwordx4 v[92:95], v171, s[8:9] offset:256
	s_waitcnt vmcnt(15)
	ds_write_b128 v130, v[96:99] offset:18432
	s_waitcnt vmcnt(14)
	ds_write_b128 v130, v[100:103] offset:23040
	s_waitcnt vmcnt(13)
	ds_write_b128 v130, v[104:107] offset:27648
	s_waitcnt vmcnt(12)
	ds_write_b128 v130, v[108:111] offset:32256
	ds_read_b128 v[96:99], v132 offset:96
	ds_read_b128 v[100:103], v132 offset:4704
	ds_read_b128 v[104:107], v131 offset:36960
	ds_read_b128 v[108:111], v131 offset:41568
	s_waitcnt vmcnt(11)
	ds_write_b128 v130, v[64:67] offset:55296
	s_waitcnt vmcnt(10)
	ds_write_b128 v130, v[68:71] offset:59904
	s_waitcnt vmcnt(9)
	ds_write_b128 v130, v[72:75] offset:64512
	s_waitcnt vmcnt(8)
	ds_write_b128 v133, v[76:79] offset:13824
	s_waitcnt lgkmcnt(5)
	v_mfma_f32_32x32x16_bf16 v[48:63], v[104:107], v[96:99], v[48:63]
	s_waitcnt lgkmcnt(0)
	s_barrier
	v_mfma_f32_32x32x16_bf16 v[32:47], v[108:111], v[96:99], v[32:47]
	v_mfma_f32_32x32x16_bf16 v[16:31], v[104:107], v[100:103], v[16:31]
	v_mfma_f32_32x32x16_bf16 v[0:15], v[108:111], v[100:103], v[0:15]
	ds_read_b128 v[64:67], v132 offset:23040
	ds_read_b128 v[72:75], v132 offset:18432
	ds_read_b128 v[68:71], v131 offset:59904
	ds_read_b128 v[100:103], v131 offset:55296
	ds_read_b128 v[76:79], v132 offset:18464
	ds_read_b128 v[96:99], v132 offset:23072
	ds_read_b128 v[104:107], v131 offset:55328
	ds_read_b128 v[108:111], v131 offset:59936
	s_waitcnt lgkmcnt(4)
	v_mfma_f32_32x32x16_bf16 v[48:63], v[100:103], v[72:75], v[48:63]
	v_mfma_f32_32x32x16_bf16 v[32:47], v[68:71], v[72:75], v[32:47]
	v_mfma_f32_32x32x16_bf16 v[16:31], v[100:103], v[64:67], v[16:31]
	v_mfma_f32_32x32x16_bf16 v[0:15], v[68:71], v[64:67], v[0:15]
	global_load_dwordx4 v[64:67], v168, s[6:7] offset:384
	global_load_dwordx4 v[68:71], v169, s[6:7] offset:384
	global_load_dwordx4 v[72:75], v170, s[6:7] offset:384
	global_load_dwordx4 v[100:103], v171, s[6:7] offset:384
	global_load_dwordx4 v[172:175], v168, s[8:9] offset:384
	global_load_dwordx4 v[176:179], v169, s[8:9] offset:384
	global_load_dwordx4 v[180:183], v170, s[8:9] offset:384
	global_load_dwordx4 v[196:199], v171, s[8:9] offset:384
	ds_read_b128 v[200:203], v132 offset:18496
	ds_read_b128 v[210:213], v132 offset:23104
	ds_read_b128 v[214:217], v131 offset:55360
	ds_read_b128 v[218:221], v131 offset:59968
	s_waitcnt vmcnt(15)
	ds_write_b128 v130, v[112:115]
	s_waitcnt vmcnt(14)
	ds_write_b128 v130, v[116:119] offset:4608
	s_waitcnt vmcnt(13)
	ds_write_b128 v130, v[120:123] offset:9216
	s_waitcnt vmcnt(12)
	ds_write_b128 v130, v[124:127] offset:13824
	s_waitcnt lgkmcnt(9)
	v_mfma_f32_32x32x16_bf16 v[48:63], v[104:107], v[76:79], v[48:63]
	s_waitcnt lgkmcnt(8)
	v_mfma_f32_32x32x16_bf16 v[32:47], v[108:111], v[76:79], v[32:47]
	v_mfma_f32_32x32x16_bf16 v[16:31], v[104:107], v[96:99], v[16:31]
	v_mfma_f32_32x32x16_bf16 v[0:15], v[108:111], v[96:99], v[0:15]
	ds_read_b128 v[76:79], v132 offset:18528
	ds_read_b128 v[96:99], v132 offset:23136
	ds_read_b128 v[104:107], v131 offset:55392
	ds_read_b128 v[108:111], v131 offset:60000
	s_waitcnt vmcnt(11)
	ds_write_b128 v130, v[80:83] offset:36864
	s_waitcnt vmcnt(10)
	ds_write_b128 v130, v[84:87] offset:41472
	s_waitcnt vmcnt(9)
	ds_write_b128 v130, v[88:91] offset:46080
	s_waitcnt vmcnt(8)
	ds_write_b128 v130, v[92:95] offset:50688
	s_waitcnt lgkmcnt(13)
	v_mfma_f32_32x32x16_bf16 v[48:63], v[214:217], v[200:203], v[48:63]
	s_waitcnt lgkmcnt(0)
	s_barrier
	v_mfma_f32_32x32x16_bf16 v[32:47], v[218:221], v[200:203], v[32:47]
	v_mfma_f32_32x32x16_bf16 v[16:31], v[214:217], v[210:213], v[16:31]
	v_mfma_f32_32x32x16_bf16 v[0:15], v[218:221], v[210:213], v[0:15]
	v_mfma_f32_32x32x16_bf16 v[48:63], v[104:107], v[76:79], v[48:63]
	v_mfma_f32_32x32x16_bf16 v[32:47], v[108:111], v[76:79], v[32:47]
	v_mfma_f32_32x32x16_bf16 v[16:31], v[104:107], v[96:99], v[16:31]
	v_mfma_f32_32x32x16_bf16 v[0:15], v[108:111], v[96:99], v[0:15]
	ds_read_b128 v[76:79], v132 offset:4608
	ds_read_b128 v[84:87], v132
	ds_read_b128 v[80:83], v131 offset:41472
	ds_read_b128 v[96:99], v131 offset:36864
	ds_read_b128 v[88:91], v132 offset:32
	ds_read_b128 v[92:95], v132 offset:4640
	ds_read_b128 v[104:107], v131 offset:36896
	ds_read_b128 v[108:111], v131 offset:41504
	s_waitcnt lgkmcnt(4)
	v_mfma_f32_32x32x16_bf16 v[48:63], v[96:99], v[84:87], v[48:63]
	v_mfma_f32_32x32x16_bf16 v[32:47], v[80:83], v[84:87], v[32:47]
	v_mfma_f32_32x32x16_bf16 v[16:31], v[96:99], v[76:79], v[16:31]
	v_mfma_f32_32x32x16_bf16 v[0:15], v[80:83], v[76:79], v[0:15]
	global_load_dwordx4 v[76:79], v168, s[6:7] offset:512
	global_load_dwordx4 v[80:83], v169, s[6:7] offset:512
	global_load_dwordx4 v[84:87], v170, s[6:7] offset:512
	global_load_dwordx4 v[96:99], v171, s[6:7] offset:512
	global_load_dwordx4 v[112:115], v168, s[8:9] offset:512
	global_load_dwordx4 v[116:119], v169, s[8:9] offset:512
	global_load_dwordx4 v[120:123], v170, s[8:9] offset:512
	global_load_dwordx4 v[124:127], v171, s[8:9] offset:512
	ds_read_b128 v[200:203], v132 offset:64
	ds_read_b128 v[210:213], v132 offset:4672
	ds_read_b128 v[214:217], v131 offset:36928
	ds_read_b128 v[218:221], v131 offset:41536
	s_waitcnt vmcnt(15)
	ds_write_b128 v130, v[64:67] offset:18432
	s_waitcnt vmcnt(14)
	ds_write_b128 v130, v[68:71] offset:23040
	s_waitcnt vmcnt(13)
	ds_write_b128 v130, v[72:75] offset:27648
	s_waitcnt vmcnt(12)
	ds_write_b128 v130, v[100:103] offset:32256
	s_waitcnt lgkmcnt(9)
	v_mfma_f32_32x32x16_bf16 v[48:63], v[104:107], v[88:91], v[48:63]
	s_waitcnt lgkmcnt(8)
	v_mfma_f32_32x32x16_bf16 v[32:47], v[108:111], v[88:91], v[32:47]
	v_mfma_f32_32x32x16_bf16 v[16:31], v[104:107], v[92:95], v[16:31]
	v_mfma_f32_32x32x16_bf16 v[0:15], v[108:111], v[92:95], v[0:15]
	ds_read_b128 v[64:67], v132 offset:96
	ds_read_b128 v[68:71], v132 offset:4704
	ds_read_b128 v[72:75], v131 offset:36960
	ds_read_b128 v[88:91], v131 offset:41568
	s_waitcnt vmcnt(11)
	ds_write_b128 v130, v[172:175] offset:55296
	s_waitcnt vmcnt(10)
	ds_write_b128 v130, v[176:179] offset:59904
	s_waitcnt vmcnt(9)
	ds_write_b128 v130, v[180:183] offset:64512
	s_waitcnt vmcnt(8)
	ds_write_b128 v133, v[196:199] offset:13824
	s_waitcnt lgkmcnt(13)
	v_mfma_f32_32x32x16_bf16 v[48:63], v[214:217], v[200:203], v[48:63]
	s_waitcnt lgkmcnt(0)
	s_barrier
	v_mfma_f32_32x32x16_bf16 v[32:47], v[218:221], v[200:203], v[32:47]
	v_mfma_f32_32x32x16_bf16 v[16:31], v[214:217], v[210:213], v[16:31]
	v_mfma_f32_32x32x16_bf16 v[0:15], v[218:221], v[210:213], v[0:15]
	v_mfma_f32_32x32x16_bf16 v[48:63], v[72:75], v[64:67], v[48:63]
	v_mfma_f32_32x32x16_bf16 v[32:47], v[88:91], v[64:67], v[32:47]
	v_mfma_f32_32x32x16_bf16 v[16:31], v[72:75], v[68:71], v[16:31]
	v_mfma_f32_32x32x16_bf16 v[0:15], v[88:91], v[68:71], v[0:15]
	ds_read_b128 v[64:67], v132 offset:23040
	ds_read_b128 v[72:75], v132 offset:18432
	ds_read_b128 v[68:71], v131 offset:59904
	ds_read_b128 v[100:103], v131 offset:55296
	ds_read_b128 v[88:91], v132 offset:18464
	ds_read_b128 v[92:95], v132 offset:23072
	ds_read_b128 v[104:107], v131 offset:55328
	ds_read_b128 v[108:111], v131 offset:59936
	s_waitcnt lgkmcnt(4)
	v_mfma_f32_32x32x16_bf16 v[48:63], v[100:103], v[72:75], v[48:63]
	v_mfma_f32_32x32x16_bf16 v[32:47], v[68:71], v[72:75], v[32:47]
	v_mfma_f32_32x32x16_bf16 v[16:31], v[100:103], v[64:67], v[16:31]
	v_mfma_f32_32x32x16_bf16 v[0:15], v[68:71], v[64:67], v[0:15]
	global_load_dwordx4 v[64:67], v168, s[6:7] offset:640
	global_load_dwordx4 v[68:71], v169, s[6:7] offset:640
	global_load_dwordx4 v[72:75], v170, s[6:7] offset:640
	global_load_dwordx4 v[100:103], v171, s[6:7] offset:640
	global_load_dwordx4 v[172:175], v168, s[8:9] offset:640
	global_load_dwordx4 v[176:179], v169, s[8:9] offset:640
	global_load_dwordx4 v[180:183], v170, s[8:9] offset:640
	global_load_dwordx4 v[196:199], v171, s[8:9] offset:640
	ds_read_b128 v[200:203], v132 offset:18496
	ds_read_b128 v[210:213], v132 offset:23104
	ds_read_b128 v[214:217], v131 offset:55360
	ds_read_b128 v[218:221], v131 offset:59968
	s_waitcnt vmcnt(15)
	ds_write_b128 v130, v[76:79]
	s_waitcnt vmcnt(14)
	ds_write_b128 v130, v[80:83] offset:4608
	s_waitcnt vmcnt(13)
	ds_write_b128 v130, v[84:87] offset:9216
	s_waitcnt vmcnt(12)
	ds_write_b128 v130, v[96:99] offset:13824
	s_waitcnt lgkmcnt(9)
	v_mfma_f32_32x32x16_bf16 v[48:63], v[104:107], v[88:91], v[48:63]
	s_waitcnt lgkmcnt(8)
	v_mfma_f32_32x32x16_bf16 v[32:47], v[108:111], v[88:91], v[32:47]
	v_mfma_f32_32x32x16_bf16 v[16:31], v[104:107], v[92:95], v[16:31]
	v_mfma_f32_32x32x16_bf16 v[0:15], v[108:111], v[92:95], v[0:15]
	ds_read_b128 v[76:79], v132 offset:18528
	ds_read_b128 v[80:83], v132 offset:23136
	ds_read_b128 v[84:87], v131 offset:55392
	ds_read_b128 v[88:91], v131 offset:60000
	s_waitcnt vmcnt(11)
	ds_write_b128 v130, v[112:115] offset:36864
	s_waitcnt vmcnt(10)
	ds_write_b128 v130, v[116:119] offset:41472
	s_waitcnt vmcnt(9)
	ds_write_b128 v130, v[120:123] offset:46080
	s_waitcnt vmcnt(8)
	ds_write_b128 v130, v[124:127] offset:50688
	s_waitcnt lgkmcnt(13)
	v_mfma_f32_32x32x16_bf16 v[48:63], v[214:217], v[200:203], v[48:63]
	s_waitcnt lgkmcnt(0)
	s_barrier
	v_mfma_f32_32x32x16_bf16 v[32:47], v[218:221], v[200:203], v[32:47]
	v_mfma_f32_32x32x16_bf16 v[16:31], v[214:217], v[210:213], v[16:31]
	v_mfma_f32_32x32x16_bf16 v[0:15], v[218:221], v[210:213], v[0:15]
	v_mfma_f32_32x32x16_bf16 v[48:63], v[84:87], v[76:79], v[48:63]
	v_mfma_f32_32x32x16_bf16 v[32:47], v[88:91], v[76:79], v[32:47]
	v_mfma_f32_32x32x16_bf16 v[16:31], v[84:87], v[80:83], v[16:31]
	v_mfma_f32_32x32x16_bf16 v[0:15], v[88:91], v[80:83], v[0:15]
	ds_read_b128 v[76:79], v132 offset:4608
	ds_read_b128 v[84:87], v132
	ds_read_b128 v[80:83], v131 offset:41472
	ds_read_b128 v[96:99], v131 offset:36864
	ds_read_b128 v[88:91], v132 offset:32
	ds_read_b128 v[92:95], v132 offset:4640
	ds_read_b128 v[104:107], v131 offset:36896
	ds_read_b128 v[108:111], v131 offset:41504
	s_waitcnt lgkmcnt(4)
	v_mfma_f32_32x32x16_bf16 v[48:63], v[96:99], v[84:87], v[48:63]
	v_mfma_f32_32x32x16_bf16 v[32:47], v[80:83], v[84:87], v[32:47]
	v_mfma_f32_32x32x16_bf16 v[16:31], v[96:99], v[76:79], v[16:31]
	v_mfma_f32_32x32x16_bf16 v[0:15], v[80:83], v[76:79], v[0:15]
	global_load_dwordx4 v[76:79], v168, s[6:7] offset:768
	global_load_dwordx4 v[80:83], v169, s[6:7] offset:768
	global_load_dwordx4 v[84:87], v170, s[6:7] offset:768
	global_load_dwordx4 v[96:99], v171, s[6:7] offset:768
	global_load_dwordx4 v[112:115], v168, s[8:9] offset:768
	global_load_dwordx4 v[116:119], v169, s[8:9] offset:768
	global_load_dwordx4 v[120:123], v170, s[8:9] offset:768
	global_load_dwordx4 v[124:127], v171, s[8:9] offset:768
	ds_read_b128 v[200:203], v132 offset:64
	ds_read_b128 v[210:213], v132 offset:4672
	ds_read_b128 v[214:217], v131 offset:36928
	ds_read_b128 v[218:221], v131 offset:41536
	s_waitcnt vmcnt(15)
	ds_write_b128 v130, v[64:67] offset:18432
	s_waitcnt vmcnt(14)
	ds_write_b128 v130, v[68:71] offset:23040
	s_waitcnt vmcnt(13)
	ds_write_b128 v130, v[72:75] offset:27648
	s_waitcnt vmcnt(12)
	ds_write_b128 v130, v[100:103] offset:32256
	s_waitcnt lgkmcnt(9)
	v_mfma_f32_32x32x16_bf16 v[48:63], v[104:107], v[88:91], v[48:63]
	s_waitcnt lgkmcnt(8)
	v_mfma_f32_32x32x16_bf16 v[32:47], v[108:111], v[88:91], v[32:47]
	v_mfma_f32_32x32x16_bf16 v[16:31], v[104:107], v[92:95], v[16:31]
	v_mfma_f32_32x32x16_bf16 v[0:15], v[108:111], v[92:95], v[0:15]
	ds_read_b128 v[64:67], v132 offset:96
	ds_read_b128 v[68:71], v132 offset:4704
	ds_read_b128 v[72:75], v131 offset:36960
	ds_read_b128 v[88:91], v131 offset:41568
	s_waitcnt vmcnt(11)
	ds_write_b128 v130, v[172:175] offset:55296
	s_waitcnt vmcnt(10)
	ds_write_b128 v130, v[176:179] offset:59904
	s_waitcnt vmcnt(9)
	ds_write_b128 v130, v[180:183] offset:64512
	s_waitcnt vmcnt(8)
	ds_write_b128 v133, v[196:199] offset:13824
	s_waitcnt lgkmcnt(13)
	v_mfma_f32_32x32x16_bf16 v[48:63], v[214:217], v[200:203], v[48:63]
	s_waitcnt lgkmcnt(0)
	s_barrier
	v_mfma_f32_32x32x16_bf16 v[32:47], v[218:221], v[200:203], v[32:47]
	v_mfma_f32_32x32x16_bf16 v[16:31], v[214:217], v[210:213], v[16:31]
	v_mfma_f32_32x32x16_bf16 v[0:15], v[218:221], v[210:213], v[0:15]
	v_mfma_f32_32x32x16_bf16 v[48:63], v[72:75], v[64:67], v[48:63]
	v_mfma_f32_32x32x16_bf16 v[32:47], v[88:91], v[64:67], v[32:47]
	v_mfma_f32_32x32x16_bf16 v[16:31], v[72:75], v[68:71], v[16:31]
	v_mfma_f32_32x32x16_bf16 v[0:15], v[88:91], v[68:71], v[0:15]
	ds_read_b128 v[64:67], v132 offset:23040
	ds_read_b128 v[72:75], v132 offset:18432
	ds_read_b128 v[68:71], v131 offset:59904
	ds_read_b128 v[100:103], v131 offset:55296
	ds_read_b128 v[88:91], v132 offset:18464
	ds_read_b128 v[92:95], v132 offset:23072
	ds_read_b128 v[104:107], v131 offset:55328
	ds_read_b128 v[108:111], v131 offset:59936
	s_waitcnt lgkmcnt(4)
	v_mfma_f32_32x32x16_bf16 v[48:63], v[100:103], v[72:75], v[48:63]
	v_mfma_f32_32x32x16_bf16 v[32:47], v[68:71], v[72:75], v[32:47]
	v_mfma_f32_32x32x16_bf16 v[16:31], v[100:103], v[64:67], v[16:31]
	v_mfma_f32_32x32x16_bf16 v[0:15], v[68:71], v[64:67], v[0:15]
	global_load_dwordx4 v[64:67], v168, s[6:7] offset:896
	global_load_dwordx4 v[68:71], v169, s[6:7] offset:896
	global_load_dwordx4 v[72:75], v170, s[6:7] offset:896
	global_load_dwordx4 v[100:103], v171, s[6:7] offset:896
	global_load_dwordx4 v[172:175], v168, s[8:9] offset:896
	global_load_dwordx4 v[176:179], v169, s[8:9] offset:896
	global_load_dwordx4 v[180:183], v170, s[8:9] offset:896
	global_load_dwordx4 v[196:199], v171, s[8:9] offset:896
	ds_read_b128 v[200:203], v132 offset:18496
	ds_read_b128 v[210:213], v132 offset:23104
	ds_read_b128 v[214:217], v131 offset:55360
	ds_read_b128 v[218:221], v131 offset:59968
	s_waitcnt vmcnt(15)
	ds_write_b128 v130, v[76:79]
	s_waitcnt vmcnt(14)
	ds_write_b128 v130, v[80:83] offset:4608
	s_waitcnt vmcnt(13)
	ds_write_b128 v130, v[84:87] offset:9216
	s_waitcnt vmcnt(12)
	ds_write_b128 v130, v[96:99] offset:13824
	s_waitcnt lgkmcnt(9)
	v_mfma_f32_32x32x16_bf16 v[48:63], v[104:107], v[88:91], v[48:63]
	s_waitcnt lgkmcnt(8)
	v_mfma_f32_32x32x16_bf16 v[32:47], v[108:111], v[88:91], v[32:47]
	v_mfma_f32_32x32x16_bf16 v[16:31], v[104:107], v[92:95], v[16:31]
	v_mfma_f32_32x32x16_bf16 v[0:15], v[108:111], v[92:95], v[0:15]
	ds_read_b128 v[76:79], v132 offset:18528
	ds_read_b128 v[80:83], v132 offset:23136
	ds_read_b128 v[84:87], v131 offset:55392
	ds_read_b128 v[88:91], v131 offset:60000
	s_waitcnt vmcnt(11)
	ds_write_b128 v130, v[112:115] offset:36864
	s_waitcnt vmcnt(10)
	ds_write_b128 v130, v[116:119] offset:41472
	s_waitcnt vmcnt(9)
	ds_write_b128 v130, v[120:123] offset:46080
	s_waitcnt vmcnt(8)
	ds_write_b128 v130, v[124:127] offset:50688
	s_waitcnt lgkmcnt(13)
	v_mfma_f32_32x32x16_bf16 v[48:63], v[214:217], v[200:203], v[48:63]
	s_waitcnt lgkmcnt(0)
	s_barrier
	v_mfma_f32_32x32x16_bf16 v[32:47], v[218:221], v[200:203], v[32:47]
	v_mfma_f32_32x32x16_bf16 v[16:31], v[214:217], v[210:213], v[16:31]
	v_mfma_f32_32x32x16_bf16 v[0:15], v[218:221], v[210:213], v[0:15]
	v_mfma_f32_32x32x16_bf16 v[48:63], v[84:87], v[76:79], v[48:63]
	v_mfma_f32_32x32x16_bf16 v[32:47], v[88:91], v[76:79], v[32:47]
	v_mfma_f32_32x32x16_bf16 v[16:31], v[84:87], v[80:83], v[16:31]
	v_mfma_f32_32x32x16_bf16 v[0:15], v[88:91], v[80:83], v[0:15]
	ds_read_b128 v[76:79], v132 offset:4608
	ds_read_b128 v[84:87], v132
	ds_read_b128 v[80:83], v131 offset:41472
	ds_read_b128 v[96:99], v131 offset:36864
	ds_read_b128 v[88:91], v132 offset:32
	ds_read_b128 v[92:95], v132 offset:4640
	ds_read_b128 v[104:107], v131 offset:36896
	ds_read_b128 v[108:111], v131 offset:41504
	s_waitcnt lgkmcnt(4)
	v_mfma_f32_32x32x16_bf16 v[48:63], v[96:99], v[84:87], v[48:63]
	v_mfma_f32_32x32x16_bf16 v[32:47], v[80:83], v[84:87], v[32:47]
	v_mfma_f32_32x32x16_bf16 v[16:31], v[96:99], v[76:79], v[16:31]
	v_mfma_f32_32x32x16_bf16 v[0:15], v[80:83], v[76:79], v[0:15]
	global_load_dwordx4 v[76:79], v168, s[6:7] offset:1024
	global_load_dwordx4 v[80:83], v169, s[6:7] offset:1024
	global_load_dwordx4 v[84:87], v170, s[6:7] offset:1024
	global_load_dwordx4 v[96:99], v171, s[6:7] offset:1024
	global_load_dwordx4 v[112:115], v168, s[8:9] offset:1024
	global_load_dwordx4 v[116:119], v169, s[8:9] offset:1024
	global_load_dwordx4 v[120:123], v170, s[8:9] offset:1024
	global_load_dwordx4 v[124:127], v171, s[8:9] offset:1024
	ds_read_b128 v[200:203], v132 offset:64
	ds_read_b128 v[210:213], v132 offset:4672
	ds_read_b128 v[214:217], v131 offset:36928
	ds_read_b128 v[218:221], v131 offset:41536
	s_waitcnt vmcnt(15)
	ds_write_b128 v130, v[64:67] offset:18432
	s_waitcnt vmcnt(14)
	ds_write_b128 v130, v[68:71] offset:23040
	s_waitcnt vmcnt(13)
	ds_write_b128 v130, v[72:75] offset:27648
	s_waitcnt vmcnt(12)
	ds_write_b128 v130, v[100:103] offset:32256
	s_waitcnt lgkmcnt(9)
	v_mfma_f32_32x32x16_bf16 v[48:63], v[104:107], v[88:91], v[48:63]
	s_waitcnt lgkmcnt(8)
	v_mfma_f32_32x32x16_bf16 v[32:47], v[108:111], v[88:91], v[32:47]
	v_mfma_f32_32x32x16_bf16 v[16:31], v[104:107], v[92:95], v[16:31]
	v_mfma_f32_32x32x16_bf16 v[0:15], v[108:111], v[92:95], v[0:15]
	ds_read_b128 v[64:67], v132 offset:96
	ds_read_b128 v[68:71], v132 offset:4704
	ds_read_b128 v[72:75], v131 offset:36960
	ds_read_b128 v[88:91], v131 offset:41568
	s_waitcnt vmcnt(11)
	ds_write_b128 v130, v[172:175] offset:55296
	s_waitcnt vmcnt(10)
	ds_write_b128 v130, v[176:179] offset:59904
	s_waitcnt vmcnt(9)
	ds_write_b128 v130, v[180:183] offset:64512
	s_waitcnt vmcnt(8)
	ds_write_b128 v133, v[196:199] offset:13824
	s_waitcnt lgkmcnt(13)
	v_mfma_f32_32x32x16_bf16 v[48:63], v[214:217], v[200:203], v[48:63]
	s_waitcnt lgkmcnt(0)
	s_barrier
	v_mfma_f32_32x32x16_bf16 v[32:47], v[218:221], v[200:203], v[32:47]
	v_mfma_f32_32x32x16_bf16 v[16:31], v[214:217], v[210:213], v[16:31]
	v_mfma_f32_32x32x16_bf16 v[0:15], v[218:221], v[210:213], v[0:15]
	v_mfma_f32_32x32x16_bf16 v[48:63], v[72:75], v[64:67], v[48:63]
	v_mfma_f32_32x32x16_bf16 v[32:47], v[88:91], v[64:67], v[32:47]
	v_mfma_f32_32x32x16_bf16 v[16:31], v[72:75], v[68:71], v[16:31]
	v_mfma_f32_32x32x16_bf16 v[0:15], v[88:91], v[68:71], v[0:15]
	ds_read_b128 v[64:67], v132 offset:23040
	ds_read_b128 v[72:75], v132 offset:18432
	ds_read_b128 v[68:71], v131 offset:59904
	ds_read_b128 v[100:103], v131 offset:55296
	ds_read_b128 v[88:91], v132 offset:18464
	ds_read_b128 v[92:95], v132 offset:23072
	ds_read_b128 v[104:107], v131 offset:55328
	ds_read_b128 v[108:111], v131 offset:59936
	s_waitcnt lgkmcnt(4)
	v_mfma_f32_32x32x16_bf16 v[48:63], v[100:103], v[72:75], v[48:63]
	v_mfma_f32_32x32x16_bf16 v[32:47], v[68:71], v[72:75], v[32:47]
	v_mfma_f32_32x32x16_bf16 v[16:31], v[100:103], v[64:67], v[16:31]
	v_mfma_f32_32x32x16_bf16 v[0:15], v[68:71], v[64:67], v[0:15]
	global_load_dwordx4 v[64:67], v168, s[6:7] offset:1152
	global_load_dwordx4 v[68:71], v169, s[6:7] offset:1152
	global_load_dwordx4 v[72:75], v170, s[6:7] offset:1152
	global_load_dwordx4 v[100:103], v171, s[6:7] offset:1152
	global_load_dwordx4 v[172:175], v168, s[8:9] offset:1152
	global_load_dwordx4 v[176:179], v169, s[8:9] offset:1152
	global_load_dwordx4 v[180:183], v170, s[8:9] offset:1152
	global_load_dwordx4 v[196:199], v171, s[8:9] offset:1152
	ds_read_b128 v[200:203], v132 offset:18496
	ds_read_b128 v[210:213], v132 offset:23104
	ds_read_b128 v[214:217], v131 offset:55360
	ds_read_b128 v[218:221], v131 offset:59968
	s_waitcnt vmcnt(15)
	ds_write_b128 v130, v[76:79]
	s_waitcnt vmcnt(14)
	ds_write_b128 v130, v[80:83] offset:4608
	s_waitcnt vmcnt(13)
	ds_write_b128 v130, v[84:87] offset:9216
	s_waitcnt vmcnt(12)
	ds_write_b128 v130, v[96:99] offset:13824
	s_waitcnt lgkmcnt(9)
	v_mfma_f32_32x32x16_bf16 v[48:63], v[104:107], v[88:91], v[48:63]
	s_waitcnt lgkmcnt(8)
	v_mfma_f32_32x32x16_bf16 v[32:47], v[108:111], v[88:91], v[32:47]
	v_mfma_f32_32x32x16_bf16 v[16:31], v[104:107], v[92:95], v[16:31]
	v_mfma_f32_32x32x16_bf16 v[0:15], v[108:111], v[92:95], v[0:15]
	ds_read_b128 v[76:79], v132 offset:18528
	ds_read_b128 v[80:83], v132 offset:23136
	ds_read_b128 v[84:87], v131 offset:55392
	ds_read_b128 v[88:91], v131 offset:60000
	s_waitcnt vmcnt(11)
	ds_write_b128 v130, v[112:115] offset:36864
	s_waitcnt vmcnt(10)
	ds_write_b128 v130, v[116:119] offset:41472
	s_waitcnt vmcnt(9)
	ds_write_b128 v130, v[120:123] offset:46080
	s_waitcnt vmcnt(8)
	ds_write_b128 v130, v[124:127] offset:50688
	s_waitcnt lgkmcnt(13)
	v_mfma_f32_32x32x16_bf16 v[48:63], v[214:217], v[200:203], v[48:63]
	s_waitcnt lgkmcnt(0)
	s_barrier
	v_mfma_f32_32x32x16_bf16 v[32:47], v[218:221], v[200:203], v[32:47]
	v_mfma_f32_32x32x16_bf16 v[16:31], v[214:217], v[210:213], v[16:31]
	v_mfma_f32_32x32x16_bf16 v[0:15], v[218:221], v[210:213], v[0:15]
	v_mfma_f32_32x32x16_bf16 v[48:63], v[84:87], v[76:79], v[48:63]
	v_mfma_f32_32x32x16_bf16 v[32:47], v[88:91], v[76:79], v[32:47]
	v_mfma_f32_32x32x16_bf16 v[16:31], v[84:87], v[80:83], v[16:31]
	v_mfma_f32_32x32x16_bf16 v[0:15], v[88:91], v[80:83], v[0:15]
	ds_read_b128 v[76:79], v132 offset:4608
	ds_read_b128 v[84:87], v132
	ds_read_b128 v[80:83], v131 offset:41472
	ds_read_b128 v[96:99], v131 offset:36864
	ds_read_b128 v[88:91], v132 offset:32
	ds_read_b128 v[92:95], v132 offset:4640
	ds_read_b128 v[104:107], v131 offset:36896
	ds_read_b128 v[108:111], v131 offset:41504
	s_waitcnt lgkmcnt(4)
	v_mfma_f32_32x32x16_bf16 v[48:63], v[96:99], v[84:87], v[48:63]
	v_mfma_f32_32x32x16_bf16 v[32:47], v[80:83], v[84:87], v[32:47]
	v_mfma_f32_32x32x16_bf16 v[16:31], v[96:99], v[76:79], v[16:31]
	v_mfma_f32_32x32x16_bf16 v[0:15], v[80:83], v[76:79], v[0:15]
	global_load_dwordx4 v[76:79], v168, s[6:7] offset:1280
	global_load_dwordx4 v[80:83], v169, s[6:7] offset:1280
	global_load_dwordx4 v[84:87], v170, s[6:7] offset:1280
	global_load_dwordx4 v[96:99], v171, s[6:7] offset:1280
	global_load_dwordx4 v[112:115], v168, s[8:9] offset:1280
	global_load_dwordx4 v[116:119], v169, s[8:9] offset:1280
	global_load_dwordx4 v[120:123], v170, s[8:9] offset:1280
	global_load_dwordx4 v[124:127], v171, s[8:9] offset:1280
	ds_read_b128 v[200:203], v132 offset:64
	ds_read_b128 v[210:213], v132 offset:4672
	ds_read_b128 v[214:217], v131 offset:36928
	ds_read_b128 v[218:221], v131 offset:41536
	s_waitcnt vmcnt(15)
	ds_write_b128 v130, v[64:67] offset:18432
	s_waitcnt vmcnt(14)
	ds_write_b128 v130, v[68:71] offset:23040
	s_waitcnt vmcnt(13)
	ds_write_b128 v130, v[72:75] offset:27648
	s_waitcnt vmcnt(12)
	ds_write_b128 v130, v[100:103] offset:32256
	s_waitcnt lgkmcnt(9)
	v_mfma_f32_32x32x16_bf16 v[48:63], v[104:107], v[88:91], v[48:63]
	s_waitcnt lgkmcnt(8)
	v_mfma_f32_32x32x16_bf16 v[32:47], v[108:111], v[88:91], v[32:47]
	v_mfma_f32_32x32x16_bf16 v[16:31], v[104:107], v[92:95], v[16:31]
	v_mfma_f32_32x32x16_bf16 v[0:15], v[108:111], v[92:95], v[0:15]
	ds_read_b128 v[64:67], v132 offset:96
	ds_read_b128 v[68:71], v132 offset:4704
	ds_read_b128 v[72:75], v131 offset:36960
	ds_read_b128 v[88:91], v131 offset:41568
	s_waitcnt vmcnt(11)
	ds_write_b128 v130, v[172:175] offset:55296
	s_waitcnt vmcnt(10)
	ds_write_b128 v130, v[176:179] offset:59904
	s_waitcnt vmcnt(9)
	ds_write_b128 v130, v[180:183] offset:64512
	s_waitcnt vmcnt(8)
	ds_write_b128 v133, v[196:199] offset:13824
	s_waitcnt lgkmcnt(13)
	v_mfma_f32_32x32x16_bf16 v[48:63], v[214:217], v[200:203], v[48:63]
	s_waitcnt lgkmcnt(0)
	s_barrier
	v_mfma_f32_32x32x16_bf16 v[32:47], v[218:221], v[200:203], v[32:47]
	v_mfma_f32_32x32x16_bf16 v[16:31], v[214:217], v[210:213], v[16:31]
	v_mfma_f32_32x32x16_bf16 v[0:15], v[218:221], v[210:213], v[0:15]
	v_mfma_f32_32x32x16_bf16 v[48:63], v[72:75], v[64:67], v[48:63]
	v_mfma_f32_32x32x16_bf16 v[32:47], v[88:91], v[64:67], v[32:47]
	v_mfma_f32_32x32x16_bf16 v[16:31], v[72:75], v[68:71], v[16:31]
	v_mfma_f32_32x32x16_bf16 v[0:15], v[88:91], v[68:71], v[0:15]
	ds_read_b128 v[64:67], v132 offset:23040
	ds_read_b128 v[72:75], v132 offset:18432
	ds_read_b128 v[68:71], v131 offset:59904
	ds_read_b128 v[100:103], v131 offset:55296
	ds_read_b128 v[88:91], v132 offset:18464
	ds_read_b128 v[92:95], v132 offset:23072
	ds_read_b128 v[104:107], v131 offset:55328
	ds_read_b128 v[108:111], v131 offset:59936
	s_waitcnt lgkmcnt(4)
	v_mfma_f32_32x32x16_bf16 v[48:63], v[100:103], v[72:75], v[48:63]
	v_mfma_f32_32x32x16_bf16 v[32:47], v[68:71], v[72:75], v[32:47]
	v_mfma_f32_32x32x16_bf16 v[16:31], v[100:103], v[64:67], v[16:31]
	v_mfma_f32_32x32x16_bf16 v[0:15], v[68:71], v[64:67], v[0:15]
	global_load_dwordx4 v[64:67], v168, s[6:7] offset:1408
	global_load_dwordx4 v[68:71], v169, s[6:7] offset:1408
	global_load_dwordx4 v[72:75], v170, s[6:7] offset:1408
	global_load_dwordx4 v[100:103], v171, s[6:7] offset:1408
	global_load_dwordx4 v[172:175], v168, s[8:9] offset:1408
	global_load_dwordx4 v[176:179], v169, s[8:9] offset:1408
	global_load_dwordx4 v[180:183], v170, s[8:9] offset:1408
	global_load_dwordx4 v[196:199], v171, s[8:9] offset:1408
	ds_read_b128 v[200:203], v132 offset:18496
	ds_read_b128 v[210:213], v132 offset:23104
	ds_read_b128 v[214:217], v131 offset:55360
	ds_read_b128 v[218:221], v131 offset:59968
	s_waitcnt vmcnt(15)
	ds_write_b128 v130, v[76:79]
	s_waitcnt vmcnt(14)
	ds_write_b128 v130, v[80:83] offset:4608
	s_waitcnt vmcnt(13)
	ds_write_b128 v130, v[84:87] offset:9216
	s_waitcnt vmcnt(12)
	ds_write_b128 v130, v[96:99] offset:13824
	s_waitcnt lgkmcnt(9)
	v_mfma_f32_32x32x16_bf16 v[48:63], v[104:107], v[88:91], v[48:63]
	s_waitcnt lgkmcnt(8)
	v_mfma_f32_32x32x16_bf16 v[32:47], v[108:111], v[88:91], v[32:47]
	v_mfma_f32_32x32x16_bf16 v[16:31], v[104:107], v[92:95], v[16:31]
	v_mfma_f32_32x32x16_bf16 v[0:15], v[108:111], v[92:95], v[0:15]
	ds_read_b128 v[76:79], v132 offset:18528
	ds_read_b128 v[80:83], v132 offset:23136
	ds_read_b128 v[84:87], v131 offset:55392
	ds_read_b128 v[88:91], v131 offset:60000
	s_waitcnt vmcnt(11)
	ds_write_b128 v130, v[112:115] offset:36864
	s_waitcnt vmcnt(10)
	ds_write_b128 v130, v[116:119] offset:41472
	s_waitcnt vmcnt(9)
	ds_write_b128 v130, v[120:123] offset:46080
	s_waitcnt vmcnt(8)
	ds_write_b128 v130, v[124:127] offset:50688
	s_waitcnt lgkmcnt(13)
	v_mfma_f32_32x32x16_bf16 v[48:63], v[214:217], v[200:203], v[48:63]
	s_waitcnt lgkmcnt(0)
	s_barrier
	v_mfma_f32_32x32x16_bf16 v[32:47], v[218:221], v[200:203], v[32:47]
	v_mfma_f32_32x32x16_bf16 v[16:31], v[214:217], v[210:213], v[16:31]
	v_mfma_f32_32x32x16_bf16 v[0:15], v[218:221], v[210:213], v[0:15]
	v_mfma_f32_32x32x16_bf16 v[48:63], v[84:87], v[76:79], v[48:63]
	v_mfma_f32_32x32x16_bf16 v[32:47], v[88:91], v[76:79], v[32:47]
	v_mfma_f32_32x32x16_bf16 v[16:31], v[84:87], v[80:83], v[16:31]
	v_mfma_f32_32x32x16_bf16 v[0:15], v[88:91], v[80:83], v[0:15]
	ds_read_b128 v[76:79], v132 offset:4608
	ds_read_b128 v[84:87], v132
	ds_read_b128 v[80:83], v131 offset:41472
	ds_read_b128 v[96:99], v131 offset:36864
	ds_read_b128 v[88:91], v132 offset:32
	ds_read_b128 v[92:95], v132 offset:4640
	ds_read_b128 v[104:107], v131 offset:36896
	ds_read_b128 v[108:111], v131 offset:41504
	s_waitcnt lgkmcnt(4)
	v_mfma_f32_32x32x16_bf16 v[48:63], v[96:99], v[84:87], v[48:63]
	v_mfma_f32_32x32x16_bf16 v[32:47], v[80:83], v[84:87], v[32:47]
	v_mfma_f32_32x32x16_bf16 v[16:31], v[96:99], v[76:79], v[16:31]
	v_mfma_f32_32x32x16_bf16 v[0:15], v[80:83], v[76:79], v[0:15]
	global_load_dwordx4 v[76:79], v168, s[6:7] offset:1536
	global_load_dwordx4 v[80:83], v169, s[6:7] offset:1536
	global_load_dwordx4 v[84:87], v170, s[6:7] offset:1536
	global_load_dwordx4 v[96:99], v171, s[6:7] offset:1536
	global_load_dwordx4 v[112:115], v168, s[8:9] offset:1536
	global_load_dwordx4 v[116:119], v169, s[8:9] offset:1536
	global_load_dwordx4 v[120:123], v170, s[8:9] offset:1536
	global_load_dwordx4 v[124:127], v171, s[8:9] offset:1536
	ds_read_b128 v[200:203], v132 offset:64
	ds_read_b128 v[210:213], v132 offset:4672
	ds_read_b128 v[214:217], v131 offset:36928
	ds_read_b128 v[218:221], v131 offset:41536
	s_waitcnt vmcnt(15)
	ds_write_b128 v130, v[64:67] offset:18432
	s_waitcnt vmcnt(14)
	ds_write_b128 v130, v[68:71] offset:23040
	s_waitcnt vmcnt(13)
	ds_write_b128 v130, v[72:75] offset:27648
	s_waitcnt vmcnt(12)
	ds_write_b128 v130, v[100:103] offset:32256
	s_waitcnt lgkmcnt(9)
	v_mfma_f32_32x32x16_bf16 v[48:63], v[104:107], v[88:91], v[48:63]
	s_waitcnt lgkmcnt(8)
	v_mfma_f32_32x32x16_bf16 v[32:47], v[108:111], v[88:91], v[32:47]
	v_mfma_f32_32x32x16_bf16 v[16:31], v[104:107], v[92:95], v[16:31]
	v_mfma_f32_32x32x16_bf16 v[0:15], v[108:111], v[92:95], v[0:15]
	ds_read_b128 v[64:67], v132 offset:96
	ds_read_b128 v[68:71], v132 offset:4704
	ds_read_b128 v[72:75], v131 offset:36960
	ds_read_b128 v[88:91], v131 offset:41568
	s_waitcnt vmcnt(11)
	ds_write_b128 v130, v[172:175] offset:55296
	s_waitcnt vmcnt(10)
	ds_write_b128 v130, v[176:179] offset:59904
	s_waitcnt vmcnt(9)
	ds_write_b128 v130, v[180:183] offset:64512
	s_waitcnt vmcnt(8)
	ds_write_b128 v133, v[196:199] offset:13824
	s_waitcnt lgkmcnt(13)
	v_mfma_f32_32x32x16_bf16 v[48:63], v[214:217], v[200:203], v[48:63]
	s_waitcnt lgkmcnt(0)
	s_barrier
	v_mfma_f32_32x32x16_bf16 v[32:47], v[218:221], v[200:203], v[32:47]
	v_mfma_f32_32x32x16_bf16 v[16:31], v[214:217], v[210:213], v[16:31]
	v_mfma_f32_32x32x16_bf16 v[0:15], v[218:221], v[210:213], v[0:15]
	v_mfma_f32_32x32x16_bf16 v[48:63], v[72:75], v[64:67], v[48:63]
	v_mfma_f32_32x32x16_bf16 v[32:47], v[88:91], v[64:67], v[32:47]
	v_mfma_f32_32x32x16_bf16 v[16:31], v[72:75], v[68:71], v[16:31]
	v_mfma_f32_32x32x16_bf16 v[0:15], v[88:91], v[68:71], v[0:15]
	ds_read_b128 v[64:67], v132 offset:23040
	ds_read_b128 v[72:75], v132 offset:18432
	ds_read_b128 v[68:71], v131 offset:59904
	ds_read_b128 v[100:103], v131 offset:55296
	ds_read_b128 v[88:91], v132 offset:18464
	ds_read_b128 v[92:95], v132 offset:23072
	ds_read_b128 v[104:107], v131 offset:55328
	ds_read_b128 v[108:111], v131 offset:59936
	s_waitcnt lgkmcnt(4)
	v_mfma_f32_32x32x16_bf16 v[48:63], v[100:103], v[72:75], v[48:63]
	v_mfma_f32_32x32x16_bf16 v[32:47], v[68:71], v[72:75], v[32:47]
	v_mfma_f32_32x32x16_bf16 v[16:31], v[100:103], v[64:67], v[16:31]
	v_mfma_f32_32x32x16_bf16 v[0:15], v[68:71], v[64:67], v[0:15]
	global_load_dwordx4 v[64:67], v168, s[6:7] offset:1664
	global_load_dwordx4 v[68:71], v169, s[6:7] offset:1664
	global_load_dwordx4 v[72:75], v170, s[6:7] offset:1664
	global_load_dwordx4 v[100:103], v171, s[6:7] offset:1664
	global_load_dwordx4 v[172:175], v168, s[8:9] offset:1664
	global_load_dwordx4 v[176:179], v169, s[8:9] offset:1664
	global_load_dwordx4 v[180:183], v170, s[8:9] offset:1664
	global_load_dwordx4 v[196:199], v171, s[8:9] offset:1664
	ds_read_b128 v[200:203], v132 offset:18496
	ds_read_b128 v[210:213], v132 offset:23104
	ds_read_b128 v[214:217], v131 offset:55360
	ds_read_b128 v[218:221], v131 offset:59968
	s_waitcnt vmcnt(15)
	ds_write_b128 v130, v[76:79]
	s_waitcnt vmcnt(14)
	ds_write_b128 v130, v[80:83] offset:4608
	s_waitcnt vmcnt(13)
	ds_write_b128 v130, v[84:87] offset:9216
	s_waitcnt vmcnt(12)
	ds_write_b128 v130, v[96:99] offset:13824
	s_waitcnt lgkmcnt(9)
	v_mfma_f32_32x32x16_bf16 v[48:63], v[104:107], v[88:91], v[48:63]
	s_waitcnt lgkmcnt(8)
	v_mfma_f32_32x32x16_bf16 v[32:47], v[108:111], v[88:91], v[32:47]
	v_mfma_f32_32x32x16_bf16 v[16:31], v[104:107], v[92:95], v[16:31]
	v_mfma_f32_32x32x16_bf16 v[0:15], v[108:111], v[92:95], v[0:15]
	ds_read_b128 v[76:79], v132 offset:18528
	ds_read_b128 v[80:83], v132 offset:23136
	ds_read_b128 v[84:87], v131 offset:55392
	ds_read_b128 v[88:91], v131 offset:60000
	s_waitcnt vmcnt(11)
	ds_write_b128 v130, v[112:115] offset:36864
	s_waitcnt vmcnt(10)
	ds_write_b128 v130, v[116:119] offset:41472
	s_waitcnt vmcnt(9)
	ds_write_b128 v130, v[120:123] offset:46080
	s_waitcnt vmcnt(8)
	ds_write_b128 v130, v[124:127] offset:50688
	s_waitcnt lgkmcnt(13)
	v_mfma_f32_32x32x16_bf16 v[48:63], v[214:217], v[200:203], v[48:63]
	s_waitcnt lgkmcnt(0)
	s_barrier
	v_mfma_f32_32x32x16_bf16 v[32:47], v[218:221], v[200:203], v[32:47]
	v_mfma_f32_32x32x16_bf16 v[16:31], v[214:217], v[210:213], v[16:31]
	v_mfma_f32_32x32x16_bf16 v[0:15], v[218:221], v[210:213], v[0:15]
	v_mfma_f32_32x32x16_bf16 v[48:63], v[84:87], v[76:79], v[48:63]
	v_mfma_f32_32x32x16_bf16 v[32:47], v[88:91], v[76:79], v[32:47]
	v_mfma_f32_32x32x16_bf16 v[16:31], v[84:87], v[80:83], v[16:31]
	v_mfma_f32_32x32x16_bf16 v[0:15], v[88:91], v[80:83], v[0:15]
	ds_read_b128 v[76:79], v132 offset:4608
	ds_read_b128 v[84:87], v132
	ds_read_b128 v[80:83], v131 offset:41472
	ds_read_b128 v[96:99], v131 offset:36864
	ds_read_b128 v[88:91], v132 offset:32
	ds_read_b128 v[92:95], v132 offset:4640
	ds_read_b128 v[104:107], v131 offset:36896
	ds_read_b128 v[108:111], v131 offset:41504
	s_waitcnt lgkmcnt(4)
	v_mfma_f32_32x32x16_bf16 v[48:63], v[96:99], v[84:87], v[48:63]
	v_mfma_f32_32x32x16_bf16 v[32:47], v[80:83], v[84:87], v[32:47]
	v_mfma_f32_32x32x16_bf16 v[16:31], v[96:99], v[76:79], v[16:31]
	v_mfma_f32_32x32x16_bf16 v[0:15], v[80:83], v[76:79], v[0:15]
	global_load_dwordx4 v[76:79], v168, s[6:7] offset:1792
	global_load_dwordx4 v[80:83], v169, s[6:7] offset:1792
	global_load_dwordx4 v[84:87], v170, s[6:7] offset:1792
	global_load_dwordx4 v[96:99], v171, s[6:7] offset:1792
	global_load_dwordx4 v[112:115], v168, s[8:9] offset:1792
	global_load_dwordx4 v[116:119], v169, s[8:9] offset:1792
	global_load_dwordx4 v[120:123], v170, s[8:9] offset:1792
	global_load_dwordx4 v[124:127], v171, s[8:9] offset:1792
	ds_read_b128 v[200:203], v132 offset:64
	ds_read_b128 v[210:213], v132 offset:4672
	ds_read_b128 v[214:217], v131 offset:36928
	ds_read_b128 v[218:221], v131 offset:41536
	s_waitcnt vmcnt(15)
	ds_write_b128 v130, v[64:67] offset:18432
	s_waitcnt vmcnt(14)
	ds_write_b128 v130, v[68:71] offset:23040
	s_waitcnt vmcnt(13)
	ds_write_b128 v130, v[72:75] offset:27648
	s_waitcnt vmcnt(12)
	ds_write_b128 v130, v[100:103] offset:32256
	s_waitcnt lgkmcnt(9)
	v_mfma_f32_32x32x16_bf16 v[48:63], v[104:107], v[88:91], v[48:63]
	s_waitcnt lgkmcnt(8)
	v_mfma_f32_32x32x16_bf16 v[32:47], v[108:111], v[88:91], v[32:47]
	v_mfma_f32_32x32x16_bf16 v[16:31], v[104:107], v[92:95], v[16:31]
	v_mfma_f32_32x32x16_bf16 v[0:15], v[108:111], v[92:95], v[0:15]
	ds_read_b128 v[64:67], v132 offset:96
	ds_read_b128 v[68:71], v132 offset:4704
	ds_read_b128 v[72:75], v131 offset:36960
	ds_read_b128 v[88:91], v131 offset:41568
	s_waitcnt vmcnt(11)
	ds_write_b128 v130, v[172:175] offset:55296
	s_waitcnt vmcnt(10)
	ds_write_b128 v130, v[176:179] offset:59904
	s_waitcnt vmcnt(9)
	ds_write_b128 v130, v[180:183] offset:64512
	s_waitcnt vmcnt(8)
	ds_write_b128 v133, v[196:199] offset:13824
	s_waitcnt lgkmcnt(13)
	v_mfma_f32_32x32x16_bf16 v[48:63], v[214:217], v[200:203], v[48:63]
	s_waitcnt lgkmcnt(0)
	s_barrier
	v_mfma_f32_32x32x16_bf16 v[32:47], v[218:221], v[200:203], v[32:47]
	v_mfma_f32_32x32x16_bf16 v[16:31], v[214:217], v[210:213], v[16:31]
	v_mfma_f32_32x32x16_bf16 v[0:15], v[218:221], v[210:213], v[0:15]
	v_mfma_f32_32x32x16_bf16 v[48:63], v[72:75], v[64:67], v[48:63]
	v_mfma_f32_32x32x16_bf16 v[32:47], v[88:91], v[64:67], v[32:47]
	v_mfma_f32_32x32x16_bf16 v[16:31], v[72:75], v[68:71], v[16:31]
	v_mfma_f32_32x32x16_bf16 v[0:15], v[88:91], v[68:71], v[0:15]
	ds_read_b128 v[64:67], v132 offset:23040
	ds_read_b128 v[72:75], v132 offset:18432
	ds_read_b128 v[68:71], v131 offset:59904
	ds_read_b128 v[100:103], v131 offset:55296
	ds_read_b128 v[88:91], v132 offset:18464
	ds_read_b128 v[92:95], v132 offset:23072
	ds_read_b128 v[104:107], v131 offset:55328
	ds_read_b128 v[108:111], v131 offset:59936
	s_waitcnt lgkmcnt(4)
	v_mfma_f32_32x32x16_bf16 v[48:63], v[100:103], v[72:75], v[48:63]
	v_mfma_f32_32x32x16_bf16 v[32:47], v[68:71], v[72:75], v[32:47]
	v_mfma_f32_32x32x16_bf16 v[16:31], v[100:103], v[64:67], v[16:31]
	v_mfma_f32_32x32x16_bf16 v[0:15], v[68:71], v[64:67], v[0:15]
	global_load_dwordx4 v[64:67], v168, s[6:7] offset:1920
	global_load_dwordx4 v[68:71], v169, s[6:7] offset:1920
	global_load_dwordx4 v[72:75], v170, s[6:7] offset:1920
	global_load_dwordx4 v[100:103], v171, s[6:7] offset:1920
	global_load_dwordx4 v[172:175], v168, s[8:9] offset:1920
	global_load_dwordx4 v[176:179], v169, s[8:9] offset:1920
	global_load_dwordx4 v[180:183], v170, s[8:9] offset:1920
	s_nop 0
	global_load_dwordx4 v[168:171], v171, s[8:9] offset:1920
	ds_read_b128 v[196:199], v132 offset:18496
	ds_read_b128 v[200:203], v132 offset:23104
	ds_read_b128 v[210:213], v131 offset:55360
	ds_read_b128 v[214:217], v131 offset:59968
	s_waitcnt vmcnt(15)
	ds_write_b128 v130, v[76:79]
	s_waitcnt vmcnt(14)
	ds_write_b128 v130, v[80:83] offset:4608
	s_waitcnt vmcnt(13)
	ds_write_b128 v130, v[84:87] offset:9216
	s_waitcnt vmcnt(12)
	ds_write_b128 v130, v[96:99] offset:13824
	s_waitcnt lgkmcnt(9)
	v_mfma_f32_32x32x16_bf16 v[48:63], v[104:107], v[88:91], v[48:63]
	s_waitcnt lgkmcnt(8)
	v_mfma_f32_32x32x16_bf16 v[32:47], v[108:111], v[88:91], v[32:47]
	v_mfma_f32_32x32x16_bf16 v[0:15], v[108:111], v[92:95], v[0:15]
	v_mfma_f32_32x32x16_bf16 v[16:31], v[104:107], v[92:95], v[16:31]
	ds_read_b128 v[76:79], v132 offset:18528
	ds_read_b128 v[80:83], v132 offset:23136
	ds_read_b128 v[84:87], v131 offset:55392
	ds_read_b128 v[88:91], v131 offset:60000
	s_waitcnt vmcnt(11)
	ds_write_b128 v130, v[112:115] offset:36864
	s_waitcnt vmcnt(10)
	ds_write_b128 v130, v[116:119] offset:41472
	s_waitcnt vmcnt(9)
	ds_write_b128 v130, v[120:123] offset:46080
	s_waitcnt vmcnt(8)
	ds_write_b128 v130, v[124:127] offset:50688
	s_waitcnt lgkmcnt(13)
	v_mfma_f32_32x32x16_bf16 v[48:63], v[210:213], v[196:199], v[48:63]
	s_waitcnt lgkmcnt(0)
	s_barrier
	ds_read_b128 v[92:95], v132
	ds_read_b128 v[96:99], v132 offset:32
	ds_read_b128 v[104:107], v131 offset:36928
	ds_read_b128 v[108:111], v131 offset:41536
	v_mfma_f32_32x32x16_bf16 v[32:47], v[214:217], v[196:199], v[32:47]
	v_mfma_f32_32x32x16_bf16 v[0:15], v[214:217], v[200:203], v[0:15]
	v_mfma_f32_32x32x16_bf16 v[16:31], v[210:213], v[200:203], v[16:31]
	v_mfma_f32_32x32x16_bf16 v[48:63], v[84:87], v[76:79], v[48:63]
	v_mfma_f32_32x32x16_bf16 v[32:47], v[88:91], v[76:79], v[32:47]
	ds_read_b128 v[76:79], v132 offset:4608
	v_mfma_f32_32x32x16_bf16 v[0:15], v[88:91], v[80:83], v[0:15]
	ds_read_b128 v[88:91], v131 offset:36896
	v_mfma_f32_32x32x16_bf16 v[16:31], v[84:87], v[80:83], v[16:31]
	ds_read_b128 v[80:83], v131 offset:41472
	ds_read_b128 v[84:87], v131 offset:36864
	s_waitcnt lgkmcnt(1)
	v_mfma_f32_32x32x16_bf16 v[32:47], v[80:83], v[92:95], v[32:47]
	v_mfma_f32_32x32x16_bf16 v[0:15], v[80:83], v[76:79], v[0:15]
	ds_read_b128 v[80:83], v132 offset:4640
	s_waitcnt lgkmcnt(1)
	v_mfma_f32_32x32x16_bf16 v[48:63], v[84:87], v[92:95], v[48:63]
	ds_read_b128 v[92:95], v132 offset:4672
	v_mfma_f32_32x32x16_bf16 v[16:31], v[84:87], v[76:79], v[16:31]
	ds_read_b128 v[76:79], v131 offset:41504
	ds_read_b128 v[84:87], v132 offset:64
	s_waitcnt vmcnt(7)
	ds_write_b128 v130, v[64:67] offset:18432
	s_waitcnt vmcnt(6)
	ds_write_b128 v130, v[68:71] offset:23040
	s_waitcnt vmcnt(5)
	ds_write_b128 v130, v[72:75] offset:27648
	s_waitcnt vmcnt(4)
	ds_write_b128 v130, v[100:103] offset:32256
	ds_read_b128 v[64:67], v132 offset:96
	v_mfma_f32_32x32x16_bf16 v[48:63], v[88:91], v[96:99], v[48:63]
	ds_read_b128 v[68:71], v132 offset:4704
	ds_read_b128 v[72:75], v131 offset:36960
	s_waitcnt lgkmcnt(8)
	v_mfma_f32_32x32x16_bf16 v[32:47], v[76:79], v[96:99], v[32:47]
	v_mfma_f32_32x32x16_bf16 v[16:31], v[88:91], v[80:83], v[16:31]
	v_mfma_f32_32x32x16_bf16 v[0:15], v[76:79], v[80:83], v[0:15]
	ds_read_b128 v[76:79], v131 offset:41568
	s_waitcnt vmcnt(3)
	ds_write_b128 v130, v[172:175] offset:55296
	s_waitcnt vmcnt(2)
	ds_write_b128 v130, v[176:179] offset:59904
	s_waitcnt vmcnt(1)
	ds_write_b128 v130, v[180:183] offset:64512
	s_waitcnt vmcnt(0)
	ds_write_b128 v133, v[168:171] offset:13824
	s_waitcnt lgkmcnt(0)
	s_barrier
	v_mfma_f32_32x32x16_bf16 v[48:63], v[104:107], v[84:87], v[48:63]
	ds_read_b128 v[80:83], v132 offset:23072
	ds_read_b128 v[88:91], v131 offset:55328
	ds_read_b128 v[96:99], v132 offset:18528
	ds_read_b128 v[100:103], v132 offset:23136
	v_mfma_f32_32x32x16_bf16 v[32:47], v[108:111], v[84:87], v[32:47]
	ds_read_b128 v[84:87], v131 offset:55296
	v_mfma_f32_32x32x16_bf16 v[16:31], v[104:107], v[92:95], v[16:31]
	ds_read_b128 v[104:107], v131 offset:55392
	v_mfma_f32_32x32x16_bf16 v[0:15], v[108:111], v[92:95], v[0:15]
	ds_read_b128 v[92:95], v131 offset:59936
	ds_read_b128 v[108:111], v131 offset:60000
	v_mfma_f32_32x32x16_bf16 v[48:63], v[72:75], v[64:67], v[48:63]
	v_mfma_f32_32x32x16_bf16 v[32:47], v[76:79], v[64:67], v[32:47]
	ds_read_b128 v[64:67], v132 offset:23040
	v_mfma_f32_32x32x16_bf16 v[16:31], v[72:75], v[68:71], v[16:31]
	ds_read_b128 v[72:75], v132 offset:18432
	v_mfma_f32_32x32x16_bf16 v[0:15], v[76:79], v[68:71], v[0:15]
	ds_read_b128 v[68:71], v131 offset:59904
	ds_read_b128 v[76:79], v132 offset:18464
	s_waitcnt lgkmcnt(2)
	v_mfma_f32_32x32x16_bf16 v[48:63], v[84:87], v[72:75], v[48:63]
	v_mfma_f32_32x32x16_bf16 v[16:31], v[84:87], v[64:67], v[16:31]
	ds_read_b128 v[84:87], v131 offset:59968
	s_waitcnt lgkmcnt(2)
	v_mfma_f32_32x32x16_bf16 v[32:47], v[68:71], v[72:75], v[32:47]
	ds_read_b128 v[72:75], v131 offset:55360
	v_mfma_f32_32x32x16_bf16 v[0:15], v[68:71], v[64:67], v[0:15]
	ds_read_b128 v[64:67], v132 offset:18496
	ds_read_b128 v[68:71], v132 offset:23104
	s_waitcnt lgkmcnt(0)
	s_barrier
	v_mfma_f32_32x32x16_bf16 v[48:63], v[88:91], v[76:79], v[48:63]
	v_mfma_f32_32x32x16_bf16 v[16:31], v[88:91], v[80:83], v[16:31]
	v_mfma_f32_32x32x16_bf16 v[32:47], v[92:95], v[76:79], v[32:47]
	v_mfma_f32_32x32x16_bf16 v[0:15], v[92:95], v[80:83], v[0:15]
	v_mfma_f32_32x32x16_bf16 v[48:63], v[72:75], v[64:67], v[48:63]
	v_mfma_f32_32x32x16_bf16 v[16:31], v[72:75], v[68:71], v[16:31]
	v_mfma_f32_32x32x16_bf16 v[32:47], v[84:87], v[64:67], v[32:47]
	v_mfma_f32_32x32x16_bf16 v[0:15], v[84:87], v[68:71], v[0:15]
	v_mfma_f32_32x32x16_bf16 v[48:63], v[104:107], v[96:99], v[48:63]
	v_mfma_f32_32x32x16_bf16 v[32:47], v[108:111], v[96:99], v[32:47]
	v_mfma_f32_32x32x16_bf16 v[16:31], v[104:107], v[100:103], v[16:31]
	v_mfma_f32_32x32x16_bf16 v[0:15], v[108:111], v[100:103], v[0:15]
	v_readfirstlane_b32 s16, v186
	v_and_b32_e32 v64, 31, v186
	v_bfe_u32 v65, v186, 5, 1
	s_lshr_b32 s16, s16, 6
	s_and_b32 s17, s16, 1
	s_lshr_b32 s16, s16, 1
	s_lshl_b32 s16, s16, 6
	v_add_u32_e32 v64, s16, v64
	v_lshlrev_b32_e32 v64, 12, v64
	v_lshl_add_u32 v64, v65, 4, v64
	s_lshl_b32 s17, s17, 8
	v_add_u32_e32 v64, s17, v64
	v_add_u32_e32 v65, 0x20000, v64
	s_lshl_b32 s16, s4, 12
	s_lshl_b32 s17, s0, 2
	s_add_u32 s16, s16, s17
	s_add_u32 s18, s46, s16
	s_addc_u32 s19, s47, 0
	s_add_u32 s20, s86, s16
	s_addc_u32 s21, s87, 0
	global_load_dwordx4 v[68:71], v64, s[18:19]
	global_load_dwordx4 v[72:75], v64, s[18:19] offset:32
	global_load_dwordx4 v[76:79], v64, s[18:19] offset:64
	global_load_dwordx4 v[80:83], v64, s[18:19] offset:96
	global_load_dwordx4 v[84:87], v64, s[18:19] offset:128
	global_load_dwordx4 v[88:91], v64, s[18:19] offset:160
	global_load_dwordx4 v[92:95], v64, s[18:19] offset:192
	global_load_dwordx4 v[96:99], v64, s[18:19] offset:224
	global_load_dwordx4 v[100:103], v65, s[18:19]
	global_load_dwordx4 v[104:107], v65, s[18:19] offset:32
	global_load_dwordx4 v[108:111], v65, s[18:19] offset:64
	global_load_dwordx4 v[112:115], v65, s[18:19] offset:96
	global_load_dwordx4 v[116:119], v65, s[18:19] offset:128
	global_load_dwordx4 v[120:123], v65, s[18:19] offset:160
	global_load_dwordx4 v[124:127], v65, s[18:19] offset:192
	global_load_dwordx4 v[128:131], v65, s[18:19] offset:224
	s_waitcnt vmcnt(15)
	v_add_f32_e32 v48, v68, v48
	v_add_f32_e32 v49, v69, v49
	v_add_f32_e32 v50, v70, v50
	v_add_f32_e32 v51, v71, v51
	global_store_dwordx4 v64, v[48:51], s[20:21]
	s_waitcnt vmcnt(15)
	v_add_f32_e32 v52, v72, v52
	v_add_f32_e32 v53, v73, v53
	v_add_f32_e32 v54, v74, v54
	v_add_f32_e32 v55, v75, v55
	global_store_dwordx4 v64, v[52:55], s[20:21] offset:32
	s_waitcnt vmcnt(15)
	v_add_f32_e32 v56, v76, v56
	v_add_f32_e32 v57, v77, v57
	v_add_f32_e32 v58, v78, v58
	v_add_f32_e32 v59, v79, v59
	global_store_dwordx4 v64, v[56:59], s[20:21] offset:64
	s_waitcnt vmcnt(15)
	v_add_f32_e32 v60, v80, v60
	v_add_f32_e32 v61, v81, v61
	v_add_f32_e32 v62, v82, v62
	v_add_f32_e32 v63, v83, v63
	global_store_dwordx4 v64, v[60:63], s[20:21] offset:96
	s_waitcnt vmcnt(15)
	v_add_f32_e32 v32, v84, v32
	v_add_f32_e32 v33, v85, v33
	v_add_f32_e32 v34, v86, v34
	v_add_f32_e32 v35, v87, v35
	global_store_dwordx4 v64, v[32:35], s[20:21] offset:128
	s_waitcnt vmcnt(15)
	v_add_f32_e32 v36, v88, v36
	v_add_f32_e32 v37, v89, v37
	v_add_f32_e32 v38, v90, v38
	v_add_f32_e32 v39, v91, v39
	global_store_dwordx4 v64, v[36:39], s[20:21] offset:160
	s_waitcnt vmcnt(15)
	v_add_f32_e32 v40, v92, v40
	v_add_f32_e32 v41, v93, v41
	v_add_f32_e32 v42, v94, v42
	v_add_f32_e32 v43, v95, v43
	global_store_dwordx4 v64, v[40:43], s[20:21] offset:192
	s_waitcnt vmcnt(15)
	v_add_f32_e32 v44, v96, v44
	v_add_f32_e32 v45, v97, v45
	v_add_f32_e32 v46, v98, v46
	v_add_f32_e32 v47, v99, v47
	global_store_dwordx4 v64, v[44:47], s[20:21] offset:224
	s_waitcnt vmcnt(15)
	v_add_f32_e32 v16, v100, v16
	v_add_f32_e32 v17, v101, v17
	v_add_f32_e32 v18, v102, v18
	v_add_f32_e32 v19, v103, v19
	global_store_dwordx4 v65, v[16:19], s[20:21]
	s_waitcnt vmcnt(15)
	v_add_f32_e32 v20, v104, v20
	v_add_f32_e32 v21, v105, v21
	v_add_f32_e32 v22, v106, v22
	v_add_f32_e32 v23, v107, v23
	global_store_dwordx4 v65, v[20:23], s[20:21] offset:32
	s_waitcnt vmcnt(15)
	v_add_f32_e32 v24, v108, v24
	v_add_f32_e32 v25, v109, v25
	v_add_f32_e32 v26, v110, v26
	v_add_f32_e32 v27, v111, v27
	global_store_dwordx4 v65, v[24:27], s[20:21] offset:64
	s_waitcnt vmcnt(15)
	v_add_f32_e32 v28, v112, v28
	v_add_f32_e32 v29, v113, v29
	v_add_f32_e32 v30, v114, v30
	v_add_f32_e32 v31, v115, v31
	global_store_dwordx4 v65, v[28:31], s[20:21] offset:96
	s_waitcnt vmcnt(15)
	v_add_f32_e32 v0, v116, v0
	v_add_f32_e32 v1, v117, v1
	v_add_f32_e32 v2, v118, v2
	v_add_f32_e32 v3, v119, v3
	global_store_dwordx4 v65, v[0:3], s[20:21] offset:128
	s_waitcnt vmcnt(15)
	v_add_f32_e32 v4, v120, v4
	v_add_f32_e32 v5, v121, v5
	v_add_f32_e32 v6, v122, v6
	v_add_f32_e32 v7, v123, v7
	global_store_dwordx4 v65, v[4:7], s[20:21] offset:160
	s_waitcnt vmcnt(15)
	v_add_f32_e32 v8, v124, v8
	v_add_f32_e32 v9, v125, v9
	v_add_f32_e32 v10, v126, v10
	v_add_f32_e32 v11, v127, v11
	global_store_dwordx4 v65, v[8:11], s[20:21] offset:192
	s_waitcnt vmcnt(15)
	v_add_f32_e32 v12, v128, v12
	v_add_f32_e32 v13, v129, v13
	v_add_f32_e32 v14, v130, v14
	v_add_f32_e32 v15, v131, v15
	global_store_dwordx4 v65, v[12:15], s[20:21] offset:224
	v_readlane_b32 s0, v252, 22
	s_nop 3
	s_add_i32 s14, s14, s0
	s_cmp_ge_i32 s14, s24
	s_cbranch_scc1 .LBB0_2152

.LBB0_2324:
	v_readfirstlane_b32 s20, v186
	v_and_b32_e32 v64, 31, v186
	v_bfe_u32 v65, v186, 5, 1
	s_lshr_b32 s20, s20, 6
	s_and_b32 s21, s20, 1
	s_lshr_b32 s20, s20, 1
	s_lshl_b32 s20, s20, 6
	v_add_u32_e32 v64, s20, v64
	v_lshlrev_b32_e32 v64, 12, v64
	v_lshl_add_u32 v64, v65, 4, v64
	s_lshl_b32 s21, s21, 8
	v_add_u32_e32 v64, s21, v64
	v_add_u32_e32 v65, 0x20000, v64
	s_lshl_b32 s20, s17, 12
	s_lshl_b32 s21, s2, 2
	s_add_u32 s20, s20, s21
	s_add_u32 s22, s86, s20
	s_addc_u32 s23, s87, 0
	s_add_u32 s24, s86, s20
	s_addc_u32 s25, s87, 0
	global_load_dwordx4 v[68:71], v64, s[22:23]
	global_load_dwordx4 v[72:75], v64, s[22:23] offset:32
	global_load_dwordx4 v[76:79], v64, s[22:23] offset:64
	global_load_dwordx4 v[80:83], v64, s[22:23] offset:96
	global_load_dwordx4 v[84:87], v64, s[22:23] offset:128
	global_load_dwordx4 v[88:91], v64, s[22:23] offset:160
	global_load_dwordx4 v[92:95], v64, s[22:23] offset:192
	global_load_dwordx4 v[96:99], v64, s[22:23] offset:224
	global_load_dwordx4 v[100:103], v65, s[22:23]
	global_load_dwordx4 v[104:107], v65, s[22:23] offset:32
	global_load_dwordx4 v[108:111], v65, s[22:23] offset:64
	global_load_dwordx4 v[112:115], v65, s[22:23] offset:96
	global_load_dwordx4 v[116:119], v65, s[22:23] offset:128
	global_load_dwordx4 v[120:123], v65, s[22:23] offset:160
	global_load_dwordx4 v[124:127], v65, s[22:23] offset:192
	global_load_dwordx4 v[128:131], v65, s[22:23] offset:224
	s_waitcnt vmcnt(15)
	v_add_f32_e32 v48, v68, v48
	v_add_f32_e32 v49, v69, v49
	v_add_f32_e32 v50, v70, v50
	v_add_f32_e32 v51, v71, v51
	global_store_dwordx4 v64, v[48:51], s[24:25]
	s_waitcnt vmcnt(15)
	v_add_f32_e32 v52, v72, v52
	v_add_f32_e32 v53, v73, v53
	v_add_f32_e32 v54, v74, v54
	v_add_f32_e32 v55, v75, v55
	global_store_dwordx4 v64, v[52:55], s[24:25] offset:32
	s_waitcnt vmcnt(15)
	v_add_f32_e32 v56, v76, v56
	v_add_f32_e32 v57, v77, v57
	v_add_f32_e32 v58, v78, v58
	v_add_f32_e32 v59, v79, v59
	global_store_dwordx4 v64, v[56:59], s[24:25] offset:64
	s_waitcnt vmcnt(15)
	v_add_f32_e32 v60, v80, v60
	v_add_f32_e32 v61, v81, v61
	v_add_f32_e32 v62, v82, v62
	v_add_f32_e32 v63, v83, v63
	global_store_dwordx4 v64, v[60:63], s[24:25] offset:96
	s_waitcnt vmcnt(15)
	v_add_f32_e32 v32, v84, v32
	v_add_f32_e32 v33, v85, v33
	v_add_f32_e32 v34, v86, v34
	v_add_f32_e32 v35, v87, v35
	global_store_dwordx4 v64, v[32:35], s[24:25] offset:128
	s_waitcnt vmcnt(15)
	v_add_f32_e32 v36, v88, v36
	v_add_f32_e32 v37, v89, v37
	v_add_f32_e32 v38, v90, v38
	v_add_f32_e32 v39, v91, v39
	global_store_dwordx4 v64, v[36:39], s[24:25] offset:160
	s_waitcnt vmcnt(15)
	v_add_f32_e32 v40, v92, v40
	v_add_f32_e32 v41, v93, v41
	v_add_f32_e32 v42, v94, v42
	v_add_f32_e32 v43, v95, v43
	global_store_dwordx4 v64, v[40:43], s[24:25] offset:192
	s_waitcnt vmcnt(15)
	v_add_f32_e32 v44, v96, v44
	v_add_f32_e32 v45, v97, v45
	v_add_f32_e32 v46, v98, v46
	v_add_f32_e32 v47, v99, v47
	global_store_dwordx4 v64, v[44:47], s[24:25] offset:224
	s_waitcnt vmcnt(15)
	v_add_f32_e32 v16, v100, v16
	v_add_f32_e32 v17, v101, v17
	v_add_f32_e32 v18, v102, v18
	v_add_f32_e32 v19, v103, v19
	global_store_dwordx4 v65, v[16:19], s[24:25]
	s_waitcnt vmcnt(15)
	v_add_f32_e32 v20, v104, v20
	v_add_f32_e32 v21, v105, v21
	v_add_f32_e32 v22, v106, v22
	v_add_f32_e32 v23, v107, v23
	global_store_dwordx4 v65, v[20:23], s[24:25] offset:32
	s_waitcnt vmcnt(15)
	v_add_f32_e32 v24, v108, v24
	v_add_f32_e32 v25, v109, v25
	v_add_f32_e32 v26, v110, v26
	v_add_f32_e32 v27, v111, v27
	global_store_dwordx4 v65, v[24:27], s[24:25] offset:64
	s_waitcnt vmcnt(15)
	v_add_f32_e32 v28, v112, v28
	v_add_f32_e32 v29, v113, v29
	v_add_f32_e32 v30, v114, v30
	v_add_f32_e32 v31, v115, v31
	global_store_dwordx4 v65, v[28:31], s[24:25] offset:96
	s_waitcnt vmcnt(15)
	v_add_f32_e32 v0, v116, v0
	v_add_f32_e32 v1, v117, v1
	v_add_f32_e32 v2, v118, v2
	v_add_f32_e32 v3, v119, v3
	global_store_dwordx4 v65, v[0:3], s[24:25] offset:128
	s_waitcnt vmcnt(15)
	v_add_f32_e32 v4, v120, v4
	v_add_f32_e32 v5, v121, v5
	v_add_f32_e32 v6, v122, v6
	v_add_f32_e32 v7, v123, v7
	global_store_dwordx4 v65, v[4:7], s[24:25] offset:160
	s_waitcnt vmcnt(15)
	v_add_f32_e32 v8, v124, v8
	v_add_f32_e32 v9, v125, v9
	v_add_f32_e32 v10, v126, v10
	v_add_f32_e32 v11, v127, v11
	global_store_dwordx4 v65, v[8:11], s[24:25] offset:192
	s_waitcnt vmcnt(15)
	v_add_f32_e32 v12, v128, v12
	v_add_f32_e32 v13, v129, v13
	v_add_f32_e32 v14, v130, v14
	v_add_f32_e32 v15, v131, v15
	global_store_dwordx4 v65, v[12:15], s[24:25] offset:224
	v_readlane_b32 s0, v252, 22
	s_nop 3
	s_add_i32 s16, s16, s0
	v_readlane_b32 s0, v252, 36
	s_nop 3
	s_cmp_ge_i32 s16, s0
	s_cbranch_scc1 .LBB0_2343

.LBB0_2334:
	s_waitcnt lgkmcnt(5)
	v_mfma_f32_32x32x16_bf16 v[48:63], v[156:159], v[152:155], v[48:63]
	s_add_i32 s18, s18, 2
	s_add_u32 s6, s6, 0x100
	s_addc_u32 s7, s7, 0
	s_andn2_b64 vcc, exec, s[8:9]
	s_waitcnt lgkmcnt(0)
	s_barrier
	v_mfma_f32_32x32x16_bf16 v[32:47], v[148:151], v[152:155], v[32:47]
	v_mfma_f32_32x32x16_bf16 v[16:31], v[156:159], v[144:147], v[16:31]
	v_mfma_f32_32x32x16_bf16 v[0:15], v[148:151], v[144:147], v[0:15]
	v_mfma_f32_32x32x16_bf16 v[48:63], v[140:143], v[136:139], v[48:63]
	v_mfma_f32_32x32x16_bf16 v[32:47], v[132:135], v[136:139], v[32:47]
	v_mfma_f32_32x32x16_bf16 v[16:31], v[140:143], v[128:131], v[16:31]
	v_mfma_f32_32x32x16_bf16 v[0:15], v[132:135], v[128:131], v[0:15]
	s_cbranch_vccz .LBB0_2324
.LBB0_2335:
	ds_read_b128 v[128:131], v168
	ds_read_b128 v[136:139], v167 offset:36864
	ds_read_b128 v[144:147], v167 offset:41472
	s_cmp_lt_u32 s18, 42
	s_cselect_b64 s[10:11], -1, 0
	s_cmp_gt_u32 s18, 41
	s_waitcnt lgkmcnt(1)
	v_mfma_f32_32x32x16_bf16 v[48:63], v[136:139], v[128:131], v[48:63]
	s_cselect_b64 s[8:9], -1, 0
	s_and_b64 vcc, exec, s[8:9]
	s_waitcnt lgkmcnt(0)
	v_mfma_f32_32x32x16_bf16 v[32:47], v[144:147], v[128:131], v[32:47]
	ds_read_b128 v[148:151], v168 offset:4608
	ds_read_b128 v[132:135], v168 offset:32
	ds_read_b128 v[128:131], v167 offset:36896
	s_waitcnt lgkmcnt(2)
	v_mfma_f32_32x32x16_bf16 v[16:31], v[136:139], v[148:151], v[16:31]
	ds_read_b128 v[136:139], v167 offset:41504
	ds_read_b128 v[140:143], v168 offset:4640
	v_mfma_f32_32x32x16_bf16 v[0:15], v[144:147], v[148:151], v[0:15]
	s_cbranch_vccnz .LBB0_2337
	v_lshl_add_u64 v[64:65], s[6:7], 0, v[184:185]
	v_add_co_u32_e32 v64, vcc, 0x4800000, v64
	v_lshl_add_u64 v[66:67], s[6:7], 0, v[182:183]
	s_nop 0
	v_addc_co_u32_e32 v65, vcc, 0, v65, vcc
	v_add_co_u32_e32 v68, vcc, 0x4800000, v66
	v_lshl_add_u64 v[72:73], s[6:7], 0, v[180:181]
	s_nop 0
	v_addc_co_u32_e32 v69, vcc, 0, v67, vcc
	v_add_co_u32_e32 v72, vcc, 0x4800000, v72
	v_lshl_add_u64 v[74:75], s[6:7], 0, v[178:179]
	s_nop 0
	v_addc_co_u32_e32 v73, vcc, 0, v73, vcc
	v_add_co_u32_e32 v76, vcc, 0x4800000, v74
	v_lshl_add_u64 v[88:89], s[6:7], 0, v[176:177]
	s_nop 0
	v_addc_co_u32_e32 v77, vcc, 0, v75, vcc
	v_add_co_u32_e32 v88, vcc, 0x1e40000, v88
	v_lshl_add_u64 v[90:91], s[6:7], 0, v[174:175]
	s_nop 0
	v_addc_co_u32_e32 v89, vcc, 0, v89, vcc
	v_add_co_u32_e32 v100, vcc, 0x1e40000, v90
	v_lshl_add_u64 v[112:113], s[6:7], 0, v[172:173]
	s_nop 0
	v_addc_co_u32_e32 v101, vcc, 0, v91, vcc
	v_add_co_u32_e32 v112, vcc, 0x1e40000, v112
	v_lshl_add_u64 v[114:115], s[6:7], 0, v[170:171]
	s_nop 0
	v_addc_co_u32_e32 v113, vcc, 0, v113, vcc
	v_add_co_u32_e32 v116, vcc, 0x1e40000, v114
	global_load_dwordx4 v[64:67], v[64:65], off offset:256
	s_nop 0
	global_load_dwordx4 v[68:71], v[68:69], off offset:256
	v_addc_co_u32_e32 v117, vcc, 0, v115, vcc
	global_load_dwordx4 v[72:75], v[72:73], off offset:256
	s_nop 0
	global_load_dwordx4 v[76:79], v[76:77], off offset:256
	s_nop 0
	global_load_dwordx4 v[88:91], v[88:89], off offset:256
	s_nop 0
	global_load_dwordx4 v[100:103], v[100:101], off offset:256
	s_nop 0
	global_load_dwordx4 v[112:115], v[112:113], off offset:256
	s_nop 0
	global_load_dwordx4 v[116:119], v[116:117], off offset:256
.LBB0_2337:
	ds_read_b128 v[148:151], v168 offset:4672
	ds_read_b128 v[144:147], v168 offset:64
	ds_read_b128 v[152:155], v167 offset:36928
	ds_read_b128 v[156:159], v167 offset:41536
	s_waitcnt lgkmcnt(4)
	v_mfma_f32_32x32x16_bf16 v[16:31], v[128:131], v[140:143], v[16:31]
	s_cmp_gt_u32 s18, 40
	v_mfma_f32_32x32x16_bf16 v[0:15], v[136:139], v[140:143], v[0:15]
	v_mfma_f32_32x32x16_bf16 v[48:63], v[128:131], v[132:135], v[48:63]
	v_mfma_f32_32x32x16_bf16 v[32:47], v[136:139], v[132:135], v[32:47]
	s_waitcnt vmcnt(7)
	ds_write_b128 v166, v[80:83] offset:18432
	s_waitcnt vmcnt(6)
	ds_write_b128 v166, v[84:87] offset:23040
	s_waitcnt vmcnt(5)
	ds_write_b128 v166, v[92:95] offset:27648
	s_waitcnt vmcnt(4)
	ds_write_b128 v166, v[96:99] offset:32256
	s_waitcnt lgkmcnt(5)
	v_mfma_f32_32x32x16_bf16 v[16:31], v[152:155], v[148:151], v[16:31]
	s_waitcnt lgkmcnt(4)
	v_mfma_f32_32x32x16_bf16 v[0:15], v[156:159], v[148:151], v[0:15]
	ds_read_b128 v[132:135], v168 offset:4704
	ds_read_b128 v[136:139], v167 offset:36960
	ds_read_b128 v[140:143], v167 offset:41568
	ds_read_b128 v[128:131], v168 offset:96
	s_waitcnt vmcnt(3)
	ds_write_b128 v166, v[104:107] offset:55296
	s_waitcnt vmcnt(2)
	ds_write_b128 v166, v[108:111] offset:59904
	s_waitcnt vmcnt(1)
	ds_write_b128 v166, v[120:123] offset:64512
	s_waitcnt vmcnt(0)
	ds_write_b128 v169, v[124:127] offset:13824
	s_waitcnt lgkmcnt(0)
	s_barrier
	ds_read_b128 v[148:151], v168 offset:23040
	v_mfma_f32_32x32x16_bf16 v[16:31], v[136:139], v[132:135], v[16:31]
	v_mfma_f32_32x32x16_bf16 v[0:15], v[140:143], v[132:135], v[0:15]
	ds_read_b128 v[132:135], v167 offset:55296
	v_mfma_f32_32x32x16_bf16 v[48:63], v[152:155], v[144:147], v[48:63]
	v_mfma_f32_32x32x16_bf16 v[32:47], v[156:159], v[144:147], v[32:47]
	ds_read_b128 v[144:147], v167 offset:59904
	v_mfma_f32_32x32x16_bf16 v[48:63], v[136:139], v[128:131], v[48:63]
	ds_read_b128 v[136:139], v167 offset:55328
	v_mfma_f32_32x32x16_bf16 v[32:47], v[140:143], v[128:131], v[32:47]
	ds_read_b128 v[128:131], v168 offset:18432
	ds_read_b128 v[140:143], v167 offset:59936
	s_waitcnt lgkmcnt(1)
	v_mfma_f32_32x32x16_bf16 v[48:63], v[132:135], v[128:131], v[48:63]
	v_mfma_f32_32x32x16_bf16 v[32:47], v[144:147], v[128:131], v[32:47]
	ds_read_b128 v[128:131], v168 offset:23072
	v_mfma_f32_32x32x16_bf16 v[16:31], v[132:135], v[148:151], v[16:31]
	ds_read_b128 v[132:135], v168 offset:18464
	v_mfma_f32_32x32x16_bf16 v[0:15], v[144:147], v[148:151], v[0:15]
	s_cbranch_scc1 .LBB0_2339
	v_lshl_add_u64 v[80:81], s[6:7], 0, v[184:185]
	v_add_co_u32_e32 v80, vcc, 0x4800000, v80
	v_lshl_add_u64 v[82:83], s[6:7], 0, v[182:183]
	s_nop 0
	v_addc_co_u32_e32 v81, vcc, 0, v81, vcc
	v_add_co_u32_e32 v84, vcc, 0x4800000, v82
	v_lshl_add_u64 v[92:93], s[6:7], 0, v[180:181]
	s_nop 0
	v_addc_co_u32_e32 v85, vcc, 0, v83, vcc
	v_add_co_u32_e32 v92, vcc, 0x4800000, v92
	v_lshl_add_u64 v[94:95], s[6:7], 0, v[178:179]
	s_nop 0
	v_addc_co_u32_e32 v93, vcc, 0, v93, vcc
	v_add_co_u32_e32 v96, vcc, 0x4800000, v94
	v_lshl_add_u64 v[104:105], s[6:7], 0, v[176:177]
	s_nop 0
	v_addc_co_u32_e32 v97, vcc, 0, v95, vcc
	v_add_co_u32_e32 v104, vcc, 0x1e40000, v104
	v_lshl_add_u64 v[106:107], s[6:7], 0, v[174:175]
	s_nop 0
	v_addc_co_u32_e32 v105, vcc, 0, v105, vcc
	v_add_co_u32_e32 v108, vcc, 0x1e40000, v106
	v_lshl_add_u64 v[120:121], s[6:7], 0, v[172:173]
	s_nop 0
	v_addc_co_u32_e32 v109, vcc, 0, v107, vcc
	v_add_co_u32_e32 v120, vcc, 0x1e40000, v120
	v_lshl_add_u64 v[122:123], s[6:7], 0, v[170:171]
	s_nop 0
	v_addc_co_u32_e32 v121, vcc, 0, v121, vcc
	v_add_co_u32_e32 v124, vcc, 0x1e40000, v122
	global_load_dwordx4 v[80:83], v[80:81], off offset:384
	s_nop 0
	global_load_dwordx4 v[84:87], v[84:85], off offset:384
	v_addc_co_u32_e32 v125, vcc, 0, v123, vcc
	global_load_dwordx4 v[92:95], v[92:93], off offset:384
	s_nop 0
	global_load_dwordx4 v[96:99], v[96:97], off offset:384
	s_nop 0
	global_load_dwordx4 v[104:107], v[104:105], off offset:384
	s_nop 0
	global_load_dwordx4 v[108:111], v[108:109], off offset:384
	s_nop 0
	global_load_dwordx4 v[120:123], v[120:121], off offset:384
	s_nop 0
	global_load_dwordx4 v[124:127], v[124:125], off offset:384

.LBB0_2341:
	s_waitcnt lgkmcnt(4)
	v_mfma_f32_32x32x16_bf16 v[48:63], v[136:139], v[132:135], v[48:63]
	s_and_b64 vcc, exec, s[0:1]
	v_mfma_f32_32x32x16_bf16 v[32:47], v[140:143], v[132:135], v[32:47]
	v_mfma_f32_32x32x16_bf16 v[16:31], v[136:139], v[128:131], v[16:31]
	v_mfma_f32_32x32x16_bf16 v[0:15], v[140:143], v[128:131], v[0:15]
	ds_read_b128 v[136:139], v168 offset:18528
	ds_read_b128 v[128:131], v168 offset:23136
	ds_read_b128 v[140:143], v167 offset:55392
	ds_read_b128 v[132:135], v167 offset:60000
	s_cbranch_vccnz .LBB0_2334
	ds_write_b128 v166, v[88:91] offset:36864
	ds_write_b128 v166, v[100:103] offset:41472
	ds_write_b128 v166, v[112:115] offset:46080
	ds_write_b128 v166, v[116:119] offset:50688
	s_branch .LBB0_2334

.LBB0_2453:
	s_lshl_b32 s0, s4, 7
	s_ashr_i32 s1, s0, 31
	s_lshl_b32 s2, s2, 6
	s_lshl_b64 s[4:5], s[0:1], 9
	v_mov_b32_e32 v0, v161
	s_add_u32 s4, s10, s4
	v_mov_b32_e32 v1, v186
	s_addc_u32 s5, s11, s5
	s_ashr_i32 s3, s2, 31
	s_lshl_b64 s[6:7], s[2:3], 9
	v_lshlrev_b32_e32 v2, 4, v1
	s_waitcnt vmcnt(17)
	v_ashrrev_i32_e32 v27, 3, v1
	v_and_b32_e32 v26, 0x70, v2
	s_add_u32 s6, s12, s6
	v_lshl_or_b32 v119, v27, 9, v26
	s_addc_u32 s7, s13, s7
	v_add_u32_e32 v120, 0x4000, v119
	v_add_u32_e32 v121, 0x8000, v119
	v_add_u32_e32 v122, 0xc000, v119
	s_barrier
	global_load_dwordx4 v[2:5], v119, s[4:5]
	global_load_dwordx4 v[6:9], v120, s[4:5]
	global_load_dwordx4 v[10:13], v121, s[4:5]
	global_load_dwordx4 v[14:17], v122, s[4:5]
	global_load_dwordx4 v[18:21], v119, s[6:7]
	global_load_dwordx4 v[22:25], v120, s[6:7]
	v_mad_u64_u32 v[84:85], s[18:19], v27, s43, v[26:27]
	s_waitcnt vmcnt(5)
	ds_write_b128 v84, v[2:5]
	s_waitcnt vmcnt(4)
	ds_write_b128 v84, v[6:9] offset:4608
	s_waitcnt vmcnt(3)
	ds_write_b128 v84, v[10:13] offset:9216
	s_waitcnt vmcnt(2)
	ds_write_b128 v84, v[14:17] offset:13824
	s_waitcnt vmcnt(1)
	ds_write_b128 v84, v[18:21] offset:36864
	s_waitcnt vmcnt(0)
	ds_write_b128 v84, v[22:25] offset:41472
	global_load_dwordx4 v[40:43], v119, s[4:5] offset:128
	global_load_dwordx4 v[44:47], v120, s[4:5] offset:128
	global_load_dwordx4 v[48:51], v121, s[4:5] offset:128
	global_load_dwordx4 v[52:55], v122, s[4:5] offset:128
	global_load_dwordx4 v[32:35], v119, s[6:7] offset:128
	global_load_dwordx4 v[36:39], v120, s[6:7] offset:128
	v_lshrrev_b32_e32 v3, 1, v1
	v_and_b32_e32 v1, 31, v1
	v_and_or_b32 v4, v3, 32, v1
	v_and_b32_e32 v2, 16, v3
	v_and_or_b32 v1, v3, s44, v1
	v_mad_u64_u32 v[82:83], s[18:19], v1, s43, v[2:3]
	s_waitcnt lgkmcnt(0)
	s_barrier
	ds_read_b128 v[56:59], v82 offset:4608
	ds_read_b128 v[60:63], v82
	v_mad_u32_u24 v85, v4, s43, v2
	ds_read_b128 v[124:127], v82 offset:32
	ds_read_b128 v[64:67], v85 offset:36864
	ds_read_b128 v[128:131], v82 offset:4640
	v_mov_b32_e32 v1, v0
	v_mov_b32_e32 v2, v0
	v_mov_b32_e32 v3, v0
	v_mov_b32_e32 v4, v0
	v_mov_b32_e32 v5, v0
	v_mov_b32_e32 v6, v0
	v_mov_b32_e32 v7, v0
	v_mov_b32_e32 v8, v0
	v_mov_b32_e32 v9, v0
	v_mov_b32_e32 v10, v0
	v_mov_b32_e32 v11, v0
	v_mov_b32_e32 v12, v0
	v_mov_b32_e32 v13, v0
	v_mov_b32_e32 v14, v0
	v_mov_b32_e32 v15, v0
	ds_read_b128 v[132:135], v85 offset:36896
	s_waitcnt lgkmcnt(2)
	v_mfma_f32_32x32x16_bf16 v[16:31], v[64:67], v[60:63], v[0:15]
	v_mfma_f32_32x32x16_bf16 v[0:15], v[64:67], v[56:59], v[0:15]
	s_waitcnt lgkmcnt(0)
	v_mfma_f32_32x32x16_bf16 v[16:31], v[132:135], v[124:127], v[16:31]
	v_mfma_f32_32x32x16_bf16 v[0:15], v[132:135], v[128:131], v[0:15]
	ds_read_b128 v[136:139], v82 offset:64
	ds_read_b128 v[140:143], v82 offset:4672
	ds_read_b128 v[144:147], v85 offset:36928
	s_waitcnt lgkmcnt(0)
	v_mfma_f32_32x32x16_bf16 v[16:31], v[144:147], v[136:139], v[16:31]
	v_mfma_f32_32x32x16_bf16 v[0:15], v[144:147], v[140:143], v[0:15]
	global_load_dwordx4 v[64:67], v119, s[4:5] offset:256
	global_load_dwordx4 v[68:71], v120, s[4:5] offset:256
	global_load_dwordx4 v[72:75], v121, s[4:5] offset:256
	global_load_dwordx4 v[76:79], v122, s[4:5] offset:256
	global_load_dwordx4 v[56:59], v119, s[6:7] offset:256
	global_load_dwordx4 v[60:63], v120, s[6:7] offset:256
	s_waitcnt vmcnt(11)
	ds_write_b128 v84, v[40:43] offset:18432
	s_waitcnt vmcnt(10)
	ds_write_b128 v84, v[44:47] offset:23040
	s_waitcnt vmcnt(9)
	ds_write_b128 v84, v[48:51] offset:27648
	s_waitcnt vmcnt(8)
	ds_write_b128 v84, v[52:55] offset:32256
	ds_read_b128 v[40:43], v82 offset:96
	ds_read_b128 v[44:47], v82 offset:4704
	ds_read_b128 v[48:51], v85 offset:36960
	s_waitcnt vmcnt(7)
	ds_write_b128 v84, v[32:35] offset:46080
	s_waitcnt vmcnt(6)
	ds_write_b128 v84, v[36:39] offset:50688
	s_waitcnt lgkmcnt(2)
	v_mfma_f32_32x32x16_bf16 v[16:31], v[48:51], v[40:43], v[16:31]
	s_waitcnt lgkmcnt(0)
	s_barrier
	v_mfma_f32_32x32x16_bf16 v[0:15], v[48:51], v[44:47], v[0:15]
	ds_read_b128 v[32:35], v82 offset:23040
	ds_read_b128 v[36:39], v82 offset:18432
	ds_read_b128 v[48:51], v85 offset:46080
	ds_read_b128 v[40:43], v82 offset:18464
	ds_read_b128 v[44:47], v82 offset:23072
	ds_read_b128 v[52:55], v85 offset:46112
	s_waitcnt lgkmcnt(3)
	v_mfma_f32_32x32x16_bf16 v[16:31], v[48:51], v[36:39], v[16:31]
	v_mfma_f32_32x32x16_bf16 v[0:15], v[48:51], v[32:35], v[0:15]
	global_load_dwordx4 v[32:35], v119, s[4:5] offset:384
	global_load_dwordx4 v[36:39], v120, s[4:5] offset:384
	global_load_dwordx4 v[48:51], v121, s[4:5] offset:384
	global_load_dwordx4 v[126:129], v119, s[6:7] offset:384
	global_load_dwordx4 v[130:133], v120, s[6:7] offset:384
	s_nop 0
	global_load_dwordx4 v[122:125], v122, s[4:5] offset:384
	ds_read_b128 v[134:137], v82 offset:18496
	ds_read_b128 v[138:141], v82 offset:23104
	ds_read_b128 v[142:145], v85 offset:46144
	s_lshl_b64 s[4:5], s[0:1], 11
	s_add_u32 s4, s8, s4
	s_addc_u32 s5, s9, s5
	s_lshl_b64 s[6:7], s[2:3], 11
	s_add_u32 s6, s14, s6
	s_addc_u32 s7, s15, s7
	s_waitcnt vmcnt(11)
	ds_write_b128 v84, v[64:67]
	s_waitcnt vmcnt(10)
	ds_write_b128 v84, v[68:71] offset:4608
	s_waitcnt vmcnt(9)
	ds_write_b128 v84, v[72:75] offset:9216
	s_waitcnt vmcnt(8)
	ds_write_b128 v84, v[76:79] offset:13824
	s_waitcnt lgkmcnt(7)
	v_mfma_f32_32x32x16_bf16 v[16:31], v[52:55], v[40:43], v[16:31]
	v_mfma_f32_32x32x16_bf16 v[0:15], v[52:55], v[44:47], v[0:15]
	ds_read_b128 v[40:43], v82 offset:18528
	ds_read_b128 v[44:47], v82 offset:23136
	ds_read_b128 v[52:55], v85 offset:46176
	s_waitcnt vmcnt(7)
	ds_write_b128 v84, v[56:59] offset:36864
	s_waitcnt vmcnt(6)
	ds_write_b128 v84, v[60:63] offset:41472
	s_waitcnt lgkmcnt(0)
	s_barrier
	v_mfma_f32_32x32x16_bf16 v[16:31], v[142:145], v[134:137], v[16:31]
	v_mfma_f32_32x32x16_bf16 v[0:15], v[142:145], v[138:141], v[0:15]
	v_mfma_f32_32x32x16_bf16 v[16:31], v[52:55], v[40:43], v[16:31]
	v_mfma_f32_32x32x16_bf16 v[0:15], v[52:55], v[44:47], v[0:15]
	ds_read_b128 v[40:43], v82 offset:4608
	ds_read_b128 v[56:59], v82
	ds_read_b128 v[44:47], v85 offset:36864
	ds_read_b128 v[52:55], v85 offset:36896
	ds_read_b128 v[60:63], v82 offset:32
	ds_read_b128 v[64:67], v85 offset:36928
	s_waitcnt lgkmcnt(3)
	v_mfma_f32_32x32x16_bf16 v[16:31], v[44:47], v[56:59], v[16:31]
	v_mfma_f32_32x32x16_bf16 v[0:15], v[44:47], v[40:43], v[0:15]
	ds_read_b128 v[40:43], v82 offset:4640
	ds_read_b128 v[44:47], v82 offset:64
	ds_read_b128 v[56:59], v82 offset:4672
	s_waitcnt vmcnt(5)
	ds_write_b128 v84, v[32:35] offset:18432
	s_waitcnt vmcnt(4)
	ds_write_b128 v84, v[36:39] offset:23040
	s_waitcnt vmcnt(3)
	ds_write_b128 v84, v[48:51] offset:27648
	s_waitcnt vmcnt(0)
	ds_write_b128 v84, v[122:125] offset:32256
	s_waitcnt lgkmcnt(8)
	v_mfma_f32_32x32x16_bf16 v[16:31], v[52:55], v[60:63], v[16:31]
	s_waitcnt lgkmcnt(6)
	v_mfma_f32_32x32x16_bf16 v[0:15], v[52:55], v[40:43], v[0:15]
	ds_read_b128 v[32:35], v82 offset:96
	ds_read_b128 v[36:39], v82 offset:4704
	ds_read_b128 v[40:43], v85 offset:36960
	ds_write_b128 v84, v[126:129] offset:46080
	ds_write_b128 v84, v[130:133] offset:50688
	s_waitcnt lgkmcnt(0)
	s_barrier
	v_mfma_f32_32x32x16_bf16 v[16:31], v[64:67], v[44:47], v[16:31]
	v_mfma_f32_32x32x16_bf16 v[0:15], v[64:67], v[56:59], v[0:15]
	v_mfma_f32_32x32x16_bf16 v[16:31], v[40:43], v[32:35], v[16:31]
	v_mfma_f32_32x32x16_bf16 v[0:15], v[40:43], v[36:39], v[0:15]
	ds_read_b128 v[32:35], v82 offset:23040
	ds_read_b128 v[36:39], v82 offset:18432
	ds_read_b128 v[48:51], v85 offset:46080
	ds_read_b128 v[44:47], v82 offset:23072
	ds_read_b128 v[40:43], v82 offset:18464
	ds_read_b128 v[52:55], v85 offset:46112
	s_waitcnt lgkmcnt(3)
	v_mfma_f32_32x32x16_bf16 v[0:15], v[48:51], v[32:35], v[0:15]
	v_mfma_f32_32x32x16_bf16 v[16:31], v[48:51], v[36:39], v[16:31]
	ds_read_b128 v[36:39], v82 offset:23104
	ds_read_b128 v[32:35], v82 offset:18496
	ds_read_b128 v[48:51], v85 offset:46144
	s_waitcnt lgkmcnt(3)
	v_mfma_f32_32x32x16_bf16 v[0:15], v[52:55], v[44:47], v[0:15]
	v_mfma_f32_32x32x16_bf16 v[16:31], v[52:55], v[40:43], v[16:31]
	ds_read_b128 v[60:63], v82 offset:23136
	ds_read_b128 v[56:59], v82 offset:18528
	ds_read_b128 v[64:67], v85 offset:46176
	s_waitcnt lgkmcnt(0)
	s_barrier
	v_mfma_f32_32x32x16_bf16 v[0:15], v[48:51], v[36:39], v[0:15]
	v_mfma_f32_32x32x16_bf16 v[16:31], v[48:51], v[32:35], v[16:31]
	v_mfma_f32_32x32x16_bf16 v[0:15], v[64:67], v[60:63], v[0:15]
	v_mfma_f32_32x32x16_bf16 v[16:31], v[64:67], v[56:59], v[16:31]
	s_nop 10
	v_cvt_pk_bf16_f32 v126, v0, v1
	v_mov_b32_e32 v0, v161
	v_mov_b32_e32 v1, v186
	v_cvt_pk_bf16_f32 v125, v2, v3
	v_cvt_pk_bf16_f32 v124, v4, v5
	v_lshlrev_b32_e32 v2, 4, v1
	v_cvt_pk_bf16_f32 v129, v26, v27
	v_ashrrev_i32_e32 v27, 3, v1
	v_and_b32_e32 v26, 0x70, v2
	v_lshl_or_b32 v135, v27, 11, v26
	v_add_u32_e32 v136, 0x10000, v135
	v_add_u32_e32 v137, 0x20000, v135
	v_add_u32_e32 v138, 0x30000, v135
	v_cvt_pk_bf16_f32 v134, v16, v17
	v_cvt_pk_bf16_f32 v133, v18, v19
	v_cvt_pk_bf16_f32 v132, v20, v21
	v_cvt_pk_bf16_f32 v131, v22, v23
	v_cvt_pk_bf16_f32 v130, v24, v25
	v_cvt_pk_bf16_f32 v123, v6, v7
	v_cvt_pk_bf16_f32 v122, v8, v9
	v_cvt_pk_bf16_f32 v121, v10, v11
	v_cvt_pk_bf16_f32 v120, v12, v13
	v_cvt_pk_bf16_f32 v119, v14, v15
	s_barrier
	global_load_dwordx4 v[2:5], v135, s[4:5]
	global_load_dwordx4 v[6:9], v136, s[4:5]
	global_load_dwordx4 v[10:13], v137, s[4:5]
	global_load_dwordx4 v[14:17], v138, s[4:5]
	global_load_dwordx4 v[18:21], v135, s[6:7]
	global_load_dwordx4 v[22:25], v136, s[6:7]
	v_mad_u64_u32 v[82:83], s[18:19], v27, s43, v[26:27]
	v_cvt_pk_bf16_f32 v128, v28, v29
	v_cvt_pk_bf16_f32 v127, v30, v31
	s_waitcnt vmcnt(5)
	ds_write_b128 v82, v[2:5]
	s_waitcnt vmcnt(4)
	ds_write_b128 v82, v[6:9] offset:4608
	s_waitcnt vmcnt(3)
	ds_write_b128 v82, v[10:13] offset:9216
	s_waitcnt vmcnt(2)
	ds_write_b128 v82, v[14:17] offset:13824
	s_waitcnt vmcnt(1)
	ds_write_b128 v82, v[18:21] offset:36864
	s_waitcnt vmcnt(0)
	ds_write_b128 v82, v[22:25] offset:41472
	global_load_dwordx4 v[40:43], v135, s[4:5] offset:128
	global_load_dwordx4 v[44:47], v136, s[4:5] offset:128
	global_load_dwordx4 v[48:51], v137, s[4:5] offset:128
	global_load_dwordx4 v[52:55], v138, s[4:5] offset:128
	global_load_dwordx4 v[32:35], v135, s[6:7] offset:128
	global_load_dwordx4 v[36:39], v136, s[6:7] offset:128
	v_lshrrev_b32_e32 v3, 1, v1
	v_and_b32_e32 v1, 31, v1
	v_and_or_b32 v4, v3, 32, v1
	v_and_b32_e32 v2, 16, v3
	v_and_or_b32 v1, v3, s44, v1
	v_mad_u64_u32 v[84:85], s[18:19], v1, s43, v[2:3]
	s_waitcnt lgkmcnt(0)
	s_barrier
	ds_read_b128 v[56:59], v84 offset:4608
	ds_read_b128 v[60:63], v84
	v_mad_u32_u24 v83, v4, s43, v2
	ds_read_b128 v[140:143], v84 offset:32
	ds_read_b128 v[64:67], v83 offset:36864
	ds_read_b128 v[144:147], v84 offset:4640
	v_mov_b32_e32 v1, v0
	v_mov_b32_e32 v2, v0
	v_mov_b32_e32 v3, v0
	v_mov_b32_e32 v4, v0
	v_mov_b32_e32 v5, v0
	v_mov_b32_e32 v6, v0
	v_mov_b32_e32 v7, v0
	v_mov_b32_e32 v8, v0
	v_mov_b32_e32 v9, v0
	v_mov_b32_e32 v10, v0
	v_mov_b32_e32 v11, v0
	v_mov_b32_e32 v12, v0
	v_mov_b32_e32 v13, v0
	v_mov_b32_e32 v14, v0
	v_mov_b32_e32 v15, v0
	ds_read_b128 v[148:151], v83 offset:36896
	s_waitcnt lgkmcnt(2)
	v_mfma_f32_32x32x16_bf16 v[16:31], v[64:67], v[60:63], v[0:15]
	v_mfma_f32_32x32x16_bf16 v[0:15], v[64:67], v[56:59], v[0:15]
	s_waitcnt lgkmcnt(0)
	v_mfma_f32_32x32x16_bf16 v[16:31], v[148:151], v[140:143], v[16:31]
	v_mfma_f32_32x32x16_bf16 v[0:15], v[148:151], v[144:147], v[0:15]
	ds_read_b128 v[152:155], v84 offset:64
	ds_read_b128 v[156:159], v84 offset:4672
	ds_read_b128 v[164:167], v83 offset:36928
	s_waitcnt lgkmcnt(0)
	v_mfma_f32_32x32x16_bf16 v[16:31], v[164:167], v[152:155], v[16:31]
	v_mfma_f32_32x32x16_bf16 v[0:15], v[164:167], v[156:159], v[0:15]
	global_load_dwordx4 v[64:67], v135, s[4:5] offset:256
	global_load_dwordx4 v[68:71], v136, s[4:5] offset:256
	global_load_dwordx4 v[72:75], v137, s[4:5] offset:256
	global_load_dwordx4 v[76:79], v138, s[4:5] offset:256
	global_load_dwordx4 v[56:59], v135, s[6:7] offset:256
	global_load_dwordx4 v[60:63], v136, s[6:7] offset:256
	s_waitcnt vmcnt(11)
	ds_write_b128 v82, v[40:43] offset:18432
	s_waitcnt vmcnt(10)
	ds_write_b128 v82, v[44:47] offset:23040
	s_waitcnt vmcnt(9)
	ds_write_b128 v82, v[48:51] offset:27648
	s_waitcnt vmcnt(8)
	ds_write_b128 v82, v[52:55] offset:32256
	ds_read_b128 v[40:43], v84 offset:96
	ds_read_b128 v[44:47], v84 offset:4704
	ds_read_b128 v[48:51], v83 offset:36960
	s_waitcnt vmcnt(7)
	ds_write_b128 v82, v[32:35] offset:46080
	s_waitcnt vmcnt(6)
	ds_write_b128 v82, v[36:39] offset:50688
	s_waitcnt lgkmcnt(2)
	v_mfma_f32_32x32x16_bf16 v[16:31], v[48:51], v[40:43], v[16:31]
	s_waitcnt lgkmcnt(0)
	s_barrier
	v_mfma_f32_32x32x16_bf16 v[0:15], v[48:51], v[44:47], v[0:15]
	ds_read_b128 v[32:35], v84 offset:23040
	ds_read_b128 v[36:39], v84 offset:18432
	ds_read_b128 v[48:51], v83 offset:46080
	ds_read_b128 v[40:43], v84 offset:18464
	ds_read_b128 v[44:47], v84 offset:23072
	ds_read_b128 v[52:55], v83 offset:46112
	s_waitcnt lgkmcnt(3)
	v_mfma_f32_32x32x16_bf16 v[16:31], v[48:51], v[36:39], v[16:31]
	v_mfma_f32_32x32x16_bf16 v[0:15], v[48:51], v[32:35], v[0:15]
	global_load_dwordx4 v[32:35], v135, s[4:5] offset:384
	global_load_dwordx4 v[36:39], v136, s[4:5] offset:384
	global_load_dwordx4 v[48:51], v137, s[4:5] offset:384
	global_load_dwordx4 v[140:143], v138, s[4:5] offset:384
	global_load_dwordx4 v[144:147], v135, s[6:7] offset:384
	global_load_dwordx4 v[148:151], v136, s[6:7] offset:384
	ds_read_b128 v[152:155], v84 offset:18496
	ds_read_b128 v[156:159], v84 offset:23104
	ds_read_b128 v[164:167], v83 offset:46144
	s_waitcnt vmcnt(11)
	ds_write_b128 v82, v[64:67]
	s_waitcnt vmcnt(10)
	ds_write_b128 v82, v[68:71] offset:4608
	s_waitcnt vmcnt(9)
	ds_write_b128 v82, v[72:75] offset:9216
	s_waitcnt vmcnt(8)
	ds_write_b128 v82, v[76:79] offset:13824
	s_waitcnt lgkmcnt(7)
	v_mfma_f32_32x32x16_bf16 v[16:31], v[52:55], v[40:43], v[16:31]
	v_mfma_f32_32x32x16_bf16 v[0:15], v[52:55], v[44:47], v[0:15]
	ds_read_b128 v[40:43], v84 offset:18528
	ds_read_b128 v[44:47], v84 offset:23136
	ds_read_b128 v[52:55], v83 offset:46176
	s_waitcnt vmcnt(7)
	ds_write_b128 v82, v[56:59] offset:36864
	s_waitcnt vmcnt(6)
	ds_write_b128 v82, v[60:63] offset:41472
	s_waitcnt lgkmcnt(0)
	s_barrier
	v_mfma_f32_32x32x16_bf16 v[16:31], v[164:167], v[152:155], v[16:31]
	v_mfma_f32_32x32x16_bf16 v[0:15], v[164:167], v[156:159], v[0:15]
	v_mfma_f32_32x32x16_bf16 v[16:31], v[52:55], v[40:43], v[16:31]
	v_mfma_f32_32x32x16_bf16 v[0:15], v[52:55], v[44:47], v[0:15]
	ds_read_b128 v[40:43], v84 offset:4608
	ds_read_b128 v[44:47], v84
	ds_read_b128 v[60:63], v83 offset:36864
	ds_read_b128 v[52:55], v84 offset:32
	ds_read_b128 v[56:59], v84 offset:4640
	ds_read_b128 v[64:67], v83 offset:36896
	s_waitcnt lgkmcnt(3)
	v_mfma_f32_32x32x16_bf16 v[16:31], v[60:63], v[44:47], v[16:31]
	v_mfma_f32_32x32x16_bf16 v[0:15], v[60:63], v[40:43], v[0:15]
	global_load_dwordx4 v[40:43], v135, s[4:5] offset:512
	global_load_dwordx4 v[44:47], v136, s[4:5] offset:512
	global_load_dwordx4 v[60:63], v137, s[4:5] offset:512
	global_load_dwordx4 v[68:71], v138, s[4:5] offset:512
	global_load_dwordx4 v[72:75], v135, s[6:7] offset:512
	global_load_dwordx4 v[76:79], v136, s[6:7] offset:512
	ds_read_b128 v[152:155], v84 offset:64
	ds_read_b128 v[156:159], v84 offset:4672
	ds_read_b128 v[164:167], v83 offset:36928
	s_waitcnt vmcnt(11)
	ds_write_b128 v82, v[32:35] offset:18432
	s_waitcnt vmcnt(10)
	ds_write_b128 v82, v[36:39] offset:23040
	s_waitcnt vmcnt(9)
	ds_write_b128 v82, v[48:51] offset:27648
	s_waitcnt vmcnt(8)
	ds_write_b128 v82, v[140:143] offset:32256
	s_waitcnt lgkmcnt(7)
	v_mfma_f32_32x32x16_bf16 v[16:31], v[64:67], v[52:55], v[16:31]
	v_mfma_f32_32x32x16_bf16 v[0:15], v[64:67], v[56:59], v[0:15]
	ds_read_b128 v[32:35], v84 offset:96
	ds_read_b128 v[36:39], v84 offset:4704
	ds_read_b128 v[48:51], v83 offset:36960
	s_waitcnt vmcnt(7)
	ds_write_b128 v82, v[144:147] offset:46080
	s_waitcnt vmcnt(6)
	ds_write_b128 v82, v[148:151] offset:50688
	s_waitcnt lgkmcnt(0)
	s_barrier
	v_mfma_f32_32x32x16_bf16 v[16:31], v[164:167], v[152:155], v[16:31]
	v_mfma_f32_32x32x16_bf16 v[0:15], v[164:167], v[156:159], v[0:15]
	v_mfma_f32_32x32x16_bf16 v[16:31], v[48:51], v[32:35], v[16:31]
	v_mfma_f32_32x32x16_bf16 v[0:15], v[48:51], v[36:39], v[0:15]
	ds_read_b128 v[32:35], v84 offset:23040
	ds_read_b128 v[36:39], v84 offset:18432
	ds_read_b128 v[56:59], v83 offset:46080
	ds_read_b128 v[48:51], v84 offset:18464
	ds_read_b128 v[52:55], v84 offset:23072
	ds_read_b128 v[64:67], v83 offset:46112
	s_waitcnt lgkmcnt(3)
	v_mfma_f32_32x32x16_bf16 v[16:31], v[56:59], v[36:39], v[16:31]
	v_mfma_f32_32x32x16_bf16 v[0:15], v[56:59], v[32:35], v[0:15]
	global_load_dwordx4 v[32:35], v135, s[4:5] offset:640
	global_load_dwordx4 v[36:39], v136, s[4:5] offset:640
	global_load_dwordx4 v[56:59], v137, s[4:5] offset:640
	global_load_dwordx4 v[140:143], v138, s[4:5] offset:640
	global_load_dwordx4 v[144:147], v135, s[6:7] offset:640
	global_load_dwordx4 v[148:151], v136, s[6:7] offset:640
	ds_read_b128 v[152:155], v84 offset:18496
	ds_read_b128 v[156:159], v84 offset:23104
	ds_read_b128 v[164:167], v83 offset:46144
	s_waitcnt vmcnt(11)
	ds_write_b128 v82, v[40:43]
	s_waitcnt vmcnt(10)
	ds_write_b128 v82, v[44:47] offset:4608
	s_waitcnt vmcnt(9)
	ds_write_b128 v82, v[60:63] offset:9216
	s_waitcnt vmcnt(8)
	ds_write_b128 v82, v[68:71] offset:13824
	s_waitcnt lgkmcnt(7)
	v_mfma_f32_32x32x16_bf16 v[16:31], v[64:67], v[48:51], v[16:31]
	v_mfma_f32_32x32x16_bf16 v[0:15], v[64:67], v[52:55], v[0:15]
	ds_read_b128 v[40:43], v84 offset:18528
	ds_read_b128 v[44:47], v84 offset:23136
	ds_read_b128 v[48:51], v83 offset:46176
	s_waitcnt vmcnt(7)
	ds_write_b128 v82, v[72:75] offset:36864
	s_waitcnt vmcnt(6)
	ds_write_b128 v82, v[76:79] offset:41472
	s_waitcnt lgkmcnt(0)
	s_barrier
	v_mfma_f32_32x32x16_bf16 v[16:31], v[164:167], v[152:155], v[16:31]
	v_mfma_f32_32x32x16_bf16 v[0:15], v[164:167], v[156:159], v[0:15]
	v_mfma_f32_32x32x16_bf16 v[16:31], v[48:51], v[40:43], v[16:31]
	v_mfma_f32_32x32x16_bf16 v[0:15], v[48:51], v[44:47], v[0:15]
	ds_read_b128 v[40:43], v84 offset:4608
	ds_read_b128 v[44:47], v84
	ds_read_b128 v[60:63], v83 offset:36864
	ds_read_b128 v[48:51], v84 offset:32
	ds_read_b128 v[52:55], v84 offset:4640
	ds_read_b128 v[64:67], v83 offset:36896
	s_waitcnt lgkmcnt(3)
	v_mfma_f32_32x32x16_bf16 v[16:31], v[60:63], v[44:47], v[16:31]
	v_mfma_f32_32x32x16_bf16 v[0:15], v[60:63], v[40:43], v[0:15]
	global_load_dwordx4 v[40:43], v135, s[4:5] offset:768
	global_load_dwordx4 v[44:47], v136, s[4:5] offset:768
	global_load_dwordx4 v[60:63], v137, s[4:5] offset:768
	global_load_dwordx4 v[68:71], v138, s[4:5] offset:768
	global_load_dwordx4 v[72:75], v135, s[6:7] offset:768
	global_load_dwordx4 v[76:79], v136, s[6:7] offset:768
	ds_read_b128 v[152:155], v84 offset:64
	ds_read_b128 v[156:159], v84 offset:4672
	ds_read_b128 v[164:167], v83 offset:36928
	s_waitcnt vmcnt(11)
	ds_write_b128 v82, v[32:35] offset:18432
	s_waitcnt vmcnt(10)
	ds_write_b128 v82, v[36:39] offset:23040
	s_waitcnt vmcnt(9)
	ds_write_b128 v82, v[56:59] offset:27648
	s_waitcnt vmcnt(8)
	ds_write_b128 v82, v[140:143] offset:32256
	s_waitcnt lgkmcnt(7)
	v_mfma_f32_32x32x16_bf16 v[16:31], v[64:67], v[48:51], v[16:31]
	v_mfma_f32_32x32x16_bf16 v[0:15], v[64:67], v[52:55], v[0:15]
	ds_read_b128 v[32:35], v84 offset:96
	ds_read_b128 v[36:39], v84 offset:4704
	ds_read_b128 v[48:51], v83 offset:36960
	s_waitcnt vmcnt(7)
	ds_write_b128 v82, v[144:147] offset:46080
	s_waitcnt vmcnt(6)
	ds_write_b128 v82, v[148:151] offset:50688
	s_waitcnt lgkmcnt(0)
	s_barrier
	v_mfma_f32_32x32x16_bf16 v[16:31], v[164:167], v[152:155], v[16:31]
	v_mfma_f32_32x32x16_bf16 v[0:15], v[164:167], v[156:159], v[0:15]
	v_mfma_f32_32x32x16_bf16 v[16:31], v[48:51], v[32:35], v[16:31]
	v_mfma_f32_32x32x16_bf16 v[0:15], v[48:51], v[36:39], v[0:15]
	ds_read_b128 v[32:35], v84 offset:23040
	ds_read_b128 v[36:39], v84 offset:18432
	ds_read_b128 v[56:59], v83 offset:46080
	ds_read_b128 v[48:51], v84 offset:18464
	ds_read_b128 v[52:55], v84 offset:23072
	ds_read_b128 v[64:67], v83 offset:46112
	s_waitcnt lgkmcnt(3)
	v_mfma_f32_32x32x16_bf16 v[16:31], v[56:59], v[36:39], v[16:31]
	v_mfma_f32_32x32x16_bf16 v[0:15], v[56:59], v[32:35], v[0:15]
	global_load_dwordx4 v[32:35], v135, s[4:5] offset:896
	global_load_dwordx4 v[36:39], v136, s[4:5] offset:896
	global_load_dwordx4 v[56:59], v137, s[4:5] offset:896
	global_load_dwordx4 v[140:143], v138, s[4:5] offset:896
	global_load_dwordx4 v[144:147], v135, s[6:7] offset:896
	global_load_dwordx4 v[148:151], v136, s[6:7] offset:896
	ds_read_b128 v[152:155], v84 offset:18496
	ds_read_b128 v[156:159], v84 offset:23104
	ds_read_b128 v[164:167], v83 offset:46144
	s_waitcnt vmcnt(11)
	ds_write_b128 v82, v[40:43]
	s_waitcnt vmcnt(10)
	ds_write_b128 v82, v[44:47] offset:4608
	s_waitcnt vmcnt(9)
	ds_write_b128 v82, v[60:63] offset:9216
	s_waitcnt vmcnt(8)
	ds_write_b128 v82, v[68:71] offset:13824
	s_waitcnt lgkmcnt(7)
	v_mfma_f32_32x32x16_bf16 v[16:31], v[64:67], v[48:51], v[16:31]
	v_mfma_f32_32x32x16_bf16 v[0:15], v[64:67], v[52:55], v[0:15]
	ds_read_b128 v[40:43], v84 offset:18528
	ds_read_b128 v[44:47], v84 offset:23136
	ds_read_b128 v[48:51], v83 offset:46176
	s_waitcnt vmcnt(7)
	ds_write_b128 v82, v[72:75] offset:36864
	s_waitcnt vmcnt(6)
	ds_write_b128 v82, v[76:79] offset:41472
	s_waitcnt lgkmcnt(0)
	s_barrier
	v_mfma_f32_32x32x16_bf16 v[16:31], v[164:167], v[152:155], v[16:31]
	v_mfma_f32_32x32x16_bf16 v[0:15], v[164:167], v[156:159], v[0:15]
	v_mfma_f32_32x32x16_bf16 v[16:31], v[48:51], v[40:43], v[16:31]
	v_mfma_f32_32x32x16_bf16 v[0:15], v[48:51], v[44:47], v[0:15]
	ds_read_b128 v[40:43], v84 offset:4608
	ds_read_b128 v[44:47], v84
	ds_read_b128 v[60:63], v83 offset:36864
	ds_read_b128 v[48:51], v84 offset:32
	ds_read_b128 v[52:55], v84 offset:4640
	ds_read_b128 v[64:67], v83 offset:36896
	s_waitcnt lgkmcnt(3)
	v_mfma_f32_32x32x16_bf16 v[16:31], v[60:63], v[44:47], v[16:31]
	v_mfma_f32_32x32x16_bf16 v[0:15], v[60:63], v[40:43], v[0:15]
	global_load_dwordx4 v[40:43], v135, s[4:5] offset:1024
	global_load_dwordx4 v[44:47], v136, s[4:5] offset:1024
	global_load_dwordx4 v[60:63], v137, s[4:5] offset:1024
	global_load_dwordx4 v[68:71], v138, s[4:5] offset:1024
	global_load_dwordx4 v[72:75], v135, s[6:7] offset:1024
	global_load_dwordx4 v[76:79], v136, s[6:7] offset:1024
	ds_read_b128 v[152:155], v84 offset:64
	ds_read_b128 v[156:159], v84 offset:4672
	ds_read_b128 v[164:167], v83 offset:36928
	s_waitcnt vmcnt(11)
	ds_write_b128 v82, v[32:35] offset:18432
	s_waitcnt vmcnt(10)
	ds_write_b128 v82, v[36:39] offset:23040
	s_waitcnt vmcnt(9)
	ds_write_b128 v82, v[56:59] offset:27648
	s_waitcnt vmcnt(8)
	ds_write_b128 v82, v[140:143] offset:32256
	s_waitcnt lgkmcnt(7)
	v_mfma_f32_32x32x16_bf16 v[16:31], v[64:67], v[48:51], v[16:31]
	v_mfma_f32_32x32x16_bf16 v[0:15], v[64:67], v[52:55], v[0:15]
	ds_read_b128 v[32:35], v84 offset:96
	ds_read_b128 v[36:39], v84 offset:4704
	ds_read_b128 v[48:51], v83 offset:36960
	s_waitcnt vmcnt(7)
	ds_write_b128 v82, v[144:147] offset:46080
	s_waitcnt vmcnt(6)
	ds_write_b128 v82, v[148:151] offset:50688
	s_waitcnt lgkmcnt(0)
	s_barrier
	v_mfma_f32_32x32x16_bf16 v[16:31], v[164:167], v[152:155], v[16:31]
	v_mfma_f32_32x32x16_bf16 v[0:15], v[164:167], v[156:159], v[0:15]
	v_mfma_f32_32x32x16_bf16 v[16:31], v[48:51], v[32:35], v[16:31]
	v_mfma_f32_32x32x16_bf16 v[0:15], v[48:51], v[36:39], v[0:15]
	ds_read_b128 v[32:35], v84 offset:23040
	ds_read_b128 v[36:39], v84 offset:18432
	ds_read_b128 v[56:59], v83 offset:46080
	ds_read_b128 v[48:51], v84 offset:18464
	ds_read_b128 v[52:55], v84 offset:23072
	ds_read_b128 v[64:67], v83 offset:46112
	s_waitcnt lgkmcnt(3)
	v_mfma_f32_32x32x16_bf16 v[16:31], v[56:59], v[36:39], v[16:31]
	v_mfma_f32_32x32x16_bf16 v[0:15], v[56:59], v[32:35], v[0:15]
	global_load_dwordx4 v[32:35], v135, s[4:5] offset:1152
	global_load_dwordx4 v[36:39], v136, s[4:5] offset:1152
	global_load_dwordx4 v[56:59], v137, s[4:5] offset:1152
	global_load_dwordx4 v[140:143], v138, s[4:5] offset:1152
	global_load_dwordx4 v[144:147], v135, s[6:7] offset:1152
	global_load_dwordx4 v[148:151], v136, s[6:7] offset:1152
	ds_read_b128 v[152:155], v84 offset:18496
	ds_read_b128 v[156:159], v84 offset:23104
	ds_read_b128 v[164:167], v83 offset:46144
	s_waitcnt vmcnt(11)
	ds_write_b128 v82, v[40:43]
	s_waitcnt vmcnt(10)
	ds_write_b128 v82, v[44:47] offset:4608
	s_waitcnt vmcnt(9)
	ds_write_b128 v82, v[60:63] offset:9216
	s_waitcnt vmcnt(8)
	ds_write_b128 v82, v[68:71] offset:13824
	s_waitcnt lgkmcnt(7)
	v_mfma_f32_32x32x16_bf16 v[16:31], v[64:67], v[48:51], v[16:31]
	v_mfma_f32_32x32x16_bf16 v[0:15], v[64:67], v[52:55], v[0:15]
	ds_read_b128 v[40:43], v84 offset:18528
	ds_read_b128 v[44:47], v84 offset:23136
	ds_read_b128 v[48:51], v83 offset:46176
	s_waitcnt vmcnt(7)
	ds_write_b128 v82, v[72:75] offset:36864
	s_waitcnt vmcnt(6)
	ds_write_b128 v82, v[76:79] offset:41472
	s_waitcnt lgkmcnt(0)
	s_barrier
	v_mfma_f32_32x32x16_bf16 v[16:31], v[164:167], v[152:155], v[16:31]
	v_mfma_f32_32x32x16_bf16 v[0:15], v[164:167], v[156:159], v[0:15]
	v_mfma_f32_32x32x16_bf16 v[16:31], v[48:51], v[40:43], v[16:31]
	v_mfma_f32_32x32x16_bf16 v[0:15], v[48:51], v[44:47], v[0:15]
	ds_read_b128 v[40:43], v84 offset:4608
	ds_read_b128 v[44:47], v84
	ds_read_b128 v[60:63], v83 offset:36864
	ds_read_b128 v[48:51], v84 offset:32
	ds_read_b128 v[52:55], v84 offset:4640
	ds_read_b128 v[64:67], v83 offset:36896
	s_waitcnt lgkmcnt(3)
	v_mfma_f32_32x32x16_bf16 v[16:31], v[60:63], v[44:47], v[16:31]
	v_mfma_f32_32x32x16_bf16 v[0:15], v[60:63], v[40:43], v[0:15]
	global_load_dwordx4 v[40:43], v135, s[4:5] offset:1280
	global_load_dwordx4 v[44:47], v136, s[4:5] offset:1280
	global_load_dwordx4 v[60:63], v137, s[4:5] offset:1280
	global_load_dwordx4 v[68:71], v138, s[4:5] offset:1280
	global_load_dwordx4 v[72:75], v135, s[6:7] offset:1280
	global_load_dwordx4 v[76:79], v136, s[6:7] offset:1280
	ds_read_b128 v[152:155], v84 offset:64
	ds_read_b128 v[156:159], v84 offset:4672
	ds_read_b128 v[164:167], v83 offset:36928
	s_waitcnt vmcnt(11)
	ds_write_b128 v82, v[32:35] offset:18432
	s_waitcnt vmcnt(10)
	ds_write_b128 v82, v[36:39] offset:23040
	s_waitcnt vmcnt(9)
	ds_write_b128 v82, v[56:59] offset:27648
	s_waitcnt vmcnt(8)
	ds_write_b128 v82, v[140:143] offset:32256
	s_waitcnt lgkmcnt(7)
	v_mfma_f32_32x32x16_bf16 v[16:31], v[64:67], v[48:51], v[16:31]
	v_mfma_f32_32x32x16_bf16 v[0:15], v[64:67], v[52:55], v[0:15]
	ds_read_b128 v[32:35], v84 offset:96
	ds_read_b128 v[36:39], v84 offset:4704
	ds_read_b128 v[48:51], v83 offset:36960
	s_waitcnt vmcnt(7)
	ds_write_b128 v82, v[144:147] offset:46080
	s_waitcnt vmcnt(6)
	ds_write_b128 v82, v[148:151] offset:50688
	s_waitcnt lgkmcnt(0)
	s_barrier
	v_mfma_f32_32x32x16_bf16 v[16:31], v[164:167], v[152:155], v[16:31]
	v_mfma_f32_32x32x16_bf16 v[0:15], v[164:167], v[156:159], v[0:15]
	v_mfma_f32_32x32x16_bf16 v[16:31], v[48:51], v[32:35], v[16:31]
	v_mfma_f32_32x32x16_bf16 v[0:15], v[48:51], v[36:39], v[0:15]
	ds_read_b128 v[32:35], v84 offset:23040
	ds_read_b128 v[36:39], v84 offset:18432
	ds_read_b128 v[56:59], v83 offset:46080
	ds_read_b128 v[48:51], v84 offset:18464
	ds_read_b128 v[52:55], v84 offset:23072
	ds_read_b128 v[64:67], v83 offset:46112
	s_waitcnt lgkmcnt(3)
	v_mfma_f32_32x32x16_bf16 v[16:31], v[56:59], v[36:39], v[16:31]
	v_mfma_f32_32x32x16_bf16 v[0:15], v[56:59], v[32:35], v[0:15]
	global_load_dwordx4 v[32:35], v135, s[4:5] offset:1408
	global_load_dwordx4 v[36:39], v136, s[4:5] offset:1408
	global_load_dwordx4 v[56:59], v137, s[4:5] offset:1408
	global_load_dwordx4 v[140:143], v138, s[4:5] offset:1408
	global_load_dwordx4 v[144:147], v135, s[6:7] offset:1408
	global_load_dwordx4 v[148:151], v136, s[6:7] offset:1408
	ds_read_b128 v[152:155], v84 offset:18496
	ds_read_b128 v[156:159], v84 offset:23104
	ds_read_b128 v[164:167], v83 offset:46144
	s_waitcnt vmcnt(11)
	ds_write_b128 v82, v[40:43]
	s_waitcnt vmcnt(10)
	ds_write_b128 v82, v[44:47] offset:4608
	s_waitcnt vmcnt(9)
	ds_write_b128 v82, v[60:63] offset:9216
	s_waitcnt vmcnt(8)
	ds_write_b128 v82, v[68:71] offset:13824
	s_waitcnt lgkmcnt(7)
	v_mfma_f32_32x32x16_bf16 v[16:31], v[64:67], v[48:51], v[16:31]
	v_mfma_f32_32x32x16_bf16 v[0:15], v[64:67], v[52:55], v[0:15]
	ds_read_b128 v[40:43], v84 offset:18528
	ds_read_b128 v[44:47], v84 offset:23136
	ds_read_b128 v[48:51], v83 offset:46176
	s_waitcnt vmcnt(7)
	ds_write_b128 v82, v[72:75] offset:36864
	s_waitcnt vmcnt(6)
	ds_write_b128 v82, v[76:79] offset:41472
	s_waitcnt lgkmcnt(0)
	s_barrier
	v_mfma_f32_32x32x16_bf16 v[16:31], v[164:167], v[152:155], v[16:31]
	v_mfma_f32_32x32x16_bf16 v[0:15], v[164:167], v[156:159], v[0:15]
	v_mfma_f32_32x32x16_bf16 v[16:31], v[48:51], v[40:43], v[16:31]
	v_mfma_f32_32x32x16_bf16 v[0:15], v[48:51], v[44:47], v[0:15]
	ds_read_b128 v[40:43], v84 offset:4608
	ds_read_b128 v[44:47], v84
	ds_read_b128 v[60:63], v83 offset:36864
	ds_read_b128 v[48:51], v84 offset:32
	ds_read_b128 v[52:55], v84 offset:4640
	ds_read_b128 v[64:67], v83 offset:36896
	s_waitcnt lgkmcnt(3)
	v_mfma_f32_32x32x16_bf16 v[16:31], v[60:63], v[44:47], v[16:31]
	v_mfma_f32_32x32x16_bf16 v[0:15], v[60:63], v[40:43], v[0:15]
	global_load_dwordx4 v[40:43], v135, s[4:5] offset:1536
	global_load_dwordx4 v[44:47], v136, s[4:5] offset:1536
	global_load_dwordx4 v[60:63], v137, s[4:5] offset:1536
	global_load_dwordx4 v[68:71], v138, s[4:5] offset:1536
	global_load_dwordx4 v[72:75], v135, s[6:7] offset:1536
	global_load_dwordx4 v[76:79], v136, s[6:7] offset:1536
	ds_read_b128 v[152:155], v84 offset:64
	ds_read_b128 v[156:159], v84 offset:4672
	ds_read_b128 v[164:167], v83 offset:36928
	s_waitcnt vmcnt(11)
	ds_write_b128 v82, v[32:35] offset:18432
	s_waitcnt vmcnt(10)
	ds_write_b128 v82, v[36:39] offset:23040
	s_waitcnt vmcnt(9)
	ds_write_b128 v82, v[56:59] offset:27648
	s_waitcnt vmcnt(8)
	ds_write_b128 v82, v[140:143] offset:32256
	s_waitcnt lgkmcnt(7)
	v_mfma_f32_32x32x16_bf16 v[16:31], v[64:67], v[48:51], v[16:31]
	v_mfma_f32_32x32x16_bf16 v[0:15], v[64:67], v[52:55], v[0:15]
	ds_read_b128 v[32:35], v84 offset:96
	ds_read_b128 v[36:39], v84 offset:4704
	ds_read_b128 v[48:51], v83 offset:36960
	s_waitcnt vmcnt(7)
	ds_write_b128 v82, v[144:147] offset:46080
	s_waitcnt vmcnt(6)
	ds_write_b128 v82, v[148:151] offset:50688
	s_waitcnt lgkmcnt(0)
	s_barrier
	v_mfma_f32_32x32x16_bf16 v[16:31], v[164:167], v[152:155], v[16:31]
	v_mfma_f32_32x32x16_bf16 v[0:15], v[164:167], v[156:159], v[0:15]
	v_mfma_f32_32x32x16_bf16 v[16:31], v[48:51], v[32:35], v[16:31]
	v_mfma_f32_32x32x16_bf16 v[0:15], v[48:51], v[36:39], v[0:15]
	ds_read_b128 v[32:35], v84 offset:23040
	ds_read_b128 v[36:39], v84 offset:18432
	ds_read_b128 v[56:59], v83 offset:46080
	ds_read_b128 v[48:51], v84 offset:18464
	ds_read_b128 v[52:55], v84 offset:23072
	ds_read_b128 v[64:67], v83 offset:46112
	s_waitcnt lgkmcnt(3)
	v_mfma_f32_32x32x16_bf16 v[16:31], v[56:59], v[36:39], v[16:31]
	v_mfma_f32_32x32x16_bf16 v[0:15], v[56:59], v[32:35], v[0:15]
	global_load_dwordx4 v[32:35], v135, s[4:5] offset:1664
	global_load_dwordx4 v[36:39], v136, s[4:5] offset:1664
	global_load_dwordx4 v[56:59], v137, s[4:5] offset:1664
	global_load_dwordx4 v[140:143], v138, s[4:5] offset:1664
	global_load_dwordx4 v[144:147], v135, s[6:7] offset:1664
	global_load_dwordx4 v[148:151], v136, s[6:7] offset:1664
	ds_read_b128 v[152:155], v84 offset:18496
	ds_read_b128 v[156:159], v84 offset:23104
	ds_read_b128 v[164:167], v83 offset:46144
	s_waitcnt vmcnt(11)
	ds_write_b128 v82, v[40:43]
	s_waitcnt vmcnt(10)
	ds_write_b128 v82, v[44:47] offset:4608
	s_waitcnt vmcnt(9)
	ds_write_b128 v82, v[60:63] offset:9216
	s_waitcnt vmcnt(8)
	ds_write_b128 v82, v[68:71] offset:13824
	s_waitcnt lgkmcnt(7)
	v_mfma_f32_32x32x16_bf16 v[16:31], v[64:67], v[48:51], v[16:31]
	v_mfma_f32_32x32x16_bf16 v[0:15], v[64:67], v[52:55], v[0:15]
	ds_read_b128 v[40:43], v84 offset:18528
	ds_read_b128 v[44:47], v84 offset:23136
	ds_read_b128 v[48:51], v83 offset:46176
	s_waitcnt vmcnt(7)
	ds_write_b128 v82, v[72:75] offset:36864
	s_waitcnt vmcnt(6)
	ds_write_b128 v82, v[76:79] offset:41472
	s_waitcnt lgkmcnt(0)
	s_barrier
	v_mfma_f32_32x32x16_bf16 v[16:31], v[164:167], v[152:155], v[16:31]
	ds_read_b128 v[60:63], v83 offset:36864
	ds_read_b128 v[52:55], v84 offset:4640
	global_load_dwordx4 v[68:71], v138, s[4:5] offset:1792
	ds_read_b128 v[64:67], v83 offset:36896
	ds_read_b128 v[152:155], v84 offset:64
	global_load_dwordx4 v[72:75], v135, s[6:7] offset:1792
	v_mfma_f32_32x32x16_bf16 v[0:15], v[164:167], v[156:159], v[0:15]
	ds_read_b128 v[156:159], v84 offset:4672
	global_load_dwordx4 v[76:79], v136, s[6:7] offset:1792
	ds_read_b128 v[164:167], v83 offset:36928
	v_mfma_f32_32x32x16_bf16 v[16:31], v[48:51], v[40:43], v[16:31]
	ds_read_b128 v[40:43], v84 offset:4608
	v_mfma_f32_32x32x16_bf16 v[0:15], v[48:51], v[44:47], v[0:15]
	ds_read_b128 v[44:47], v84
	ds_read_b128 v[48:51], v84 offset:32
	s_waitcnt vmcnt(8)
	ds_write_b128 v82, v[32:35] offset:18432
	s_waitcnt lgkmcnt(2)
	v_mfma_f32_32x32x16_bf16 v[16:31], v[60:63], v[44:47], v[16:31]
	global_load_dwordx4 v[44:47], v136, s[4:5] offset:1792
	s_waitcnt vmcnt(8)
	ds_write_b128 v82, v[36:39] offset:23040
	s_waitcnt vmcnt(7)
	ds_write_b128 v82, v[56:59] offset:27648
	s_waitcnt vmcnt(6)
	ds_write_b128 v82, v[140:143] offset:32256
	ds_read_b128 v[32:35], v84 offset:96
	ds_read_b128 v[36:39], v84 offset:4704
	v_mfma_f32_32x32x16_bf16 v[0:15], v[60:63], v[40:43], v[0:15]
	global_load_dwordx4 v[40:43], v135, s[4:5] offset:1792
	global_load_dwordx4 v[60:63], v137, s[4:5] offset:1792
	s_waitcnt lgkmcnt(6)
	v_mfma_f32_32x32x16_bf16 v[16:31], v[64:67], v[48:51], v[16:31]
	ds_read_b128 v[48:51], v83 offset:36960
	s_waitcnt vmcnt(7)
	ds_write_b128 v82, v[144:147] offset:46080
	s_waitcnt vmcnt(6)
	ds_write_b128 v82, v[148:151] offset:50688
	s_waitcnt lgkmcnt(0)
	s_barrier
	ds_read_b128 v[56:59], v83 offset:46080
	v_mfma_f32_32x32x16_bf16 v[0:15], v[64:67], v[52:55], v[0:15]
	global_load_dwordx4 v[138:141], v138, s[4:5] offset:1920
	ds_read_b128 v[52:55], v84 offset:23072
	global_load_dwordx4 v[142:145], v135, s[6:7] offset:1920
	global_load_dwordx4 v[146:149], v136, s[6:7] offset:1920
	ds_read_b128 v[64:67], v83 offset:46112
	v_mfma_f32_32x32x16_bf16 v[16:31], v[164:167], v[152:155], v[16:31]
	ds_read_b128 v[150:153], v84 offset:18496
	v_mfma_f32_32x32x16_bf16 v[0:15], v[164:167], v[156:159], v[0:15]
	ds_read_b128 v[154:157], v84 offset:23104
	ds_read_b128 v[164:167], v83 offset:46144
	v_mfma_f32_32x32x16_bf16 v[16:31], v[48:51], v[32:35], v[16:31]
	ds_read_b128 v[32:35], v84 offset:23040
	v_mfma_f32_32x32x16_bf16 v[0:15], v[48:51], v[36:39], v[0:15]
	ds_read_b128 v[36:39], v84 offset:18432
	ds_read_b128 v[48:51], v84 offset:18464
	s_waitcnt vmcnt(8)
	ds_write_b128 v82, v[68:71] offset:13824
	s_waitcnt vmcnt(5)
	ds_write_b128 v82, v[44:47] offset:4608
	s_waitcnt lgkmcnt(3)
	v_mfma_f32_32x32x16_bf16 v[16:31], v[56:59], v[36:39], v[16:31]
	global_load_dwordx4 v[36:39], v136, s[4:5] offset:1920
	s_waitcnt vmcnt(5)
	ds_write_b128 v82, v[40:43]
	v_mfma_f32_32x32x16_bf16 v[0:15], v[56:59], v[32:35], v[0:15]
	global_load_dwordx4 v[32:35], v135, s[4:5] offset:1920
	global_load_dwordx4 v[56:59], v137, s[4:5] offset:1920
	s_waitcnt vmcnt(6)
	ds_write_b128 v82, v[60:63] offset:9216
	ds_read_b128 v[40:43], v84 offset:18528
	ds_read_b128 v[44:47], v84 offset:23136
	s_waitcnt lgkmcnt(6)
	v_mfma_f32_32x32x16_bf16 v[16:31], v[64:67], v[48:51], v[16:31]
	ds_read_b128 v[48:51], v83 offset:46176
	ds_write_b128 v82, v[72:75] offset:36864
	ds_write_b128 v82, v[76:79] offset:41472
	s_waitcnt lgkmcnt(0)
	s_barrier
	ds_read_b128 v[60:63], v84 offset:32
	v_mfma_f32_32x32x16_bf16 v[0:15], v[64:67], v[52:55], v[0:15]
	ds_read_b128 v[52:55], v84
	ds_read_b128 v[64:67], v83 offset:36928
	v_mfma_f32_32x32x16_bf16 v[16:31], v[164:167], v[150:153], v[16:31]
	v_mfma_f32_32x32x16_bf16 v[0:15], v[164:167], v[154:157], v[0:15]
	v_mfma_f32_32x32x16_bf16 v[16:31], v[48:51], v[40:43], v[16:31]
	ds_read_b128 v[40:43], v84 offset:4608
	v_mfma_f32_32x32x16_bf16 v[0:15], v[48:51], v[44:47], v[0:15]
	ds_read_b128 v[44:47], v83 offset:36864
	ds_read_b128 v[48:51], v83 offset:36896
	s_waitcnt lgkmcnt(1)
	v_mfma_f32_32x32x16_bf16 v[0:15], v[44:47], v[40:43], v[0:15]
	ds_read_b128 v[40:43], v84 offset:4640
	v_mfma_f32_32x32x16_bf16 v[16:31], v[44:47], v[52:55], v[16:31]
	ds_read_b128 v[52:55], v84 offset:4672
	ds_read_b128 v[44:47], v84 offset:64
	s_waitcnt vmcnt(5)
	ds_write_b128 v82, v[138:141] offset:32256
	s_waitcnt vmcnt(2)
	ds_write_b128 v82, v[36:39] offset:23040
	s_waitcnt lgkmcnt(4)
	v_mfma_f32_32x32x16_bf16 v[0:15], v[48:51], v[40:43], v[0:15]
	s_waitcnt vmcnt(1)
	ds_write_b128 v82, v[32:35] offset:18432
	v_mfma_f32_32x32x16_bf16 v[16:31], v[48:51], v[60:63], v[16:31]
	s_waitcnt vmcnt(0)
	ds_write_b128 v82, v[56:59] offset:27648
	ds_read_b128 v[36:39], v84 offset:4704
	ds_read_b128 v[32:35], v84 offset:96
	ds_read_b128 v[40:43], v83 offset:36960
	ds_write_b128 v82, v[142:145] offset:46080
	ds_write_b128 v82, v[146:149] offset:50688
	s_waitcnt lgkmcnt(0)
	v_mfma_f32_32x32x16_bf16 v[0:15], v[64:67], v[52:55], v[0:15]
	s_barrier
	ds_read_b128 v[48:51], v83 offset:46080
	ds_read_b128 v[52:55], v83 offset:46112
	ds_read_b128 v[56:59], v84 offset:18528
	ds_read_b128 v[60:63], v84 offset:23136
	v_mfma_f32_32x32x16_bf16 v[16:31], v[64:67], v[44:47], v[16:31]
	ds_read_b128 v[64:67], v83 offset:46176
	ds_read_b128 v[44:47], v84 offset:23072
	v_mfma_f32_32x32x16_bf16 v[0:15], v[40:43], v[36:39], v[0:15]
	ds_read_b128 v[36:39], v84 offset:18432
	v_mfma_f32_32x32x16_bf16 v[16:31], v[40:43], v[32:35], v[16:31]
	ds_read_b128 v[32:35], v84 offset:23040
	ds_read_b128 v[40:43], v84 offset:18464
	s_waitcnt lgkmcnt(2)
	v_mfma_f32_32x32x16_bf16 v[16:31], v[48:51], v[36:39], v[16:31]
	ds_read_b128 v[36:39], v84 offset:23104
	s_waitcnt lgkmcnt(2)
	v_mfma_f32_32x32x16_bf16 v[0:15], v[48:51], v[32:35], v[0:15]
	ds_read_b128 v[32:35], v84 offset:18496
	ds_read_b128 v[48:51], v83 offset:46144
	s_waitcnt lgkmcnt(0)
	s_barrier
	v_mfma_f32_32x32x16_bf16 v[16:31], v[52:55], v[40:43], v[16:31]
	v_mfma_f32_32x32x16_bf16 v[16:31], v[48:51], v[32:35], v[16:31]
	v_mfma_f32_32x32x16_bf16 v[16:31], v[64:67], v[56:59], v[16:31]
	v_mfma_f32_32x32x16_bf16 v[0:15], v[52:55], v[44:47], v[0:15]
	v_mfma_f32_32x32x16_bf16 v[0:15], v[48:51], v[36:39], v[0:15]
	v_mfma_f32_32x32x16_bf16 v[0:15], v[64:67], v[60:63], v[0:15]
	v_readfirstlane_b32 s18, v186
	v_and_b32_e32 v64, 31, v186
	v_bfe_u32 v65, v186, 5, 1
	s_lshr_b32 s18, s18, 6
	s_and_b32 s19, s18, 1
	s_lshr_b32 s18, s18, 1
	s_lshl_b32 s18, s18, 6
	v_add_u32_e32 v64, s18, v64
	v_lshlrev_b32_e32 v64, 12, v64
	v_lshl_add_u32 v64, v65, 4, v64
	s_lshl_b32 s19, s19, 7
	v_add_u32_e32 v64, s19, v64
	v_add_u32_e32 v65, 0x20000, v64
	s_lshl_b32 s18, s0, 12
	s_lshl_b32 s19, s2, 2
	s_add_u32 s18, s18, s19
	s_add_u32 s20, s86, s18
	s_addc_u32 s21, s87, 0
	global_load_dwordx4 v[68:71], v64, s[20:21]
	global_load_dwordx4 v[72:75], v64, s[20:21] offset:32
	global_load_dwordx4 v[76:79], v64, s[20:21] offset:64
	global_load_dwordx4 v[80:83], v64, s[20:21] offset:96
	global_load_dwordx4 v[84:87], v65, s[20:21]
	global_load_dwordx4 v[88:91], v65, s[20:21] offset:32
	global_load_dwordx4 v[92:95], v65, s[20:21] offset:64
	global_load_dwordx4 v[96:99], v65, s[20:21] offset:96
	v_mul_f32_e32 v100, 0xbfb8aa3b, v16
	v_mul_f32_e32 v101, 0xbfb8aa3b, v17
	v_mul_f32_e32 v102, 0xbfb8aa3b, v18
	v_mul_f32_e32 v103, 0xbfb8aa3b, v19
	v_exp_f32_e32 v100, v100
	v_exp_f32_e32 v101, v101
	v_exp_f32_e32 v102, v102
	v_exp_f32_e32 v103, v103
	v_lshlrev_b32_e32 v104, 16, v134
	v_and_b32_e32 v105, 0xffff0000, v134
	v_lshlrev_b32_e32 v106, 16, v133
	v_and_b32_e32 v107, 0xffff0000, v133
	v_add_f32_e32 v100, 1.0, v100
	v_add_f32_e32 v101, 1.0, v101
	v_add_f32_e32 v102, 1.0, v102
	v_add_f32_e32 v103, 1.0, v103
	v_rcp_f32_e32 v100, v100
	v_rcp_f32_e32 v101, v101
	v_rcp_f32_e32 v102, v102
	v_rcp_f32_e32 v103, v103
	s_waitcnt vmcnt(7)
	v_fmac_f32_e32 v68, v100, v104
	v_fmac_f32_e32 v69, v101, v105
	v_fmac_f32_e32 v70, v102, v106
	v_fmac_f32_e32 v71, v103, v107
	global_store_dwordx4 v64, v[68:71], s[20:21]
	v_mul_f32_e32 v100, 0xbfb8aa3b, v20
	v_mul_f32_e32 v101, 0xbfb8aa3b, v21
	v_mul_f32_e32 v102, 0xbfb8aa3b, v22
	v_mul_f32_e32 v103, 0xbfb8aa3b, v23
	v_exp_f32_e32 v100, v100
	v_exp_f32_e32 v101, v101
	v_exp_f32_e32 v102, v102
	v_exp_f32_e32 v103, v103
	v_lshlrev_b32_e32 v104, 16, v132
	v_and_b32_e32 v105, 0xffff0000, v132
	v_lshlrev_b32_e32 v106, 16, v131
	v_and_b32_e32 v107, 0xffff0000, v131
	v_add_f32_e32 v100, 1.0, v100
	v_add_f32_e32 v101, 1.0, v101
	v_add_f32_e32 v102, 1.0, v102
	v_add_f32_e32 v103, 1.0, v103
	v_rcp_f32_e32 v100, v100
	v_rcp_f32_e32 v101, v101
	v_rcp_f32_e32 v102, v102
	v_rcp_f32_e32 v103, v103
	s_waitcnt vmcnt(7)
	v_fmac_f32_e32 v72, v100, v104
	v_fmac_f32_e32 v73, v101, v105
	v_fmac_f32_e32 v74, v102, v106
	v_fmac_f32_e32 v75, v103, v107
	global_store_dwordx4 v64, v[72:75], s[20:21] offset:32
	v_mul_f32_e32 v100, 0xbfb8aa3b, v24
	v_mul_f32_e32 v101, 0xbfb8aa3b, v25
	v_mul_f32_e32 v102, 0xbfb8aa3b, v26
	v_mul_f32_e32 v103, 0xbfb8aa3b, v27
	v_exp_f32_e32 v100, v100
	v_exp_f32_e32 v101, v101
	v_exp_f32_e32 v102, v102
	v_exp_f32_e32 v103, v103
	v_lshlrev_b32_e32 v104, 16, v130
	v_and_b32_e32 v105, 0xffff0000, v130
	v_lshlrev_b32_e32 v106, 16, v129
	v_and_b32_e32 v107, 0xffff0000, v129
	v_add_f32_e32 v100, 1.0, v100
	v_add_f32_e32 v101, 1.0, v101
	v_add_f32_e32 v102, 1.0, v102
	v_add_f32_e32 v103, 1.0, v103
	v_rcp_f32_e32 v100, v100
	v_rcp_f32_e32 v101, v101
	v_rcp_f32_e32 v102, v102
	v_rcp_f32_e32 v103, v103
	s_waitcnt vmcnt(7)
	v_fmac_f32_e32 v76, v100, v104
	v_fmac_f32_e32 v77, v101, v105
	v_fmac_f32_e32 v78, v102, v106
	v_fmac_f32_e32 v79, v103, v107
	global_store_dwordx4 v64, v[76:79], s[20:21] offset:64
	v_mul_f32_e32 v100, 0xbfb8aa3b, v28
	v_mul_f32_e32 v101, 0xbfb8aa3b, v29
	v_mul_f32_e32 v102, 0xbfb8aa3b, v30
	v_mul_f32_e32 v103, 0xbfb8aa3b, v31
	v_exp_f32_e32 v100, v100
	v_exp_f32_e32 v101, v101
	v_exp_f32_e32 v102, v102
	v_exp_f32_e32 v103, v103
	v_lshlrev_b32_e32 v104, 16, v128
	v_and_b32_e32 v105, 0xffff0000, v128
	v_lshlrev_b32_e32 v106, 16, v127
	v_and_b32_e32 v107, 0xffff0000, v127
	v_add_f32_e32 v100, 1.0, v100
	v_add_f32_e32 v101, 1.0, v101
	v_add_f32_e32 v102, 1.0, v102
	v_add_f32_e32 v103, 1.0, v103
	v_rcp_f32_e32 v100, v100
	v_rcp_f32_e32 v101, v101
	v_rcp_f32_e32 v102, v102
	v_rcp_f32_e32 v103, v103
	s_waitcnt vmcnt(7)
	v_fmac_f32_e32 v80, v100, v104
	v_fmac_f32_e32 v81, v101, v105
	v_fmac_f32_e32 v82, v102, v106
	v_fmac_f32_e32 v83, v103, v107
	global_store_dwordx4 v64, v[80:83], s[20:21] offset:96
	v_mul_f32_e32 v100, 0xbfb8aa3b, v0
	v_mul_f32_e32 v101, 0xbfb8aa3b, v1
	v_mul_f32_e32 v102, 0xbfb8aa3b, v2
	v_mul_f32_e32 v103, 0xbfb8aa3b, v3
	v_exp_f32_e32 v100, v100
	v_exp_f32_e32 v101, v101
	v_exp_f32_e32 v102, v102
	v_exp_f32_e32 v103, v103
	v_lshlrev_b32_e32 v104, 16, v126
	v_and_b32_e32 v105, 0xffff0000, v126
	v_lshlrev_b32_e32 v106, 16, v125
	v_and_b32_e32 v107, 0xffff0000, v125
	v_add_f32_e32 v100, 1.0, v100
	v_add_f32_e32 v101, 1.0, v101
	v_add_f32_e32 v102, 1.0, v102
	v_add_f32_e32 v103, 1.0, v103
	v_rcp_f32_e32 v100, v100
	v_rcp_f32_e32 v101, v101
	v_rcp_f32_e32 v102, v102
	v_rcp_f32_e32 v103, v103
	s_waitcnt vmcnt(7)
	v_fmac_f32_e32 v84, v100, v104
	v_fmac_f32_e32 v85, v101, v105
	v_fmac_f32_e32 v86, v102, v106
	v_fmac_f32_e32 v87, v103, v107
	global_store_dwordx4 v65, v[84:87], s[20:21]
	v_mul_f32_e32 v100, 0xbfb8aa3b, v4
	v_mul_f32_e32 v101, 0xbfb8aa3b, v5
	v_mul_f32_e32 v102, 0xbfb8aa3b, v6
	v_mul_f32_e32 v103, 0xbfb8aa3b, v7
	v_exp_f32_e32 v100, v100
	v_exp_f32_e32 v101, v101
	v_exp_f32_e32 v102, v102
	v_exp_f32_e32 v103, v103
	v_lshlrev_b32_e32 v104, 16, v124
	v_and_b32_e32 v105, 0xffff0000, v124
	v_lshlrev_b32_e32 v106, 16, v123
	v_and_b32_e32 v107, 0xffff0000, v123
	v_add_f32_e32 v100, 1.0, v100
	v_add_f32_e32 v101, 1.0, v101
	v_add_f32_e32 v102, 1.0, v102
	v_add_f32_e32 v103, 1.0, v103
	v_rcp_f32_e32 v100, v100
	v_rcp_f32_e32 v101, v101
	v_rcp_f32_e32 v102, v102
	v_rcp_f32_e32 v103, v103
	s_waitcnt vmcnt(7)
	v_fmac_f32_e32 v88, v100, v104
	v_fmac_f32_e32 v89, v101, v105
	v_fmac_f32_e32 v90, v102, v106
	v_fmac_f32_e32 v91, v103, v107
	global_store_dwordx4 v65, v[88:91], s[20:21] offset:32
	v_mul_f32_e32 v100, 0xbfb8aa3b, v8
	v_mul_f32_e32 v101, 0xbfb8aa3b, v9
	v_mul_f32_e32 v102, 0xbfb8aa3b, v10
	v_mul_f32_e32 v103, 0xbfb8aa3b, v11
	v_exp_f32_e32 v100, v100
	v_exp_f32_e32 v101, v101
	v_exp_f32_e32 v102, v102
	v_exp_f32_e32 v103, v103
	v_lshlrev_b32_e32 v104, 16, v122
	v_and_b32_e32 v105, 0xffff0000, v122
	v_lshlrev_b32_e32 v106, 16, v121
	v_and_b32_e32 v107, 0xffff0000, v121
	v_add_f32_e32 v100, 1.0, v100
	v_add_f32_e32 v101, 1.0, v101
	v_add_f32_e32 v102, 1.0, v102
	v_add_f32_e32 v103, 1.0, v103
	v_rcp_f32_e32 v100, v100
	v_rcp_f32_e32 v101, v101
	v_rcp_f32_e32 v102, v102
	v_rcp_f32_e32 v103, v103
	s_waitcnt vmcnt(7)
	v_fmac_f32_e32 v92, v100, v104
	v_fmac_f32_e32 v93, v101, v105
	v_fmac_f32_e32 v94, v102, v106
	v_fmac_f32_e32 v95, v103, v107
	global_store_dwordx4 v65, v[92:95], s[20:21] offset:64
	v_mul_f32_e32 v100, 0xbfb8aa3b, v12
	v_mul_f32_e32 v101, 0xbfb8aa3b, v13
	v_mul_f32_e32 v102, 0xbfb8aa3b, v14
	v_mul_f32_e32 v103, 0xbfb8aa3b, v15
	v_exp_f32_e32 v100, v100
	v_exp_f32_e32 v101, v101
	v_exp_f32_e32 v102, v102
	v_exp_f32_e32 v103, v103
	v_lshlrev_b32_e32 v104, 16, v120
	v_and_b32_e32 v105, 0xffff0000, v120
	v_lshlrev_b32_e32 v106, 16, v119
	v_and_b32_e32 v107, 0xffff0000, v119
	v_add_f32_e32 v100, 1.0, v100
	v_add_f32_e32 v101, 1.0, v101
	v_add_f32_e32 v102, 1.0, v102
	v_add_f32_e32 v103, 1.0, v103
	v_rcp_f32_e32 v100, v100
	v_rcp_f32_e32 v101, v101
	v_rcp_f32_e32 v102, v102
	v_rcp_f32_e32 v103, v103
	s_waitcnt vmcnt(7)
	v_fmac_f32_e32 v96, v100, v104
	v_fmac_f32_e32 v97, v101, v105
	v_fmac_f32_e32 v98, v102, v106
	v_fmac_f32_e32 v99, v103, v107
	global_store_dwordx4 v65, v[96:99], s[20:21] offset:96
	v_readlane_b32 s0, v252, 22
	s_nop 3
	s_add_i32 s16, s16, s0
	s_cmp_ge_i32 s16, s41
	s_cbranch_scc1 .LBB0_2461
